# all_gemm_loop_trims_plus_compressed_softmax_rewrite
# speedup vs baseline: 1.0073x; 1.0073x over previous
.LBB0_150:
	ds_read_b128 v[152:155], v148
	ds_read_b128 v[156:159], v148 offset:1024
	ds_read_b128 v[160:163], v148 offset:2048
	ds_read_b128 v[164:167], v148 offset:3072
	s_add_u32 s40, s38, 0xfffc0080
	s_addc_u32 s41, s39, -1
	s_cmp_eq_u32 s75, 12
	s_cselect_b32 s43, s13, s41
	s_cselect_b32 s42, s37, s40
	s_cselect_b32 s41, s9, s74
	s_cselect_b32 s40, s72, s73
	v_lshl_add_u64 v[200:201], s[38:39], 0, v[136:137]
	s_add_i32 m0, s51, 0xc000
	ds_read_b128 v[168:171], v149
	ds_read_b128 v[172:175], v149 offset:1024
	ds_read_b128 v[176:179], v149 offset:2048
	ds_read_b128 v[180:183], v149 offset:3072
	ds_read_b128 v[184:187], v149 offset:4096
	ds_read_b128 v[188:191], v149 offset:5120
	ds_read_b128 v[192:195], v149 offset:6144
	ds_read_b128 v[196:199], v149 offset:7168
	global_load_lds_dwordx4 v[200:201], off
	s_add_i32 m0, s51, 0xe000
	v_lshl_add_u64 v[200:201], s[38:39], 0, v[138:139]
	global_load_lds_dwordx4 v[200:201], off
	s_waitcnt lgkmcnt(8)
	s_setprio 1
	s_barrier
	s_waitcnt lgkmcnt(0)
	v_mfma_f32_16x16x32_bf16 v[124:127], v[152:155], v[168:171], v[124:127]
	v_mfma_f32_16x16x32_bf16 v[120:123], v[160:163], v[168:171], v[120:123]
	v_mfma_f32_16x16x32_bf16 v[116:119], v[152:155], v[176:179], v[116:119]
	v_mfma_f32_16x16x32_bf16 v[112:115], v[160:163], v[176:179], v[112:115]
	v_mfma_f32_16x16x32_bf16 v[108:111], v[152:155], v[184:187], v[108:111]
	v_mfma_f32_16x16x32_bf16 v[104:107], v[160:163], v[184:187], v[104:107]
	v_mfma_f32_16x16x32_bf16 v[100:103], v[152:155], v[192:195], v[100:103]
	v_mfma_f32_16x16x32_bf16 v[96:99], v[160:163], v[192:195], v[96:99]
	v_mfma_f32_16x16x32_bf16 v[124:127], v[156:159], v[172:175], v[124:127]
	v_mfma_f32_16x16x32_bf16 v[120:123], v[164:167], v[172:175], v[120:123]
	v_mfma_f32_16x16x32_bf16 v[116:119], v[156:159], v[180:183], v[116:119]
	v_mfma_f32_16x16x32_bf16 v[112:115], v[164:167], v[180:183], v[112:115]
	v_mfma_f32_16x16x32_bf16 v[108:111], v[156:159], v[188:191], v[108:111]
	v_mfma_f32_16x16x32_bf16 v[104:107], v[164:167], v[188:191], v[104:107]
	v_mfma_f32_16x16x32_bf16 v[100:103], v[156:159], v[196:199], v[100:103]
	v_mfma_f32_16x16x32_bf16 v[96:99], v[164:167], v[196:199], v[96:99]
	s_barrier
	s_setprio 0
	s_add_i32 s76, s69, s48
	v_lshl_add_u64 v[208:209], s[40:41], 0, v[132:133]
	s_mov_b32 m0, s76
	ds_read_b128 v[200:203], v150
	ds_read_b128 v[204:207], v150 offset:1024
	ds_read_b128 v[212:215], v150 offset:2048
	ds_read_b128 v[216:219], v150 offset:3072
	global_load_lds_dwordx4 v[208:209], off
	s_add_i32 m0, s76, 0x2000
	v_lshl_add_u64 v[220:221], s[40:41], 0, v[128:129]
	global_load_lds_dwordx4 v[220:221], off
	s_setprio 1
	s_barrier
	s_waitcnt lgkmcnt(0)
	v_mfma_f32_16x16x32_bf16 v[76:79], v[200:203], v[168:171], v[76:79]
	v_mfma_f32_16x16x32_bf16 v[72:75], v[212:215], v[168:171], v[72:75]
	v_mfma_f32_16x16x32_bf16 v[60:63], v[200:203], v[176:179], v[60:63]
	v_mfma_f32_16x16x32_bf16 v[56:59], v[212:215], v[176:179], v[56:59]
	v_mfma_f32_16x16x32_bf16 v[44:47], v[200:203], v[184:187], v[44:47]
	v_mfma_f32_16x16x32_bf16 v[40:43], v[212:215], v[184:187], v[40:43]
	v_mfma_f32_16x16x32_bf16 v[36:39], v[200:203], v[192:195], v[36:39]
	v_mfma_f32_16x16x32_bf16 v[32:35], v[212:215], v[192:195], v[32:35]
	v_mfma_f32_16x16x32_bf16 v[76:79], v[204:207], v[172:175], v[76:79]
	v_mfma_f32_16x16x32_bf16 v[72:75], v[216:219], v[172:175], v[72:75]
	v_mfma_f32_16x16x32_bf16 v[60:63], v[204:207], v[180:183], v[60:63]
	v_mfma_f32_16x16x32_bf16 v[56:59], v[216:219], v[180:183], v[56:59]
	v_mfma_f32_16x16x32_bf16 v[44:47], v[204:207], v[188:191], v[44:47]
	v_mfma_f32_16x16x32_bf16 v[40:43], v[216:219], v[188:191], v[40:43]
	v_mfma_f32_16x16x32_bf16 v[36:39], v[204:207], v[196:199], v[36:39]
	v_mfma_f32_16x16x32_bf16 v[32:35], v[216:219], v[196:199], v[32:35]
	s_barrier
	s_setprio 0
	s_mov_b32 m0, s51
	v_lshl_add_u64 v[222:223], s[42:43], 0, v[134:135]
	ds_read_b128 v[168:171], v149 offset:16384
	ds_read_b128 v[172:175], v149 offset:17408
	ds_read_b128 v[176:179], v149 offset:18432
	ds_read_b128 v[180:183], v149 offset:19456
	ds_read_b128 v[184:187], v149 offset:20480
	ds_read_b128 v[188:191], v149 offset:21504
	ds_read_b128 v[192:195], v149 offset:22528
	ds_read_b128 v[196:199], v149 offset:23552
	global_load_lds_dwordx4 v[222:223], off
	s_mov_b32 m0, s54
	v_lshl_add_u64 v[224:225], s[42:43], 0, v[130:131]
	global_load_lds_dwordx4 v[224:225], off
	s_setprio 1
	s_barrier
	s_waitcnt lgkmcnt(0)
	v_mfma_f32_16x16x32_bf16 v[92:95], v[152:155], v[168:171], v[92:95]
	v_mfma_f32_16x16x32_bf16 v[88:91], v[160:163], v[168:171], v[88:91]
	v_mfma_f32_16x16x32_bf16 v[84:87], v[152:155], v[176:179], v[84:87]
	v_mfma_f32_16x16x32_bf16 v[80:83], v[160:163], v[176:179], v[80:83]
	v_mfma_f32_16x16x32_bf16 v[68:71], v[152:155], v[184:187], v[68:71]
	v_mfma_f32_16x16x32_bf16 v[64:67], v[160:163], v[184:187], v[64:67]
	v_mfma_f32_16x16x32_bf16 v[52:55], v[152:155], v[192:195], v[52:55]
	v_mfma_f32_16x16x32_bf16 v[48:51], v[160:163], v[192:195], v[48:51]
	v_mfma_f32_16x16x32_bf16 v[92:95], v[156:159], v[172:175], v[92:95]
	v_mfma_f32_16x16x32_bf16 v[88:91], v[164:167], v[172:175], v[88:91]
	v_mfma_f32_16x16x32_bf16 v[84:87], v[156:159], v[180:183], v[84:87]
	v_mfma_f32_16x16x32_bf16 v[80:83], v[164:167], v[180:183], v[80:83]
	v_mfma_f32_16x16x32_bf16 v[68:71], v[156:159], v[188:191], v[68:71]
	v_mfma_f32_16x16x32_bf16 v[64:67], v[164:167], v[188:191], v[64:67]
	v_mfma_f32_16x16x32_bf16 v[52:55], v[156:159], v[196:199], v[52:55]
	v_mfma_f32_16x16x32_bf16 v[48:51], v[164:167], v[196:199], v[48:51]
	s_barrier
	s_setprio 0
	s_add_u32 s76, s40, 0x40000
	s_addc_u32 s77, s41, 0
	s_add_i32 s78, s70, s48
	s_mov_b32 m0, s78
	v_lshl_add_u64 v[152:153], s[76:77], 0, v[132:133]
	global_load_lds_dwordx4 v[152:153], off
	s_add_i32 m0, s78, 0x2000
	v_lshl_add_u64 v[152:153], s[76:77], 0, v[128:129]
	global_load_lds_dwordx4 v[152:153], off
	s_waitcnt vmcnt(6)
	s_setprio 1
	s_barrier
	v_mfma_f32_16x16x32_bf16 v[28:31], v[200:203], v[168:171], v[28:31]
	v_mfma_f32_16x16x32_bf16 v[24:27], v[212:215], v[168:171], v[24:27]
	v_mfma_f32_16x16x32_bf16 v[20:23], v[200:203], v[176:179], v[20:23]
	v_mfma_f32_16x16x32_bf16 v[16:19], v[212:215], v[176:179], v[16:19]
	v_mfma_f32_16x16x32_bf16 v[12:15], v[200:203], v[184:187], v[12:15]
	v_mfma_f32_16x16x32_bf16 v[8:11], v[212:215], v[184:187], v[8:11]
	v_mfma_f32_16x16x32_bf16 v[4:7], v[200:203], v[192:195], v[4:7]
	v_mfma_f32_16x16x32_bf16 v[0:3], v[212:215], v[192:195], v[0:3]
	v_mfma_f32_16x16x32_bf16 v[28:31], v[204:207], v[172:175], v[28:31]
	v_mfma_f32_16x16x32_bf16 v[24:27], v[216:219], v[172:175], v[24:27]
	v_mfma_f32_16x16x32_bf16 v[20:23], v[204:207], v[180:183], v[20:23]
	v_mfma_f32_16x16x32_bf16 v[16:19], v[216:219], v[180:183], v[16:19]
	v_mfma_f32_16x16x32_bf16 v[12:15], v[204:207], v[188:191], v[12:15]
	v_mfma_f32_16x16x32_bf16 v[8:11], v[216:219], v[188:191], v[8:11]
	v_mfma_f32_16x16x32_bf16 v[4:7], v[204:207], v[196:199], v[4:7]
	v_mfma_f32_16x16x32_bf16 v[0:3], v[216:219], v[196:199], v[0:3]
	s_barrier
	s_setprio 0
	s_add_i32 s76, 0, 0x18000
	v_add_u32_e32 v151, s76, v146
	ds_read_b128 v[152:155], v151
	ds_read_b128 v[156:159], v151 offset:1024
	ds_read_b128 v[160:163], v151 offset:2048
	ds_read_b128 v[164:167], v151 offset:3072
	s_add_u32 s42, s42, 0x40000
	s_addc_u32 s43, s43, 0
	s_mov_b32 m0, s55
	v_lshl_add_u64 v[200:201], s[42:43], 0, v[134:135]
	ds_read_b128 v[168:171], v149 offset:32768
	ds_read_b128 v[172:175], v149 offset:33792
	ds_read_b128 v[176:179], v149 offset:34816
	ds_read_b128 v[180:183], v149 offset:35840
	ds_read_b128 v[184:187], v149 offset:36864
	ds_read_b128 v[188:191], v149 offset:37888
	ds_read_b128 v[192:195], v149 offset:38912
	ds_read_b128 v[196:199], v149 offset:39936
	global_load_lds_dwordx4 v[200:201], off
	s_mov_b32 m0, s62
	v_lshl_add_u64 v[200:201], s[42:43], 0, v[130:131]
	global_load_lds_dwordx4 v[200:201], off
	s_waitcnt lgkmcnt(8)
	s_setprio 1
	s_barrier
	s_waitcnt lgkmcnt(0)
	v_mfma_f32_16x16x32_bf16 v[124:127], v[152:155], v[168:171], v[124:127]
	v_mfma_f32_16x16x32_bf16 v[120:123], v[160:163], v[168:171], v[120:123]
	v_mfma_f32_16x16x32_bf16 v[116:119], v[152:155], v[176:179], v[116:119]
	v_mfma_f32_16x16x32_bf16 v[112:115], v[160:163], v[176:179], v[112:115]
	v_mfma_f32_16x16x32_bf16 v[108:111], v[152:155], v[184:187], v[108:111]
	v_mfma_f32_16x16x32_bf16 v[104:107], v[160:163], v[184:187], v[104:107]
	v_mfma_f32_16x16x32_bf16 v[100:103], v[152:155], v[192:195], v[100:103]
	v_mfma_f32_16x16x32_bf16 v[96:99], v[160:163], v[192:195], v[96:99]
	v_mfma_f32_16x16x32_bf16 v[124:127], v[156:159], v[172:175], v[124:127]
	v_mfma_f32_16x16x32_bf16 v[120:123], v[164:167], v[172:175], v[120:123]
	v_mfma_f32_16x16x32_bf16 v[116:119], v[156:159], v[180:183], v[116:119]
	v_mfma_f32_16x16x32_bf16 v[112:115], v[164:167], v[180:183], v[112:115]
	v_mfma_f32_16x16x32_bf16 v[108:111], v[156:159], v[188:191], v[108:111]
	v_mfma_f32_16x16x32_bf16 v[104:107], v[164:167], v[188:191], v[104:107]
	v_mfma_f32_16x16x32_bf16 v[100:103], v[156:159], v[196:199], v[100:103]
	v_mfma_f32_16x16x32_bf16 v[96:99], v[164:167], v[196:199], v[96:99]
	s_barrier
	s_setprio 0
	s_add_i32 s42, 0, 0x1c000
	s_add_i32 s43, s76, s48
	v_add_u32_e32 v151, s42, v146
	v_lshl_add_u64 v[208:209], v[208:209], 0, s[0:1]
	s_mov_b32 m0, s43
	ds_read_b128 v[200:203], v151
	ds_read_b128 v[204:207], v151 offset:1024
	ds_read_b128 v[212:215], v151 offset:2048
	ds_read_b128 v[216:219], v151 offset:3072
	global_load_lds_dwordx4 v[208:209], off
	s_add_i32 m0, s43, 0x2000
	v_lshl_add_u64 v[208:209], v[220:221], 0, s[0:1]
	global_load_lds_dwordx4 v[208:209], off
	s_setprio 1
	s_barrier
	s_waitcnt lgkmcnt(0)
	v_mfma_f32_16x16x32_bf16 v[76:79], v[200:203], v[168:171], v[76:79]
	v_mfma_f32_16x16x32_bf16 v[72:75], v[212:215], v[168:171], v[72:75]
	v_mfma_f32_16x16x32_bf16 v[60:63], v[200:203], v[176:179], v[60:63]
	v_mfma_f32_16x16x32_bf16 v[56:59], v[212:215], v[176:179], v[56:59]
	v_mfma_f32_16x16x32_bf16 v[44:47], v[200:203], v[184:187], v[44:47]
	v_mfma_f32_16x16x32_bf16 v[40:43], v[212:215], v[184:187], v[40:43]
	v_mfma_f32_16x16x32_bf16 v[36:39], v[200:203], v[192:195], v[36:39]
	v_mfma_f32_16x16x32_bf16 v[32:35], v[212:215], v[192:195], v[32:35]
	v_mfma_f32_16x16x32_bf16 v[76:79], v[204:207], v[172:175], v[76:79]
	v_mfma_f32_16x16x32_bf16 v[72:75], v[216:219], v[172:175], v[72:75]
	v_mfma_f32_16x16x32_bf16 v[60:63], v[204:207], v[180:183], v[60:63]
	v_mfma_f32_16x16x32_bf16 v[56:59], v[216:219], v[180:183], v[56:59]
	v_mfma_f32_16x16x32_bf16 v[44:47], v[204:207], v[188:191], v[44:47]
	v_mfma_f32_16x16x32_bf16 v[40:43], v[216:219], v[188:191], v[40:43]
	v_mfma_f32_16x16x32_bf16 v[36:39], v[204:207], v[196:199], v[36:39]
	v_mfma_f32_16x16x32_bf16 v[32:35], v[216:219], v[196:199], v[32:35]
	s_barrier
	s_setprio 0
	s_mov_b32 m0, s63
	v_lshl_add_u64 v[208:209], v[222:223], 0, s[0:1]
	ds_read_b128 v[168:171], v149 offset:49152
	ds_read_b128 v[172:175], v149 offset:50176
	ds_read_b128 v[176:179], v149 offset:51200
	ds_read_b128 v[180:183], v149 offset:52224
	ds_read_b128 v[184:187], v149 offset:53248
	ds_read_b128 v[188:191], v149 offset:54272
	ds_read_b128 v[192:195], v149 offset:55296
	ds_read_b128 v[196:199], v149 offset:56320
	global_load_lds_dwordx4 v[208:209], off
	s_mov_b32 m0, s64
	v_lshl_add_u64 v[208:209], v[224:225], 0, s[0:1]
	global_load_lds_dwordx4 v[208:209], off
	s_setprio 1
	s_barrier
	s_waitcnt lgkmcnt(0)
	v_mfma_f32_16x16x32_bf16 v[92:95], v[152:155], v[168:171], v[92:95]
	v_mfma_f32_16x16x32_bf16 v[88:91], v[160:163], v[168:171], v[88:91]
	v_mfma_f32_16x16x32_bf16 v[84:87], v[152:155], v[176:179], v[84:87]
	v_mfma_f32_16x16x32_bf16 v[80:83], v[160:163], v[176:179], v[80:83]
	v_mfma_f32_16x16x32_bf16 v[68:71], v[152:155], v[184:187], v[68:71]
	v_mfma_f32_16x16x32_bf16 v[64:67], v[160:163], v[184:187], v[64:67]
	v_mfma_f32_16x16x32_bf16 v[52:55], v[152:155], v[192:195], v[52:55]
	v_mfma_f32_16x16x32_bf16 v[48:51], v[160:163], v[192:195], v[48:51]
	v_mfma_f32_16x16x32_bf16 v[92:95], v[156:159], v[172:175], v[92:95]
	v_mfma_f32_16x16x32_bf16 v[88:91], v[164:167], v[172:175], v[88:91]
	v_mfma_f32_16x16x32_bf16 v[84:87], v[156:159], v[180:183], v[84:87]
	v_mfma_f32_16x16x32_bf16 v[80:83], v[164:167], v[180:183], v[80:83]
	v_mfma_f32_16x16x32_bf16 v[68:71], v[156:159], v[188:191], v[68:71]
	v_mfma_f32_16x16x32_bf16 v[64:67], v[164:167], v[188:191], v[64:67]
	v_mfma_f32_16x16x32_bf16 v[52:55], v[156:159], v[196:199], v[52:55]
	v_mfma_f32_16x16x32_bf16 v[48:51], v[164:167], v[196:199], v[48:51]
	s_barrier
	s_setprio 0
	s_add_u32 s40, s40, 0x40080
	s_addc_u32 s41, s41, 0
	s_add_i32 s42, s42, s48
	s_mov_b32 m0, s42
	v_lshl_add_u64 v[152:153], s[40:41], 0, v[132:133]
	global_load_lds_dwordx4 v[152:153], off
	s_add_i32 m0, s42, 0x2000
	v_lshl_add_u64 v[152:153], s[40:41], 0, v[128:129]
	global_load_lds_dwordx4 v[152:153], off
	s_waitcnt vmcnt(6)
	s_setprio 1
	s_barrier
	v_mfma_f32_16x16x32_bf16 v[28:31], v[200:203], v[168:171], v[28:31]
	v_mfma_f32_16x16x32_bf16 v[24:27], v[212:215], v[168:171], v[24:27]
	v_mfma_f32_16x16x32_bf16 v[20:23], v[200:203], v[176:179], v[20:23]
	v_mfma_f32_16x16x32_bf16 v[16:19], v[212:215], v[176:179], v[16:19]
	v_mfma_f32_16x16x32_bf16 v[12:15], v[200:203], v[184:187], v[12:15]
	v_mfma_f32_16x16x32_bf16 v[8:11], v[212:215], v[184:187], v[8:11]
	v_mfma_f32_16x16x32_bf16 v[4:7], v[200:203], v[192:195], v[4:7]
	v_mfma_f32_16x16x32_bf16 v[0:3], v[212:215], v[192:195], v[0:3]
	v_mfma_f32_16x16x32_bf16 v[28:31], v[204:207], v[172:175], v[28:31]
	v_mfma_f32_16x16x32_bf16 v[24:27], v[216:219], v[172:175], v[24:27]
	v_mfma_f32_16x16x32_bf16 v[20:23], v[204:207], v[180:183], v[20:23]
	v_mfma_f32_16x16x32_bf16 v[16:19], v[216:219], v[180:183], v[16:19]
	v_mfma_f32_16x16x32_bf16 v[12:15], v[204:207], v[188:191], v[12:15]
	v_mfma_f32_16x16x32_bf16 v[8:11], v[216:219], v[188:191], v[8:11]
	v_mfma_f32_16x16x32_bf16 v[4:7], v[204:207], v[196:199], v[4:7]
	v_mfma_f32_16x16x32_bf16 v[0:3], v[216:219], v[196:199], v[0:3]
	s_barrier
	s_setprio 0
	s_add_i32 s75, s75, 2
	s_add_u32 s38, s38, 0x100
	s_addc_u32 s39, s39, 0
	s_add_u32 s73, s73, 0x100
	s_addc_u32 s74, s74, 0
	s_cmp_gt_u32 s75, 13
	s_cbranch_scc0 .LBB0_150
	v_lshl_add_u32 v151, s36, 8, v144
	s_cmp_gt_i32 s71, 11
	s_mov_b64 s[36:37], -1
	s_cbranch_scc0 .LBB0_155
	s_and_saveexec_b64 s[36:37], s[2:3]
	s_cbranch_execz .LBB0_154
	v_lshl_or_b32 v152, v151, 8, v147
	v_readlane_b32 s38, v253, 59
	v_readlane_b32 s39, v253, 60
	v_or_b32_e32 v153, 0x1000, v152
	s_nop 3
	global_store_dwordx4 v153, v[116:119], s[38:39] nt
	v_or_b32_e32 v153, 0x2000, v152
	global_store_dwordx4 v153, v[108:111], s[38:39] nt
	v_or_b32_e32 v153, 0x3000, v152
	global_store_dwordx4 v153, v[100:103], s[38:39] nt
	v_add_u32_e32 v153, 0x8000, v152
	global_store_dwordx4 v153, v[92:95], s[38:39] nt
	v_add_u32_e32 v153, 0x9000, v152
	global_store_dwordx4 v153, v[84:87], s[38:39] nt
	v_add_u32_e32 v153, 0xa000, v152
	global_store_dwordx4 v153, v[68:71], s[38:39] nt
	v_add_u32_e32 v153, 0xb000, v152
	global_store_dwordx4 v153, v[52:55], s[38:39] nt
	v_or_b32_e32 v153, 16, v152
	global_store_dwordx4 v153, v[120:123], s[38:39] nt
	v_or_b32_e32 v153, 0x1010, v152
	global_store_dwordx4 v153, v[112:115], s[38:39] nt
	v_or_b32_e32 v153, 0x2010, v152
	global_store_dwordx4 v153, v[104:107], s[38:39] nt
	v_or_b32_e32 v153, 0x3010, v152
	global_store_dwordx4 v153, v[96:99], s[38:39] nt
	v_add_u32_e32 v153, 0x8010, v152
	global_store_dwordx4 v153, v[88:91], s[38:39] nt
	v_add_u32_e32 v153, 0x9010, v152
	global_store_dwordx4 v152, v[124:127], s[38:39] nt
	global_store_dwordx4 v153, v[80:83], s[38:39] nt
	v_add_u32_e32 v153, 0xa010, v152
	v_add_u32_e32 v152, 0xb010, v152
	global_store_dwordx4 v153, v[64:67], s[38:39] nt
	global_store_dwordx4 v152, v[48:51], s[38:39] nt

.LBB0_177:
	ds_read_b128 v[152:155], v149
	ds_read_b128 v[156:159], v149 offset:1024
	ds_read_b128 v[160:163], v149 offset:2048
	ds_read_b128 v[164:167], v149 offset:3072
	s_add_u32 s36, s34, 0xfffc0080
	s_addc_u32 s37, s35, -1
	s_cmp_eq_u32 s68, 12
	s_cselect_b32 s39, s9, s37
	s_cselect_b32 s38, s64, s36
	s_cselect_b32 s37, s3, s67
	s_cselect_b32 s36, s65, s66
	v_lshl_add_u64 v[144:145], s[34:35], 0, v[136:137]
	s_add_i32 m0, s13, 0xc000
	ds_read_b128 v[168:171], v150
	ds_read_b128 v[172:175], v150 offset:1024
	ds_read_b128 v[176:179], v150 offset:2048
	ds_read_b128 v[180:183], v150 offset:3072
	ds_read_b128 v[184:187], v150 offset:4096
	ds_read_b128 v[188:191], v150 offset:5120
	ds_read_b128 v[192:195], v150 offset:6144
	ds_read_b128 v[196:199], v150 offset:7168
	global_load_lds_dwordx4 v[144:145], off
	s_add_i32 m0, s13, 0xe000
	v_lshl_add_u64 v[144:145], s[34:35], 0, v[138:139]
	global_load_lds_dwordx4 v[144:145], off
	s_waitcnt lgkmcnt(8)
	s_setprio 1
	s_barrier
	s_waitcnt lgkmcnt(0)
	v_mfma_f32_16x16x32_bf16 v[124:127], v[152:155], v[168:171], v[124:127]
	v_mfma_f32_16x16x32_bf16 v[120:123], v[160:163], v[168:171], v[120:123]
	v_mfma_f32_16x16x32_bf16 v[112:115], v[152:155], v[176:179], v[112:115]
	v_mfma_f32_16x16x32_bf16 v[104:107], v[160:163], v[176:179], v[104:107]
	v_mfma_f32_16x16x32_bf16 v[96:99], v[152:155], v[184:187], v[96:99]
	v_mfma_f32_16x16x32_bf16 v[88:91], v[160:163], v[184:187], v[88:91]
	v_mfma_f32_16x16x32_bf16 v[80:83], v[152:155], v[192:195], v[80:83]
	v_mfma_f32_16x16x32_bf16 v[72:75], v[160:163], v[192:195], v[72:75]
	v_mfma_f32_16x16x32_bf16 v[124:127], v[156:159], v[172:175], v[124:127]
	v_mfma_f32_16x16x32_bf16 v[120:123], v[164:167], v[172:175], v[120:123]
	v_mfma_f32_16x16x32_bf16 v[112:115], v[156:159], v[180:183], v[112:115]
	v_mfma_f32_16x16x32_bf16 v[104:107], v[164:167], v[180:183], v[104:107]
	v_mfma_f32_16x16x32_bf16 v[96:99], v[156:159], v[188:191], v[96:99]
	v_mfma_f32_16x16x32_bf16 v[88:91], v[164:167], v[188:191], v[88:91]
	v_mfma_f32_16x16x32_bf16 v[80:83], v[156:159], v[196:199], v[80:83]
	v_mfma_f32_16x16x32_bf16 v[72:75], v[164:167], v[196:199], v[72:75]
	s_barrier
	s_setprio 0
	s_add_i32 s69, s55, s42
	v_lshl_add_u64 v[144:145], s[36:37], 0, v[130:131]
	s_mov_b32 m0, s69
	ds_read_b128 v[200:203], v151
	ds_read_b128 v[204:207], v151 offset:1024
	ds_read_b128 v[212:215], v151 offset:2048
	ds_read_b128 v[216:219], v151 offset:3072
	global_load_lds_dwordx4 v[144:145], off
	s_add_i32 m0, s69, 0x2000
	v_lshl_add_u64 v[208:209], s[36:37], 0, v[134:135]
	global_load_lds_dwordx4 v[208:209], off
	s_setprio 1
	s_barrier
	s_waitcnt lgkmcnt(0)
	v_mfma_f32_16x16x32_bf16 v[116:119], v[200:203], v[168:171], v[116:119]
	v_mfma_f32_16x16x32_bf16 v[108:111], v[212:215], v[168:171], v[108:111]
	v_mfma_f32_16x16x32_bf16 v[100:103], v[200:203], v[176:179], v[100:103]
	v_mfma_f32_16x16x32_bf16 v[92:95], v[212:215], v[176:179], v[92:95]
	v_mfma_f32_16x16x32_bf16 v[84:87], v[200:203], v[184:187], v[84:87]
	v_mfma_f32_16x16x32_bf16 v[76:79], v[212:215], v[184:187], v[76:79]
	v_mfma_f32_16x16x32_bf16 v[68:71], v[200:203], v[192:195], v[68:71]
	v_mfma_f32_16x16x32_bf16 v[64:67], v[212:215], v[192:195], v[64:67]
	v_mfma_f32_16x16x32_bf16 v[116:119], v[204:207], v[172:175], v[116:119]
	v_mfma_f32_16x16x32_bf16 v[108:111], v[216:219], v[172:175], v[108:111]
	v_mfma_f32_16x16x32_bf16 v[100:103], v[204:207], v[180:183], v[100:103]
	v_mfma_f32_16x16x32_bf16 v[92:95], v[216:219], v[180:183], v[92:95]
	v_mfma_f32_16x16x32_bf16 v[84:87], v[204:207], v[188:191], v[84:87]
	v_mfma_f32_16x16x32_bf16 v[76:79], v[216:219], v[188:191], v[76:79]
	v_mfma_f32_16x16x32_bf16 v[68:71], v[204:207], v[196:199], v[68:71]
	v_mfma_f32_16x16x32_bf16 v[64:67], v[216:219], v[196:199], v[64:67]
	s_barrier
	s_setprio 0
	s_mov_b32 m0, s13
	v_lshl_add_u64 v[220:221], s[38:39], 0, v[128:129]
	ds_read_b128 v[168:171], v150 offset:16384
	ds_read_b128 v[172:175], v150 offset:17408
	ds_read_b128 v[176:179], v150 offset:18432
	ds_read_b128 v[180:183], v150 offset:19456
	ds_read_b128 v[184:187], v150 offset:20480
	ds_read_b128 v[188:191], v150 offset:21504
	ds_read_b128 v[192:195], v150 offset:22528
	ds_read_b128 v[196:199], v150 offset:23552
	global_load_lds_dwordx4 v[220:221], off
	s_mov_b32 m0, s43
	v_lshl_add_u64 v[222:223], s[38:39], 0, v[132:133]
	global_load_lds_dwordx4 v[222:223], off
	s_setprio 1
	s_barrier
	s_waitcnt lgkmcnt(0)
	v_mfma_f32_16x16x32_bf16 v[60:63], v[152:155], v[168:171], v[60:63]
	v_mfma_f32_16x16x32_bf16 v[56:59], v[160:163], v[168:171], v[56:59]
	v_mfma_f32_16x16x32_bf16 v[52:55], v[152:155], v[176:179], v[52:55]
	v_mfma_f32_16x16x32_bf16 v[44:47], v[160:163], v[176:179], v[44:47]
	v_mfma_f32_16x16x32_bf16 v[36:39], v[152:155], v[184:187], v[36:39]
	v_mfma_f32_16x16x32_bf16 v[28:31], v[160:163], v[184:187], v[28:31]
	v_mfma_f32_16x16x32_bf16 v[20:23], v[152:155], v[192:195], v[20:23]
	v_mfma_f32_16x16x32_bf16 v[12:15], v[160:163], v[192:195], v[12:15]
	v_mfma_f32_16x16x32_bf16 v[60:63], v[156:159], v[172:175], v[60:63]
	v_mfma_f32_16x16x32_bf16 v[56:59], v[164:167], v[172:175], v[56:59]
	v_mfma_f32_16x16x32_bf16 v[52:55], v[156:159], v[180:183], v[52:55]
	v_mfma_f32_16x16x32_bf16 v[44:47], v[164:167], v[180:183], v[44:47]
	v_mfma_f32_16x16x32_bf16 v[36:39], v[156:159], v[188:191], v[36:39]
	v_mfma_f32_16x16x32_bf16 v[28:31], v[164:167], v[188:191], v[28:31]
	v_mfma_f32_16x16x32_bf16 v[20:23], v[156:159], v[196:199], v[20:23]
	v_mfma_f32_16x16x32_bf16 v[12:15], v[164:167], v[196:199], v[12:15]
	s_barrier
	s_setprio 0
	s_add_u32 s70, s36, 0x40000
	s_addc_u32 s71, s37, 0
	s_add_i32 s69, s62, s42
	s_mov_b32 m0, s69
	v_lshl_add_u64 v[152:153], s[70:71], 0, v[130:131]
	global_load_lds_dwordx4 v[152:153], off
	s_add_i32 m0, s69, 0x2000
	v_lshl_add_u64 v[152:153], s[70:71], 0, v[134:135]
	global_load_lds_dwordx4 v[152:153], off
	s_waitcnt vmcnt(6)
	s_setprio 1
	s_barrier
	v_mfma_f32_16x16x32_bf16 v[48:51], v[200:203], v[168:171], v[48:51]
	v_mfma_f32_16x16x32_bf16 v[40:43], v[212:215], v[168:171], v[40:43]
	v_mfma_f32_16x16x32_bf16 v[32:35], v[200:203], v[176:179], v[32:35]
	v_mfma_f32_16x16x32_bf16 v[24:27], v[212:215], v[176:179], v[24:27]
	v_mfma_f32_16x16x32_bf16 v[16:19], v[200:203], v[184:187], v[16:19]
	v_mfma_f32_16x16x32_bf16 v[8:11], v[212:215], v[184:187], v[8:11]
	v_mfma_f32_16x16x32_bf16 v[4:7], v[200:203], v[192:195], v[4:7]
	v_mfma_f32_16x16x32_bf16 v[0:3], v[212:215], v[192:195], v[0:3]
	v_mfma_f32_16x16x32_bf16 v[48:51], v[204:207], v[172:175], v[48:51]
	v_mfma_f32_16x16x32_bf16 v[40:43], v[216:219], v[172:175], v[40:43]
	v_mfma_f32_16x16x32_bf16 v[32:35], v[204:207], v[180:183], v[32:35]
	v_mfma_f32_16x16x32_bf16 v[24:27], v[216:219], v[180:183], v[24:27]
	v_mfma_f32_16x16x32_bf16 v[16:19], v[204:207], v[188:191], v[16:19]
	v_mfma_f32_16x16x32_bf16 v[8:11], v[216:219], v[188:191], v[8:11]
	v_mfma_f32_16x16x32_bf16 v[4:7], v[204:207], v[196:199], v[4:7]
	v_mfma_f32_16x16x32_bf16 v[0:3], v[216:219], v[196:199], v[0:3]
	s_barrier
	s_setprio 0
	s_add_i32 s69, 0, 0x18000
	v_add_u32_e32 v164, s69, v147
	ds_read_b128 v[152:155], v164
	ds_read_b128 v[156:159], v164 offset:1024
	ds_read_b128 v[160:163], v164 offset:2048
	ds_read_b128 v[164:167], v164 offset:3072
	s_add_u32 s38, s38, 0x40000
	s_addc_u32 s39, s39, 0
	s_mov_b32 m0, s48
	v_lshl_add_u64 v[200:201], s[38:39], 0, v[128:129]
	ds_read_b128 v[168:171], v150 offset:32768
	ds_read_b128 v[172:175], v150 offset:33792
	ds_read_b128 v[176:179], v150 offset:34816
	ds_read_b128 v[180:183], v150 offset:35840
	ds_read_b128 v[184:187], v150 offset:36864
	ds_read_b128 v[188:191], v150 offset:37888
	ds_read_b128 v[192:195], v150 offset:38912
	ds_read_b128 v[196:199], v150 offset:39936
	global_load_lds_dwordx4 v[200:201], off
	s_mov_b32 m0, s49
	v_lshl_add_u64 v[200:201], s[38:39], 0, v[132:133]
	global_load_lds_dwordx4 v[200:201], off
	s_waitcnt lgkmcnt(8)
	s_setprio 1
	s_barrier
	s_waitcnt lgkmcnt(0)
	v_mfma_f32_16x16x32_bf16 v[124:127], v[152:155], v[168:171], v[124:127]
	v_mfma_f32_16x16x32_bf16 v[120:123], v[160:163], v[168:171], v[120:123]
	v_mfma_f32_16x16x32_bf16 v[112:115], v[152:155], v[176:179], v[112:115]
	v_mfma_f32_16x16x32_bf16 v[104:107], v[160:163], v[176:179], v[104:107]
	v_mfma_f32_16x16x32_bf16 v[96:99], v[152:155], v[184:187], v[96:99]
	v_mfma_f32_16x16x32_bf16 v[88:91], v[160:163], v[184:187], v[88:91]
	v_mfma_f32_16x16x32_bf16 v[80:83], v[152:155], v[192:195], v[80:83]
	v_mfma_f32_16x16x32_bf16 v[72:75], v[160:163], v[192:195], v[72:75]
	v_mfma_f32_16x16x32_bf16 v[124:127], v[156:159], v[172:175], v[124:127]
	v_mfma_f32_16x16x32_bf16 v[120:123], v[164:167], v[172:175], v[120:123]
	v_mfma_f32_16x16x32_bf16 v[112:115], v[156:159], v[180:183], v[112:115]
	v_mfma_f32_16x16x32_bf16 v[104:107], v[164:167], v[180:183], v[104:107]
	v_mfma_f32_16x16x32_bf16 v[96:99], v[156:159], v[188:191], v[96:99]
	v_mfma_f32_16x16x32_bf16 v[88:91], v[164:167], v[188:191], v[88:91]
	v_mfma_f32_16x16x32_bf16 v[80:83], v[156:159], v[196:199], v[80:83]
	v_mfma_f32_16x16x32_bf16 v[72:75], v[164:167], v[196:199], v[72:75]
	s_barrier
	s_setprio 0
	s_add_i32 s38, 0, 0x1c000
	s_add_i32 s39, s69, s42
	v_add_u32_e32 v211, s38, v147
	v_lshl_add_u64 v[144:145], v[144:145], 0, s[0:1]
	s_mov_b32 m0, s39
	ds_read_b128 v[200:203], v211
	ds_read_b128 v[204:207], v211 offset:1024
	ds_read_b128 v[212:215], v211 offset:2048
	ds_read_b128 v[216:219], v211 offset:3072
	global_load_lds_dwordx4 v[144:145], off
	s_add_i32 m0, s39, 0x2000
	v_lshl_add_u64 v[144:145], v[208:209], 0, s[0:1]
	global_load_lds_dwordx4 v[144:145], off
	s_setprio 1
	s_barrier
	s_waitcnt lgkmcnt(0)
	v_mfma_f32_16x16x32_bf16 v[116:119], v[200:203], v[168:171], v[116:119]
	v_mfma_f32_16x16x32_bf16 v[108:111], v[212:215], v[168:171], v[108:111]
	v_mfma_f32_16x16x32_bf16 v[100:103], v[200:203], v[176:179], v[100:103]
	v_mfma_f32_16x16x32_bf16 v[92:95], v[212:215], v[176:179], v[92:95]
	v_mfma_f32_16x16x32_bf16 v[84:87], v[200:203], v[184:187], v[84:87]
	v_mfma_f32_16x16x32_bf16 v[76:79], v[212:215], v[184:187], v[76:79]
	v_mfma_f32_16x16x32_bf16 v[68:71], v[200:203], v[192:195], v[68:71]
	v_mfma_f32_16x16x32_bf16 v[64:67], v[212:215], v[192:195], v[64:67]
	v_mfma_f32_16x16x32_bf16 v[116:119], v[204:207], v[172:175], v[116:119]
	v_mfma_f32_16x16x32_bf16 v[108:111], v[216:219], v[172:175], v[108:111]
	v_mfma_f32_16x16x32_bf16 v[100:103], v[204:207], v[180:183], v[100:103]
	v_mfma_f32_16x16x32_bf16 v[92:95], v[216:219], v[180:183], v[92:95]
	v_mfma_f32_16x16x32_bf16 v[84:87], v[204:207], v[188:191], v[84:87]
	v_mfma_f32_16x16x32_bf16 v[76:79], v[216:219], v[188:191], v[76:79]
	v_mfma_f32_16x16x32_bf16 v[68:71], v[204:207], v[196:199], v[68:71]
	v_mfma_f32_16x16x32_bf16 v[64:67], v[216:219], v[196:199], v[64:67]
	s_barrier
	s_setprio 0
	s_mov_b32 m0, s51
	v_lshl_add_u64 v[144:145], v[220:221], 0, s[0:1]
	ds_read_b128 v[168:171], v150 offset:49152
	ds_read_b128 v[172:175], v150 offset:50176
	ds_read_b128 v[176:179], v150 offset:51200
	ds_read_b128 v[180:183], v150 offset:52224
	ds_read_b128 v[184:187], v150 offset:53248
	ds_read_b128 v[188:191], v150 offset:54272
	ds_read_b128 v[192:195], v150 offset:55296
	ds_read_b128 v[196:199], v150 offset:56320
	global_load_lds_dwordx4 v[144:145], off
	s_mov_b32 m0, s54
	v_lshl_add_u64 v[144:145], v[222:223], 0, s[0:1]
	global_load_lds_dwordx4 v[144:145], off
	s_setprio 1
	s_barrier
	s_waitcnt lgkmcnt(0)
	v_mfma_f32_16x16x32_bf16 v[60:63], v[152:155], v[168:171], v[60:63]
	v_mfma_f32_16x16x32_bf16 v[56:59], v[160:163], v[168:171], v[56:59]
	v_mfma_f32_16x16x32_bf16 v[52:55], v[152:155], v[176:179], v[52:55]
	v_mfma_f32_16x16x32_bf16 v[44:47], v[160:163], v[176:179], v[44:47]
	v_mfma_f32_16x16x32_bf16 v[36:39], v[152:155], v[184:187], v[36:39]
	v_mfma_f32_16x16x32_bf16 v[28:31], v[160:163], v[184:187], v[28:31]
	v_mfma_f32_16x16x32_bf16 v[20:23], v[152:155], v[192:195], v[20:23]
	v_mfma_f32_16x16x32_bf16 v[12:15], v[160:163], v[192:195], v[12:15]
	v_mfma_f32_16x16x32_bf16 v[60:63], v[156:159], v[172:175], v[60:63]
	v_mfma_f32_16x16x32_bf16 v[56:59], v[164:167], v[172:175], v[56:59]
	v_mfma_f32_16x16x32_bf16 v[52:55], v[156:159], v[180:183], v[52:55]
	v_mfma_f32_16x16x32_bf16 v[44:47], v[164:167], v[180:183], v[44:47]
	v_mfma_f32_16x16x32_bf16 v[36:39], v[156:159], v[188:191], v[36:39]
	v_mfma_f32_16x16x32_bf16 v[28:31], v[164:167], v[188:191], v[28:31]
	v_mfma_f32_16x16x32_bf16 v[20:23], v[156:159], v[196:199], v[20:23]
	v_mfma_f32_16x16x32_bf16 v[12:15], v[164:167], v[196:199], v[12:15]
	s_barrier
	s_setprio 0
	s_add_u32 s36, s36, 0x40080
	s_addc_u32 s37, s37, 0
	s_add_i32 s38, s38, s42
	s_mov_b32 m0, s38
	v_lshl_add_u64 v[144:145], s[36:37], 0, v[130:131]
	global_load_lds_dwordx4 v[144:145], off
	s_add_i32 m0, s38, 0x2000
	v_lshl_add_u64 v[144:145], s[36:37], 0, v[134:135]
	global_load_lds_dwordx4 v[144:145], off
	s_waitcnt vmcnt(6)
	s_setprio 1
	s_barrier
	v_mfma_f32_16x16x32_bf16 v[48:51], v[200:203], v[168:171], v[48:51]
	v_mfma_f32_16x16x32_bf16 v[40:43], v[212:215], v[168:171], v[40:43]
	v_mfma_f32_16x16x32_bf16 v[32:35], v[200:203], v[176:179], v[32:35]
	v_mfma_f32_16x16x32_bf16 v[24:27], v[212:215], v[176:179], v[24:27]
	v_mfma_f32_16x16x32_bf16 v[16:19], v[200:203], v[184:187], v[16:19]
	v_mfma_f32_16x16x32_bf16 v[8:11], v[212:215], v[184:187], v[8:11]
	v_mfma_f32_16x16x32_bf16 v[4:7], v[200:203], v[192:195], v[4:7]
	v_mfma_f32_16x16x32_bf16 v[0:3], v[212:215], v[192:195], v[0:3]
	v_mfma_f32_16x16x32_bf16 v[48:51], v[204:207], v[172:175], v[48:51]
	v_mfma_f32_16x16x32_bf16 v[40:43], v[216:219], v[172:175], v[40:43]
	v_mfma_f32_16x16x32_bf16 v[32:35], v[204:207], v[180:183], v[32:35]
	v_mfma_f32_16x16x32_bf16 v[24:27], v[216:219], v[180:183], v[24:27]
	v_mfma_f32_16x16x32_bf16 v[16:19], v[204:207], v[188:191], v[16:19]
	v_mfma_f32_16x16x32_bf16 v[8:11], v[216:219], v[188:191], v[8:11]
	v_mfma_f32_16x16x32_bf16 v[4:7], v[204:207], v[196:199], v[4:7]
	v_mfma_f32_16x16x32_bf16 v[0:3], v[216:219], v[196:199], v[0:3]
	s_barrier
	s_setprio 0
	s_add_i32 s68, s68, 2
	s_add_u32 s34, s34, 0x100
	s_addc_u32 s35, s35, 0
	s_add_u32 s66, s66, 0x100
	s_addc_u32 s67, s67, 0
	s_cmp_gt_u32 s68, 13
	s_cbranch_scc0 .LBB0_177
	v_lshl_add_u32 v152, s12, 8, v146
	v_ashrrev_i32_e32 v153, 31, v152
	v_lshl_or_b32 v144, s63, 8, v148
	v_readlane_b32 s34, v253, 61
	v_ashrrev_i32_e32 v145, 31, v144
	v_lshlrev_b64 v[154:155], 17, v[152:153]
	v_readlane_b32 s35, v253, 62
	v_lshlrev_b64 v[156:157], 1, v[144:145]
	v_cvt_pk_bf16_f32 v124, v124, v125
	v_cvt_pk_bf16_f32 v125, v126, v127
	v_cvt_pk_bf16_f32 v126, v120, v121
	s_nop 0
	v_lshl_add_u64 v[154:155], s[34:35], 0, v[154:155]
	v_lshl_add_u64 v[144:145], v[154:155], 0, v[156:157]
	v_cvt_pk_bf16_f32 v127, v122, v123
	global_store_dwordx4 v[144:145], v[124:127], off nt
	v_cvt_pk_bf16_f32 v116, v116, v117
	v_cvt_pk_bf16_f32 v117, v118, v119
	v_cvt_pk_bf16_f32 v118, v108, v109
	v_or_b32_e32 v108, 16, v152
	v_ashrrev_i32_e32 v109, 31, v108
	v_lshlrev_b64 v[108:109], 17, v[108:109]
	v_lshl_add_u64 v[108:109], s[34:35], 0, v[108:109]
	v_cvt_pk_bf16_f32 v119, v110, v111
	global_store_dwordx4 v[144:145], v[116:119], off offset:256 nt
	s_mov_b32 s3, 0x1000000
	s_mov_b32 s63, s2
	v_lshl_add_u64 v[116:117], v[108:109], 0, v[156:157]
	v_cvt_pk_bf16_f32 v108, v112, v113
	v_cvt_pk_bf16_f32 v109, v114, v115
	v_cvt_pk_bf16_f32 v110, v104, v105
	v_cvt_pk_bf16_f32 v111, v106, v107
	global_store_dwordx4 v[116:117], v[108:111], off nt
	v_cvt_pk_bf16_f32 v100, v100, v101
	v_cvt_pk_bf16_f32 v101, v102, v103
	v_cvt_pk_bf16_f32 v102, v92, v93
	v_or_b32_e32 v92, 32, v152
	v_ashrrev_i32_e32 v93, 31, v92
	v_lshlrev_b64 v[92:93], 17, v[92:93]
	v_lshl_add_u64 v[92:93], s[34:35], 0, v[92:93]
	v_cvt_pk_bf16_f32 v103, v94, v95
	global_store_dwordx4 v[116:117], v[100:103], off offset:256 nt
	s_mov_b32 s12, s8
	s_mov_b64 s[36:37], s[30:31]
	v_lshl_add_u64 v[100:101], v[92:93], 0, v[156:157]
	v_cvt_pk_bf16_f32 v92, v96, v97
	v_cvt_pk_bf16_f32 v93, v98, v99
	v_cvt_pk_bf16_f32 v94, v88, v89
	v_cvt_pk_bf16_f32 v95, v90, v91
	global_store_dwordx4 v[100:101], v[92:95], off nt
	v_cvt_pk_bf16_f32 v84, v84, v85
	v_cvt_pk_bf16_f32 v85, v86, v87
	v_cvt_pk_bf16_f32 v86, v76, v77
	v_or_b32_e32 v76, 48, v152
	v_ashrrev_i32_e32 v77, 31, v76
	v_lshlrev_b64 v[76:77], 17, v[76:77]
	v_lshl_add_u64 v[76:77], s[34:35], 0, v[76:77]
	v_cvt_pk_bf16_f32 v87, v78, v79
	global_store_dwordx4 v[100:101], v[84:87], off offset:256 nt
	s_mov_b64 s[34:35], 0x1000000
	s_nop 0
	v_lshl_add_u64 v[84:85], v[76:77], 0, v[156:157]
	v_cvt_pk_bf16_f32 v76, v80, v81
	v_cvt_pk_bf16_f32 v77, v82, v83
	v_cvt_pk_bf16_f32 v78, v72, v73
	v_cvt_pk_bf16_f32 v79, v74, v75
	global_store_dwordx4 v[84:85], v[76:79], off nt
	v_cvt_pk_bf16_f32 v68, v68, v69
	v_cvt_pk_bf16_f32 v69, v70, v71
	v_cvt_pk_bf16_f32 v70, v64, v65
	v_cvt_pk_bf16_f32 v71, v66, v67
	global_store_dwordx4 v[84:85], v[68:71], off offset:256 nt
	v_cvt_pk_bf16_f32 v60, v60, v61
	v_cvt_pk_bf16_f32 v61, v62, v63
	v_cvt_pk_bf16_f32 v62, v56, v57
	v_add_co_u32_e32 v56, vcc, s3, v144
	v_lshl_add_u64 v[64:65], v[144:145], 0, s[34:35]
	s_nop 0
	v_addc_co_u32_e32 v57, vcc, 0, v145, vcc
	s_mov_b32 s3, 0x1200000
	v_cvt_pk_bf16_f32 v63, v58, v59
	global_store_dwordx4 v[56:57], v[60:63], off nt
	v_cvt_pk_bf16_f32 v48, v48, v49
	v_cvt_pk_bf16_f32 v49, v50, v51
	v_cvt_pk_bf16_f32 v50, v40, v41
	v_cvt_pk_bf16_f32 v51, v42, v43
	global_store_dwordx4 v[64:65], v[48:51], off offset:256 nt
	s_mov_b64 s[34:35], 0x1200000
	v_cvt_pk_bf16_f32 v40, v52, v53
	v_cvt_pk_bf16_f32 v41, v54, v55
	v_cvt_pk_bf16_f32 v42, v44, v45
	v_add_co_u32_e32 v44, vcc, s3, v144
	v_lshl_add_u64 v[48:49], v[144:145], 0, s[34:35]
	s_nop 0
	v_addc_co_u32_e32 v45, vcc, 0, v145, vcc
	s_mov_b32 s3, 0x1400000
	v_cvt_pk_bf16_f32 v43, v46, v47
	global_store_dwordx4 v[44:45], v[40:43], off nt
	v_cvt_pk_bf16_f32 v32, v32, v33
	v_cvt_pk_bf16_f32 v33, v34, v35
	v_cvt_pk_bf16_f32 v34, v24, v25
	v_cvt_pk_bf16_f32 v35, v26, v27
	global_store_dwordx4 v[48:49], v[32:35], off offset:256 nt
	s_mov_b64 s[34:35], 0x1400000
	v_cvt_pk_bf16_f32 v24, v36, v37
	v_cvt_pk_bf16_f32 v25, v38, v39
	v_cvt_pk_bf16_f32 v26, v28, v29
	v_add_co_u32_e32 v28, vcc, s3, v144
	v_lshl_add_u64 v[32:33], v[144:145], 0, s[34:35]
	s_nop 0
	v_addc_co_u32_e32 v29, vcc, 0, v145, vcc
	s_mov_b32 s3, 0x1600000
	v_cvt_pk_bf16_f32 v27, v30, v31
	global_store_dwordx4 v[28:29], v[24:27], off nt
	v_cvt_pk_bf16_f32 v16, v16, v17
	v_cvt_pk_bf16_f32 v17, v18, v19
	v_cvt_pk_bf16_f32 v18, v8, v9
	v_cvt_pk_bf16_f32 v19, v10, v11
	global_store_dwordx4 v[32:33], v[16:19], off offset:256 nt
	v_cvt_pk_bf16_f32 v8, v20, v21
	v_cvt_pk_bf16_f32 v9, v22, v23
	v_cvt_pk_bf16_f32 v10, v12, v13
	v_add_co_u32_e32 v12, vcc, s3, v144
	s_mov_b64 s[34:35], 0x1600000
	s_nop 0
	v_addc_co_u32_e32 v13, vcc, 0, v145, vcc
	v_lshl_add_u64 v[16:17], v[144:145], 0, s[34:35]
	s_and_b64 vcc, exec, s[4:5]
	s_mov_b64 s[34:35], s[14:15]
	v_cvt_pk_bf16_f32 v11, v14, v15
	global_store_dwordx4 v[12:13], v[8:11], off nt
	v_cvt_pk_bf16_f32 v4, v4, v5
	v_cvt_pk_bf16_f32 v5, v6, v7
	v_cvt_pk_bf16_f32 v6, v0, v1
	v_cvt_pk_bf16_f32 v7, v2, v3
	global_store_dwordx4 v[16:17], v[4:7], off offset:256 nt
	s_cbranch_vccz .LBB0_170
	s_waitcnt vmcnt(0)
	s_cmpk_gt_u32 s40, 0xff
	s_cbranch_scc1 .LBB0_181
	s_barrier

.LBB0_200:
	s_add_u32 s48, s42, 0xfffc0080
	s_addc_u32 s49, s43, -1
	s_add_i32 s81, 0, 0x10000
	v_add_u32_e32 v140, s81, v144
	ds_read_b128 v[148:151], v140
	ds_read_b128 v[152:155], v140 offset:1024
	ds_read_b128 v[156:159], v140 offset:2048
	ds_read_b128 v[160:163], v140 offset:3072
	s_cmp_eq_u32 s80, 12
	s_cselect_b32 s51, s35, s49
	s_cselect_b32 s50, s76, s48
	s_cselect_b32 s49, s31, s79
	s_cselect_b32 s48, s77, s78
	v_lshl_add_u64 v[140:141], s[42:43], 0, v[136:137]
	s_add_i32 m0, s37, 0xc000
	ds_read_b128 v[164:167], v146
	ds_read_b128 v[168:171], v146 offset:1024
	ds_read_b128 v[172:175], v146 offset:2048
	ds_read_b128 v[176:179], v146 offset:3072
	ds_read_b128 v[180:183], v146 offset:4096
	ds_read_b128 v[184:187], v146 offset:5120
	ds_read_b128 v[188:191], v146 offset:6144
	ds_read_b128 v[192:195], v146 offset:7168
	global_load_lds_dwordx4 v[140:141], off
	s_add_i32 m0, s37, 0xe000
	v_lshl_add_u64 v[140:141], s[42:43], 0, v[138:139]
	global_load_lds_dwordx4 v[140:141], off
	s_waitcnt lgkmcnt(8)
	s_setprio 1
	s_barrier
	s_waitcnt lgkmcnt(0)
	v_mfma_f32_16x16x32_bf16 v[124:127], v[148:151], v[164:167], v[124:127]
	v_mfma_f32_16x16x32_bf16 v[120:123], v[156:159], v[164:167], v[120:123]
	v_mfma_f32_16x16x32_bf16 v[116:119], v[148:151], v[172:175], v[116:119]
	v_mfma_f32_16x16x32_bf16 v[108:111], v[156:159], v[172:175], v[108:111]
	v_mfma_f32_16x16x32_bf16 v[100:103], v[148:151], v[180:183], v[100:103]
	v_mfma_f32_16x16x32_bf16 v[92:95], v[156:159], v[180:183], v[92:95]
	v_mfma_f32_16x16x32_bf16 v[84:87], v[148:151], v[188:191], v[84:87]
	v_mfma_f32_16x16x32_bf16 v[76:79], v[156:159], v[188:191], v[76:79]
	v_mfma_f32_16x16x32_bf16 v[124:127], v[152:155], v[168:171], v[124:127]
	v_mfma_f32_16x16x32_bf16 v[120:123], v[160:163], v[168:171], v[120:123]
	v_mfma_f32_16x16x32_bf16 v[116:119], v[152:155], v[176:179], v[116:119]
	v_mfma_f32_16x16x32_bf16 v[108:111], v[160:163], v[176:179], v[108:111]
	v_mfma_f32_16x16x32_bf16 v[100:103], v[152:155], v[184:187], v[100:103]
	v_mfma_f32_16x16x32_bf16 v[92:95], v[160:163], v[184:187], v[92:95]
	v_mfma_f32_16x16x32_bf16 v[84:87], v[152:155], v[192:195], v[84:87]
	v_mfma_f32_16x16x32_bf16 v[76:79], v[160:163], v[192:195], v[76:79]
	s_barrier
	s_setprio 0
	s_add_i32 s84, 0, 0x14000
	v_add_u32_e32 v140, s84, v144
	s_add_i32 s81, s81, s69
	ds_read_b128 v[196:199], v140
	ds_read_b128 v[200:203], v140 offset:1024
	ds_read_b128 v[204:207], v140 offset:2048
	ds_read_b128 v[212:215], v140 offset:3072
	v_lshl_add_u64 v[140:141], s[48:49], 0, v[128:129]
	s_mov_b32 m0, s81
	v_lshl_add_u64 v[208:209], s[48:49], 0, v[134:135]
	global_load_lds_dwordx4 v[140:141], off
	s_add_i32 m0, s81, 0x2000
	s_nop 0
	global_load_lds_dwordx4 v[208:209], off
	s_setprio 1
	s_barrier
	s_waitcnt lgkmcnt(0)
	v_mfma_f32_16x16x32_bf16 v[112:115], v[196:199], v[164:167], v[112:115]
	v_mfma_f32_16x16x32_bf16 v[104:107], v[204:207], v[164:167], v[104:107]
	v_mfma_f32_16x16x32_bf16 v[96:99], v[196:199], v[172:175], v[96:99]
	v_mfma_f32_16x16x32_bf16 v[88:91], v[204:207], v[172:175], v[88:91]
	v_mfma_f32_16x16x32_bf16 v[80:83], v[196:199], v[180:183], v[80:83]
	v_mfma_f32_16x16x32_bf16 v[72:75], v[204:207], v[180:183], v[72:75]
	v_mfma_f32_16x16x32_bf16 v[68:71], v[196:199], v[188:191], v[68:71]
	v_mfma_f32_16x16x32_bf16 v[64:67], v[204:207], v[188:191], v[64:67]
	v_mfma_f32_16x16x32_bf16 v[112:115], v[200:203], v[168:171], v[112:115]
	v_mfma_f32_16x16x32_bf16 v[104:107], v[212:215], v[168:171], v[104:107]
	v_mfma_f32_16x16x32_bf16 v[96:99], v[200:203], v[176:179], v[96:99]
	v_mfma_f32_16x16x32_bf16 v[88:91], v[212:215], v[176:179], v[88:91]
	v_mfma_f32_16x16x32_bf16 v[80:83], v[200:203], v[184:187], v[80:83]
	v_mfma_f32_16x16x32_bf16 v[72:75], v[212:215], v[184:187], v[72:75]
	v_mfma_f32_16x16x32_bf16 v[68:71], v[200:203], v[192:195], v[68:71]
	v_mfma_f32_16x16x32_bf16 v[64:67], v[212:215], v[192:195], v[64:67]
	s_barrier
	s_setprio 0
	s_mov_b32 m0, s37
	v_lshl_add_u64 v[216:217], s[50:51], 0, v[130:131]
	ds_read_b128 v[164:167], v146 offset:16384
	ds_read_b128 v[168:171], v146 offset:17408
	ds_read_b128 v[172:175], v146 offset:18432
	ds_read_b128 v[176:179], v146 offset:19456
	ds_read_b128 v[180:183], v146 offset:20480
	ds_read_b128 v[184:187], v146 offset:21504
	ds_read_b128 v[188:191], v146 offset:22528
	ds_read_b128 v[192:195], v146 offset:23552
	global_load_lds_dwordx4 v[216:217], off
	s_mov_b32 m0, s70
	v_lshl_add_u64 v[218:219], s[50:51], 0, v[132:133]
	global_load_lds_dwordx4 v[218:219], off
	s_setprio 1
	s_barrier
	s_waitcnt lgkmcnt(0)
	v_mfma_f32_16x16x32_bf16 v[60:63], v[148:151], v[164:167], v[60:63]
	v_mfma_f32_16x16x32_bf16 v[56:59], v[156:159], v[164:167], v[56:59]
	v_mfma_f32_16x16x32_bf16 v[52:55], v[148:151], v[172:175], v[52:55]
	v_mfma_f32_16x16x32_bf16 v[44:47], v[156:159], v[172:175], v[44:47]
	v_mfma_f32_16x16x32_bf16 v[36:39], v[148:151], v[180:183], v[36:39]
	v_mfma_f32_16x16x32_bf16 v[28:31], v[156:159], v[180:183], v[28:31]
	v_mfma_f32_16x16x32_bf16 v[20:23], v[148:151], v[188:191], v[20:23]
	v_mfma_f32_16x16x32_bf16 v[12:15], v[156:159], v[188:191], v[12:15]
	v_mfma_f32_16x16x32_bf16 v[60:63], v[152:155], v[168:171], v[60:63]
	v_mfma_f32_16x16x32_bf16 v[56:59], v[160:163], v[168:171], v[56:59]
	v_mfma_f32_16x16x32_bf16 v[52:55], v[152:155], v[176:179], v[52:55]
	v_mfma_f32_16x16x32_bf16 v[44:47], v[160:163], v[176:179], v[44:47]
	v_mfma_f32_16x16x32_bf16 v[36:39], v[152:155], v[184:187], v[36:39]
	v_mfma_f32_16x16x32_bf16 v[28:31], v[160:163], v[184:187], v[28:31]
	v_mfma_f32_16x16x32_bf16 v[20:23], v[152:155], v[192:195], v[20:23]
	v_mfma_f32_16x16x32_bf16 v[12:15], v[160:163], v[192:195], v[12:15]
	s_barrier
	s_setprio 0
	s_add_u32 s82, s48, 0x40000
	s_addc_u32 s83, s49, 0
	s_add_i32 s81, s84, s69
	s_mov_b32 m0, s81
	v_lshl_add_u64 v[148:149], s[82:83], 0, v[128:129]
	global_load_lds_dwordx4 v[148:149], off
	s_add_i32 m0, s81, 0x2000
	v_lshl_add_u64 v[148:149], s[82:83], 0, v[134:135]
	global_load_lds_dwordx4 v[148:149], off
	s_waitcnt vmcnt(6)
	s_setprio 1
	s_barrier
	v_mfma_f32_16x16x32_bf16 v[48:51], v[196:199], v[164:167], v[48:51]
	v_mfma_f32_16x16x32_bf16 v[40:43], v[204:207], v[164:167], v[40:43]
	v_mfma_f32_16x16x32_bf16 v[32:35], v[196:199], v[172:175], v[32:35]
	v_mfma_f32_16x16x32_bf16 v[24:27], v[204:207], v[172:175], v[24:27]
	v_mfma_f32_16x16x32_bf16 v[16:19], v[196:199], v[180:183], v[16:19]
	v_mfma_f32_16x16x32_bf16 v[8:11], v[204:207], v[180:183], v[8:11]
	v_mfma_f32_16x16x32_bf16 v[4:7], v[196:199], v[188:191], v[4:7]
	v_mfma_f32_16x16x32_bf16 v[0:3], v[204:207], v[188:191], v[0:3]
	v_mfma_f32_16x16x32_bf16 v[48:51], v[200:203], v[168:171], v[48:51]
	v_mfma_f32_16x16x32_bf16 v[40:43], v[212:215], v[168:171], v[40:43]
	v_mfma_f32_16x16x32_bf16 v[32:35], v[200:203], v[176:179], v[32:35]
	v_mfma_f32_16x16x32_bf16 v[24:27], v[212:215], v[176:179], v[24:27]
	v_mfma_f32_16x16x32_bf16 v[16:19], v[200:203], v[184:187], v[16:19]
	v_mfma_f32_16x16x32_bf16 v[8:11], v[212:215], v[184:187], v[8:11]
	v_mfma_f32_16x16x32_bf16 v[4:7], v[200:203], v[192:195], v[4:7]
	v_mfma_f32_16x16x32_bf16 v[0:3], v[212:215], v[192:195], v[0:3]
	s_barrier
	s_setprio 0
	s_add_i32 s81, 0, 0x18000
	v_add_u32_e32 v147, s81, v144
	ds_read_b128 v[148:151], v147
	ds_read_b128 v[152:155], v147 offset:1024
	ds_read_b128 v[156:159], v147 offset:2048
	ds_read_b128 v[160:163], v147 offset:3072
	s_add_u32 s50, s50, 0x40000
	s_addc_u32 s51, s51, 0
	s_mov_b32 m0, s71
	v_lshl_add_u64 v[196:197], s[50:51], 0, v[130:131]
	ds_read_b128 v[164:167], v146 offset:32768
	ds_read_b128 v[168:171], v146 offset:33792
	ds_read_b128 v[172:175], v146 offset:34816
	ds_read_b128 v[176:179], v146 offset:35840
	ds_read_b128 v[180:183], v146 offset:36864
	ds_read_b128 v[184:187], v146 offset:37888
	ds_read_b128 v[188:191], v146 offset:38912
	ds_read_b128 v[192:195], v146 offset:39936
	global_load_lds_dwordx4 v[196:197], off
	s_mov_b32 m0, s72
	v_lshl_add_u64 v[196:197], s[50:51], 0, v[132:133]
	global_load_lds_dwordx4 v[196:197], off
	s_waitcnt lgkmcnt(8)
	s_setprio 1
	s_barrier
	s_waitcnt lgkmcnt(0)
	v_mfma_f32_16x16x32_bf16 v[124:127], v[148:151], v[164:167], v[124:127]
	v_mfma_f32_16x16x32_bf16 v[120:123], v[156:159], v[164:167], v[120:123]
	v_mfma_f32_16x16x32_bf16 v[116:119], v[148:151], v[172:175], v[116:119]
	v_mfma_f32_16x16x32_bf16 v[108:111], v[156:159], v[172:175], v[108:111]
	v_mfma_f32_16x16x32_bf16 v[100:103], v[148:151], v[180:183], v[100:103]
	v_mfma_f32_16x16x32_bf16 v[92:95], v[156:159], v[180:183], v[92:95]
	v_mfma_f32_16x16x32_bf16 v[84:87], v[148:151], v[188:191], v[84:87]
	v_mfma_f32_16x16x32_bf16 v[76:79], v[156:159], v[188:191], v[76:79]
	v_mfma_f32_16x16x32_bf16 v[124:127], v[152:155], v[168:171], v[124:127]
	v_mfma_f32_16x16x32_bf16 v[120:123], v[160:163], v[168:171], v[120:123]
	v_mfma_f32_16x16x32_bf16 v[116:119], v[152:155], v[176:179], v[116:119]
	v_mfma_f32_16x16x32_bf16 v[108:111], v[160:163], v[176:179], v[108:111]
	v_mfma_f32_16x16x32_bf16 v[100:103], v[152:155], v[184:187], v[100:103]
	v_mfma_f32_16x16x32_bf16 v[92:95], v[160:163], v[184:187], v[92:95]
	v_mfma_f32_16x16x32_bf16 v[84:87], v[152:155], v[192:195], v[84:87]
	v_mfma_f32_16x16x32_bf16 v[76:79], v[160:163], v[192:195], v[76:79]
	s_barrier
	s_setprio 0
	s_add_i32 s50, 0, 0x1c000
	s_add_i32 s51, s81, s69
	v_add_u32_e32 v147, s50, v144
	v_lshl_add_u64 v[140:141], v[140:141], 0, s[2:3]
	s_mov_b32 m0, s51
	ds_read_b128 v[196:199], v147
	ds_read_b128 v[200:203], v147 offset:1024
	ds_read_b128 v[204:207], v147 offset:2048
	ds_read_b128 v[212:215], v147 offset:3072
	global_load_lds_dwordx4 v[140:141], off
	s_add_i32 m0, s51, 0x2000
	v_lshl_add_u64 v[140:141], v[208:209], 0, s[2:3]
	global_load_lds_dwordx4 v[140:141], off
	s_setprio 1
	s_barrier
	s_waitcnt lgkmcnt(0)
	v_mfma_f32_16x16x32_bf16 v[112:115], v[196:199], v[164:167], v[112:115]
	v_mfma_f32_16x16x32_bf16 v[104:107], v[204:207], v[164:167], v[104:107]
	v_mfma_f32_16x16x32_bf16 v[96:99], v[196:199], v[172:175], v[96:99]
	v_mfma_f32_16x16x32_bf16 v[88:91], v[204:207], v[172:175], v[88:91]
	v_mfma_f32_16x16x32_bf16 v[80:83], v[196:199], v[180:183], v[80:83]
	v_mfma_f32_16x16x32_bf16 v[72:75], v[204:207], v[180:183], v[72:75]
	v_mfma_f32_16x16x32_bf16 v[68:71], v[196:199], v[188:191], v[68:71]
	v_mfma_f32_16x16x32_bf16 v[64:67], v[204:207], v[188:191], v[64:67]
	v_mfma_f32_16x16x32_bf16 v[112:115], v[200:203], v[168:171], v[112:115]
	v_mfma_f32_16x16x32_bf16 v[104:107], v[212:215], v[168:171], v[104:107]
	v_mfma_f32_16x16x32_bf16 v[96:99], v[200:203], v[176:179], v[96:99]
	v_mfma_f32_16x16x32_bf16 v[88:91], v[212:215], v[176:179], v[88:91]
	v_mfma_f32_16x16x32_bf16 v[80:83], v[200:203], v[184:187], v[80:83]
	v_mfma_f32_16x16x32_bf16 v[72:75], v[212:215], v[184:187], v[72:75]
	v_mfma_f32_16x16x32_bf16 v[68:71], v[200:203], v[192:195], v[68:71]
	v_mfma_f32_16x16x32_bf16 v[64:67], v[212:215], v[192:195], v[64:67]
	s_barrier
	s_setprio 0
	s_mov_b32 m0, s0
	v_lshl_add_u64 v[140:141], v[216:217], 0, s[2:3]
	ds_read_b128 v[164:167], v146 offset:49152
	ds_read_b128 v[168:171], v146 offset:50176
	ds_read_b128 v[172:175], v146 offset:51200
	ds_read_b128 v[176:179], v146 offset:52224
	ds_read_b128 v[180:183], v146 offset:53248
	ds_read_b128 v[184:187], v146 offset:54272
	ds_read_b128 v[188:191], v146 offset:55296
	ds_read_b128 v[192:195], v146 offset:56320
	global_load_lds_dwordx4 v[140:141], off
	s_mov_b32 m0, s73
	v_lshl_add_u64 v[140:141], v[218:219], 0, s[2:3]
	global_load_lds_dwordx4 v[140:141], off
	s_setprio 1
	s_barrier
	s_waitcnt lgkmcnt(0)
	v_mfma_f32_16x16x32_bf16 v[60:63], v[148:151], v[164:167], v[60:63]
	v_mfma_f32_16x16x32_bf16 v[56:59], v[156:159], v[164:167], v[56:59]
	v_mfma_f32_16x16x32_bf16 v[52:55], v[148:151], v[172:175], v[52:55]
	v_mfma_f32_16x16x32_bf16 v[44:47], v[156:159], v[172:175], v[44:47]
	v_mfma_f32_16x16x32_bf16 v[36:39], v[148:151], v[180:183], v[36:39]
	v_mfma_f32_16x16x32_bf16 v[28:31], v[156:159], v[180:183], v[28:31]
	v_mfma_f32_16x16x32_bf16 v[20:23], v[148:151], v[188:191], v[20:23]
	v_mfma_f32_16x16x32_bf16 v[12:15], v[156:159], v[188:191], v[12:15]
	v_mfma_f32_16x16x32_bf16 v[60:63], v[152:155], v[168:171], v[60:63]
	v_mfma_f32_16x16x32_bf16 v[56:59], v[160:163], v[168:171], v[56:59]
	v_mfma_f32_16x16x32_bf16 v[52:55], v[152:155], v[176:179], v[52:55]
	v_mfma_f32_16x16x32_bf16 v[44:47], v[160:163], v[176:179], v[44:47]
	v_mfma_f32_16x16x32_bf16 v[36:39], v[152:155], v[184:187], v[36:39]
	v_mfma_f32_16x16x32_bf16 v[28:31], v[160:163], v[184:187], v[28:31]
	v_mfma_f32_16x16x32_bf16 v[20:23], v[152:155], v[192:195], v[20:23]
	v_mfma_f32_16x16x32_bf16 v[12:15], v[160:163], v[192:195], v[12:15]
	s_barrier
	s_setprio 0
	s_add_u32 s48, s48, 0x40080
	s_addc_u32 s49, s49, 0
	s_add_i32 s50, s50, s69
	s_mov_b32 m0, s50
	v_lshl_add_u64 v[140:141], s[48:49], 0, v[128:129]
	global_load_lds_dwordx4 v[140:141], off
	s_add_i32 m0, s50, 0x2000
	v_lshl_add_u64 v[140:141], s[48:49], 0, v[134:135]
	global_load_lds_dwordx4 v[140:141], off
	s_waitcnt vmcnt(6)
	s_setprio 1
	s_barrier
	v_mfma_f32_16x16x32_bf16 v[48:51], v[196:199], v[164:167], v[48:51]
	v_mfma_f32_16x16x32_bf16 v[40:43], v[204:207], v[164:167], v[40:43]
	v_mfma_f32_16x16x32_bf16 v[32:35], v[196:199], v[172:175], v[32:35]
	v_mfma_f32_16x16x32_bf16 v[24:27], v[204:207], v[172:175], v[24:27]
	v_mfma_f32_16x16x32_bf16 v[16:19], v[196:199], v[180:183], v[16:19]
	v_mfma_f32_16x16x32_bf16 v[8:11], v[204:207], v[180:183], v[8:11]
	v_mfma_f32_16x16x32_bf16 v[4:7], v[196:199], v[188:191], v[4:7]
	v_mfma_f32_16x16x32_bf16 v[0:3], v[204:207], v[188:191], v[0:3]
	v_mfma_f32_16x16x32_bf16 v[48:51], v[200:203], v[168:171], v[48:51]
	v_mfma_f32_16x16x32_bf16 v[40:43], v[212:215], v[168:171], v[40:43]
	v_mfma_f32_16x16x32_bf16 v[32:35], v[200:203], v[176:179], v[32:35]
	v_mfma_f32_16x16x32_bf16 v[24:27], v[212:215], v[176:179], v[24:27]
	v_mfma_f32_16x16x32_bf16 v[16:19], v[200:203], v[184:187], v[16:19]
	v_mfma_f32_16x16x32_bf16 v[8:11], v[212:215], v[184:187], v[8:11]
	v_mfma_f32_16x16x32_bf16 v[4:7], v[200:203], v[192:195], v[4:7]
	v_mfma_f32_16x16x32_bf16 v[0:3], v[212:215], v[192:195], v[0:3]
	s_barrier
	s_setprio 0
	s_add_i32 s80, s80, 2
	s_add_u32 s42, s42, 0x100
	s_addc_u32 s43, s43, 0
	s_add_u32 s78, s78, 0x100
	s_addc_u32 s79, s79, 0
	s_cmp_gt_u32 s80, 13
	s_cbranch_scc0 .LBB0_200
	v_lshl_add_u32 v148, s36, 8, v143
	v_ashrrev_i32_e32 v149, 31, v148
	v_lshl_or_b32 v140, s75, 8, v145
	v_ashrrev_i32_e32 v141, 31, v140
	v_lshlrev_b64 v[150:151], 10, v[148:149]
	v_lshl_add_u64 v[150:151], s[14:15], 0, v[150:151]
	v_lshlrev_b64 v[152:153], 1, v[140:141]
	v_lshl_add_u64 v[140:141], v[150:151], 0, v[152:153]
	v_cvt_pk_bf16_f32 v124, v124, v125
	v_cvt_pk_bf16_f32 v125, v126, v127
	v_cvt_pk_bf16_f32 v126, v120, v121
	v_cvt_pk_bf16_f32 v127, v122, v123
	global_store_dwordx4 v[140:141], v[124:127], off nt
	v_cvt_pk_bf16_f32 v112, v112, v113
	v_cvt_pk_bf16_f32 v113, v114, v115
	v_cvt_pk_bf16_f32 v114, v104, v105
	v_or_b32_e32 v104, 16, v148
	v_ashrrev_i32_e32 v105, 31, v104
	v_lshlrev_b64 v[104:105], 10, v[104:105]
	v_lshl_add_u64 v[104:105], s[14:15], 0, v[104:105]
	v_cvt_pk_bf16_f32 v115, v106, v107
	global_store_dwordx4 v[140:141], v[112:115], off offset:256 nt
	s_mov_b32 s31, 0x20000
	s_mov_b64 s[42:43], 0x20000
	v_lshl_add_u64 v[112:113], v[104:105], 0, v[152:153]
	v_cvt_pk_bf16_f32 v104, v116, v117
	v_cvt_pk_bf16_f32 v105, v118, v119
	v_cvt_pk_bf16_f32 v106, v108, v109
	v_cvt_pk_bf16_f32 v107, v110, v111
	global_store_dwordx4 v[112:113], v[104:107], off nt
	v_cvt_pk_bf16_f32 v96, v96, v97
	v_cvt_pk_bf16_f32 v97, v98, v99
	v_cvt_pk_bf16_f32 v98, v88, v89
	v_or_b32_e32 v88, 32, v148
	v_ashrrev_i32_e32 v89, 31, v88
	v_lshlrev_b64 v[88:89], 10, v[88:89]
	v_lshl_add_u64 v[88:89], s[14:15], 0, v[88:89]
	v_cvt_pk_bf16_f32 v99, v90, v91
	global_store_dwordx4 v[112:113], v[96:99], off offset:256 nt
	s_mov_b32 s75, s30
	s_mov_b32 s36, s34
	v_lshl_add_u64 v[96:97], v[88:89], 0, v[152:153]
	v_cvt_pk_bf16_f32 v88, v100, v101
	v_cvt_pk_bf16_f32 v89, v102, v103
	v_cvt_pk_bf16_f32 v90, v92, v93
	v_cvt_pk_bf16_f32 v91, v94, v95
	global_store_dwordx4 v[96:97], v[88:91], off nt
	v_cvt_pk_bf16_f32 v80, v80, v81
	v_cvt_pk_bf16_f32 v81, v82, v83
	v_cvt_pk_bf16_f32 v82, v72, v73
	v_or_b32_e32 v72, 48, v148
	v_ashrrev_i32_e32 v73, 31, v72
	v_lshlrev_b64 v[72:73], 10, v[72:73]
	v_lshl_add_u64 v[72:73], s[14:15], 0, v[72:73]
	v_cvt_pk_bf16_f32 v83, v74, v75
	global_store_dwordx4 v[96:97], v[80:83], off offset:256 nt
	s_mov_b64 s[48:49], s[40:41]
	s_nop 0
	v_lshl_add_u64 v[80:81], v[72:73], 0, v[152:153]
	v_cvt_pk_bf16_f32 v72, v84, v85
	v_cvt_pk_bf16_f32 v73, v86, v87
	v_cvt_pk_bf16_f32 v74, v76, v77
	v_cvt_pk_bf16_f32 v75, v78, v79
	global_store_dwordx4 v[80:81], v[72:75], off nt
	v_cvt_pk_bf16_f32 v68, v68, v69
	v_cvt_pk_bf16_f32 v69, v70, v71
	v_cvt_pk_bf16_f32 v70, v64, v65
	v_cvt_pk_bf16_f32 v71, v66, v67
	global_store_dwordx4 v[80:81], v[68:71], off offset:256 nt
	v_cvt_pk_bf16_f32 v60, v60, v61
	v_cvt_pk_bf16_f32 v61, v62, v63
	v_cvt_pk_bf16_f32 v62, v56, v57
	v_add_co_u32_e32 v56, vcc, s31, v140
	v_lshl_add_u64 v[64:65], v[140:141], 0, s[42:43]
	s_nop 0
	v_addc_co_u32_e32 v57, vcc, 0, v141, vcc
	s_mov_b32 s31, 0x24000
	v_cvt_pk_bf16_f32 v63, v58, v59
	global_store_dwordx4 v[56:57], v[60:63], off nt
	v_cvt_pk_bf16_f32 v48, v48, v49
	v_cvt_pk_bf16_f32 v49, v50, v51
	v_cvt_pk_bf16_f32 v50, v40, v41
	v_cvt_pk_bf16_f32 v51, v42, v43
	global_store_dwordx4 v[64:65], v[48:51], off offset:256 nt
	s_mov_b64 s[42:43], 0x24000
	v_cvt_pk_bf16_f32 v40, v52, v53
	v_cvt_pk_bf16_f32 v41, v54, v55
	v_cvt_pk_bf16_f32 v42, v44, v45
	v_add_co_u32_e32 v44, vcc, s31, v140
	v_lshl_add_u64 v[48:49], v[140:141], 0, s[42:43]
	s_nop 0
	v_addc_co_u32_e32 v45, vcc, 0, v141, vcc
	s_mov_b32 s31, 0x28000
	v_cvt_pk_bf16_f32 v43, v46, v47
	global_store_dwordx4 v[44:45], v[40:43], off nt
	v_cvt_pk_bf16_f32 v32, v32, v33
	v_cvt_pk_bf16_f32 v33, v34, v35
	v_cvt_pk_bf16_f32 v34, v24, v25
	v_cvt_pk_bf16_f32 v35, v26, v27
	global_store_dwordx4 v[48:49], v[32:35], off offset:256 nt
	s_mov_b64 s[42:43], 0x28000
	v_cvt_pk_bf16_f32 v24, v36, v37
	v_cvt_pk_bf16_f32 v25, v38, v39
	v_cvt_pk_bf16_f32 v26, v28, v29
	v_add_co_u32_e32 v28, vcc, s31, v140
	v_lshl_add_u64 v[32:33], v[140:141], 0, s[42:43]
	s_nop 0
	v_addc_co_u32_e32 v29, vcc, 0, v141, vcc
	s_mov_b32 s31, 0x2c000
	v_cvt_pk_bf16_f32 v27, v30, v31
	global_store_dwordx4 v[28:29], v[24:27], off nt
	v_cvt_pk_bf16_f32 v16, v16, v17
	v_cvt_pk_bf16_f32 v17, v18, v19
	v_cvt_pk_bf16_f32 v18, v8, v9
	v_cvt_pk_bf16_f32 v19, v10, v11
	global_store_dwordx4 v[32:33], v[16:19], off offset:256 nt
	v_cvt_pk_bf16_f32 v8, v20, v21
	v_cvt_pk_bf16_f32 v9, v22, v23
	v_cvt_pk_bf16_f32 v10, v12, v13
	v_add_co_u32_e32 v12, vcc, s31, v140
	s_mov_b64 s[42:43], 0x2c000
	s_nop 0
	v_addc_co_u32_e32 v13, vcc, 0, v141, vcc
	v_lshl_add_u64 v[16:17], v[140:141], 0, s[42:43]
	s_and_b64 vcc, exec, s[28:29]
	s_mov_b64 s[42:43], s[38:39]
	v_cvt_pk_bf16_f32 v11, v14, v15
	global_store_dwordx4 v[12:13], v[8:11], off nt
	v_cvt_pk_bf16_f32 v4, v4, v5
	v_cvt_pk_bf16_f32 v5, v6, v7
	v_cvt_pk_bf16_f32 v6, v0, v1
	v_cvt_pk_bf16_f32 v7, v2, v3
	global_store_dwordx4 v[16:17], v[4:7], off offset:256 nt
	s_cbranch_vccz .LBB0_193
	s_waitcnt vmcnt(0)
	s_cmpk_gt_u32 s65, 0xff
	s_cbranch_scc1 .LBB0_204
	s_barrier

.LBB0_220:
	s_add_u32 s40, s38, 0xfffc0080
	s_addc_u32 s41, s39, -1
	s_add_i32 s76, 0, 0x10000
	v_add_u32_e32 v140, s76, v144
	ds_read_b128 v[148:151], v140
	ds_read_b128 v[152:155], v140 offset:1024
	ds_read_b128 v[156:159], v140 offset:2048
	ds_read_b128 v[160:163], v140 offset:3072
	s_cmp_eq_u32 s75, 12
	s_cselect_b32 s43, s29, s41
	s_cselect_b32 s42, s71, s40
	s_cselect_b32 s41, s15, s74
	s_cselect_b32 s40, s72, s73
	v_lshl_add_u64 v[140:141], s[38:39], 0, v[136:137]
	s_add_i32 m0, s31, 0xc000
	ds_read_b128 v[164:167], v146
	ds_read_b128 v[168:171], v146 offset:1024
	ds_read_b128 v[172:175], v146 offset:2048
	ds_read_b128 v[176:179], v146 offset:3072
	ds_read_b128 v[180:183], v146 offset:4096
	ds_read_b128 v[184:187], v146 offset:5120
	ds_read_b128 v[188:191], v146 offset:6144
	ds_read_b128 v[192:195], v146 offset:7168
	global_load_lds_dwordx4 v[140:141], off
	s_add_i32 m0, s31, 0xe000
	v_lshl_add_u64 v[140:141], s[38:39], 0, v[138:139]
	global_load_lds_dwordx4 v[140:141], off
	s_waitcnt lgkmcnt(8)
	s_setprio 1
	s_barrier
	s_waitcnt lgkmcnt(0)
	v_mfma_f32_16x16x32_bf16 v[124:127], v[148:151], v[164:167], v[124:127]
	v_mfma_f32_16x16x32_bf16 v[120:123], v[156:159], v[164:167], v[120:123]
	v_mfma_f32_16x16x32_bf16 v[116:119], v[148:151], v[172:175], v[116:119]
	v_mfma_f32_16x16x32_bf16 v[108:111], v[156:159], v[172:175], v[108:111]
	v_mfma_f32_16x16x32_bf16 v[100:103], v[148:151], v[180:183], v[100:103]
	v_mfma_f32_16x16x32_bf16 v[92:95], v[156:159], v[180:183], v[92:95]
	v_mfma_f32_16x16x32_bf16 v[84:87], v[148:151], v[188:191], v[84:87]
	v_mfma_f32_16x16x32_bf16 v[76:79], v[156:159], v[188:191], v[76:79]
	v_mfma_f32_16x16x32_bf16 v[124:127], v[152:155], v[168:171], v[124:127]
	v_mfma_f32_16x16x32_bf16 v[120:123], v[160:163], v[168:171], v[120:123]
	v_mfma_f32_16x16x32_bf16 v[116:119], v[152:155], v[176:179], v[116:119]
	v_mfma_f32_16x16x32_bf16 v[108:111], v[160:163], v[176:179], v[108:111]
	v_mfma_f32_16x16x32_bf16 v[100:103], v[152:155], v[184:187], v[100:103]
	v_mfma_f32_16x16x32_bf16 v[92:95], v[160:163], v[184:187], v[92:95]
	v_mfma_f32_16x16x32_bf16 v[84:87], v[152:155], v[192:195], v[84:87]
	v_mfma_f32_16x16x32_bf16 v[76:79], v[160:163], v[192:195], v[76:79]
	s_barrier
	s_setprio 0
	s_add_i32 s78, 0, 0x14000
	v_add_u32_e32 v140, s78, v144
	s_add_i32 s76, s76, s64
	ds_read_b128 v[196:199], v140
	ds_read_b128 v[200:203], v140 offset:1024
	ds_read_b128 v[204:207], v140 offset:2048
	ds_read_b128 v[212:215], v140 offset:3072
	v_lshl_add_u64 v[140:141], s[40:41], 0, v[128:129]
	s_mov_b32 m0, s76
	v_lshl_add_u64 v[208:209], s[40:41], 0, v[134:135]
	global_load_lds_dwordx4 v[140:141], off
	s_add_i32 m0, s76, 0x2000
	s_nop 0
	global_load_lds_dwordx4 v[208:209], off
	s_setprio 1
	s_barrier
	s_waitcnt lgkmcnt(0)
	v_mfma_f32_16x16x32_bf16 v[112:115], v[196:199], v[164:167], v[112:115]
	v_mfma_f32_16x16x32_bf16 v[104:107], v[204:207], v[164:167], v[104:107]
	v_mfma_f32_16x16x32_bf16 v[96:99], v[196:199], v[172:175], v[96:99]
	v_mfma_f32_16x16x32_bf16 v[88:91], v[204:207], v[172:175], v[88:91]
	v_mfma_f32_16x16x32_bf16 v[80:83], v[196:199], v[180:183], v[80:83]
	v_mfma_f32_16x16x32_bf16 v[72:75], v[204:207], v[180:183], v[72:75]
	v_mfma_f32_16x16x32_bf16 v[68:71], v[196:199], v[188:191], v[68:71]
	v_mfma_f32_16x16x32_bf16 v[64:67], v[204:207], v[188:191], v[64:67]
	v_mfma_f32_16x16x32_bf16 v[112:115], v[200:203], v[168:171], v[112:115]
	v_mfma_f32_16x16x32_bf16 v[104:107], v[212:215], v[168:171], v[104:107]
	v_mfma_f32_16x16x32_bf16 v[96:99], v[200:203], v[176:179], v[96:99]
	v_mfma_f32_16x16x32_bf16 v[88:91], v[212:215], v[176:179], v[88:91]
	v_mfma_f32_16x16x32_bf16 v[80:83], v[200:203], v[184:187], v[80:83]
	v_mfma_f32_16x16x32_bf16 v[72:75], v[212:215], v[184:187], v[72:75]
	v_mfma_f32_16x16x32_bf16 v[68:71], v[200:203], v[192:195], v[68:71]
	v_mfma_f32_16x16x32_bf16 v[64:67], v[212:215], v[192:195], v[64:67]
	s_barrier
	s_setprio 0
	s_mov_b32 m0, s31
	v_lshl_add_u64 v[216:217], s[42:43], 0, v[130:131]
	ds_read_b128 v[164:167], v146 offset:16384
	ds_read_b128 v[168:171], v146 offset:17408
	ds_read_b128 v[172:175], v146 offset:18432
	ds_read_b128 v[176:179], v146 offset:19456
	ds_read_b128 v[180:183], v146 offset:20480
	ds_read_b128 v[184:187], v146 offset:21504
	ds_read_b128 v[188:191], v146 offset:22528
	ds_read_b128 v[192:195], v146 offset:23552
	global_load_lds_dwordx4 v[216:217], off
	s_mov_b32 m0, s65
	v_lshl_add_u64 v[218:219], s[42:43], 0, v[132:133]
	global_load_lds_dwordx4 v[218:219], off
	s_setprio 1
	s_barrier
	s_waitcnt lgkmcnt(0)
	v_mfma_f32_16x16x32_bf16 v[60:63], v[148:151], v[164:167], v[60:63]
	v_mfma_f32_16x16x32_bf16 v[56:59], v[156:159], v[164:167], v[56:59]
	v_mfma_f32_16x16x32_bf16 v[52:55], v[148:151], v[172:175], v[52:55]
	v_mfma_f32_16x16x32_bf16 v[44:47], v[156:159], v[172:175], v[44:47]
	v_mfma_f32_16x16x32_bf16 v[36:39], v[148:151], v[180:183], v[36:39]
	v_mfma_f32_16x16x32_bf16 v[28:31], v[156:159], v[180:183], v[28:31]
	v_mfma_f32_16x16x32_bf16 v[20:23], v[148:151], v[188:191], v[20:23]
	v_mfma_f32_16x16x32_bf16 v[12:15], v[156:159], v[188:191], v[12:15]
	v_mfma_f32_16x16x32_bf16 v[60:63], v[152:155], v[168:171], v[60:63]
	v_mfma_f32_16x16x32_bf16 v[56:59], v[160:163], v[168:171], v[56:59]
	v_mfma_f32_16x16x32_bf16 v[52:55], v[152:155], v[176:179], v[52:55]
	v_mfma_f32_16x16x32_bf16 v[44:47], v[160:163], v[176:179], v[44:47]
	v_mfma_f32_16x16x32_bf16 v[36:39], v[152:155], v[184:187], v[36:39]
	v_mfma_f32_16x16x32_bf16 v[28:31], v[160:163], v[184:187], v[28:31]
	v_mfma_f32_16x16x32_bf16 v[20:23], v[152:155], v[192:195], v[20:23]
	v_mfma_f32_16x16x32_bf16 v[12:15], v[160:163], v[192:195], v[12:15]
	s_barrier
	s_setprio 0
	s_add_u32 s76, s40, 0x40000
	s_addc_u32 s77, s41, 0
	s_add_i32 s78, s78, s64
	s_mov_b32 m0, s78
	v_lshl_add_u64 v[148:149], s[76:77], 0, v[128:129]
	global_load_lds_dwordx4 v[148:149], off
	s_add_i32 m0, s78, 0x2000
	v_lshl_add_u64 v[148:149], s[76:77], 0, v[134:135]
	global_load_lds_dwordx4 v[148:149], off
	s_waitcnt vmcnt(6)
	s_setprio 1
	s_barrier
	v_mfma_f32_16x16x32_bf16 v[48:51], v[196:199], v[164:167], v[48:51]
	v_mfma_f32_16x16x32_bf16 v[40:43], v[204:207], v[164:167], v[40:43]
	v_mfma_f32_16x16x32_bf16 v[32:35], v[196:199], v[172:175], v[32:35]
	v_mfma_f32_16x16x32_bf16 v[24:27], v[204:207], v[172:175], v[24:27]
	v_mfma_f32_16x16x32_bf16 v[16:19], v[196:199], v[180:183], v[16:19]
	v_mfma_f32_16x16x32_bf16 v[8:11], v[204:207], v[180:183], v[8:11]
	v_mfma_f32_16x16x32_bf16 v[4:7], v[196:199], v[188:191], v[4:7]
	v_mfma_f32_16x16x32_bf16 v[0:3], v[204:207], v[188:191], v[0:3]
	v_mfma_f32_16x16x32_bf16 v[48:51], v[200:203], v[168:171], v[48:51]
	v_mfma_f32_16x16x32_bf16 v[40:43], v[212:215], v[168:171], v[40:43]
	v_mfma_f32_16x16x32_bf16 v[32:35], v[200:203], v[176:179], v[32:35]
	v_mfma_f32_16x16x32_bf16 v[24:27], v[212:215], v[176:179], v[24:27]
	v_mfma_f32_16x16x32_bf16 v[16:19], v[200:203], v[184:187], v[16:19]
	v_mfma_f32_16x16x32_bf16 v[8:11], v[212:215], v[184:187], v[8:11]
	v_mfma_f32_16x16x32_bf16 v[4:7], v[200:203], v[192:195], v[4:7]
	v_mfma_f32_16x16x32_bf16 v[0:3], v[212:215], v[192:195], v[0:3]
	s_barrier
	s_setprio 0
	s_add_i32 s76, 0, 0x18000
	v_add_u32_e32 v147, s76, v144
	ds_read_b128 v[148:151], v147
	ds_read_b128 v[152:155], v147 offset:1024
	ds_read_b128 v[156:159], v147 offset:2048
	ds_read_b128 v[160:163], v147 offset:3072
	s_add_u32 s42, s42, 0x40000
	s_addc_u32 s43, s43, 0
	s_mov_b32 m0, s66
	v_lshl_add_u64 v[196:197], s[42:43], 0, v[130:131]
	ds_read_b128 v[164:167], v146 offset:32768
	ds_read_b128 v[168:171], v146 offset:33792
	ds_read_b128 v[172:175], v146 offset:34816
	ds_read_b128 v[176:179], v146 offset:35840
	ds_read_b128 v[180:183], v146 offset:36864
	ds_read_b128 v[184:187], v146 offset:37888
	ds_read_b128 v[188:191], v146 offset:38912
	ds_read_b128 v[192:195], v146 offset:39936
	global_load_lds_dwordx4 v[196:197], off
	s_mov_b32 m0, s67
	v_lshl_add_u64 v[196:197], s[42:43], 0, v[132:133]
	global_load_lds_dwordx4 v[196:197], off
	s_waitcnt lgkmcnt(8)
	s_setprio 1
	s_barrier
	s_waitcnt lgkmcnt(0)
	v_mfma_f32_16x16x32_bf16 v[124:127], v[148:151], v[164:167], v[124:127]
	v_mfma_f32_16x16x32_bf16 v[120:123], v[156:159], v[164:167], v[120:123]
	v_mfma_f32_16x16x32_bf16 v[116:119], v[148:151], v[172:175], v[116:119]
	v_mfma_f32_16x16x32_bf16 v[108:111], v[156:159], v[172:175], v[108:111]
	v_mfma_f32_16x16x32_bf16 v[100:103], v[148:151], v[180:183], v[100:103]
	v_mfma_f32_16x16x32_bf16 v[92:95], v[156:159], v[180:183], v[92:95]
	v_mfma_f32_16x16x32_bf16 v[84:87], v[148:151], v[188:191], v[84:87]
	v_mfma_f32_16x16x32_bf16 v[76:79], v[156:159], v[188:191], v[76:79]
	v_mfma_f32_16x16x32_bf16 v[124:127], v[152:155], v[168:171], v[124:127]
	v_mfma_f32_16x16x32_bf16 v[120:123], v[160:163], v[168:171], v[120:123]
	v_mfma_f32_16x16x32_bf16 v[116:119], v[152:155], v[176:179], v[116:119]
	v_mfma_f32_16x16x32_bf16 v[108:111], v[160:163], v[176:179], v[108:111]
	v_mfma_f32_16x16x32_bf16 v[100:103], v[152:155], v[184:187], v[100:103]
	v_mfma_f32_16x16x32_bf16 v[92:95], v[160:163], v[184:187], v[92:95]
	v_mfma_f32_16x16x32_bf16 v[84:87], v[152:155], v[192:195], v[84:87]
	v_mfma_f32_16x16x32_bf16 v[76:79], v[160:163], v[192:195], v[76:79]
	s_barrier
	s_setprio 0
	s_add_i32 s42, 0, 0x1c000
	s_add_i32 s43, s76, s64
	v_add_u32_e32 v147, s42, v144
	v_lshl_add_u64 v[140:141], v[140:141], 0, s[2:3]
	s_mov_b32 m0, s43
	ds_read_b128 v[196:199], v147
	ds_read_b128 v[200:203], v147 offset:1024
	ds_read_b128 v[204:207], v147 offset:2048
	ds_read_b128 v[212:215], v147 offset:3072
	global_load_lds_dwordx4 v[140:141], off
	s_add_i32 m0, s43, 0x2000
	v_lshl_add_u64 v[140:141], v[208:209], 0, s[2:3]
	global_load_lds_dwordx4 v[140:141], off
	s_setprio 1
	s_barrier
	s_waitcnt lgkmcnt(0)
	v_mfma_f32_16x16x32_bf16 v[112:115], v[196:199], v[164:167], v[112:115]
	v_mfma_f32_16x16x32_bf16 v[104:107], v[204:207], v[164:167], v[104:107]
	v_mfma_f32_16x16x32_bf16 v[96:99], v[196:199], v[172:175], v[96:99]
	v_mfma_f32_16x16x32_bf16 v[88:91], v[204:207], v[172:175], v[88:91]
	v_mfma_f32_16x16x32_bf16 v[80:83], v[196:199], v[180:183], v[80:83]
	v_mfma_f32_16x16x32_bf16 v[72:75], v[204:207], v[180:183], v[72:75]
	v_mfma_f32_16x16x32_bf16 v[68:71], v[196:199], v[188:191], v[68:71]
	v_mfma_f32_16x16x32_bf16 v[64:67], v[204:207], v[188:191], v[64:67]
	v_mfma_f32_16x16x32_bf16 v[112:115], v[200:203], v[168:171], v[112:115]
	v_mfma_f32_16x16x32_bf16 v[104:107], v[212:215], v[168:171], v[104:107]
	v_mfma_f32_16x16x32_bf16 v[96:99], v[200:203], v[176:179], v[96:99]
	v_mfma_f32_16x16x32_bf16 v[88:91], v[212:215], v[176:179], v[88:91]
	v_mfma_f32_16x16x32_bf16 v[80:83], v[200:203], v[184:187], v[80:83]
	v_mfma_f32_16x16x32_bf16 v[72:75], v[212:215], v[184:187], v[72:75]
	v_mfma_f32_16x16x32_bf16 v[68:71], v[200:203], v[192:195], v[68:71]
	v_mfma_f32_16x16x32_bf16 v[64:67], v[212:215], v[192:195], v[64:67]
	s_barrier
	s_setprio 0
	s_mov_b32 m0, s0
	v_lshl_add_u64 v[140:141], v[216:217], 0, s[2:3]
	ds_read_b128 v[164:167], v146 offset:49152
	ds_read_b128 v[168:171], v146 offset:50176
	ds_read_b128 v[172:175], v146 offset:51200
	ds_read_b128 v[176:179], v146 offset:52224
	ds_read_b128 v[180:183], v146 offset:53248
	ds_read_b128 v[184:187], v146 offset:54272
	ds_read_b128 v[188:191], v146 offset:55296
	ds_read_b128 v[192:195], v146 offset:56320
	global_load_lds_dwordx4 v[140:141], off
	s_mov_b32 m0, s68
	v_lshl_add_u64 v[140:141], v[218:219], 0, s[2:3]
	global_load_lds_dwordx4 v[140:141], off
	s_setprio 1
	s_barrier
	s_waitcnt lgkmcnt(0)
	v_mfma_f32_16x16x32_bf16 v[60:63], v[148:151], v[164:167], v[60:63]
	v_mfma_f32_16x16x32_bf16 v[56:59], v[156:159], v[164:167], v[56:59]
	v_mfma_f32_16x16x32_bf16 v[52:55], v[148:151], v[172:175], v[52:55]
	v_mfma_f32_16x16x32_bf16 v[44:47], v[156:159], v[172:175], v[44:47]
	v_mfma_f32_16x16x32_bf16 v[36:39], v[148:151], v[180:183], v[36:39]
	v_mfma_f32_16x16x32_bf16 v[28:31], v[156:159], v[180:183], v[28:31]
	v_mfma_f32_16x16x32_bf16 v[20:23], v[148:151], v[188:191], v[20:23]
	v_mfma_f32_16x16x32_bf16 v[12:15], v[156:159], v[188:191], v[12:15]
	v_mfma_f32_16x16x32_bf16 v[60:63], v[152:155], v[168:171], v[60:63]
	v_mfma_f32_16x16x32_bf16 v[56:59], v[160:163], v[168:171], v[56:59]
	v_mfma_f32_16x16x32_bf16 v[52:55], v[152:155], v[176:179], v[52:55]
	v_mfma_f32_16x16x32_bf16 v[44:47], v[160:163], v[176:179], v[44:47]
	v_mfma_f32_16x16x32_bf16 v[36:39], v[152:155], v[184:187], v[36:39]
	v_mfma_f32_16x16x32_bf16 v[28:31], v[160:163], v[184:187], v[28:31]
	v_mfma_f32_16x16x32_bf16 v[20:23], v[152:155], v[192:195], v[20:23]
	v_mfma_f32_16x16x32_bf16 v[12:15], v[160:163], v[192:195], v[12:15]
	s_barrier
	s_setprio 0
	s_add_u32 s40, s40, 0x40080
	s_addc_u32 s41, s41, 0
	s_add_i32 s42, s42, s64
	s_mov_b32 m0, s42
	v_lshl_add_u64 v[140:141], s[40:41], 0, v[128:129]
	global_load_lds_dwordx4 v[140:141], off
	s_add_i32 m0, s42, 0x2000
	v_lshl_add_u64 v[140:141], s[40:41], 0, v[134:135]
	global_load_lds_dwordx4 v[140:141], off
	s_waitcnt vmcnt(6)
	s_setprio 1
	s_barrier
	v_mfma_f32_16x16x32_bf16 v[48:51], v[196:199], v[164:167], v[48:51]
	v_mfma_f32_16x16x32_bf16 v[40:43], v[204:207], v[164:167], v[40:43]
	v_mfma_f32_16x16x32_bf16 v[32:35], v[196:199], v[172:175], v[32:35]
	v_mfma_f32_16x16x32_bf16 v[24:27], v[204:207], v[172:175], v[24:27]
	v_mfma_f32_16x16x32_bf16 v[16:19], v[196:199], v[180:183], v[16:19]
	v_mfma_f32_16x16x32_bf16 v[8:11], v[204:207], v[180:183], v[8:11]
	v_mfma_f32_16x16x32_bf16 v[4:7], v[196:199], v[188:191], v[4:7]
	v_mfma_f32_16x16x32_bf16 v[0:3], v[204:207], v[188:191], v[0:3]
	v_mfma_f32_16x16x32_bf16 v[48:51], v[200:203], v[168:171], v[48:51]
	v_mfma_f32_16x16x32_bf16 v[40:43], v[212:215], v[168:171], v[40:43]
	v_mfma_f32_16x16x32_bf16 v[32:35], v[200:203], v[176:179], v[32:35]
	v_mfma_f32_16x16x32_bf16 v[24:27], v[212:215], v[176:179], v[24:27]
	v_mfma_f32_16x16x32_bf16 v[16:19], v[200:203], v[184:187], v[16:19]
	v_mfma_f32_16x16x32_bf16 v[8:11], v[212:215], v[184:187], v[8:11]
	v_mfma_f32_16x16x32_bf16 v[4:7], v[200:203], v[192:195], v[4:7]
	v_mfma_f32_16x16x32_bf16 v[0:3], v[212:215], v[192:195], v[0:3]
	s_barrier
	s_setprio 0
	s_add_i32 s75, s75, 2
	s_add_u32 s38, s38, 0x100
	s_addc_u32 s39, s39, 0
	s_add_u32 s73, s73, 0x100
	s_addc_u32 s74, s74, 0
	s_cmp_gt_u32 s75, 13
	s_cbranch_scc0 .LBB0_220
	v_lshl_add_u32 v148, s30, 8, v143
	v_ashrrev_i32_e32 v149, 31, v148
	v_lshl_or_b32 v140, s70, 8, v145
	v_ashrrev_i32_e32 v141, 31, v140
	v_lshlrev_b64 v[150:151], 13, v[148:149]
	v_lshl_add_u64 v[150:151], s[8:9], 0, v[150:151]
	v_lshlrev_b64 v[152:153], 1, v[140:141]
	v_lshl_add_u64 v[140:141], v[150:151], 0, v[152:153]
	v_cvt_pk_bf16_f32 v124, v124, v125
	v_cvt_pk_bf16_f32 v125, v126, v127
	v_cvt_pk_bf16_f32 v126, v120, v121
	v_cvt_pk_bf16_f32 v127, v122, v123
	global_store_dwordx4 v[140:141], v[124:127], off nt
	v_cvt_pk_bf16_f32 v112, v112, v113
	v_cvt_pk_bf16_f32 v113, v114, v115
	v_cvt_pk_bf16_f32 v114, v104, v105
	v_or_b32_e32 v104, 16, v148
	v_ashrrev_i32_e32 v105, 31, v104
	v_lshlrev_b64 v[104:105], 13, v[104:105]
	v_lshl_add_u64 v[104:105], s[8:9], 0, v[104:105]
	v_cvt_pk_bf16_f32 v115, v106, v107
	global_store_dwordx4 v[140:141], v[112:115], off offset:256 nt
	s_mov_b32 s15, 0x100000
	s_mov_b64 s[38:39], 0x100000
	v_lshl_add_u64 v[112:113], v[104:105], 0, v[152:153]
	v_cvt_pk_bf16_f32 v104, v116, v117
	v_cvt_pk_bf16_f32 v105, v118, v119
	v_cvt_pk_bf16_f32 v106, v108, v109
	v_cvt_pk_bf16_f32 v107, v110, v111
	global_store_dwordx4 v[112:113], v[104:107], off nt
	v_cvt_pk_bf16_f32 v96, v96, v97
	v_cvt_pk_bf16_f32 v97, v98, v99
	v_cvt_pk_bf16_f32 v98, v88, v89
	v_or_b32_e32 v88, 32, v148
	v_ashrrev_i32_e32 v89, 31, v88
	v_lshlrev_b64 v[88:89], 13, v[88:89]
	v_lshl_add_u64 v[88:89], s[8:9], 0, v[88:89]
	v_cvt_pk_bf16_f32 v99, v90, v91
	global_store_dwordx4 v[112:113], v[96:99], off offset:256 nt
	s_mov_b32 s70, s14
	s_mov_b32 s30, s28
	v_lshl_add_u64 v[96:97], v[88:89], 0, v[152:153]
	v_cvt_pk_bf16_f32 v88, v100, v101
	v_cvt_pk_bf16_f32 v89, v102, v103
	v_cvt_pk_bf16_f32 v90, v92, v93
	v_cvt_pk_bf16_f32 v91, v94, v95
	global_store_dwordx4 v[96:97], v[88:91], off nt
	v_cvt_pk_bf16_f32 v80, v80, v81
	v_cvt_pk_bf16_f32 v81, v82, v83
	v_cvt_pk_bf16_f32 v82, v72, v73
	v_or_b32_e32 v72, 48, v148
	v_ashrrev_i32_e32 v73, 31, v72
	v_lshlrev_b64 v[72:73], 13, v[72:73]
	v_lshl_add_u64 v[72:73], s[8:9], 0, v[72:73]
	v_cvt_pk_bf16_f32 v83, v74, v75
	global_store_dwordx4 v[96:97], v[80:83], off offset:256 nt
	s_mov_b64 s[40:41], s[36:37]
	s_nop 0
	v_lshl_add_u64 v[80:81], v[72:73], 0, v[152:153]
	v_cvt_pk_bf16_f32 v72, v84, v85
	v_cvt_pk_bf16_f32 v73, v86, v87
	v_cvt_pk_bf16_f32 v74, v76, v77
	v_cvt_pk_bf16_f32 v75, v78, v79
	global_store_dwordx4 v[80:81], v[72:75], off nt
	v_cvt_pk_bf16_f32 v68, v68, v69
	v_cvt_pk_bf16_f32 v69, v70, v71
	v_cvt_pk_bf16_f32 v70, v64, v65
	v_cvt_pk_bf16_f32 v71, v66, v67
	global_store_dwordx4 v[80:81], v[68:71], off offset:256 nt
	v_cvt_pk_bf16_f32 v60, v60, v61
	v_cvt_pk_bf16_f32 v61, v62, v63
	v_cvt_pk_bf16_f32 v62, v56, v57
	v_add_co_u32_e32 v56, vcc, s15, v140
	v_lshl_add_u64 v[64:65], v[140:141], 0, s[38:39]
	s_nop 0
	v_addc_co_u32_e32 v57, vcc, 0, v141, vcc
	s_mov_b32 s15, 0x120000
	v_cvt_pk_bf16_f32 v63, v58, v59
	global_store_dwordx4 v[56:57], v[60:63], off nt
	v_cvt_pk_bf16_f32 v48, v48, v49
	v_cvt_pk_bf16_f32 v49, v50, v51
	v_cvt_pk_bf16_f32 v50, v40, v41
	v_cvt_pk_bf16_f32 v51, v42, v43
	global_store_dwordx4 v[64:65], v[48:51], off offset:256 nt
	s_mov_b64 s[38:39], 0x120000
	v_cvt_pk_bf16_f32 v40, v52, v53
	v_cvt_pk_bf16_f32 v41, v54, v55
	v_cvt_pk_bf16_f32 v42, v44, v45
	v_add_co_u32_e32 v44, vcc, s15, v140
	v_lshl_add_u64 v[48:49], v[140:141], 0, s[38:39]
	s_nop 0
	v_addc_co_u32_e32 v45, vcc, 0, v141, vcc
	s_mov_b32 s15, 0x140000
	v_cvt_pk_bf16_f32 v43, v46, v47
	global_store_dwordx4 v[44:45], v[40:43], off nt
	v_cvt_pk_bf16_f32 v32, v32, v33
	v_cvt_pk_bf16_f32 v33, v34, v35
	v_cvt_pk_bf16_f32 v34, v24, v25
	v_cvt_pk_bf16_f32 v35, v26, v27
	global_store_dwordx4 v[48:49], v[32:35], off offset:256 nt
	s_mov_b64 s[38:39], 0x140000
	v_cvt_pk_bf16_f32 v24, v36, v37
	v_cvt_pk_bf16_f32 v25, v38, v39
	v_cvt_pk_bf16_f32 v26, v28, v29
	v_add_co_u32_e32 v28, vcc, s15, v140
	v_lshl_add_u64 v[32:33], v[140:141], 0, s[38:39]
	s_nop 0
	v_addc_co_u32_e32 v29, vcc, 0, v141, vcc
	s_mov_b32 s15, 0x160000
	v_cvt_pk_bf16_f32 v27, v30, v31
	global_store_dwordx4 v[28:29], v[24:27], off nt
	v_cvt_pk_bf16_f32 v16, v16, v17
	v_cvt_pk_bf16_f32 v17, v18, v19
	v_cvt_pk_bf16_f32 v18, v8, v9
	v_cvt_pk_bf16_f32 v19, v10, v11
	global_store_dwordx4 v[32:33], v[16:19], off offset:256 nt
	v_cvt_pk_bf16_f32 v8, v20, v21
	v_cvt_pk_bf16_f32 v9, v22, v23
	v_cvt_pk_bf16_f32 v10, v12, v13
	v_add_co_u32_e32 v12, vcc, s15, v140
	s_mov_b64 s[38:39], 0x160000
	s_nop 0
	v_addc_co_u32_e32 v13, vcc, 0, v141, vcc
	v_lshl_add_u64 v[16:17], v[140:141], 0, s[38:39]
	s_and_b64 vcc, exec, s[12:13]
	s_mov_b64 s[38:39], s[34:35]
	v_cvt_pk_bf16_f32 v11, v14, v15
	global_store_dwordx4 v[12:13], v[8:11], off nt
	v_cvt_pk_bf16_f32 v4, v4, v5
	v_cvt_pk_bf16_f32 v5, v6, v7
	v_cvt_pk_bf16_f32 v6, v0, v1
	v_cvt_pk_bf16_f32 v7, v2, v3
	global_store_dwordx4 v[16:17], v[4:7], off offset:256 nt
	s_cbranch_vccz .LBB0_213
	s_waitcnt vmcnt(0)
	s_cmpk_gt_u32 s49, 0xff
	s_cbranch_scc1 .LBB0_183
	s_barrier
	s_branch .LBB0_183

.LBB0_262:
	ds_read_b128 v[128:131], v157
	ds_read_b128 v[132:135], v157 offset:1024
	ds_read_b128 v[160:163], v157 offset:2048
	ds_read_b128 v[164:167], v157 offset:3072
	s_add_u32 s34, s30, 0xfffc0080
	s_addc_u32 s35, s31, -1
	s_cmp_eq_u32 s59, 28
	s_cselect_b32 s37, s1, s35
	s_cselect_b32 s36, s2, s34
	s_cselect_b32 s35, s13, s58
	s_cselect_b32 s34, s15, s55
	v_lshl_add_u64 v[152:153], s[30:31], 0, v[148:149]
	s_add_i32 m0, s40, 0xc000
	ds_read_b128 v[168:171], v158
	ds_read_b128 v[172:175], v158 offset:1024
	ds_read_b128 v[176:179], v158 offset:2048
	ds_read_b128 v[180:183], v158 offset:3072
	ds_read_b128 v[184:187], v158 offset:4096
	ds_read_b128 v[188:191], v158 offset:5120
	ds_read_b128 v[192:195], v158 offset:6144
	ds_read_b128 v[196:199], v158 offset:7168
	global_load_lds_dwordx4 v[152:153], off
	s_add_i32 m0, s40, 0xe000
	v_lshl_add_u64 v[152:153], s[30:31], 0, v[150:151]
	global_load_lds_dwordx4 v[152:153], off
	s_waitcnt lgkmcnt(8)
	s_setprio 1
	s_barrier
	s_waitcnt lgkmcnt(0)
	v_mfma_f32_16x16x32_bf16 v[124:127], v[128:131], v[168:171], v[124:127]
	v_mfma_f32_16x16x32_bf16 v[100:103], v[160:163], v[168:171], v[100:103]
	v_mfma_f32_16x16x32_bf16 v[116:119], v[128:131], v[176:179], v[116:119]
	v_mfma_f32_16x16x32_bf16 v[96:99], v[160:163], v[176:179], v[96:99]
	v_mfma_f32_16x16x32_bf16 v[92:95], v[128:131], v[184:187], v[92:95]
	v_mfma_f32_16x16x32_bf16 v[72:75], v[160:163], v[184:187], v[72:75]
	v_mfma_f32_16x16x32_bf16 v[84:87], v[128:131], v[192:195], v[84:87]
	v_mfma_f32_16x16x32_bf16 v[60:63], v[160:163], v[192:195], v[60:63]
	v_mfma_f32_16x16x32_bf16 v[124:127], v[132:135], v[172:175], v[124:127]
	v_mfma_f32_16x16x32_bf16 v[100:103], v[164:167], v[172:175], v[100:103]
	v_mfma_f32_16x16x32_bf16 v[116:119], v[132:135], v[180:183], v[116:119]
	v_mfma_f32_16x16x32_bf16 v[96:99], v[164:167], v[180:183], v[96:99]
	v_mfma_f32_16x16x32_bf16 v[92:95], v[132:135], v[188:191], v[92:95]
	v_mfma_f32_16x16x32_bf16 v[72:75], v[164:167], v[188:191], v[72:75]
	v_mfma_f32_16x16x32_bf16 v[84:87], v[132:135], v[196:199], v[84:87]
	v_mfma_f32_16x16x32_bf16 v[60:63], v[164:167], v[196:199], v[60:63]
	s_barrier
	s_setprio 0
	s_add_i32 s60, s51, s39
	v_lshl_add_u64 v[152:153], s[34:35], 0, v[138:139]
	s_mov_b32 m0, s60
	ds_read_b128 v[200:203], v159
	ds_read_b128 v[204:207], v159 offset:1024
	ds_read_b128 v[212:215], v159 offset:2048
	ds_read_b128 v[216:219], v159 offset:3072
	global_load_lds_dwordx4 v[152:153], off
	s_add_i32 m0, s60, 0x2000
	v_lshl_add_u64 v[208:209], s[34:35], 0, v[142:143]
	global_load_lds_dwordx4 v[208:209], off
	s_setprio 1
	s_barrier
	s_waitcnt lgkmcnt(0)
	v_mfma_f32_16x16x32_bf16 v[120:123], v[200:203], v[168:171], v[120:123]
	v_mfma_f32_16x16x32_bf16 v[108:111], v[212:215], v[168:171], v[108:111]
	v_mfma_f32_16x16x32_bf16 v[112:115], v[200:203], v[176:179], v[112:115]
	v_mfma_f32_16x16x32_bf16 v[104:107], v[212:215], v[176:179], v[104:107]
	v_mfma_f32_16x16x32_bf16 v[88:91], v[200:203], v[184:187], v[88:91]
	v_mfma_f32_16x16x32_bf16 v[80:83], v[212:215], v[184:187], v[80:83]
	v_mfma_f32_16x16x32_bf16 v[76:79], v[200:203], v[192:195], v[76:79]
	v_mfma_f32_16x16x32_bf16 v[68:71], v[212:215], v[192:195], v[68:71]
	v_mfma_f32_16x16x32_bf16 v[120:123], v[204:207], v[172:175], v[120:123]
	v_mfma_f32_16x16x32_bf16 v[108:111], v[216:219], v[172:175], v[108:111]
	v_mfma_f32_16x16x32_bf16 v[112:115], v[204:207], v[180:183], v[112:115]
	v_mfma_f32_16x16x32_bf16 v[104:107], v[216:219], v[180:183], v[104:107]
	v_mfma_f32_16x16x32_bf16 v[88:91], v[204:207], v[188:191], v[88:91]
	v_mfma_f32_16x16x32_bf16 v[80:83], v[216:219], v[188:191], v[80:83]
	v_mfma_f32_16x16x32_bf16 v[76:79], v[204:207], v[196:199], v[76:79]
	v_mfma_f32_16x16x32_bf16 v[68:71], v[216:219], v[196:199], v[68:71]
	s_barrier
	s_setprio 0
	s_mov_b32 m0, s40
	v_lshl_add_u64 v[220:221], s[36:37], 0, v[136:137]
	ds_read_b128 v[168:171], v158 offset:16384
	ds_read_b128 v[172:175], v158 offset:17408
	ds_read_b128 v[176:179], v158 offset:18432
	ds_read_b128 v[180:183], v158 offset:19456
	ds_read_b128 v[184:187], v158 offset:20480
	ds_read_b128 v[188:191], v158 offset:21504
	ds_read_b128 v[192:195], v158 offset:22528
	ds_read_b128 v[196:199], v158 offset:23552
	global_load_lds_dwordx4 v[220:221], off
	s_mov_b32 m0, s41
	v_lshl_add_u64 v[222:223], s[36:37], 0, v[140:141]
	global_load_lds_dwordx4 v[222:223], off
	s_setprio 1
	s_barrier
	s_waitcnt lgkmcnt(0)
	v_mfma_f32_16x16x32_bf16 v[64:67], v[128:131], v[168:171], v[64:67]
	v_mfma_f32_16x16x32_bf16 v[48:51], v[160:163], v[168:171], v[48:51]
	v_mfma_f32_16x16x32_bf16 v[44:47], v[128:131], v[176:179], v[44:47]
	v_mfma_f32_16x16x32_bf16 v[32:35], v[160:163], v[176:179], v[32:35]
	v_mfma_f32_16x16x32_bf16 v[28:31], v[128:131], v[184:187], v[28:31]
	v_mfma_f32_16x16x32_bf16 v[16:19], v[160:163], v[184:187], v[16:19]
	v_mfma_f32_16x16x32_bf16 v[12:15], v[128:131], v[192:195], v[12:15]
	v_mfma_f32_16x16x32_bf16 v[0:3], v[160:163], v[192:195], v[0:3]
	v_mfma_f32_16x16x32_bf16 v[64:67], v[132:135], v[172:175], v[64:67]
	v_mfma_f32_16x16x32_bf16 v[48:51], v[164:167], v[172:175], v[48:51]
	v_mfma_f32_16x16x32_bf16 v[44:47], v[132:135], v[180:183], v[44:47]
	v_mfma_f32_16x16x32_bf16 v[32:35], v[164:167], v[180:183], v[32:35]
	v_mfma_f32_16x16x32_bf16 v[28:31], v[132:135], v[188:191], v[28:31]
	v_mfma_f32_16x16x32_bf16 v[16:19], v[164:167], v[188:191], v[16:19]
	v_mfma_f32_16x16x32_bf16 v[12:15], v[132:135], v[196:199], v[12:15]
	v_mfma_f32_16x16x32_bf16 v[0:3], v[164:167], v[196:199], v[0:3]
	s_barrier
	s_setprio 0
	s_add_u32 s60, s34, 0x80000
	s_addc_u32 s61, s35, 0
	s_add_i32 s62, s53, s39
	s_mov_b32 m0, s62
	v_lshl_add_u64 v[128:129], s[60:61], 0, v[138:139]
	global_load_lds_dwordx4 v[128:129], off
	s_add_i32 m0, s62, 0x2000
	v_lshl_add_u64 v[128:129], s[60:61], 0, v[142:143]
	global_load_lds_dwordx4 v[128:129], off
	s_waitcnt vmcnt(6)
	s_setprio 1
	s_barrier
	v_mfma_f32_16x16x32_bf16 v[56:59], v[200:203], v[168:171], v[56:59]
	v_mfma_f32_16x16x32_bf16 v[52:55], v[212:215], v[168:171], v[52:55]
	v_mfma_f32_16x16x32_bf16 v[40:43], v[200:203], v[176:179], v[40:43]
	v_mfma_f32_16x16x32_bf16 v[36:39], v[212:215], v[176:179], v[36:39]
	v_mfma_f32_16x16x32_bf16 v[24:27], v[200:203], v[184:187], v[24:27]
	v_mfma_f32_16x16x32_bf16 v[20:23], v[212:215], v[184:187], v[20:23]
	v_mfma_f32_16x16x32_bf16 v[8:11], v[200:203], v[192:195], v[8:11]
	v_mfma_f32_16x16x32_bf16 v[4:7], v[212:215], v[192:195], v[4:7]
	v_mfma_f32_16x16x32_bf16 v[56:59], v[204:207], v[172:175], v[56:59]
	v_mfma_f32_16x16x32_bf16 v[52:55], v[216:219], v[172:175], v[52:55]
	v_mfma_f32_16x16x32_bf16 v[40:43], v[204:207], v[180:183], v[40:43]
	v_mfma_f32_16x16x32_bf16 v[36:39], v[216:219], v[180:183], v[36:39]
	v_mfma_f32_16x16x32_bf16 v[24:27], v[204:207], v[188:191], v[24:27]
	v_mfma_f32_16x16x32_bf16 v[20:23], v[216:219], v[188:191], v[20:23]
	v_mfma_f32_16x16x32_bf16 v[8:11], v[204:207], v[196:199], v[8:11]
	v_mfma_f32_16x16x32_bf16 v[4:7], v[216:219], v[196:199], v[4:7]
	s_barrier
	s_setprio 0
	s_add_i32 s60, 0, 0x18000
	v_add_u32_e32 v164, s60, v156
	ds_read_b128 v[128:131], v164
	ds_read_b128 v[132:135], v164 offset:1024
	ds_read_b128 v[160:163], v164 offset:2048
	ds_read_b128 v[164:167], v164 offset:3072
	s_add_u32 s36, s36, 0x40000
	s_addc_u32 s37, s37, 0
	s_mov_b32 m0, s42
	v_lshl_add_u64 v[200:201], s[36:37], 0, v[136:137]
	ds_read_b128 v[168:171], v158 offset:32768
	ds_read_b128 v[172:175], v158 offset:33792
	ds_read_b128 v[176:179], v158 offset:34816
	ds_read_b128 v[180:183], v158 offset:35840
	ds_read_b128 v[184:187], v158 offset:36864
	ds_read_b128 v[188:191], v158 offset:37888
	ds_read_b128 v[192:195], v158 offset:38912
	ds_read_b128 v[196:199], v158 offset:39936
	global_load_lds_dwordx4 v[200:201], off
	s_mov_b32 m0, s43
	v_lshl_add_u64 v[200:201], s[36:37], 0, v[140:141]
	global_load_lds_dwordx4 v[200:201], off
	s_waitcnt lgkmcnt(8)
	s_setprio 1
	s_barrier
	s_waitcnt lgkmcnt(0)
	v_mfma_f32_16x16x32_bf16 v[124:127], v[128:131], v[168:171], v[124:127]
	v_mfma_f32_16x16x32_bf16 v[100:103], v[160:163], v[168:171], v[100:103]
	v_mfma_f32_16x16x32_bf16 v[116:119], v[128:131], v[176:179], v[116:119]
	v_mfma_f32_16x16x32_bf16 v[96:99], v[160:163], v[176:179], v[96:99]
	v_mfma_f32_16x16x32_bf16 v[92:95], v[128:131], v[184:187], v[92:95]
	v_mfma_f32_16x16x32_bf16 v[72:75], v[160:163], v[184:187], v[72:75]
	v_mfma_f32_16x16x32_bf16 v[84:87], v[128:131], v[192:195], v[84:87]
	v_mfma_f32_16x16x32_bf16 v[60:63], v[160:163], v[192:195], v[60:63]
	v_mfma_f32_16x16x32_bf16 v[124:127], v[132:135], v[172:175], v[124:127]
	v_mfma_f32_16x16x32_bf16 v[100:103], v[164:167], v[172:175], v[100:103]
	v_mfma_f32_16x16x32_bf16 v[116:119], v[132:135], v[180:183], v[116:119]
	v_mfma_f32_16x16x32_bf16 v[96:99], v[164:167], v[180:183], v[96:99]
	v_mfma_f32_16x16x32_bf16 v[92:95], v[132:135], v[188:191], v[92:95]
	v_mfma_f32_16x16x32_bf16 v[72:75], v[164:167], v[188:191], v[72:75]
	v_mfma_f32_16x16x32_bf16 v[84:87], v[132:135], v[196:199], v[84:87]
	v_mfma_f32_16x16x32_bf16 v[60:63], v[164:167], v[196:199], v[60:63]
	s_barrier
	s_setprio 0
	s_add_i32 s36, 0, 0x1c000
	s_add_i32 s37, s60, s39
	v_add_u32_e32 v211, s36, v156
	v_lshl_add_u64 v[152:153], v[152:153], 0, s[4:5]
	s_mov_b32 m0, s37
	ds_read_b128 v[200:203], v211
	ds_read_b128 v[204:207], v211 offset:1024
	ds_read_b128 v[212:215], v211 offset:2048
	ds_read_b128 v[216:219], v211 offset:3072
	global_load_lds_dwordx4 v[152:153], off
	s_add_i32 m0, s37, 0x2000
	v_lshl_add_u64 v[152:153], v[208:209], 0, s[4:5]
	global_load_lds_dwordx4 v[152:153], off
	s_setprio 1
	s_barrier
	s_waitcnt lgkmcnt(0)
	v_mfma_f32_16x16x32_bf16 v[120:123], v[200:203], v[168:171], v[120:123]
	v_mfma_f32_16x16x32_bf16 v[108:111], v[212:215], v[168:171], v[108:111]
	v_mfma_f32_16x16x32_bf16 v[112:115], v[200:203], v[176:179], v[112:115]
	v_mfma_f32_16x16x32_bf16 v[104:107], v[212:215], v[176:179], v[104:107]
	v_mfma_f32_16x16x32_bf16 v[88:91], v[200:203], v[184:187], v[88:91]
	v_mfma_f32_16x16x32_bf16 v[80:83], v[212:215], v[184:187], v[80:83]
	v_mfma_f32_16x16x32_bf16 v[76:79], v[200:203], v[192:195], v[76:79]
	v_mfma_f32_16x16x32_bf16 v[68:71], v[212:215], v[192:195], v[68:71]
	v_mfma_f32_16x16x32_bf16 v[120:123], v[204:207], v[172:175], v[120:123]
	v_mfma_f32_16x16x32_bf16 v[108:111], v[216:219], v[172:175], v[108:111]
	v_mfma_f32_16x16x32_bf16 v[112:115], v[204:207], v[180:183], v[112:115]
	v_mfma_f32_16x16x32_bf16 v[104:107], v[216:219], v[180:183], v[104:107]
	v_mfma_f32_16x16x32_bf16 v[88:91], v[204:207], v[188:191], v[88:91]
	v_mfma_f32_16x16x32_bf16 v[80:83], v[216:219], v[188:191], v[80:83]
	v_mfma_f32_16x16x32_bf16 v[76:79], v[204:207], v[196:199], v[76:79]
	v_mfma_f32_16x16x32_bf16 v[68:71], v[216:219], v[196:199], v[68:71]
	s_barrier
	s_setprio 0
	s_mov_b32 m0, s48
	v_lshl_add_u64 v[152:153], v[220:221], 0, s[4:5]
	ds_read_b128 v[168:171], v158 offset:49152
	ds_read_b128 v[172:175], v158 offset:50176
	ds_read_b128 v[176:179], v158 offset:51200
	ds_read_b128 v[180:183], v158 offset:52224
	ds_read_b128 v[184:187], v158 offset:53248
	ds_read_b128 v[188:191], v158 offset:54272
	ds_read_b128 v[192:195], v158 offset:55296
	ds_read_b128 v[196:199], v158 offset:56320
	global_load_lds_dwordx4 v[152:153], off
	s_mov_b32 m0, s49
	v_lshl_add_u64 v[152:153], v[222:223], 0, s[4:5]
	global_load_lds_dwordx4 v[152:153], off
	s_setprio 1
	s_barrier
	s_waitcnt lgkmcnt(0)
	v_mfma_f32_16x16x32_bf16 v[64:67], v[128:131], v[168:171], v[64:67]
	v_mfma_f32_16x16x32_bf16 v[48:51], v[160:163], v[168:171], v[48:51]
	v_mfma_f32_16x16x32_bf16 v[44:47], v[128:131], v[176:179], v[44:47]
	v_mfma_f32_16x16x32_bf16 v[32:35], v[160:163], v[176:179], v[32:35]
	v_mfma_f32_16x16x32_bf16 v[28:31], v[128:131], v[184:187], v[28:31]
	v_mfma_f32_16x16x32_bf16 v[16:19], v[160:163], v[184:187], v[16:19]
	v_mfma_f32_16x16x32_bf16 v[12:15], v[128:131], v[192:195], v[12:15]
	v_mfma_f32_16x16x32_bf16 v[0:3], v[160:163], v[192:195], v[0:3]
	v_mfma_f32_16x16x32_bf16 v[64:67], v[132:135], v[172:175], v[64:67]
	v_mfma_f32_16x16x32_bf16 v[48:51], v[164:167], v[172:175], v[48:51]
	v_mfma_f32_16x16x32_bf16 v[44:47], v[132:135], v[180:183], v[44:47]
	v_mfma_f32_16x16x32_bf16 v[32:35], v[164:167], v[180:183], v[32:35]
	v_mfma_f32_16x16x32_bf16 v[28:31], v[132:135], v[188:191], v[28:31]
	v_mfma_f32_16x16x32_bf16 v[16:19], v[164:167], v[188:191], v[16:19]
	v_mfma_f32_16x16x32_bf16 v[12:15], v[132:135], v[196:199], v[12:15]
	v_mfma_f32_16x16x32_bf16 v[0:3], v[164:167], v[196:199], v[0:3]
	s_barrier
	s_setprio 0
	s_add_u32 s34, s34, 0x80080
	s_addc_u32 s35, s35, 0
	s_add_i32 s36, s36, s39
	s_mov_b32 m0, s36
	v_lshl_add_u64 v[128:129], s[34:35], 0, v[138:139]
	global_load_lds_dwordx4 v[128:129], off
	s_add_i32 m0, s36, 0x2000
	v_lshl_add_u64 v[128:129], s[34:35], 0, v[142:143]
	global_load_lds_dwordx4 v[128:129], off
	s_waitcnt vmcnt(6)
	s_setprio 1
	s_barrier
	v_mfma_f32_16x16x32_bf16 v[56:59], v[200:203], v[168:171], v[56:59]
	v_mfma_f32_16x16x32_bf16 v[52:55], v[212:215], v[168:171], v[52:55]
	v_mfma_f32_16x16x32_bf16 v[40:43], v[200:203], v[176:179], v[40:43]
	v_mfma_f32_16x16x32_bf16 v[36:39], v[212:215], v[176:179], v[36:39]
	v_mfma_f32_16x16x32_bf16 v[24:27], v[200:203], v[184:187], v[24:27]
	v_mfma_f32_16x16x32_bf16 v[20:23], v[212:215], v[184:187], v[20:23]
	v_mfma_f32_16x16x32_bf16 v[8:11], v[200:203], v[192:195], v[8:11]
	v_mfma_f32_16x16x32_bf16 v[4:7], v[212:215], v[192:195], v[4:7]
	v_mfma_f32_16x16x32_bf16 v[56:59], v[204:207], v[172:175], v[56:59]
	v_mfma_f32_16x16x32_bf16 v[52:55], v[216:219], v[172:175], v[52:55]
	v_mfma_f32_16x16x32_bf16 v[40:43], v[204:207], v[180:183], v[40:43]
	v_mfma_f32_16x16x32_bf16 v[36:39], v[216:219], v[180:183], v[36:39]
	v_mfma_f32_16x16x32_bf16 v[24:27], v[204:207], v[188:191], v[24:27]
	v_mfma_f32_16x16x32_bf16 v[20:23], v[216:219], v[188:191], v[20:23]
	v_mfma_f32_16x16x32_bf16 v[8:11], v[204:207], v[196:199], v[8:11]
	v_mfma_f32_16x16x32_bf16 v[4:7], v[216:219], v[196:199], v[4:7]
	s_barrier
	s_setprio 0
	s_add_i32 s59, s59, 2
	s_add_u32 s30, s30, 0x100
	s_addc_u32 s31, s31, 0
	s_add_u32 s55, s55, 0x100
	s_addc_u32 s58, s58, 0
	s_cmp_gt_u32 s59, 29
	s_cbranch_scc0 .LBB0_262
	s_cmp_gt_i32 s0, 31
	s_cselect_b64 vcc, -1, 0
	s_and_b64 s[30:31], vcc, exec
	s_cselect_b32 s2, 0x200, 0
	v_lshl_add_u64 v[128:129], v[144:145], 0, s[2:3]
	global_load_dwordx4 v[132:135], v[128:129], off
	s_nop 0
	global_load_dwordx4 v[128:131], v[128:129], off offset:16
	v_cndmask_b32_e32 v121, v125, v121, vcc
	v_cndmask_b32_e32 v120, v124, v120, vcc
	v_cndmask_b32_e32 v101, v101, v109, vcc
	v_cndmask_b32_e32 v100, v100, v108, vcc
	v_cndmask_b32_e32 v123, v127, v123, vcc
	v_cndmask_b32_e32 v122, v126, v122, vcc
	v_cndmask_b32_e32 v103, v103, v111, vcc
	v_cndmask_b32_e32 v102, v102, v110, vcc
	v_cndmask_b32_e32 v111, v119, v115, vcc
	v_cndmask_b32_e32 v110, v118, v114, vcc
	v_cndmask_b32_e32 v99, v99, v107, vcc
	v_cndmask_b32_e32 v98, v98, v106, vcc
	v_cndmask_b32_e32 v109, v117, v113, vcc
	v_cndmask_b32_e32 v108, v116, v112, vcc
	v_cndmask_b32_e32 v89, v93, v89, vcc
	v_cndmask_b32_e32 v88, v92, v88, vcc
	v_cndmask_b32_e32 v73, v73, v81, vcc
	v_cndmask_b32_e32 v72, v72, v80, vcc
	v_cndmask_b32_e32 v105, v97, v105, vcc
	v_cndmask_b32_e32 v104, v96, v104, vcc
	v_cndmask_b32_e32 v74, v74, v82, vcc
	v_lshl_add_u32 v152, s0, 8, v155
	v_ashrrev_i32_e32 v153, 31, v152
	v_lshlrev_b64 v[162:163], 8, v[152:153]
	v_cndmask_b32_e32 v75, v75, v83, vcc
	v_lshl_add_u64 v[96:97], v[146:147], 0, v[162:163]
	v_cndmask_b32_e32 v91, v95, v91, vcc
	v_cndmask_b32_e32 v90, v94, v90, vcc
	v_or_b32_e32 v160, 16, v152
	v_ashrrev_i32_e32 v161, 31, v160
	v_lshlrev_b64 v[106:107], 8, v[160:161]
	v_cndmask_b32_e32 v61, v61, v69, vcc
	v_cndmask_b32_e32 v60, v60, v68, vcc
	v_cndmask_b32_e32 v57, v65, v57, vcc
	v_cndmask_b32_e32 v56, v64, v56, vcc
	v_cndmask_b32_e32 v49, v49, v53, vcc
	v_cndmask_b32_e32 v48, v48, v52, vcc
	v_cndmask_b32_e32 v62, v62, v70, vcc
	v_cndmask_b32_e32 v50, v50, v54, vcc
	v_cndmask_b32_e32 v41, v45, v41, vcc
	v_cndmask_b32_e32 v40, v44, v40, vcc
	v_cndmask_b32_e32 v33, v33, v37, vcc
	v_cndmask_b32_e32 v32, v32, v36, vcc
	v_cndmask_b32_e32 v25, v29, v25, vcc
	v_cndmask_b32_e32 v24, v28, v24, vcc
	v_cndmask_b32_e32 v17, v17, v21, vcc
	v_cndmask_b32_e32 v16, v16, v20, vcc
	v_cndmask_b32_e32 v34, v34, v38, vcc
	v_cndmask_b32_e32 v18, v18, v22, vcc
	v_cndmask_b32_e32 v9, v13, v9, vcc
	v_cndmask_b32_e32 v8, v12, v8, vcc
	v_cndmask_b32_e32 v1, v1, v5, vcc
	v_cndmask_b32_e32 v0, v0, v4, vcc
	v_cndmask_b32_e32 v63, v63, v71, vcc
	v_cndmask_b32_e32 v51, v51, v55, vcc
	v_cndmask_b32_e32 v2, v2, v6, vcc
	v_cndmask_b32_e32 v35, v35, v39, vcc
	v_cndmask_b32_e32 v59, v67, v59, vcc
	v_cndmask_b32_e32 v58, v66, v58, vcc
	v_cndmask_b32_e32 v19, v19, v23, vcc
	v_cndmask_b32_e32 v43, v47, v43, vcc
	v_cndmask_b32_e32 v42, v46, v42, vcc
	v_cndmask_b32_e32 v3, v3, v7, vcc
	v_cndmask_b32_e32 v27, v31, v27, vcc
	v_cndmask_b32_e32 v26, v30, v26, vcc
	v_cndmask_b32_e32 v11, v15, v11, vcc
	v_cndmask_b32_e32 v10, v14, v10, vcc
	s_mov_b32 s0, 0x9000
	s_mov_b64 s[34:35], s[28:29]
	s_mov_b64 s[30:31], s[26:27]
	s_waitcnt vmcnt(0)
	v_pk_add_f32 v[114:115], v[120:121], v[132:133]
	v_pk_add_f32 v[100:101], v[100:101], v[128:129]
	v_pk_add_f32 v[112:113], v[122:123], v[134:135]
	v_pk_add_f32 v[102:103], v[102:103], v[130:131]
	v_pk_add_f32 v[116:117], v[98:99], v[130:131]
	v_mul_f32_e32 v98, 0xbfb8aa3b, v114
	v_mul_f32_e32 v99, 0xbfb8aa3b, v100
	v_mul_f32_e32 v118, 0xbfb8aa3b, v115
	v_mul_f32_e32 v119, 0xbfb8aa3b, v101
	v_mul_f32_e32 v120, 0xbfb8aa3b, v112
	v_mul_f32_e32 v121, 0xbfb8aa3b, v102
	v_mul_f32_e32 v122, 0xbfb8aa3b, v113
	v_mul_f32_e32 v123, 0xbfb8aa3b, v103
	v_exp_f32_e32 v98, v98
	v_exp_f32_e32 v99, v99
	v_exp_f32_e32 v118, v118
	v_exp_f32_e32 v119, v119
	v_exp_f32_e32 v120, v120
	v_exp_f32_e32 v121, v121
	v_exp_f32_e32 v122, v122
	v_exp_f32_e32 v123, v123
	v_pk_add_f32 v[88:89], v[88:89], v[132:133]
	v_pk_add_f32 v[72:73], v[72:73], v[128:129]
	v_add_f32_e32 v98, 1.0, v98
	v_add_f32_e32 v99, 1.0, v99
	v_add_f32_e32 v118, 1.0, v118
	v_add_f32_e32 v119, 1.0, v119
	v_mul_f32_e32 v80, 0xbfb8aa3b, v88
	v_mul_f32_e32 v81, 0xbfb8aa3b, v72
	v_mul_f32_e32 v82, 0xbfb8aa3b, v89
	v_pk_add_f32 v[104:105], v[104:105], v[128:129]
	v_add_f32_e32 v120, 1.0, v120
	v_add_f32_e32 v121, 1.0, v121
	v_add_f32_e32 v122, 1.0, v122
	v_add_f32_e32 v123, 1.0, v123
	v_rcp_f32_e32 v98, v98
	v_rcp_f32_e32 v99, v99
	v_rcp_f32_e32 v118, v118
	v_rcp_f32_e32 v119, v119
	v_exp_f32_e32 v80, v80
	v_exp_f32_e32 v81, v81
	v_exp_f32_e32 v82, v82
	v_mul_f32_e32 v127, 0xbfb8aa3b, v105
	v_rcp_f32_e32 v120, v120
	v_rcp_f32_e32 v121, v121
	v_rcp_f32_e32 v122, v122
	v_rcp_f32_e32 v123, v123
	v_exp_f32_e32 v127, v127
	v_mul_f32_e32 v98, v114, v98
	v_mul_f32_e32 v100, v100, v99
	v_mul_f32_e32 v99, v115, v118
	v_mul_f32_e32 v101, v101, v119
	v_add_f32_e32 v80, 1.0, v80
	v_add_f32_e32 v81, 1.0, v81
	v_add_f32_e32 v82, 1.0, v82
	v_mul_f32_e32 v83, 0xbfb8aa3b, v73
	v_pk_add_f32 v[110:111], v[110:111], v[134:135]
	v_mul_f32_e32 v112, v112, v120
	v_mul_f32_e32 v102, v102, v121
	v_mul_f32_e32 v113, v113, v122
	v_mul_f32_e32 v103, v103, v123
	v_cvt_pk_bf16_f32 v98, v98, v99
	v_cvt_pk_bf16_f32 v99, v112, v113
	v_cvt_pk_bf16_f32 v100, v100, v101
	v_cvt_pk_bf16_f32 v101, v102, v103
	v_rcp_f32_e32 v80, v80
	v_rcp_f32_e32 v81, v81
	v_rcp_f32_e32 v82, v82
	v_exp_f32_e32 v83, v83
	global_store_dwordx4 v[96:97], v[98:101], off
	v_pk_add_f32 v[90:91], v[90:91], v[134:135]
	v_pk_add_f32 v[74:75], v[74:75], v[130:131]
	v_add_f32_e32 v99, 1.0, v127
	v_mul_f32_e32 v100, 0xbfb8aa3b, v110
	v_mul_f32_e32 v101, 0xbfb8aa3b, v116
	v_rcp_f32_e32 v99, v99
	v_exp_f32_e32 v100, v100
	v_exp_f32_e32 v101, v101
	v_pk_add_f32 v[108:109], v[108:109], v[132:133]
	v_mul_f32_e32 v88, v88, v80
	v_mul_f32_e32 v92, v72, v81
	v_mul_f32_e32 v72, v89, v82
	v_add_f32_e32 v80, 1.0, v83
	v_mul_f32_e32 v81, 0xbfb8aa3b, v90
	v_mul_f32_e32 v82, 0xbfb8aa3b, v74
	v_mul_f32_e32 v126, 0xbfb8aa3b, v109
	v_rcp_f32_e32 v80, v80
	v_exp_f32_e32 v81, v81
	v_exp_f32_e32 v82, v82
	v_mul_f32_e32 v124, 0xbfb8aa3b, v108
	v_exp_f32_e32 v126, v126
	v_mul_f32_e32 v105, v105, v99
	v_add_f32_e32 v99, 1.0, v100
	v_add_f32_e32 v100, 1.0, v101
	v_mul_f32_e32 v101, 0xbfb8aa3b, v111
	v_mul_f32_e32 v102, 0xbfb8aa3b, v117
	v_mul_f32_e32 v125, 0xbfb8aa3b, v104
	v_exp_f32_e32 v124, v124
	v_exp_f32_e32 v101, v101
	v_exp_f32_e32 v102, v102
	v_exp_f32_e32 v125, v125
	v_mul_f32_e32 v83, v73, v80
	v_add_f32_e32 v73, 1.0, v81
	v_add_f32_e32 v80, 1.0, v82
	v_mul_f32_e32 v81, 0xbfb8aa3b, v91
	v_mul_f32_e32 v82, 0xbfb8aa3b, v75
	v_add_f32_e32 v126, 1.0, v126
	v_exp_f32_e32 v81, v81
	v_exp_f32_e32 v82, v82
	v_add_f32_e32 v124, 1.0, v124
	v_rcp_f32_e32 v126, v126
	v_add_f32_e32 v101, 1.0, v101
	v_add_f32_e32 v102, 1.0, v102
	v_add_f32_e32 v125, 1.0, v125
	v_rcp_f32_e32 v124, v124
	v_rcp_f32_e32 v99, v99
	v_rcp_f32_e32 v100, v100
	v_rcp_f32_e32 v101, v101
	v_rcp_f32_e32 v102, v102
	v_rcp_f32_e32 v125, v125
	v_add_f32_e32 v81, 1.0, v81
	v_add_f32_e32 v82, 1.0, v82
	v_mul_f32_e32 v98, v109, v126
	v_rcp_f32_e32 v73, v73
	v_rcp_f32_e32 v80, v80
	v_rcp_f32_e32 v81, v81
	v_rcp_f32_e32 v82, v82
	v_mul_f32_e32 v108, v108, v124
	v_mul_f32_e32 v99, v110, v99
	v_mul_f32_e32 v109, v116, v100
	v_mul_f32_e32 v100, v111, v101
	v_mul_f32_e32 v101, v117, v102
	v_lshl_add_u64 v[102:103], v[146:147], 0, v[106:107]
	v_cvt_pk_bf16_f32 v98, v108, v98
	v_mul_f32_e32 v104, v104, v125
	v_cvt_pk_bf16_f32 v99, v99, v100
	v_cvt_pk_bf16_f32 v100, v104, v105
	v_cvt_pk_bf16_f32 v101, v109, v101
	global_store_dwordx4 v[102:103], v[98:101], off
	v_mul_f32_e32 v73, v90, v73
	v_mul_f32_e32 v89, v74, v80
	v_or_b32_e32 v98, 32, v152
	v_ashrrev_i32_e32 v99, 31, v98
	v_lshlrev_b64 v[98:99], 8, v[98:99]
	v_mul_f32_e32 v74, v91, v81
	v_mul_f32_e32 v75, v75, v82
	v_lshl_add_u64 v[80:81], v[146:147], 0, v[98:99]
	v_cvt_pk_bf16_f32 v72, v88, v72
	v_cvt_pk_bf16_f32 v73, v73, v74
	v_cvt_pk_bf16_f32 v74, v92, v83
	v_cvt_pk_bf16_f32 v75, v89, v75
	global_store_dwordx4 v[80:81], v[72:75], off
	v_pk_add_f32 v[60:61], v[60:61], v[128:129]
	v_pk_add_f32 v[56:57], v[56:57], v[132:133]
	v_cndmask_b32_e32 v75, v85, v77, vcc
	v_cndmask_b32_e32 v74, v84, v76, vcc
	v_pk_add_f32 v[74:75], v[74:75], v[132:133]
	v_mul_f32_e32 v69, 0xbfb8aa3b, v60
	v_mul_f32_e32 v68, 0xbfb8aa3b, v74
	v_mul_f32_e32 v70, 0xbfb8aa3b, v75
	v_pk_add_f32 v[48:49], v[48:49], v[128:129]
	v_exp_f32_e32 v68, v68
	v_exp_f32_e32 v69, v69
	v_exp_f32_e32 v70, v70
	v_mul_f32_e32 v52, 0xbfb8aa3b, v56
	v_mul_f32_e32 v53, 0xbfb8aa3b, v48
	v_mul_f32_e32 v54, 0xbfb8aa3b, v57
	v_exp_f32_e32 v52, v52
	v_exp_f32_e32 v53, v53
	v_exp_f32_e32 v54, v54
	v_pk_add_f32 v[40:41], v[40:41], v[132:133]
	v_pk_add_f32 v[32:33], v[32:33], v[128:129]
	v_mul_f32_e32 v36, 0xbfb8aa3b, v40
	v_mul_f32_e32 v37, 0xbfb8aa3b, v32
	v_mul_f32_e32 v38, 0xbfb8aa3b, v41
	v_pk_add_f32 v[24:25], v[24:25], v[132:133]
	v_pk_add_f32 v[16:17], v[16:17], v[128:129]
	v_exp_f32_e32 v36, v36
	v_exp_f32_e32 v37, v37
	v_exp_f32_e32 v38, v38
	v_mul_f32_e32 v20, 0xbfb8aa3b, v24
	v_mul_f32_e32 v21, 0xbfb8aa3b, v16
	v_mul_f32_e32 v22, 0xbfb8aa3b, v25
	v_add_f32_e32 v68, 1.0, v68
	v_add_f32_e32 v69, 1.0, v69
	v_add_f32_e32 v70, 1.0, v70
	v_mul_f32_e32 v71, 0xbfb8aa3b, v61
	v_exp_f32_e32 v20, v20
	v_exp_f32_e32 v21, v21
	v_exp_f32_e32 v22, v22
	v_pk_add_f32 v[8:9], v[8:9], v[132:133]
	v_pk_add_f32 v[0:1], v[0:1], v[128:129]
	v_rcp_f32_e32 v68, v68
	v_rcp_f32_e32 v69, v69
	v_rcp_f32_e32 v70, v70
	v_exp_f32_e32 v71, v71
	v_add_f32_e32 v52, 1.0, v52
	v_add_f32_e32 v53, 1.0, v53
	v_add_f32_e32 v54, 1.0, v54
	v_mul_f32_e32 v55, 0xbfb8aa3b, v49
	v_mul_f32_e32 v4, 0xbfb8aa3b, v8
	v_mul_f32_e32 v5, 0xbfb8aa3b, v0
	v_mul_f32_e32 v6, 0xbfb8aa3b, v9
	v_rcp_f32_e32 v52, v52
	v_rcp_f32_e32 v53, v53
	v_rcp_f32_e32 v54, v54
	v_exp_f32_e32 v55, v55
	v_exp_f32_e32 v4, v4
	v_exp_f32_e32 v5, v5
	v_exp_f32_e32 v6, v6
	v_cndmask_b32_e32 v77, v87, v79, vcc
	v_cndmask_b32_e32 v76, v86, v78, vcc
	v_add_f32_e32 v36, 1.0, v36
	v_add_f32_e32 v37, 1.0, v37
	v_add_f32_e32 v38, 1.0, v38
	v_mul_f32_e32 v39, 0xbfb8aa3b, v33
	v_pk_add_f32 v[76:77], v[76:77], v[134:135]
	v_pk_add_f32 v[62:63], v[62:63], v[130:131]
	v_rcp_f32_e32 v36, v36
	v_rcp_f32_e32 v37, v37
	v_rcp_f32_e32 v38, v38
	v_exp_f32_e32 v39, v39
	v_add_f32_e32 v20, 1.0, v20
	v_add_f32_e32 v21, 1.0, v21
	v_add_f32_e32 v22, 1.0, v22
	v_mul_f32_e32 v23, 0xbfb8aa3b, v17
	v_mul_f32_e32 v74, v74, v68
	v_mul_f32_e32 v78, v60, v69
	v_mul_f32_e32 v60, v75, v70
	v_add_f32_e32 v68, 1.0, v71
	v_mul_f32_e32 v69, 0xbfb8aa3b, v76
	v_mul_f32_e32 v70, 0xbfb8aa3b, v62
	v_pk_add_f32 v[58:59], v[58:59], v[134:135]
	v_pk_add_f32 v[50:51], v[50:51], v[130:131]
	v_rcp_f32_e32 v20, v20
	v_rcp_f32_e32 v21, v21
	v_rcp_f32_e32 v22, v22
	v_exp_f32_e32 v23, v23
	v_rcp_f32_e32 v68, v68
	v_exp_f32_e32 v69, v69
	v_exp_f32_e32 v70, v70
	v_mul_f32_e32 v52, v56, v52
	v_mul_f32_e32 v53, v48, v53
	v_mul_f32_e32 v48, v57, v54
	v_add_f32_e32 v54, 1.0, v55
	v_mul_f32_e32 v55, 0xbfb8aa3b, v58
	v_mul_f32_e32 v56, 0xbfb8aa3b, v50
	v_add_f32_e32 v4, 1.0, v4
	v_add_f32_e32 v5, 1.0, v5
	v_add_f32_e32 v6, 1.0, v6
	v_mul_f32_e32 v7, 0xbfb8aa3b, v1
	v_rcp_f32_e32 v54, v54
	v_exp_f32_e32 v55, v55
	v_exp_f32_e32 v56, v56
	v_pk_add_f32 v[42:43], v[42:43], v[134:135]
	v_pk_add_f32 v[34:35], v[34:35], v[130:131]
	v_rcp_f32_e32 v4, v4
	v_rcp_f32_e32 v5, v5
	v_rcp_f32_e32 v6, v6
	v_exp_f32_e32 v7, v7
	v_mul_f32_e32 v36, v40, v36
	v_mul_f32_e32 v37, v32, v37
	v_mul_f32_e32 v32, v41, v38
	v_add_f32_e32 v38, 1.0, v39
	v_mul_f32_e32 v39, 0xbfb8aa3b, v42
	v_mul_f32_e32 v40, 0xbfb8aa3b, v34
	v_pk_add_f32 v[26:27], v[26:27], v[134:135]
	v_pk_add_f32 v[18:19], v[18:19], v[130:131]
	v_rcp_f32_e32 v38, v38
	v_exp_f32_e32 v39, v39
	v_exp_f32_e32 v40, v40
	v_mul_f32_e32 v20, v24, v20
	v_mul_f32_e32 v21, v16, v21
	v_mul_f32_e32 v16, v25, v22
	v_add_f32_e32 v22, 1.0, v23
	v_mul_f32_e32 v23, 0xbfb8aa3b, v26
	v_mul_f32_e32 v24, 0xbfb8aa3b, v18
	v_mul_f32_e32 v71, v61, v68
	v_add_f32_e32 v61, 1.0, v69
	v_add_f32_e32 v68, 1.0, v70
	v_mul_f32_e32 v69, 0xbfb8aa3b, v77
	v_mul_f32_e32 v70, 0xbfb8aa3b, v63
	v_rcp_f32_e32 v22, v22
	v_exp_f32_e32 v23, v23
	v_exp_f32_e32 v24, v24
	v_pk_add_f32 v[10:11], v[10:11], v[134:135]
	v_pk_add_f32 v[2:3], v[2:3], v[130:131]
	v_exp_f32_e32 v69, v69
	v_exp_f32_e32 v70, v70
	v_mul_f32_e32 v54, v49, v54
	v_add_f32_e32 v49, 1.0, v55
	v_add_f32_e32 v55, 1.0, v56
	v_mul_f32_e32 v56, 0xbfb8aa3b, v59
	v_mul_f32_e32 v4, v8, v4
	v_mul_f32_e32 v5, v0, v5
	v_mul_f32_e32 v0, v9, v6
	v_add_f32_e32 v6, 1.0, v7
	v_mul_f32_e32 v7, 0xbfb8aa3b, v10
	v_mul_f32_e32 v8, 0xbfb8aa3b, v2
	v_exp_f32_e32 v56, v56
	v_rcp_f32_e32 v6, v6
	v_exp_f32_e32 v7, v7
	v_exp_f32_e32 v8, v8
	v_mul_f32_e32 v57, 0xbfb8aa3b, v51
	v_mul_f32_e32 v38, v33, v38
	v_add_f32_e32 v33, 1.0, v39
	v_add_f32_e32 v39, 1.0, v40
	v_mul_f32_e32 v40, 0xbfb8aa3b, v43
	v_mul_f32_e32 v41, 0xbfb8aa3b, v35
	v_exp_f32_e32 v57, v57
	v_exp_f32_e32 v40, v40
	v_exp_f32_e32 v41, v41
	v_mul_f32_e32 v22, v17, v22
	v_add_f32_e32 v17, 1.0, v23
	v_add_f32_e32 v23, 1.0, v24
	v_mul_f32_e32 v24, 0xbfb8aa3b, v27
	v_add_f32_e32 v69, 1.0, v69
	v_add_f32_e32 v70, 1.0, v70
	v_exp_f32_e32 v24, v24
	v_mul_f32_e32 v25, 0xbfb8aa3b, v19
	v_rcp_f32_e32 v61, v61
	v_rcp_f32_e32 v68, v68
	v_rcp_f32_e32 v69, v69
	v_rcp_f32_e32 v70, v70
	v_add_f32_e32 v56, 1.0, v56
	v_exp_f32_e32 v25, v25
	v_mul_f32_e32 v6, v1, v6
	v_add_f32_e32 v1, 1.0, v7
	v_add_f32_e32 v7, 1.0, v8
	v_mul_f32_e32 v8, 0xbfb8aa3b, v11
	v_or_b32_e32 v72, 48, v152
	v_rcp_f32_e32 v49, v49
	v_rcp_f32_e32 v55, v55
	v_rcp_f32_e32 v56, v56
	v_exp_f32_e32 v8, v8
	v_ashrrev_i32_e32 v73, 31, v72
	v_add_f32_e32 v57, 1.0, v57
	v_add_f32_e32 v40, 1.0, v40
	v_add_f32_e32 v41, 1.0, v41
	v_mul_f32_e32 v9, 0xbfb8aa3b, v3
	v_lshlrev_b64 v[72:73], 8, v[72:73]
	v_rcp_f32_e32 v57, v57
	v_rcp_f32_e32 v33, v33
	v_rcp_f32_e32 v39, v39
	v_rcp_f32_e32 v40, v40
	v_rcp_f32_e32 v41, v41
	v_add_f32_e32 v24, 1.0, v24
	v_exp_f32_e32 v9, v9
	v_mul_f32_e32 v61, v76, v61
	v_mul_f32_e32 v75, v62, v68
	v_mul_f32_e32 v62, v77, v69
	v_mul_f32_e32 v63, v63, v70
	v_lshl_add_u64 v[68:69], v[146:147], 0, v[72:73]
	v_rcp_f32_e32 v17, v17
	v_rcp_f32_e32 v23, v23
	v_rcp_f32_e32 v24, v24
	v_add_f32_e32 v25, 1.0, v25
	v_cvt_pk_bf16_f32 v60, v74, v60
	v_cvt_pk_bf16_f32 v61, v61, v62
	v_cvt_pk_bf16_f32 v62, v78, v71
	v_cvt_pk_bf16_f32 v63, v75, v63
	global_store_dwordx4 v[68:69], v[60:63], off
	v_mul_f32_e32 v49, v58, v49
	v_mul_f32_e32 v55, v50, v55
	v_mul_f32_e32 v50, v59, v56
	v_cvt_pk_bf16_f32 v48, v52, v48
	v_add_co_u32_e64 v52, s[0:1], s0, v96
	v_rcp_f32_e32 v25, v25
	v_add_f32_e32 v8, 1.0, v8
	v_cvt_pk_bf16_f32 v49, v49, v50
	v_cvt_pk_bf16_f32 v50, v53, v54
	v_addc_co_u32_e64 v53, s[0:1], 0, v97, s[0:1]
	v_rcp_f32_e32 v1, v1
	v_rcp_f32_e32 v7, v7
	v_rcp_f32_e32 v8, v8
	v_mul_f32_e32 v51, v51, v57
	v_mul_f32_e32 v33, v42, v33
	v_mul_f32_e32 v39, v34, v39
	v_mul_f32_e32 v34, v43, v40
	v_mul_f32_e32 v35, v35, v41
	s_mov_b32 s0, 0xa000
	v_add_f32_e32 v9, 1.0, v9
	v_cvt_pk_bf16_f32 v51, v55, v51
	global_store_dwordx4 v[52:53], v[48:51], off offset:-4096
	v_cvt_pk_bf16_f32 v32, v36, v32
	v_cvt_pk_bf16_f32 v33, v33, v34
	v_cvt_pk_bf16_f32 v34, v37, v38
	v_cvt_pk_bf16_f32 v35, v39, v35
	global_store_dwordx4 v[52:53], v[32:35], off
	v_mul_f32_e32 v17, v26, v17
	v_mul_f32_e32 v23, v18, v23
	v_mul_f32_e32 v18, v27, v24
	v_cvt_pk_bf16_f32 v16, v20, v16
	v_add_co_u32_e64 v20, s[0:1], s0, v96
	v_rcp_f32_e32 v9, v9
	v_mul_f32_e32 v19, v19, v25
	v_cvt_pk_bf16_f32 v17, v17, v18
	v_cvt_pk_bf16_f32 v18, v21, v22
	v_addc_co_u32_e64 v21, s[0:1], 0, v97, s[0:1]
	v_cvt_pk_bf16_f32 v19, v23, v19
	global_store_dwordx4 v[20:21], v[16:19], off
	v_mul_f32_e32 v1, v10, v1
	v_mul_f32_e32 v7, v2, v7
	v_mul_f32_e32 v2, v11, v8
	v_cvt_pk_bf16_f32 v0, v4, v0
	v_add_co_u32_e32 v4, vcc, 0xb000, v96
	v_cvt_pk_bf16_f32 v1, v1, v2
	v_cvt_pk_bf16_f32 v2, v5, v6
	v_mul_f32_e32 v3, v3, v9
	s_nop 0
	v_addc_co_u32_e32 v5, vcc, 0, v97, vcc
	s_and_b64 vcc, exec, s[8:9]
	s_mov_b32 s0, s14
	v_cvt_pk_bf16_f32 v3, v7, v3
	global_store_dwordx4 v[4:5], v[0:3], off
	s_cbranch_vccz .LBB0_255
	s_waitcnt vmcnt(0)
	s_cmpk_gt_u32 s33, 0xff
	s_cbranch_scc1 .LBB0_266
	s_barrier

.LBB0_654:
	ds_read_b128 v[144:147], v157
	ds_read_b128 v[148:151], v157 offset:1024
	ds_read_b128 v[160:163], v157 offset:2048
	ds_read_b128 v[164:167], v157 offset:3072
	s_add_u32 s24, s22, 0xfffc0080
	s_addc_u32 s25, s23, -1
	s_cmp_eq_u32 s49, 12
	s_cselect_b32 s27, s13, s25
	s_cselect_b32 s26, s19, s24
	s_cselect_b32 s25, s3, s48
	s_cselect_b32 s24, s42, s43
	v_lshl_add_u64 v[152:153], s[22:23], 0, v[136:137]
	s_add_i32 m0, s21, 0xc000
	ds_read_b128 v[168:171], v158
	ds_read_b128 v[176:179], v158 offset:1024
	ds_read_b128 v[180:183], v158 offset:2048
	ds_read_b128 v[184:187], v158 offset:3072
	ds_read_b128 v[188:191], v158 offset:4096
	ds_read_b128 v[192:195], v158 offset:5120
	ds_read_b128 v[196:199], v158 offset:6144
	ds_read_b128 v[200:203], v158 offset:7168
	global_load_lds_dwordx4 v[152:153], off
	s_add_i32 m0, s21, 0xe000
	v_lshl_add_u64 v[152:153], s[22:23], 0, v[138:139]
	global_load_lds_dwordx4 v[152:153], off
	s_waitcnt lgkmcnt(8)
	s_setprio 1
	s_barrier
	s_waitcnt lgkmcnt(0)
	v_mfma_f32_16x16x32_bf16 v[124:127], v[144:147], v[168:171], v[124:127]
	v_mfma_f32_16x16x32_bf16 v[120:123], v[160:163], v[168:171], v[120:123]
	v_mfma_f32_16x16x32_bf16 v[116:119], v[144:147], v[180:183], v[116:119]
	v_mfma_f32_16x16x32_bf16 v[112:115], v[160:163], v[180:183], v[112:115]
	v_mfma_f32_16x16x32_bf16 v[96:99], v[144:147], v[188:191], v[96:99]
	v_mfma_f32_16x16x32_bf16 v[88:91], v[160:163], v[188:191], v[88:91]
	v_mfma_f32_16x16x32_bf16 v[80:83], v[144:147], v[196:199], v[80:83]
	v_mfma_f32_16x16x32_bf16 v[72:75], v[160:163], v[196:199], v[72:75]
	v_mfma_f32_16x16x32_bf16 v[124:127], v[148:151], v[176:179], v[124:127]
	v_mfma_f32_16x16x32_bf16 v[120:123], v[164:167], v[176:179], v[120:123]
	v_mfma_f32_16x16x32_bf16 v[116:119], v[148:151], v[184:187], v[116:119]
	v_mfma_f32_16x16x32_bf16 v[112:115], v[164:167], v[184:187], v[112:115]
	v_mfma_f32_16x16x32_bf16 v[96:99], v[148:151], v[192:195], v[96:99]
	v_mfma_f32_16x16x32_bf16 v[88:91], v[164:167], v[192:195], v[88:91]
	v_mfma_f32_16x16x32_bf16 v[80:83], v[148:151], v[200:203], v[80:83]
	v_mfma_f32_16x16x32_bf16 v[72:75], v[164:167], v[200:203], v[72:75]
	s_barrier
	s_setprio 0
	s_add_i32 s50, s40, s29
	v_lshl_add_u64 v[152:153], s[24:25], 0, v[130:131]
	s_mov_b32 m0, s50
	ds_read_b128 v[204:207], v159
	ds_read_b128 v[212:215], v159 offset:1024
	ds_read_b128 v[216:219], v159 offset:2048
	ds_read_b128 v[220:223], v159 offset:3072
	global_load_lds_dwordx4 v[152:153], off
	s_add_i32 m0, s50, 0x2000
	v_lshl_add_u64 v[172:173], s[24:25], 0, v[134:135]
	global_load_lds_dwordx4 v[172:173], off
	s_setprio 1
	s_barrier
	s_waitcnt lgkmcnt(0)
	v_mfma_f32_16x16x32_bf16 v[108:111], v[204:207], v[168:171], v[108:111]
	v_mfma_f32_16x16x32_bf16 v[104:107], v[216:219], v[168:171], v[104:107]
	v_mfma_f32_16x16x32_bf16 v[100:103], v[204:207], v[180:183], v[100:103]
	v_mfma_f32_16x16x32_bf16 v[92:95], v[216:219], v[180:183], v[92:95]
	v_mfma_f32_16x16x32_bf16 v[84:87], v[204:207], v[188:191], v[84:87]
	v_mfma_f32_16x16x32_bf16 v[76:79], v[216:219], v[188:191], v[76:79]
	v_mfma_f32_16x16x32_bf16 v[68:71], v[204:207], v[196:199], v[68:71]
	v_mfma_f32_16x16x32_bf16 v[64:67], v[216:219], v[196:199], v[64:67]
	v_mfma_f32_16x16x32_bf16 v[108:111], v[212:215], v[176:179], v[108:111]
	v_mfma_f32_16x16x32_bf16 v[104:107], v[220:223], v[176:179], v[104:107]
	v_mfma_f32_16x16x32_bf16 v[100:103], v[212:215], v[184:187], v[100:103]
	v_mfma_f32_16x16x32_bf16 v[92:95], v[220:223], v[184:187], v[92:95]
	v_mfma_f32_16x16x32_bf16 v[84:87], v[212:215], v[192:195], v[84:87]
	v_mfma_f32_16x16x32_bf16 v[76:79], v[220:223], v[192:195], v[76:79]
	v_mfma_f32_16x16x32_bf16 v[68:71], v[212:215], v[200:203], v[68:71]
	v_mfma_f32_16x16x32_bf16 v[64:67], v[220:223], v[200:203], v[64:67]
	s_barrier
	s_setprio 0
	s_mov_b32 m0, s21
	v_lshl_add_u64 v[208:209], s[26:27], 0, v[128:129]
	ds_read_b128 v[168:171], v158 offset:16384
	ds_read_b128 v[176:179], v158 offset:17408
	ds_read_b128 v[180:183], v158 offset:18432
	ds_read_b128 v[184:187], v158 offset:19456
	ds_read_b128 v[188:191], v158 offset:20480
	ds_read_b128 v[192:195], v158 offset:21504
	ds_read_b128 v[196:199], v158 offset:22528
	ds_read_b128 v[200:203], v158 offset:23552
	global_load_lds_dwordx4 v[208:209], off
	s_mov_b32 m0, s30
	v_lshl_add_u64 v[224:225], s[26:27], 0, v[132:133]
	global_load_lds_dwordx4 v[224:225], off
	s_setprio 1
	s_barrier
	s_waitcnt lgkmcnt(0)
	v_mfma_f32_16x16x32_bf16 v[60:63], v[144:147], v[168:171], v[60:63]
	v_mfma_f32_16x16x32_bf16 v[56:59], v[160:163], v[168:171], v[56:59]
	v_mfma_f32_16x16x32_bf16 v[52:55], v[144:147], v[180:183], v[52:55]
	v_mfma_f32_16x16x32_bf16 v[48:51], v[160:163], v[180:183], v[48:51]
	v_mfma_f32_16x16x32_bf16 v[32:35], v[144:147], v[188:191], v[32:35]
	v_mfma_f32_16x16x32_bf16 v[24:27], v[160:163], v[188:191], v[24:27]
	v_mfma_f32_16x16x32_bf16 v[16:19], v[144:147], v[196:199], v[16:19]
	v_mfma_f32_16x16x32_bf16 v[8:11], v[160:163], v[196:199], v[8:11]
	v_mfma_f32_16x16x32_bf16 v[60:63], v[148:151], v[176:179], v[60:63]
	v_mfma_f32_16x16x32_bf16 v[56:59], v[164:167], v[176:179], v[56:59]
	v_mfma_f32_16x16x32_bf16 v[52:55], v[148:151], v[184:187], v[52:55]
	v_mfma_f32_16x16x32_bf16 v[48:51], v[164:167], v[184:187], v[48:51]
	v_mfma_f32_16x16x32_bf16 v[32:35], v[148:151], v[192:195], v[32:35]
	v_mfma_f32_16x16x32_bf16 v[24:27], v[164:167], v[192:195], v[24:27]
	v_mfma_f32_16x16x32_bf16 v[16:19], v[148:151], v[200:203], v[16:19]
	v_mfma_f32_16x16x32_bf16 v[8:11], v[164:167], v[200:203], v[8:11]
	s_barrier
	s_setprio 0
	s_add_u32 s50, s24, 0x40000
	s_addc_u32 s51, s25, 0
	s_add_i32 s52, s41, s29
	s_mov_b32 m0, s52
	v_lshl_add_u64 v[144:145], s[50:51], 0, v[130:131]
	global_load_lds_dwordx4 v[144:145], off
	s_add_i32 m0, s52, 0x2000
	v_lshl_add_u64 v[144:145], s[50:51], 0, v[134:135]
	global_load_lds_dwordx4 v[144:145], off
	s_waitcnt vmcnt(6)
	s_setprio 1
	s_barrier
	v_mfma_f32_16x16x32_bf16 v[44:47], v[204:207], v[168:171], v[44:47]
	v_mfma_f32_16x16x32_bf16 v[40:43], v[216:219], v[168:171], v[40:43]
	v_mfma_f32_16x16x32_bf16 v[36:39], v[204:207], v[180:183], v[36:39]
	v_mfma_f32_16x16x32_bf16 v[28:31], v[216:219], v[180:183], v[28:31]
	v_mfma_f32_16x16x32_bf16 v[20:23], v[204:207], v[188:191], v[20:23]
	v_mfma_f32_16x16x32_bf16 v[12:15], v[216:219], v[188:191], v[12:15]
	v_mfma_f32_16x16x32_bf16 v[4:7], v[204:207], v[196:199], v[4:7]
	v_mfma_f32_16x16x32_bf16 v[0:3], v[216:219], v[196:199], v[0:3]
	v_mfma_f32_16x16x32_bf16 v[44:47], v[212:215], v[176:179], v[44:47]
	v_mfma_f32_16x16x32_bf16 v[40:43], v[220:223], v[176:179], v[40:43]
	v_mfma_f32_16x16x32_bf16 v[36:39], v[212:215], v[184:187], v[36:39]
	v_mfma_f32_16x16x32_bf16 v[28:31], v[220:223], v[184:187], v[28:31]
	v_mfma_f32_16x16x32_bf16 v[20:23], v[212:215], v[192:195], v[20:23]
	v_mfma_f32_16x16x32_bf16 v[12:15], v[220:223], v[192:195], v[12:15]
	v_mfma_f32_16x16x32_bf16 v[4:7], v[212:215], v[200:203], v[4:7]
	v_mfma_f32_16x16x32_bf16 v[0:3], v[220:223], v[200:203], v[0:3]
	s_barrier
	s_setprio 0
	s_add_i32 s50, 0, 0x18000
	v_add_u32_e32 v164, s50, v155
	ds_read_b128 v[144:147], v164
	ds_read_b128 v[148:151], v164 offset:1024
	ds_read_b128 v[160:163], v164 offset:2048
	ds_read_b128 v[164:167], v164 offset:3072
	s_add_u32 s26, s26, 0x40000
	s_addc_u32 s27, s27, 0
	s_mov_b32 m0, s31
	v_lshl_add_u64 v[204:205], s[26:27], 0, v[128:129]
	ds_read_b128 v[168:171], v158 offset:32768
	ds_read_b128 v[176:179], v158 offset:33792
	ds_read_b128 v[180:183], v158 offset:34816
	ds_read_b128 v[184:187], v158 offset:35840
	ds_read_b128 v[188:191], v158 offset:36864
	ds_read_b128 v[192:195], v158 offset:37888
	ds_read_b128 v[196:199], v158 offset:38912
	ds_read_b128 v[200:203], v158 offset:39936
	global_load_lds_dwordx4 v[204:205], off
	s_mov_b32 m0, s33
	v_lshl_add_u64 v[204:205], s[26:27], 0, v[132:133]
	global_load_lds_dwordx4 v[204:205], off
	s_waitcnt lgkmcnt(8)
	s_setprio 1
	s_barrier
	s_waitcnt lgkmcnt(0)
	v_mfma_f32_16x16x32_bf16 v[124:127], v[144:147], v[168:171], v[124:127]
	v_mfma_f32_16x16x32_bf16 v[120:123], v[160:163], v[168:171], v[120:123]
	v_mfma_f32_16x16x32_bf16 v[116:119], v[144:147], v[180:183], v[116:119]
	v_mfma_f32_16x16x32_bf16 v[112:115], v[160:163], v[180:183], v[112:115]
	v_mfma_f32_16x16x32_bf16 v[96:99], v[144:147], v[188:191], v[96:99]
	v_mfma_f32_16x16x32_bf16 v[88:91], v[160:163], v[188:191], v[88:91]
	v_mfma_f32_16x16x32_bf16 v[80:83], v[144:147], v[196:199], v[80:83]
	v_mfma_f32_16x16x32_bf16 v[72:75], v[160:163], v[196:199], v[72:75]
	v_mfma_f32_16x16x32_bf16 v[124:127], v[148:151], v[176:179], v[124:127]
	v_mfma_f32_16x16x32_bf16 v[120:123], v[164:167], v[176:179], v[120:123]
	v_mfma_f32_16x16x32_bf16 v[116:119], v[148:151], v[184:187], v[116:119]
	v_mfma_f32_16x16x32_bf16 v[112:115], v[164:167], v[184:187], v[112:115]
	v_mfma_f32_16x16x32_bf16 v[96:99], v[148:151], v[192:195], v[96:99]
	v_mfma_f32_16x16x32_bf16 v[88:91], v[164:167], v[192:195], v[88:91]
	v_mfma_f32_16x16x32_bf16 v[80:83], v[148:151], v[200:203], v[80:83]
	v_mfma_f32_16x16x32_bf16 v[72:75], v[164:167], v[200:203], v[72:75]
	s_barrier
	s_setprio 0
	s_add_i32 s26, 0, 0x1c000
	s_add_i32 s27, s50, s29
	v_add_u32_e32 v175, s26, v155
	v_lshl_add_u64 v[152:153], v[152:153], 0, s[0:1]
	s_mov_b32 m0, s27
	ds_read_b128 v[204:207], v175
	ds_read_b128 v[212:215], v175 offset:1024
	ds_read_b128 v[216:219], v175 offset:2048
	ds_read_b128 v[220:223], v175 offset:3072
	global_load_lds_dwordx4 v[152:153], off
	s_add_i32 m0, s27, 0x2000
	v_lshl_add_u64 v[152:153], v[172:173], 0, s[0:1]
	global_load_lds_dwordx4 v[152:153], off
	s_setprio 1
	s_barrier
	s_waitcnt lgkmcnt(0)
	v_mfma_f32_16x16x32_bf16 v[108:111], v[204:207], v[168:171], v[108:111]
	v_mfma_f32_16x16x32_bf16 v[104:107], v[216:219], v[168:171], v[104:107]
	v_mfma_f32_16x16x32_bf16 v[100:103], v[204:207], v[180:183], v[100:103]
	v_mfma_f32_16x16x32_bf16 v[92:95], v[216:219], v[180:183], v[92:95]
	v_mfma_f32_16x16x32_bf16 v[84:87], v[204:207], v[188:191], v[84:87]
	v_mfma_f32_16x16x32_bf16 v[76:79], v[216:219], v[188:191], v[76:79]
	v_mfma_f32_16x16x32_bf16 v[68:71], v[204:207], v[196:199], v[68:71]
	v_mfma_f32_16x16x32_bf16 v[64:67], v[216:219], v[196:199], v[64:67]
	v_mfma_f32_16x16x32_bf16 v[108:111], v[212:215], v[176:179], v[108:111]
	v_mfma_f32_16x16x32_bf16 v[104:107], v[220:223], v[176:179], v[104:107]
	v_mfma_f32_16x16x32_bf16 v[100:103], v[212:215], v[184:187], v[100:103]
	v_mfma_f32_16x16x32_bf16 v[92:95], v[220:223], v[184:187], v[92:95]
	v_mfma_f32_16x16x32_bf16 v[84:87], v[212:215], v[192:195], v[84:87]
	v_mfma_f32_16x16x32_bf16 v[76:79], v[220:223], v[192:195], v[76:79]
	v_mfma_f32_16x16x32_bf16 v[68:71], v[212:215], v[200:203], v[68:71]
	v_mfma_f32_16x16x32_bf16 v[64:67], v[220:223], v[200:203], v[64:67]
	s_barrier
	s_setprio 0
	s_mov_b32 m0, s35
	v_lshl_add_u64 v[152:153], v[208:209], 0, s[0:1]
	ds_read_b128 v[168:171], v158 offset:49152
	ds_read_b128 v[176:179], v158 offset:50176
	ds_read_b128 v[180:183], v158 offset:51200
	ds_read_b128 v[184:187], v158 offset:52224
	ds_read_b128 v[188:191], v158 offset:53248
	ds_read_b128 v[192:195], v158 offset:54272
	ds_read_b128 v[196:199], v158 offset:55296
	ds_read_b128 v[200:203], v158 offset:56320
	global_load_lds_dwordx4 v[152:153], off
	s_mov_b32 m0, s36
	v_lshl_add_u64 v[152:153], v[224:225], 0, s[0:1]
	global_load_lds_dwordx4 v[152:153], off
	s_setprio 1
	s_barrier
	s_waitcnt lgkmcnt(0)
	v_mfma_f32_16x16x32_bf16 v[60:63], v[144:147], v[168:171], v[60:63]
	v_mfma_f32_16x16x32_bf16 v[56:59], v[160:163], v[168:171], v[56:59]
	v_mfma_f32_16x16x32_bf16 v[52:55], v[144:147], v[180:183], v[52:55]
	v_mfma_f32_16x16x32_bf16 v[48:51], v[160:163], v[180:183], v[48:51]
	v_mfma_f32_16x16x32_bf16 v[32:35], v[144:147], v[188:191], v[32:35]
	v_mfma_f32_16x16x32_bf16 v[24:27], v[160:163], v[188:191], v[24:27]
	v_mfma_f32_16x16x32_bf16 v[16:19], v[144:147], v[196:199], v[16:19]
	v_mfma_f32_16x16x32_bf16 v[8:11], v[160:163], v[196:199], v[8:11]
	v_mfma_f32_16x16x32_bf16 v[60:63], v[148:151], v[176:179], v[60:63]
	v_mfma_f32_16x16x32_bf16 v[56:59], v[164:167], v[176:179], v[56:59]
	v_mfma_f32_16x16x32_bf16 v[52:55], v[148:151], v[184:187], v[52:55]
	v_mfma_f32_16x16x32_bf16 v[48:51], v[164:167], v[184:187], v[48:51]
	v_mfma_f32_16x16x32_bf16 v[32:35], v[148:151], v[192:195], v[32:35]
	v_mfma_f32_16x16x32_bf16 v[24:27], v[164:167], v[192:195], v[24:27]
	v_mfma_f32_16x16x32_bf16 v[16:19], v[148:151], v[200:203], v[16:19]
	v_mfma_f32_16x16x32_bf16 v[8:11], v[164:167], v[200:203], v[8:11]
	s_barrier
	s_setprio 0
	s_add_u32 s24, s24, 0x40080
	s_addc_u32 s25, s25, 0
	s_add_i32 s26, s26, s29
	s_mov_b32 m0, s26
	v_lshl_add_u64 v[144:145], s[24:25], 0, v[130:131]
	global_load_lds_dwordx4 v[144:145], off
	s_add_i32 m0, s26, 0x2000
	v_lshl_add_u64 v[144:145], s[24:25], 0, v[134:135]
	global_load_lds_dwordx4 v[144:145], off
	s_waitcnt vmcnt(6)
	s_setprio 1
	s_barrier
	v_mfma_f32_16x16x32_bf16 v[44:47], v[204:207], v[168:171], v[44:47]
	v_mfma_f32_16x16x32_bf16 v[40:43], v[216:219], v[168:171], v[40:43]
	v_mfma_f32_16x16x32_bf16 v[36:39], v[204:207], v[180:183], v[36:39]
	v_mfma_f32_16x16x32_bf16 v[28:31], v[216:219], v[180:183], v[28:31]
	v_mfma_f32_16x16x32_bf16 v[20:23], v[204:207], v[188:191], v[20:23]
	v_mfma_f32_16x16x32_bf16 v[12:15], v[216:219], v[188:191], v[12:15]
	v_mfma_f32_16x16x32_bf16 v[4:7], v[204:207], v[196:199], v[4:7]
	v_mfma_f32_16x16x32_bf16 v[0:3], v[216:219], v[196:199], v[0:3]
	v_mfma_f32_16x16x32_bf16 v[44:47], v[212:215], v[176:179], v[44:47]
	v_mfma_f32_16x16x32_bf16 v[40:43], v[220:223], v[176:179], v[40:43]
	v_mfma_f32_16x16x32_bf16 v[36:39], v[212:215], v[184:187], v[36:39]
	v_mfma_f32_16x16x32_bf16 v[28:31], v[220:223], v[184:187], v[28:31]
	v_mfma_f32_16x16x32_bf16 v[20:23], v[212:215], v[192:195], v[20:23]
	v_mfma_f32_16x16x32_bf16 v[12:15], v[220:223], v[192:195], v[12:15]
	v_mfma_f32_16x16x32_bf16 v[4:7], v[212:215], v[200:203], v[4:7]
	v_mfma_f32_16x16x32_bf16 v[0:3], v[220:223], v[200:203], v[0:3]
	s_barrier
	s_setprio 0
	s_add_i32 s49, s49, 2
	s_add_u32 s22, s22, 0x100
	s_addc_u32 s23, s23, 0
	s_add_u32 s43, s43, 0x100
	s_addc_u32 s48, s48, 0
	s_cmp_gt_u32 s49, 13
	s_cbranch_scc0 .LBB0_654
	v_lshl_add_u32 v148, s18, 8, v154
	v_lshl_or_b32 v144, s20, 8, v156
	v_readlane_b32 s48, v253, 12
	v_ashrrev_i32_e32 v145, 31, v144
	v_ashrrev_i32_e32 v149, 31, v148
	v_readlane_b32 s49, v253, 13
	v_lshlrev_b64 v[150:151], 12, v[148:149]
	v_or_b32_e32 v172, 16, v148
	v_lshl_add_u64 v[146:147], v[144:145], 2, s[48:49]
	v_lshl_add_u64 v[150:151], v[146:147], 0, v[150:151]
	v_ashrrev_i32_e32 v173, 31, v172
	global_load_dwordx4 v[160:163], v[150:151], off
	global_load_dwordx4 v[164:167], v[150:151], off offset:16
	global_load_dwordx4 v[168:171], v[150:151], off offset:512
	global_load_dwordx4 v[176:179], v[150:151], off offset:528
	v_lshlrev_b64 v[150:151], 12, v[172:173]
	v_or_b32_e32 v152, 32, v148
	v_lshl_add_u64 v[150:151], v[146:147], 0, v[150:151]
	v_ashrrev_i32_e32 v153, 31, v152
	global_load_dwordx4 v[180:183], v[150:151], off
	global_load_dwordx4 v[184:187], v[150:151], off offset:16
	global_load_dwordx4 v[188:191], v[150:151], off offset:512
	global_load_dwordx4 v[192:195], v[150:151], off offset:528
	v_lshlrev_b64 v[150:151], 12, v[152:153]
	v_lshl_add_u64 v[208:209], v[146:147], 0, v[150:151]
	v_or_b32_e32 v150, 48, v148
	global_load_dwordx4 v[196:199], v[208:209], off
	global_load_dwordx4 v[200:203], v[208:209], off offset:16
	v_ashrrev_i32_e32 v151, 31, v150
	v_lshlrev_b64 v[204:205], 11, v[148:149]
	v_lshlrev_b64 v[216:217], 12, v[150:151]
	v_lshl_add_u64 v[218:219], s[10:11], 0, v[204:205]
	global_load_dwordx4 v[204:207], v[208:209], off offset:528
	global_load_dwordx4 v[212:215], v[208:209], off offset:512
	v_lshlrev_b64 v[144:145], 1, v[144:145]
	v_lshl_add_u64 v[208:209], v[146:147], 0, v[216:217]
	v_lshl_add_u64 v[232:233], v[218:219], 0, v[144:145]
	global_load_dwordx4 v[216:219], v[208:209], off offset:16
	global_load_dwordx4 v[220:223], v[208:209], off
	global_load_dwordx4 v[224:227], v[208:209], off offset:528
	global_load_dwordx4 v[228:231], v[208:209], off offset:512
	v_lshlrev_b64 v[172:173], 11, v[172:173]
	v_lshl_add_u64 v[172:173], s[10:11], 0, v[172:173]
	v_lshl_add_u64 v[172:173], v[172:173], 0, v[144:145]
	v_readlane_b32 s50, v253, 14
	v_readlane_b32 s51, v253, 15
	v_readlane_b32 s52, v253, 16
	v_readlane_b32 s53, v253, 17
	v_readlane_b32 s54, v253, 18
	v_readlane_b32 s55, v253, 19
	v_readlane_b32 s56, v253, 20
	v_readlane_b32 s57, v253, 21
	v_readlane_b32 s58, v253, 22
	v_readlane_b32 s59, v253, 23
	v_readlane_b32 s60, v253, 24
	v_readlane_b32 s61, v253, 25
	v_readlane_b32 s62, v253, 26
	v_readlane_b32 s63, v253, 27
	s_waitcnt vmcnt(0)
	v_pk_add_f32 v[126:127], v[126:127], v[162:163]
	v_pk_add_f32 v[124:125], v[124:125], v[160:161]
	v_pk_add_f32 v[160:161], v[122:123], v[166:167]
	v_pk_add_f32 v[162:163], v[120:121], v[164:165]
	v_pk_add_f32 v[164:165], v[110:111], v[170:171]
	v_pk_add_f32 v[166:167], v[108:109], v[168:169]
	v_pk_add_f32 v[168:169], v[106:107], v[178:179]
	v_cvt_pk_bf16_f32 v120, v124, v125
	v_cvt_pk_bf16_f32 v121, v126, v127
	v_cvt_pk_bf16_f32 v122, v162, v163
	v_cvt_pk_bf16_f32 v123, v160, v161
	v_pk_add_f32 v[106:107], v[112:113], v[184:185]
	global_store_dwordx4 v[232:233], v[120:123], off
	v_cvt_pk_bf16_f32 v112, v166, v167
	v_cvt_pk_bf16_f32 v113, v164, v165
	v_pk_add_f32 v[170:171], v[104:105], v[176:177]
	v_pk_add_f32 v[108:109], v[118:119], v[182:183]
	v_pk_add_f32 v[110:111], v[116:117], v[180:181]
	v_pk_add_f32 v[104:105], v[114:115], v[186:187]
	v_cvt_pk_bf16_f32 v114, v170, v171
	v_cvt_pk_bf16_f32 v115, v168, v169
	global_store_dwordx4 v[232:233], v[112:115], off offset:256
	v_mul_f32_e32 v175, v125, v125
	v_mul_f32_e32 v176, v127, v127
	v_cvt_pk_bf16_f32 v112, v110, v111
	v_cvt_pk_bf16_f32 v113, v108, v109
	v_mul_f32_e32 v125, v167, v167
	v_mul_f32_e32 v127, v165, v165
	v_cvt_pk_bf16_f32 v114, v106, v107
	v_cvt_pk_bf16_f32 v115, v104, v105
	global_store_dwordx4 v[172:173], v[112:115], off
	v_mul_f32_e32 v177, v163, v163
	v_mul_f32_e32 v178, v161, v161
	v_pk_add_f32 v[112:113], v[100:101], v[188:189]
	v_pk_add_f32 v[100:101], v[92:93], v[192:193]
	v_pk_add_f32 v[92:93], v[98:99], v[198:199]
	v_lshlrev_b64 v[98:99], 11, v[152:153]
	v_mul_f32_e32 v161, v171, v171
	v_fmac_f32_e32 v175, v124, v124
	v_fmac_f32_e32 v176, v126, v126
	v_fmac_f32_e32 v125, v166, v166
	v_fmac_f32_e32 v127, v164, v164
	v_lshl_add_u64 v[98:99], s[10:11], 0, v[98:99]
	v_mul_f32_e32 v163, v169, v169
	v_fmac_f32_e32 v177, v162, v162
	v_fmac_f32_e32 v161, v170, v170
	v_add_f32_e32 v116, v175, v176
	v_add_f32_e32 v117, v125, v127
	v_lshl_add_u64 v[118:119], v[98:99], 0, v[144:145]
	v_pk_add_f32 v[98:99], v[84:85], v[212:213]
	v_pk_add_f32 v[84:85], v[76:77], v[204:205]
	v_pk_add_f32 v[76:77], v[82:83], v[222:223]
	v_lshlrev_b64 v[82:83], 11, v[150:151]
	v_fmac_f32_e32 v178, v160, v160
	v_fmac_f32_e32 v163, v168, v168
	v_add_f32_e32 v116, v116, v177
	v_add_f32_e32 v117, v117, v161
	v_lshl_add_u64 v[82:83], s[10:11], 0, v[82:83]
	v_add_f32_e32 v116, v178, v116
	v_add_f32_e32 v117, v163, v117
	v_cvt_pk_bf16_f32 v114, v112, v113
	v_lshl_add_u64 v[122:123], v[82:83], 0, v[144:145]
	v_pk_add_f32 v[82:83], v[68:69], v[228:229]
	v_pk_add_f32 v[68:69], v[64:65], v[224:225]
	v_and_b32_e32 v65, 64, v174
	v_add_f32_e32 v120, v116, v117
	v_pk_add_f32 v[102:103], v[102:103], v[190:191]
	v_pk_add_f32 v[94:95], v[94:95], v[194:195]
	v_cvt_pk_bf16_f32 v115, v102, v103
	v_cvt_pk_bf16_f32 v116, v100, v101
	v_pk_add_f32 v[96:97], v[96:97], v[196:197]
	v_cvt_pk_bf16_f32 v117, v94, v95
	global_store_dwordx4 v[172:173], v[114:117], off offset:256
	v_xor_b32_e32 v64, 16, v174
	v_add_u32_e32 v65, 64, v65
	v_cvt_pk_bf16_f32 v114, v96, v97
	v_pk_add_f32 v[90:91], v[90:91], v[202:203]
	v_pk_add_f32 v[88:89], v[88:89], v[200:201]
	v_cvt_pk_bf16_f32 v115, v92, v93
	v_cmp_lt_i32_e32 vcc, v64, v65
	v_cvt_pk_bf16_f32 v116, v88, v89
	v_cvt_pk_bf16_f32 v117, v90, v91
	global_store_dwordx4 v[118:119], v[114:117], off
	v_pk_add_f32 v[86:87], v[86:87], v[214:215]
	v_pk_add_f32 v[78:79], v[78:79], v[206:207]
	v_cvt_pk_bf16_f32 v114, v98, v99
	v_cvt_pk_bf16_f32 v115, v86, v87
	v_cvt_pk_bf16_f32 v116, v84, v85
	v_pk_add_f32 v[80:81], v[80:81], v[220:221]
	v_cvt_pk_bf16_f32 v117, v78, v79
	global_store_dwordx4 v[118:119], v[114:117], off offset:256
	v_cndmask_b32_e32 v64, v174, v64, vcc
	v_pk_add_f32 v[74:75], v[74:75], v[218:219]
	v_cvt_pk_bf16_f32 v114, v80, v81
	v_pk_add_f32 v[72:73], v[72:73], v[216:217]
	v_cvt_pk_bf16_f32 v115, v76, v77
	v_pk_add_f32 v[70:71], v[70:71], v[230:231]
	v_cvt_pk_bf16_f32 v116, v72, v73
	v_cvt_pk_bf16_f32 v117, v74, v75
	global_store_dwordx4 v[122:123], v[114:117], off
	v_pk_add_f32 v[66:67], v[66:67], v[226:227]
	v_cvt_pk_bf16_f32 v118, v82, v83
	v_cvt_pk_bf16_f32 v119, v70, v71
	s_nop 0
	v_lshlrev_b32_e32 v114, 2, v64
	ds_bpermute_b32 v64, v114, v120
	v_xor_b32_e32 v115, 32, v174
	v_cmp_lt_i32_e32 vcc, v115, v65
	s_waitcnt lgkmcnt(0)
	v_add_f32_e32 v116, v120, v64
	v_cndmask_b32_e32 v65, v174, v115, vcc
	v_lshlrev_b32_e32 v115, 2, v65
	ds_bpermute_b32 v117, v115, v116
	v_lshl_add_u64 v[64:65], v[148:149], 2, s[66:67]
	v_cvt_pk_bf16_f32 v120, v68, v69
	v_cvt_pk_bf16_f32 v121, v66, v67
	global_store_dwordx4 v[122:123], v[118:121], off offset:256
	s_and_saveexec_b64 s[18:19], s[6:7]
	s_cbranch_execz .LBB0_657
	s_waitcnt lgkmcnt(0)
	v_add_f32_e32 v116, v116, v117
	global_atomic_add_f32 v[64:65], v116, off

.LBB0_712:
	ds_read_b128 v[144:147], v151
	ds_read_b128 v[156:159], v151 offset:1024
	ds_read_b128 v[160:163], v151 offset:2048
	ds_read_b128 v[164:167], v151 offset:3072
	s_add_u32 s26, s2, 0xfffc0080
	s_addc_u32 s27, s3, -1
	s_cmp_eq_u32 s56, 12
	s_cselect_b32 s29, s21, s27
	s_cselect_b32 s28, s52, s26
	s_cselect_b32 s27, s19, s55
	s_cselect_b32 s26, s53, s54
	v_lshl_add_u64 v[172:173], s[2:3], 0, v[136:137]
	s_add_i32 m0, s34, 0xc000
	ds_read_b128 v[168:171], v152
	ds_read_b128 v[176:179], v152 offset:1024
	ds_read_b128 v[180:183], v152 offset:2048
	ds_read_b128 v[184:187], v152 offset:3072
	ds_read_b128 v[188:191], v152 offset:4096
	ds_read_b128 v[192:195], v152 offset:5120
	ds_read_b128 v[196:199], v152 offset:6144
	ds_read_b128 v[200:203], v152 offset:7168
	global_load_lds_dwordx4 v[172:173], off
	s_add_i32 m0, s34, 0xe000
	v_lshl_add_u64 v[172:173], s[2:3], 0, v[138:139]
	global_load_lds_dwordx4 v[172:173], off
	s_waitcnt lgkmcnt(8)
	s_setprio 1
	s_barrier
	s_waitcnt lgkmcnt(0)
	v_mfma_f32_16x16x32_bf16 v[124:127], v[144:147], v[168:171], v[124:127]
	v_mfma_f32_16x16x32_bf16 v[120:123], v[160:163], v[168:171], v[120:123]
	v_mfma_f32_16x16x32_bf16 v[116:119], v[144:147], v[180:183], v[116:119]
	v_mfma_f32_16x16x32_bf16 v[112:115], v[160:163], v[180:183], v[112:115]
	v_mfma_f32_16x16x32_bf16 v[104:107], v[144:147], v[188:191], v[104:107]
	v_mfma_f32_16x16x32_bf16 v[96:99], v[160:163], v[188:191], v[96:99]
	v_mfma_f32_16x16x32_bf16 v[76:79], v[144:147], v[196:199], v[76:79]
	v_mfma_f32_16x16x32_bf16 v[72:75], v[160:163], v[196:199], v[72:75]
	v_mfma_f32_16x16x32_bf16 v[124:127], v[156:159], v[176:179], v[124:127]
	v_mfma_f32_16x16x32_bf16 v[120:123], v[164:167], v[176:179], v[120:123]
	v_mfma_f32_16x16x32_bf16 v[116:119], v[156:159], v[184:187], v[116:119]
	v_mfma_f32_16x16x32_bf16 v[112:115], v[164:167], v[184:187], v[112:115]
	v_mfma_f32_16x16x32_bf16 v[104:107], v[156:159], v[192:195], v[104:107]
	v_mfma_f32_16x16x32_bf16 v[96:99], v[164:167], v[192:195], v[96:99]
	v_mfma_f32_16x16x32_bf16 v[76:79], v[156:159], v[200:203], v[76:79]
	v_mfma_f32_16x16x32_bf16 v[72:75], v[164:167], v[200:203], v[72:75]
	s_barrier
	s_setprio 0
	s_add_i32 s57, s43, s33
	v_lshl_add_u64 v[172:173], s[26:27], 0, v[130:131]
	s_mov_b32 m0, s57
	ds_read_b128 v[204:207], v153
	ds_read_b128 v[212:215], v153 offset:1024
	ds_read_b128 v[216:219], v153 offset:2048
	ds_read_b128 v[220:223], v153 offset:3072
	global_load_lds_dwordx4 v[172:173], off
	s_add_i32 m0, s57, 0x2000
	v_lshl_add_u64 v[208:209], s[26:27], 0, v[134:135]
	global_load_lds_dwordx4 v[208:209], off
	s_setprio 1
	s_barrier
	s_waitcnt lgkmcnt(0)
	v_mfma_f32_16x16x32_bf16 v[108:111], v[204:207], v[168:171], v[108:111]
	v_mfma_f32_16x16x32_bf16 v[100:103], v[216:219], v[168:171], v[100:103]
	v_mfma_f32_16x16x32_bf16 v[92:95], v[204:207], v[180:183], v[92:95]
	v_mfma_f32_16x16x32_bf16 v[88:91], v[216:219], v[180:183], v[88:91]
	v_mfma_f32_16x16x32_bf16 v[84:87], v[204:207], v[188:191], v[84:87]
	v_mfma_f32_16x16x32_bf16 v[80:83], v[216:219], v[188:191], v[80:83]
	v_mfma_f32_16x16x32_bf16 v[68:71], v[204:207], v[196:199], v[68:71]
	v_mfma_f32_16x16x32_bf16 v[64:67], v[216:219], v[196:199], v[64:67]
	v_mfma_f32_16x16x32_bf16 v[108:111], v[212:215], v[176:179], v[108:111]
	v_mfma_f32_16x16x32_bf16 v[100:103], v[220:223], v[176:179], v[100:103]
	v_mfma_f32_16x16x32_bf16 v[92:95], v[212:215], v[184:187], v[92:95]
	v_mfma_f32_16x16x32_bf16 v[88:91], v[220:223], v[184:187], v[88:91]
	v_mfma_f32_16x16x32_bf16 v[84:87], v[212:215], v[192:195], v[84:87]
	v_mfma_f32_16x16x32_bf16 v[80:83], v[220:223], v[192:195], v[80:83]
	v_mfma_f32_16x16x32_bf16 v[68:71], v[212:215], v[200:203], v[68:71]
	v_mfma_f32_16x16x32_bf16 v[64:67], v[220:223], v[200:203], v[64:67]
	s_barrier
	s_setprio 0
	s_mov_b32 m0, s34
	v_lshl_add_u64 v[224:225], s[28:29], 0, v[128:129]
	ds_read_b128 v[168:171], v152 offset:16384
	ds_read_b128 v[176:179], v152 offset:17408
	ds_read_b128 v[180:183], v152 offset:18432
	ds_read_b128 v[184:187], v152 offset:19456
	ds_read_b128 v[188:191], v152 offset:20480
	ds_read_b128 v[192:195], v152 offset:21504
	ds_read_b128 v[196:199], v152 offset:22528
	ds_read_b128 v[200:203], v152 offset:23552
	global_load_lds_dwordx4 v[224:225], off
	s_mov_b32 m0, s35
	v_lshl_add_u64 v[226:227], s[28:29], 0, v[132:133]
	global_load_lds_dwordx4 v[226:227], off
	s_setprio 1
	s_barrier
	s_waitcnt lgkmcnt(0)
	v_mfma_f32_16x16x32_bf16 v[60:63], v[144:147], v[168:171], v[60:63]
	v_mfma_f32_16x16x32_bf16 v[56:59], v[160:163], v[168:171], v[56:59]
	v_mfma_f32_16x16x32_bf16 v[44:47], v[144:147], v[180:183], v[44:47]
	v_mfma_f32_16x16x32_bf16 v[40:43], v[160:163], v[180:183], v[40:43]
	v_mfma_f32_16x16x32_bf16 v[28:31], v[144:147], v[188:191], v[28:31]
	v_mfma_f32_16x16x32_bf16 v[24:27], v[160:163], v[188:191], v[24:27]
	v_mfma_f32_16x16x32_bf16 v[12:15], v[144:147], v[196:199], v[12:15]
	v_mfma_f32_16x16x32_bf16 v[8:11], v[160:163], v[196:199], v[8:11]
	v_mfma_f32_16x16x32_bf16 v[60:63], v[156:159], v[176:179], v[60:63]
	v_mfma_f32_16x16x32_bf16 v[56:59], v[164:167], v[176:179], v[56:59]
	v_mfma_f32_16x16x32_bf16 v[44:47], v[156:159], v[184:187], v[44:47]
	v_mfma_f32_16x16x32_bf16 v[40:43], v[164:167], v[184:187], v[40:43]
	v_mfma_f32_16x16x32_bf16 v[28:31], v[156:159], v[192:195], v[28:31]
	v_mfma_f32_16x16x32_bf16 v[24:27], v[164:167], v[192:195], v[24:27]
	v_mfma_f32_16x16x32_bf16 v[12:15], v[156:159], v[200:203], v[12:15]
	v_mfma_f32_16x16x32_bf16 v[8:11], v[164:167], v[200:203], v[8:11]
	s_barrier
	s_setprio 0
	s_add_u32 s58, s26, 0x40000
	s_addc_u32 s59, s27, 0
	s_add_i32 s57, s48, s33
	s_mov_b32 m0, s57
	v_lshl_add_u64 v[144:145], s[58:59], 0, v[130:131]
	global_load_lds_dwordx4 v[144:145], off
	s_add_i32 m0, s57, 0x2000
	v_lshl_add_u64 v[144:145], s[58:59], 0, v[134:135]
	global_load_lds_dwordx4 v[144:145], off
	s_waitcnt vmcnt(6)
	s_setprio 1
	s_barrier
	v_mfma_f32_16x16x32_bf16 v[52:55], v[204:207], v[168:171], v[52:55]
	v_mfma_f32_16x16x32_bf16 v[48:51], v[216:219], v[168:171], v[48:51]
	v_mfma_f32_16x16x32_bf16 v[36:39], v[204:207], v[180:183], v[36:39]
	v_mfma_f32_16x16x32_bf16 v[32:35], v[216:219], v[180:183], v[32:35]
	v_mfma_f32_16x16x32_bf16 v[20:23], v[204:207], v[188:191], v[20:23]
	v_mfma_f32_16x16x32_bf16 v[16:19], v[216:219], v[188:191], v[16:19]
	v_mfma_f32_16x16x32_bf16 v[4:7], v[204:207], v[196:199], v[4:7]
	v_mfma_f32_16x16x32_bf16 v[0:3], v[216:219], v[196:199], v[0:3]
	v_mfma_f32_16x16x32_bf16 v[52:55], v[212:215], v[176:179], v[52:55]
	v_mfma_f32_16x16x32_bf16 v[48:51], v[220:223], v[176:179], v[48:51]
	v_mfma_f32_16x16x32_bf16 v[36:39], v[212:215], v[184:187], v[36:39]
	v_mfma_f32_16x16x32_bf16 v[32:35], v[220:223], v[184:187], v[32:35]
	v_mfma_f32_16x16x32_bf16 v[20:23], v[212:215], v[192:195], v[20:23]
	v_mfma_f32_16x16x32_bf16 v[16:19], v[220:223], v[192:195], v[16:19]
	v_mfma_f32_16x16x32_bf16 v[4:7], v[212:215], v[200:203], v[4:7]
	v_mfma_f32_16x16x32_bf16 v[0:3], v[220:223], v[200:203], v[0:3]
	s_barrier
	s_setprio 0
	s_add_i32 s57, 0, 0x18000
	v_add_u32_e32 v155, s57, v149
	ds_read_b128 v[144:147], v155
	ds_read_b128 v[156:159], v155 offset:1024
	ds_read_b128 v[160:163], v155 offset:2048
	ds_read_b128 v[164:167], v155 offset:3072
	s_add_u32 s28, s28, 0x40000
	s_addc_u32 s29, s29, 0
	s_mov_b32 m0, s36
	v_lshl_add_u64 v[204:205], s[28:29], 0, v[128:129]
	ds_read_b128 v[168:171], v152 offset:32768
	ds_read_b128 v[176:179], v152 offset:33792
	ds_read_b128 v[180:183], v152 offset:34816
	ds_read_b128 v[184:187], v152 offset:35840
	ds_read_b128 v[188:191], v152 offset:36864
	ds_read_b128 v[192:195], v152 offset:37888
	ds_read_b128 v[196:199], v152 offset:38912
	ds_read_b128 v[200:203], v152 offset:39936
	global_load_lds_dwordx4 v[204:205], off
	s_mov_b32 m0, s37
	v_lshl_add_u64 v[204:205], s[28:29], 0, v[132:133]
	global_load_lds_dwordx4 v[204:205], off
	s_waitcnt lgkmcnt(8)
	s_setprio 1
	s_barrier
	s_waitcnt lgkmcnt(0)
	v_mfma_f32_16x16x32_bf16 v[124:127], v[144:147], v[168:171], v[124:127]
	v_mfma_f32_16x16x32_bf16 v[120:123], v[160:163], v[168:171], v[120:123]
	v_mfma_f32_16x16x32_bf16 v[116:119], v[144:147], v[180:183], v[116:119]
	v_mfma_f32_16x16x32_bf16 v[112:115], v[160:163], v[180:183], v[112:115]
	v_mfma_f32_16x16x32_bf16 v[104:107], v[144:147], v[188:191], v[104:107]
	v_mfma_f32_16x16x32_bf16 v[96:99], v[160:163], v[188:191], v[96:99]
	v_mfma_f32_16x16x32_bf16 v[76:79], v[144:147], v[196:199], v[76:79]
	v_mfma_f32_16x16x32_bf16 v[72:75], v[160:163], v[196:199], v[72:75]
	v_mfma_f32_16x16x32_bf16 v[124:127], v[156:159], v[176:179], v[124:127]
	v_mfma_f32_16x16x32_bf16 v[120:123], v[164:167], v[176:179], v[120:123]
	v_mfma_f32_16x16x32_bf16 v[116:119], v[156:159], v[184:187], v[116:119]
	v_mfma_f32_16x16x32_bf16 v[112:115], v[164:167], v[184:187], v[112:115]
	v_mfma_f32_16x16x32_bf16 v[104:107], v[156:159], v[192:195], v[104:107]
	v_mfma_f32_16x16x32_bf16 v[96:99], v[164:167], v[192:195], v[96:99]
	v_mfma_f32_16x16x32_bf16 v[76:79], v[156:159], v[200:203], v[76:79]
	v_mfma_f32_16x16x32_bf16 v[72:75], v[164:167], v[200:203], v[72:75]
	s_barrier
	s_setprio 0
	s_add_i32 s28, 0, 0x1c000
	s_add_i32 s29, s57, s33
	v_add_u32_e32 v155, s28, v149
	v_lshl_add_u64 v[172:173], v[172:173], 0, s[8:9]
	s_mov_b32 m0, s29
	ds_read_b128 v[204:207], v155
	ds_read_b128 v[212:215], v155 offset:1024
	ds_read_b128 v[216:219], v155 offset:2048
	ds_read_b128 v[220:223], v155 offset:3072
	global_load_lds_dwordx4 v[172:173], off
	s_add_i32 m0, s29, 0x2000
	v_lshl_add_u64 v[172:173], v[208:209], 0, s[8:9]
	global_load_lds_dwordx4 v[172:173], off
	s_setprio 1
	s_barrier
	s_waitcnt lgkmcnt(0)
	v_mfma_f32_16x16x32_bf16 v[108:111], v[204:207], v[168:171], v[108:111]
	v_mfma_f32_16x16x32_bf16 v[100:103], v[216:219], v[168:171], v[100:103]
	v_mfma_f32_16x16x32_bf16 v[92:95], v[204:207], v[180:183], v[92:95]
	v_mfma_f32_16x16x32_bf16 v[88:91], v[216:219], v[180:183], v[88:91]
	v_mfma_f32_16x16x32_bf16 v[84:87], v[204:207], v[188:191], v[84:87]
	v_mfma_f32_16x16x32_bf16 v[80:83], v[216:219], v[188:191], v[80:83]
	v_mfma_f32_16x16x32_bf16 v[68:71], v[204:207], v[196:199], v[68:71]
	v_mfma_f32_16x16x32_bf16 v[64:67], v[216:219], v[196:199], v[64:67]
	v_mfma_f32_16x16x32_bf16 v[108:111], v[212:215], v[176:179], v[108:111]
	v_mfma_f32_16x16x32_bf16 v[100:103], v[220:223], v[176:179], v[100:103]
	v_mfma_f32_16x16x32_bf16 v[92:95], v[212:215], v[184:187], v[92:95]
	v_mfma_f32_16x16x32_bf16 v[88:91], v[220:223], v[184:187], v[88:91]
	v_mfma_f32_16x16x32_bf16 v[84:87], v[212:215], v[192:195], v[84:87]
	v_mfma_f32_16x16x32_bf16 v[80:83], v[220:223], v[192:195], v[80:83]
	v_mfma_f32_16x16x32_bf16 v[68:71], v[212:215], v[200:203], v[68:71]
	v_mfma_f32_16x16x32_bf16 v[64:67], v[220:223], v[200:203], v[64:67]
	s_barrier
	s_setprio 0
	s_mov_b32 m0, s39
	v_lshl_add_u64 v[172:173], v[224:225], 0, s[8:9]
	ds_read_b128 v[168:171], v152 offset:49152
	ds_read_b128 v[176:179], v152 offset:50176
	ds_read_b128 v[180:183], v152 offset:51200
	ds_read_b128 v[184:187], v152 offset:52224
	ds_read_b128 v[188:191], v152 offset:53248
	ds_read_b128 v[192:195], v152 offset:54272
	ds_read_b128 v[196:199], v152 offset:55296
	ds_read_b128 v[200:203], v152 offset:56320
	global_load_lds_dwordx4 v[172:173], off
	s_mov_b32 m0, s40
	v_lshl_add_u64 v[172:173], v[226:227], 0, s[8:9]
	global_load_lds_dwordx4 v[172:173], off
	s_setprio 1
	s_barrier
	s_waitcnt lgkmcnt(0)
	v_mfma_f32_16x16x32_bf16 v[60:63], v[144:147], v[168:171], v[60:63]
	v_mfma_f32_16x16x32_bf16 v[56:59], v[160:163], v[168:171], v[56:59]
	v_mfma_f32_16x16x32_bf16 v[44:47], v[144:147], v[180:183], v[44:47]
	v_mfma_f32_16x16x32_bf16 v[40:43], v[160:163], v[180:183], v[40:43]
	v_mfma_f32_16x16x32_bf16 v[28:31], v[144:147], v[188:191], v[28:31]
	v_mfma_f32_16x16x32_bf16 v[24:27], v[160:163], v[188:191], v[24:27]
	v_mfma_f32_16x16x32_bf16 v[12:15], v[144:147], v[196:199], v[12:15]
	v_mfma_f32_16x16x32_bf16 v[8:11], v[160:163], v[196:199], v[8:11]
	v_mfma_f32_16x16x32_bf16 v[60:63], v[156:159], v[176:179], v[60:63]
	v_mfma_f32_16x16x32_bf16 v[56:59], v[164:167], v[176:179], v[56:59]
	v_mfma_f32_16x16x32_bf16 v[44:47], v[156:159], v[184:187], v[44:47]
	v_mfma_f32_16x16x32_bf16 v[40:43], v[164:167], v[184:187], v[40:43]
	v_mfma_f32_16x16x32_bf16 v[28:31], v[156:159], v[192:195], v[28:31]
	v_mfma_f32_16x16x32_bf16 v[24:27], v[164:167], v[192:195], v[24:27]
	v_mfma_f32_16x16x32_bf16 v[12:15], v[156:159], v[200:203], v[12:15]
	v_mfma_f32_16x16x32_bf16 v[8:11], v[164:167], v[200:203], v[8:11]
	s_barrier
	s_setprio 0
	s_add_u32 s26, s26, 0x40080
	s_addc_u32 s27, s27, 0
	s_add_i32 s28, s28, s33
	s_mov_b32 m0, s28
	v_lshl_add_u64 v[144:145], s[26:27], 0, v[130:131]
	global_load_lds_dwordx4 v[144:145], off
	s_add_i32 m0, s28, 0x2000
	v_lshl_add_u64 v[144:145], s[26:27], 0, v[134:135]
	global_load_lds_dwordx4 v[144:145], off
	s_waitcnt vmcnt(6)
	s_setprio 1
	s_barrier
	v_mfma_f32_16x16x32_bf16 v[52:55], v[204:207], v[168:171], v[52:55]
	v_mfma_f32_16x16x32_bf16 v[48:51], v[216:219], v[168:171], v[48:51]
	v_mfma_f32_16x16x32_bf16 v[36:39], v[204:207], v[180:183], v[36:39]
	v_mfma_f32_16x16x32_bf16 v[32:35], v[216:219], v[180:183], v[32:35]
	v_mfma_f32_16x16x32_bf16 v[20:23], v[204:207], v[188:191], v[20:23]
	v_mfma_f32_16x16x32_bf16 v[16:19], v[216:219], v[188:191], v[16:19]
	v_mfma_f32_16x16x32_bf16 v[4:7], v[204:207], v[196:199], v[4:7]
	v_mfma_f32_16x16x32_bf16 v[0:3], v[216:219], v[196:199], v[0:3]
	v_mfma_f32_16x16x32_bf16 v[52:55], v[212:215], v[176:179], v[52:55]
	v_mfma_f32_16x16x32_bf16 v[48:51], v[220:223], v[176:179], v[48:51]
	v_mfma_f32_16x16x32_bf16 v[36:39], v[212:215], v[184:187], v[36:39]
	v_mfma_f32_16x16x32_bf16 v[32:35], v[220:223], v[184:187], v[32:35]
	v_mfma_f32_16x16x32_bf16 v[20:23], v[212:215], v[192:195], v[20:23]
	v_mfma_f32_16x16x32_bf16 v[16:19], v[220:223], v[192:195], v[16:19]
	v_mfma_f32_16x16x32_bf16 v[4:7], v[212:215], v[200:203], v[4:7]
	v_mfma_f32_16x16x32_bf16 v[0:3], v[220:223], v[200:203], v[0:3]
	s_barrier
	s_setprio 0
	s_add_i32 s56, s56, 2
	s_add_u32 s2, s2, 0x100
	s_addc_u32 s3, s3, 0
	s_add_u32 s54, s54, 0x100
	s_addc_u32 s55, s55, 0
	s_cmp_gt_u32 s56, 13
	s_cbranch_scc0 .LBB0_712
	v_lshl_add_u32 v146, s0, 8, v148
	v_ashrrev_i32_e32 v147, 31, v146
	v_lshl_add_u64 v[144:145], v[146:147], 2, s[66:67]
	global_load_dword v155, v[144:145], off
	global_load_dword v164, v[144:145], off offset:64
	global_load_dword v165, v[144:145], off offset:128
	global_load_dword v166, v[144:145], off offset:192
	global_load_dword v167, v[144:145], off offset:512
	global_load_dword v168, v[144:145], off offset:576
	global_load_dword v169, v[144:145], off offset:640
	global_load_dword v170, v[144:145], off offset:704
	v_lshl_or_b32 v144, s1, 8, v150
	v_ashrrev_i32_e32 v145, 31, v144
	v_lshlrev_b64 v[160:161], 10, v[146:147]
	v_lshlrev_b64 v[162:163], 1, v[144:145]
	v_lshl_add_u64 v[144:145], s[92:93], 0, v[160:161]
	v_or_b32_e32 v156, 16, v146
	v_ashrrev_i32_e32 v157, 31, v156
	v_or_b32_e32 v158, 32, v146
	v_lshlrev_b64 v[156:157], 10, v[156:157]
	v_lshl_add_u64 v[144:145], v[144:145], 0, v[162:163]
	v_ashrrev_i32_e32 v159, 31, v158
	v_lshl_add_u64 v[156:157], s[92:93], 0, v[156:157]
	v_lshlrev_b64 v[158:159], 10, v[158:159]
	v_lshl_add_u64 v[156:157], v[156:157], 0, v[162:163]
	v_lshl_add_u64 v[158:159], s[92:93], 0, v[158:159]
	v_lshl_add_u64 v[158:159], v[158:159], 0, v[162:163]
	s_mov_b64 s[26:27], s[24:25]
	s_waitcnt vmcnt(0)
	v_fmamk_f32 v147, v155, 0x3a800000, v154
	v_fmamk_f32 v155, v164, 0x3a800000, v154
	v_fmamk_f32 v160, v165, 0x3a800000, v154
	v_mul_f32_e32 v161, 0x4b800000, v147
	v_mul_f32_e32 v164, 0x4b800000, v155
	v_cmp_gt_f32_e32 vcc, s49, v147
	v_cmp_gt_f32_e64 s[0:1], s49, v155
	v_mul_f32_e32 v165, 0x4b800000, v160
	v_cndmask_b32_e32 v147, v147, v161, vcc
	v_cndmask_b32_e64 v155, v155, v164, s[0:1]
	v_cmp_gt_f32_e64 s[2:3], s49, v160
	v_rsq_f32_e32 v147, v147
	v_rsq_f32_e32 v155, v155
	v_cndmask_b32_e64 v160, v160, v165, s[2:3]
	v_rsq_f32_e32 v160, v160
	v_mul_f32_e32 v161, 0x45800000, v147
	v_mul_f32_e32 v164, 0x45800000, v155
	v_cndmask_b32_e32 v147, v147, v161, vcc
	v_mul_f32_e32 v165, 0x45800000, v160
	v_cndmask_b32_e64 v155, v155, v164, s[0:1]
	v_cndmask_b32_e64 v161, v160, v165, s[2:3]
	v_mul_f32_e32 v160, 0x3e0293ee, v147
	v_mul_f32_e32 v164, 0x3e0293ee, v155
	v_fmamk_f32 v171, v166, 0x3a800000, v154
	v_mul_f32_e32 v166, 0x3e0293ee, v161
	v_pk_mul_f32 v[126:127], v[126:127], v[160:161] op_sel_hi:[1,0]
	v_pk_mul_f32 v[124:125], v[124:125], v[160:161] op_sel_hi:[1,0]
	v_pk_mul_f32 v[122:123], v[122:123], v[160:161] op_sel_hi:[1,0]
	v_pk_mul_f32 v[120:121], v[120:121], v[160:161] op_sel_hi:[1,0]
	v_pk_mul_f32 v[110:111], v[110:111], v[160:161] op_sel_hi:[1,0]
	v_pk_mul_f32 v[108:109], v[108:109], v[160:161] op_sel_hi:[1,0]
	v_pk_mul_f32 v[102:103], v[102:103], v[160:161] op_sel_hi:[1,0]
	v_pk_mul_f32 v[100:101], v[100:101], v[160:161] op_sel_hi:[1,0]
	v_pk_mul_f32 v[118:119], v[118:119], v[164:165] op_sel_hi:[1,0]
	v_pk_mul_f32 v[116:117], v[116:117], v[164:165] op_sel_hi:[1,0]
	v_pk_mul_f32 v[114:115], v[114:115], v[164:165] op_sel_hi:[1,0]
	v_pk_mul_f32 v[112:113], v[112:113], v[164:165] op_sel_hi:[1,0]
	v_pk_mul_f32 v[94:95], v[94:95], v[164:165] op_sel_hi:[1,0]
	v_pk_mul_f32 v[92:93], v[92:93], v[164:165] op_sel_hi:[1,0]
	v_pk_mul_f32 v[160:161], v[90:91], v[164:165] op_sel_hi:[1,0]
	v_pk_mul_f32 v[164:165], v[88:89], v[164:165] op_sel_hi:[1,0]
	v_cvt_pk_bf16_f32 v88, v124, v125
	v_cvt_pk_bf16_f32 v89, v126, v127
	v_cvt_pk_bf16_f32 v90, v120, v121
	v_cvt_pk_bf16_f32 v91, v122, v123
	global_store_dwordx4 v[144:145], v[88:91], off
	v_fmamk_f32 v167, v167, 0x3a800000, v154
	v_pk_mul_f32 v[106:107], v[106:107], v[166:167] op_sel_hi:[1,0]
	v_cvt_pk_bf16_f32 v88, v108, v109
	v_cvt_pk_bf16_f32 v89, v110, v111
	v_cvt_pk_bf16_f32 v90, v100, v101
	v_cvt_pk_bf16_f32 v91, v102, v103
	global_store_dwordx4 v[144:145], v[88:91], off offset:256
	v_pk_mul_f32 v[104:105], v[104:105], v[166:167] op_sel_hi:[1,0]
	v_pk_mul_f32 v[98:99], v[98:99], v[166:167] op_sel_hi:[1,0]
	v_cvt_pk_bf16_f32 v88, v116, v117
	v_cvt_pk_bf16_f32 v89, v118, v119
	v_cvt_pk_bf16_f32 v90, v112, v113
	v_cvt_pk_bf16_f32 v91, v114, v115
	global_store_dwordx4 v[156:157], v[88:91], off
	v_pk_mul_f32 v[96:97], v[96:97], v[166:167] op_sel_hi:[1,0]
	v_pk_mul_f32 v[86:87], v[86:87], v[166:167] op_sel_hi:[1,0]
	v_cvt_pk_bf16_f32 v88, v92, v93
	v_cvt_pk_bf16_f32 v89, v94, v95
	v_cvt_pk_bf16_f32 v90, v164, v165
	v_cvt_pk_bf16_f32 v91, v160, v161
	global_store_dwordx4 v[156:157], v[88:91], off offset:256
	v_pk_mul_f32 v[84:85], v[84:85], v[166:167] op_sel_hi:[1,0]
	v_cmp_gt_f32_e32 vcc, s49, v171
	v_cvt_pk_bf16_f32 v88, v104, v105
	v_cvt_pk_bf16_f32 v89, v106, v107
	v_cvt_pk_bf16_f32 v90, v96, v97
	v_cvt_pk_bf16_f32 v91, v98, v99
	global_store_dwordx4 v[158:159], v[88:91], off
	s_mov_b64 s[0:1], 0x20000
	v_fmamk_f32 v168, v168, 0x3a800000, v154
	v_pk_mul_f32 v[88:89], v[82:83], v[166:167] op_sel_hi:[1,0]
	v_pk_mul_f32 v[82:83], v[80:81], v[166:167] op_sel_hi:[1,0]
	v_cvt_pk_bf16_f32 v80, v84, v85
	v_cvt_pk_bf16_f32 v81, v86, v87
	v_fmamk_f32 v169, v169, 0x3a800000, v154
	v_cvt_pk_bf16_f32 v82, v82, v83
	v_cvt_pk_bf16_f32 v83, v88, v89
	global_store_dwordx4 v[158:159], v[80:83], off offset:256
	v_fmamk_f32 v170, v170, 0x3a800000, v154
	s_mov_b64 s[2:3], s[22:23]
	v_mul_f32_e32 v82, 0x4b800000, v171
	v_cndmask_b32_e32 v82, v171, v82, vcc
	v_rsq_f32_e32 v82, v82
	v_or_b32_e32 v80, 48, v146
	v_ashrrev_i32_e32 v81, 31, v80
	v_lshlrev_b64 v[80:81], 10, v[80:81]
	v_mul_f32_e32 v83, 0x45800000, v82
	v_cndmask_b32_e32 v82, v82, v83, vcc
	v_lshl_add_u64 v[80:81], s[92:93], 0, v[80:81]
	v_mul_f32_e32 v82, 0x3e0293ee, v82
	v_lshl_add_u64 v[80:81], v[80:81], 0, v[162:163]
	v_pk_mul_f32 v[78:79], v[78:79], v[82:83] op_sel_hi:[1,0]
	v_pk_mul_f32 v[76:77], v[76:77], v[82:83] op_sel_hi:[1,0]
	v_pk_mul_f32 v[84:85], v[74:75], v[82:83] op_sel_hi:[1,0]
	v_pk_mul_f32 v[74:75], v[72:73], v[82:83] op_sel_hi:[1,0]
	v_cvt_pk_bf16_f32 v72, v76, v77
	v_cvt_pk_bf16_f32 v73, v78, v79
	v_pk_mul_f32 v[70:71], v[70:71], v[82:83] op_sel_hi:[1,0]
	v_cvt_pk_bf16_f32 v74, v74, v75
	v_cvt_pk_bf16_f32 v75, v84, v85
	global_store_dwordx4 v[80:81], v[72:75], off
	v_pk_mul_f32 v[68:69], v[68:69], v[82:83] op_sel_hi:[1,0]
	v_cmp_gt_f32_e32 vcc, s49, v167
	v_pk_mul_f32 v[72:73], v[66:67], v[82:83] op_sel_hi:[1,0]
	v_pk_mul_f32 v[66:67], v[64:65], v[82:83] op_sel_hi:[1,0]
	v_cvt_pk_bf16_f32 v64, v68, v69
	v_cvt_pk_bf16_f32 v65, v70, v71
	s_nop 0
	v_cvt_pk_bf16_f32 v66, v66, v67
	v_mul_f32_e32 v67, 0x4b800000, v167
	v_cndmask_b32_e32 v67, v167, v67, vcc
	v_rsq_f32_e32 v68, v67
	v_cvt_pk_bf16_f32 v67, v72, v73
	global_store_dwordx4 v[80:81], v[64:67], off offset:256
	s_nop 1
	v_mul_f32_e32 v66, 0x45800000, v68
	v_cndmask_b32_e32 v66, v68, v66, vcc
	v_mul_f32_e32 v66, 0x3e0293ee, v66
	v_lshl_add_u64 v[64:65], v[144:145], 0, s[0:1]
	v_pk_mul_f32 v[60:61], v[60:61], v[66:67] op_sel_hi:[1,0]
	s_mov_b32 s0, 0x20000
	v_pk_mul_f32 v[68:69], v[58:59], v[66:67] op_sel_hi:[1,0]
	v_pk_mul_f32 v[58:59], v[56:57], v[66:67] op_sel_hi:[1,0]
	v_cvt_pk_bf16_f32 v56, v60, v61
	v_add_co_u32_e32 v60, vcc, s0, v144
	v_pk_mul_f32 v[62:63], v[62:63], v[66:67] op_sel_hi:[1,0]
	s_nop 0
	v_addc_co_u32_e32 v61, vcc, 0, v145, vcc
	v_cvt_pk_bf16_f32 v57, v62, v63
	v_cvt_pk_bf16_f32 v58, v58, v59
	v_cvt_pk_bf16_f32 v59, v68, v69
	global_store_dwordx4 v[60:61], v[56:59], off
	v_pk_mul_f32 v[54:55], v[54:55], v[66:67] op_sel_hi:[1,0]
	v_pk_mul_f32 v[52:53], v[52:53], v[66:67] op_sel_hi:[1,0]
	v_pk_mul_f32 v[56:57], v[50:51], v[66:67] op_sel_hi:[1,0]
	v_pk_mul_f32 v[50:51], v[48:49], v[66:67] op_sel_hi:[1,0]
	v_cvt_pk_bf16_f32 v48, v52, v53
	v_cvt_pk_bf16_f32 v49, v54, v55
	v_cmp_gt_f32_e32 vcc, s49, v168
	v_cvt_pk_bf16_f32 v50, v50, v51
	v_mul_f32_e32 v51, 0x4b800000, v168
	s_mov_b64 s[0:1], 0x24000
	v_cndmask_b32_e32 v51, v168, v51, vcc
	v_rsq_f32_e32 v52, v51
	v_cvt_pk_bf16_f32 v51, v56, v57
	global_store_dwordx4 v[64:65], v[48:51], off offset:256
	s_nop 1
	v_mul_f32_e32 v50, 0x45800000, v52
	v_cndmask_b32_e32 v50, v52, v50, vcc
	v_mul_f32_e32 v50, 0x3e0293ee, v50
	v_lshl_add_u64 v[48:49], v[144:145], 0, s[0:1]
	v_pk_mul_f32 v[44:45], v[44:45], v[50:51] op_sel_hi:[1,0]
	s_mov_b32 s0, 0x24000
	v_pk_mul_f32 v[52:53], v[42:43], v[50:51] op_sel_hi:[1,0]
	v_pk_mul_f32 v[42:43], v[40:41], v[50:51] op_sel_hi:[1,0]
	v_cvt_pk_bf16_f32 v40, v44, v45
	v_add_co_u32_e32 v44, vcc, s0, v144
	v_pk_mul_f32 v[46:47], v[46:47], v[50:51] op_sel_hi:[1,0]
	s_nop 0
	v_addc_co_u32_e32 v45, vcc, 0, v145, vcc
	v_cvt_pk_bf16_f32 v41, v46, v47
	v_cvt_pk_bf16_f32 v42, v42, v43
	v_cvt_pk_bf16_f32 v43, v52, v53
	global_store_dwordx4 v[44:45], v[40:43], off
	v_pk_mul_f32 v[38:39], v[38:39], v[50:51] op_sel_hi:[1,0]
	v_pk_mul_f32 v[36:37], v[36:37], v[50:51] op_sel_hi:[1,0]
	v_pk_mul_f32 v[40:41], v[34:35], v[50:51] op_sel_hi:[1,0]
	v_pk_mul_f32 v[34:35], v[32:33], v[50:51] op_sel_hi:[1,0]
	v_cvt_pk_bf16_f32 v32, v36, v37
	v_cvt_pk_bf16_f32 v33, v38, v39
	v_cmp_gt_f32_e32 vcc, s49, v169
	v_cvt_pk_bf16_f32 v34, v34, v35
	v_mul_f32_e32 v35, 0x4b800000, v169
	s_mov_b32 s1, s18
	v_cndmask_b32_e32 v35, v169, v35, vcc
	v_rsq_f32_e32 v36, v35
	v_cvt_pk_bf16_f32 v35, v40, v41
	global_store_dwordx4 v[48:49], v[32:35], off offset:256
	s_mov_b32 s0, s20
	s_nop 0
	v_mul_f32_e32 v34, 0x45800000, v36
	v_cndmask_b32_e32 v34, v36, v34, vcc
	v_mul_f32_e32 v34, 0x3e0293ee, v34
	v_pk_mul_f32 v[28:29], v[28:29], v[34:35] op_sel_hi:[1,0]
	v_pk_mul_f32 v[36:37], v[26:27], v[34:35] op_sel_hi:[1,0]
	v_pk_mul_f32 v[26:27], v[24:25], v[34:35] op_sel_hi:[1,0]
	v_cvt_pk_bf16_f32 v24, v28, v29
	v_add_co_u32_e32 v28, vcc, s50, v144
	v_pk_mul_f32 v[30:31], v[30:31], v[34:35] op_sel_hi:[1,0]
	s_nop 0
	v_addc_co_u32_e32 v29, vcc, 0, v145, vcc
	v_cvt_pk_bf16_f32 v25, v30, v31
	v_cvt_pk_bf16_f32 v26, v26, v27
	v_cvt_pk_bf16_f32 v27, v36, v37
	global_store_dwordx4 v[28:29], v[24:27], off
	v_pk_mul_f32 v[22:23], v[22:23], v[34:35] op_sel_hi:[1,0]
	v_pk_mul_f32 v[20:21], v[20:21], v[34:35] op_sel_hi:[1,0]
	v_pk_mul_f32 v[24:25], v[18:19], v[34:35] op_sel_hi:[1,0]
	v_pk_mul_f32 v[18:19], v[16:17], v[34:35] op_sel_hi:[1,0]
	v_cvt_pk_bf16_f32 v16, v20, v21
	v_cvt_pk_bf16_f32 v17, v22, v23
	v_cmp_gt_f32_e32 vcc, s49, v170
	v_cvt_pk_bf16_f32 v18, v18, v19
	v_mul_f32_e32 v19, 0x4b800000, v170
	v_lshl_add_u64 v[32:33], v[144:145], 0, s[12:13]
	v_cndmask_b32_e32 v19, v170, v19, vcc
	v_rsq_f32_e32 v20, v19
	v_cvt_pk_bf16_f32 v19, v24, v25
	global_store_dwordx4 v[32:33], v[16:19], off offset:256
	s_nop 1
	v_mul_f32_e32 v18, 0x45800000, v20
	v_cndmask_b32_e32 v18, v20, v18, vcc
	v_mul_f32_e32 v18, 0x3e0293ee, v18
	v_pk_mul_f32 v[12:13], v[12:13], v[18:19] op_sel_hi:[1,0]
	v_pk_mul_f32 v[20:21], v[10:11], v[18:19] op_sel_hi:[1,0]
	v_pk_mul_f32 v[10:11], v[8:9], v[18:19] op_sel_hi:[1,0]
	v_cvt_pk_bf16_f32 v8, v12, v13
	v_add_co_u32_e32 v12, vcc, s51, v144
	v_pk_mul_f32 v[14:15], v[14:15], v[18:19] op_sel_hi:[1,0]
	s_nop 0
	v_addc_co_u32_e32 v13, vcc, 0, v145, vcc
	v_cvt_pk_bf16_f32 v9, v14, v15
	v_lshl_add_u64 v[16:17], v[144:145], 0, s[16:17]
	v_cvt_pk_bf16_f32 v10, v10, v11
	v_cvt_pk_bf16_f32 v11, v20, v21
	global_store_dwordx4 v[12:13], v[8:11], off
	s_and_b64 vcc, exec, s[6:7]
	v_pk_mul_f32 v[6:7], v[6:7], v[18:19] op_sel_hi:[1,0]
	v_pk_mul_f32 v[8:9], v[2:3], v[18:19] op_sel_hi:[1,0]
	v_pk_mul_f32 v[2:3], v[0:1], v[18:19] op_sel_hi:[1,0]
	v_pk_mul_f32 v[4:5], v[4:5], v[18:19] op_sel_hi:[1,0]
	s_nop 0
	v_cvt_pk_bf16_f32 v0, v4, v5
	v_cvt_pk_bf16_f32 v1, v6, v7
	v_cvt_pk_bf16_f32 v2, v2, v3
	v_cvt_pk_bf16_f32 v3, v8, v9
	global_store_dwordx4 v[16:17], v[0:3], off offset:256
	s_cbranch_vccz .LBB0_705
	s_waitcnt vmcnt(0)
	s_cmpk_gt_u32 s30, 0xff
	s_cbranch_scc1 .LBB0_716
	s_barrier

.LBB0_792:
	ds_read_b128 v[144:147], v178
	ds_read_b128 v[148:151], v178 offset:1024
	ds_read_b128 v[152:155], v178 offset:2048
	ds_read_b128 v[156:159], v178 offset:3072
	s_add_u32 s40, s38, 0xfffe0080
	s_addc_u32 s41, s39, -1
	s_cmp_eq_u32 s63, 4
	s_cselect_b32 s43, s27, s41
	s_cselect_b32 s42, s35, s40
	s_cselect_b32 s41, s25, s62
	s_cselect_b32 s40, s60, s61
	v_lshl_add_u64 v[172:173], s[38:39], 0, v[136:137]
	s_add_i32 m0, s37, 0xc000
	ds_read_b128 v[160:163], v179
	ds_read_b128 v[164:167], v179 offset:1024
	ds_read_b128 v[168:171], v179 offset:2048
	ds_read_b128 v[182:185], v179 offset:3072
	ds_read_b128 v[186:189], v179 offset:4096
	ds_read_b128 v[190:193], v179 offset:5120
	ds_read_b128 v[194:197], v179 offset:6144
	ds_read_b128 v[198:201], v179 offset:7168
	global_load_lds_dwordx4 v[172:173], off
	s_add_i32 m0, s37, 0xe000
	v_lshl_add_u64 v[172:173], s[38:39], 0, v[138:139]
	global_load_lds_dwordx4 v[172:173], off
	s_waitcnt lgkmcnt(8)
	s_setprio 1
	s_barrier
	s_waitcnt lgkmcnt(0)
	v_mfma_f32_16x16x32_bf16 v[124:127], v[144:147], v[160:163], v[124:127]
	v_mfma_f32_16x16x32_bf16 v[120:123], v[152:155], v[160:163], v[120:123]
	v_mfma_f32_16x16x32_bf16 v[108:111], v[144:147], v[168:171], v[108:111]
	v_mfma_f32_16x16x32_bf16 v[104:107], v[152:155], v[168:171], v[104:107]
	v_mfma_f32_16x16x32_bf16 v[96:99], v[144:147], v[186:189], v[96:99]
	v_mfma_f32_16x16x32_bf16 v[88:91], v[152:155], v[186:189], v[88:91]
	v_mfma_f32_16x16x32_bf16 v[80:83], v[144:147], v[194:197], v[80:83]
	v_mfma_f32_16x16x32_bf16 v[72:75], v[152:155], v[194:197], v[72:75]
	v_mfma_f32_16x16x32_bf16 v[124:127], v[148:151], v[164:167], v[124:127]
	v_mfma_f32_16x16x32_bf16 v[120:123], v[156:159], v[164:167], v[120:123]
	v_mfma_f32_16x16x32_bf16 v[108:111], v[148:151], v[182:185], v[108:111]
	v_mfma_f32_16x16x32_bf16 v[104:107], v[156:159], v[182:185], v[104:107]
	v_mfma_f32_16x16x32_bf16 v[96:99], v[148:151], v[190:193], v[96:99]
	v_mfma_f32_16x16x32_bf16 v[88:91], v[156:159], v[190:193], v[88:91]
	v_mfma_f32_16x16x32_bf16 v[80:83], v[148:151], v[198:201], v[80:83]
	v_mfma_f32_16x16x32_bf16 v[72:75], v[156:159], v[198:201], v[72:75]
	s_barrier
	s_setprio 0
	s_add_i32 s64, s58, s48
	v_lshl_add_u64 v[172:173], s[40:41], 0, v[130:131]
	s_mov_b32 m0, s64
	ds_read_b128 v[202:205], v180
	ds_read_b128 v[206:209], v180 offset:1024
	ds_read_b128 v[212:215], v180 offset:2048
	ds_read_b128 v[216:219], v180 offset:3072
	global_load_lds_dwordx4 v[172:173], off
	s_add_i32 m0, s64, 0x2000
	v_lshl_add_u64 v[220:221], s[40:41], 0, v[134:135]
	global_load_lds_dwordx4 v[220:221], off
	s_setprio 1
	s_barrier
	s_waitcnt lgkmcnt(0)
	v_mfma_f32_16x16x32_bf16 v[116:119], v[202:205], v[160:163], v[116:119]
	v_mfma_f32_16x16x32_bf16 v[112:115], v[212:215], v[160:163], v[112:115]
	v_mfma_f32_16x16x32_bf16 v[100:103], v[202:205], v[168:171], v[100:103]
	v_mfma_f32_16x16x32_bf16 v[92:95], v[212:215], v[168:171], v[92:95]
	v_mfma_f32_16x16x32_bf16 v[84:87], v[202:205], v[186:189], v[84:87]
	v_mfma_f32_16x16x32_bf16 v[76:79], v[212:215], v[186:189], v[76:79]
	v_mfma_f32_16x16x32_bf16 v[68:71], v[202:205], v[194:197], v[68:71]
	v_mfma_f32_16x16x32_bf16 v[64:67], v[212:215], v[194:197], v[64:67]
	v_mfma_f32_16x16x32_bf16 v[116:119], v[206:209], v[164:167], v[116:119]
	v_mfma_f32_16x16x32_bf16 v[112:115], v[216:219], v[164:167], v[112:115]
	v_mfma_f32_16x16x32_bf16 v[100:103], v[206:209], v[182:185], v[100:103]
	v_mfma_f32_16x16x32_bf16 v[92:95], v[216:219], v[182:185], v[92:95]
	v_mfma_f32_16x16x32_bf16 v[84:87], v[206:209], v[190:193], v[84:87]
	v_mfma_f32_16x16x32_bf16 v[76:79], v[216:219], v[190:193], v[76:79]
	v_mfma_f32_16x16x32_bf16 v[68:71], v[206:209], v[198:201], v[68:71]
	v_mfma_f32_16x16x32_bf16 v[64:67], v[216:219], v[198:201], v[64:67]
	s_barrier
	s_setprio 0
	s_mov_b32 m0, s37
	v_lshl_add_u64 v[222:223], s[42:43], 0, v[128:129]
	ds_read_b128 v[160:163], v179 offset:16384
	ds_read_b128 v[164:167], v179 offset:17408
	ds_read_b128 v[168:171], v179 offset:18432
	ds_read_b128 v[182:185], v179 offset:19456
	ds_read_b128 v[186:189], v179 offset:20480
	ds_read_b128 v[190:193], v179 offset:21504
	ds_read_b128 v[194:197], v179 offset:22528
	ds_read_b128 v[198:201], v179 offset:23552
	global_load_lds_dwordx4 v[222:223], off
	s_mov_b32 m0, s49
	v_lshl_add_u64 v[224:225], s[42:43], 0, v[132:133]
	global_load_lds_dwordx4 v[224:225], off
	s_setprio 1
	s_barrier
	s_waitcnt lgkmcnt(0)
	v_mfma_f32_16x16x32_bf16 v[60:63], v[144:147], v[160:163], v[60:63]
	v_mfma_f32_16x16x32_bf16 v[56:59], v[152:155], v[160:163], v[56:59]
	v_mfma_f32_16x16x32_bf16 v[44:47], v[144:147], v[168:171], v[44:47]
	v_mfma_f32_16x16x32_bf16 v[40:43], v[152:155], v[168:171], v[40:43]
	v_mfma_f32_16x16x32_bf16 v[32:35], v[144:147], v[186:189], v[32:35]
	v_mfma_f32_16x16x32_bf16 v[24:27], v[152:155], v[186:189], v[24:27]
	v_mfma_f32_16x16x32_bf16 v[16:19], v[144:147], v[194:197], v[16:19]
	v_mfma_f32_16x16x32_bf16 v[8:11], v[152:155], v[194:197], v[8:11]
	v_mfma_f32_16x16x32_bf16 v[60:63], v[148:151], v[164:167], v[60:63]
	v_mfma_f32_16x16x32_bf16 v[56:59], v[156:159], v[164:167], v[56:59]
	v_mfma_f32_16x16x32_bf16 v[44:47], v[148:151], v[182:185], v[44:47]
	v_mfma_f32_16x16x32_bf16 v[40:43], v[156:159], v[182:185], v[40:43]
	v_mfma_f32_16x16x32_bf16 v[32:35], v[148:151], v[190:193], v[32:35]
	v_mfma_f32_16x16x32_bf16 v[24:27], v[156:159], v[190:193], v[24:27]
	v_mfma_f32_16x16x32_bf16 v[16:19], v[148:151], v[198:201], v[16:19]
	v_mfma_f32_16x16x32_bf16 v[8:11], v[156:159], v[198:201], v[8:11]
	s_barrier
	s_setprio 0
	s_add_u32 s64, s40, 0x20000
	s_addc_u32 s65, s41, 0
	s_add_i32 s66, s59, s48
	s_mov_b32 m0, s66
	v_lshl_add_u64 v[144:145], s[64:65], 0, v[130:131]
	global_load_lds_dwordx4 v[144:145], off
	s_add_i32 m0, s66, 0x2000
	v_lshl_add_u64 v[144:145], s[64:65], 0, v[134:135]
	global_load_lds_dwordx4 v[144:145], off
	s_waitcnt vmcnt(6)
	s_setprio 1
	s_barrier
	v_mfma_f32_16x16x32_bf16 v[52:55], v[202:205], v[160:163], v[52:55]
	v_mfma_f32_16x16x32_bf16 v[48:51], v[212:215], v[160:163], v[48:51]
	v_mfma_f32_16x16x32_bf16 v[36:39], v[202:205], v[168:171], v[36:39]
	v_mfma_f32_16x16x32_bf16 v[28:31], v[212:215], v[168:171], v[28:31]
	v_mfma_f32_16x16x32_bf16 v[20:23], v[202:205], v[186:189], v[20:23]
	v_mfma_f32_16x16x32_bf16 v[12:15], v[212:215], v[186:189], v[12:15]
	v_mfma_f32_16x16x32_bf16 v[4:7], v[202:205], v[194:197], v[4:7]
	v_mfma_f32_16x16x32_bf16 v[0:3], v[212:215], v[194:197], v[0:3]
	v_mfma_f32_16x16x32_bf16 v[52:55], v[206:209], v[164:167], v[52:55]
	v_mfma_f32_16x16x32_bf16 v[48:51], v[216:219], v[164:167], v[48:51]
	v_mfma_f32_16x16x32_bf16 v[36:39], v[206:209], v[182:185], v[36:39]
	v_mfma_f32_16x16x32_bf16 v[28:31], v[216:219], v[182:185], v[28:31]
	v_mfma_f32_16x16x32_bf16 v[20:23], v[206:209], v[190:193], v[20:23]
	v_mfma_f32_16x16x32_bf16 v[12:15], v[216:219], v[190:193], v[12:15]
	v_mfma_f32_16x16x32_bf16 v[4:7], v[206:209], v[198:201], v[4:7]
	v_mfma_f32_16x16x32_bf16 v[0:3], v[216:219], v[198:201], v[0:3]
	s_barrier
	s_setprio 0
	s_add_i32 s64, 0, 0x18000
	v_add_u32_e32 v156, s64, v176
	ds_read_b128 v[144:147], v156
	ds_read_b128 v[148:151], v156 offset:1024
	ds_read_b128 v[152:155], v156 offset:2048
	ds_read_b128 v[156:159], v156 offset:3072
	s_add_u32 s42, s42, 0x20000
	s_addc_u32 s43, s43, 0
	s_mov_b32 m0, s50
	v_lshl_add_u64 v[202:203], s[42:43], 0, v[128:129]
	ds_read_b128 v[160:163], v179 offset:32768
	ds_read_b128 v[164:167], v179 offset:33792
	ds_read_b128 v[168:171], v179 offset:34816
	ds_read_b128 v[182:185], v179 offset:35840
	ds_read_b128 v[186:189], v179 offset:36864
	ds_read_b128 v[190:193], v179 offset:37888
	ds_read_b128 v[194:197], v179 offset:38912
	ds_read_b128 v[198:201], v179 offset:39936
	global_load_lds_dwordx4 v[202:203], off
	s_mov_b32 m0, s51
	v_lshl_add_u64 v[202:203], s[42:43], 0, v[132:133]
	global_load_lds_dwordx4 v[202:203], off
	s_waitcnt lgkmcnt(8)
	s_setprio 1
	s_barrier
	s_waitcnt lgkmcnt(0)
	v_mfma_f32_16x16x32_bf16 v[124:127], v[144:147], v[160:163], v[124:127]
	v_mfma_f32_16x16x32_bf16 v[120:123], v[152:155], v[160:163], v[120:123]
	v_mfma_f32_16x16x32_bf16 v[108:111], v[144:147], v[168:171], v[108:111]
	v_mfma_f32_16x16x32_bf16 v[104:107], v[152:155], v[168:171], v[104:107]
	v_mfma_f32_16x16x32_bf16 v[96:99], v[144:147], v[186:189], v[96:99]
	v_mfma_f32_16x16x32_bf16 v[88:91], v[152:155], v[186:189], v[88:91]
	v_mfma_f32_16x16x32_bf16 v[80:83], v[144:147], v[194:197], v[80:83]
	v_mfma_f32_16x16x32_bf16 v[72:75], v[152:155], v[194:197], v[72:75]
	v_mfma_f32_16x16x32_bf16 v[124:127], v[148:151], v[164:167], v[124:127]
	v_mfma_f32_16x16x32_bf16 v[120:123], v[156:159], v[164:167], v[120:123]
	v_mfma_f32_16x16x32_bf16 v[108:111], v[148:151], v[182:185], v[108:111]
	v_mfma_f32_16x16x32_bf16 v[104:107], v[156:159], v[182:185], v[104:107]
	v_mfma_f32_16x16x32_bf16 v[96:99], v[148:151], v[190:193], v[96:99]
	v_mfma_f32_16x16x32_bf16 v[88:91], v[156:159], v[190:193], v[88:91]
	v_mfma_f32_16x16x32_bf16 v[80:83], v[148:151], v[198:201], v[80:83]
	v_mfma_f32_16x16x32_bf16 v[72:75], v[156:159], v[198:201], v[72:75]
	s_barrier
	s_setprio 0
	s_add_i32 s42, 0, 0x1c000
	s_add_i32 s43, s64, s48
	v_add_u32_e32 v181, s42, v176
	v_lshl_add_u64 v[172:173], v[172:173], 0, s[0:1]
	s_mov_b32 m0, s43
	ds_read_b128 v[202:205], v181
	ds_read_b128 v[206:209], v181 offset:1024
	ds_read_b128 v[212:215], v181 offset:2048
	ds_read_b128 v[216:219], v181 offset:3072
	global_load_lds_dwordx4 v[172:173], off
	s_add_i32 m0, s43, 0x2000
	v_lshl_add_u64 v[172:173], v[220:221], 0, s[0:1]
	global_load_lds_dwordx4 v[172:173], off
	s_setprio 1
	s_barrier
	s_waitcnt lgkmcnt(0)
	v_mfma_f32_16x16x32_bf16 v[116:119], v[202:205], v[160:163], v[116:119]
	v_mfma_f32_16x16x32_bf16 v[112:115], v[212:215], v[160:163], v[112:115]
	v_mfma_f32_16x16x32_bf16 v[100:103], v[202:205], v[168:171], v[100:103]
	v_mfma_f32_16x16x32_bf16 v[92:95], v[212:215], v[168:171], v[92:95]
	v_mfma_f32_16x16x32_bf16 v[84:87], v[202:205], v[186:189], v[84:87]
	v_mfma_f32_16x16x32_bf16 v[76:79], v[212:215], v[186:189], v[76:79]
	v_mfma_f32_16x16x32_bf16 v[68:71], v[202:205], v[194:197], v[68:71]
	v_mfma_f32_16x16x32_bf16 v[64:67], v[212:215], v[194:197], v[64:67]
	v_mfma_f32_16x16x32_bf16 v[116:119], v[206:209], v[164:167], v[116:119]
	v_mfma_f32_16x16x32_bf16 v[112:115], v[216:219], v[164:167], v[112:115]
	v_mfma_f32_16x16x32_bf16 v[100:103], v[206:209], v[182:185], v[100:103]
	v_mfma_f32_16x16x32_bf16 v[92:95], v[216:219], v[182:185], v[92:95]
	v_mfma_f32_16x16x32_bf16 v[84:87], v[206:209], v[190:193], v[84:87]
	v_mfma_f32_16x16x32_bf16 v[76:79], v[216:219], v[190:193], v[76:79]
	v_mfma_f32_16x16x32_bf16 v[68:71], v[206:209], v[198:201], v[68:71]
	v_mfma_f32_16x16x32_bf16 v[64:67], v[216:219], v[198:201], v[64:67]
	s_barrier
	s_setprio 0
	s_mov_b32 m0, s53
	v_lshl_add_u64 v[172:173], v[222:223], 0, s[0:1]
	ds_read_b128 v[160:163], v179 offset:49152
	ds_read_b128 v[164:167], v179 offset:50176
	ds_read_b128 v[168:171], v179 offset:51200
	ds_read_b128 v[182:185], v179 offset:52224
	ds_read_b128 v[186:189], v179 offset:53248
	ds_read_b128 v[190:193], v179 offset:54272
	ds_read_b128 v[194:197], v179 offset:55296
	ds_read_b128 v[198:201], v179 offset:56320
	global_load_lds_dwordx4 v[172:173], off
	s_mov_b32 m0, s54
	v_lshl_add_u64 v[172:173], v[224:225], 0, s[0:1]
	global_load_lds_dwordx4 v[172:173], off
	s_setprio 1
	s_barrier
	s_waitcnt lgkmcnt(0)
	v_mfma_f32_16x16x32_bf16 v[60:63], v[144:147], v[160:163], v[60:63]
	v_mfma_f32_16x16x32_bf16 v[56:59], v[152:155], v[160:163], v[56:59]
	v_mfma_f32_16x16x32_bf16 v[44:47], v[144:147], v[168:171], v[44:47]
	v_mfma_f32_16x16x32_bf16 v[40:43], v[152:155], v[168:171], v[40:43]
	v_mfma_f32_16x16x32_bf16 v[32:35], v[144:147], v[186:189], v[32:35]
	v_mfma_f32_16x16x32_bf16 v[24:27], v[152:155], v[186:189], v[24:27]
	v_mfma_f32_16x16x32_bf16 v[16:19], v[144:147], v[194:197], v[16:19]
	v_mfma_f32_16x16x32_bf16 v[8:11], v[152:155], v[194:197], v[8:11]
	v_mfma_f32_16x16x32_bf16 v[60:63], v[148:151], v[164:167], v[60:63]
	v_mfma_f32_16x16x32_bf16 v[56:59], v[156:159], v[164:167], v[56:59]
	v_mfma_f32_16x16x32_bf16 v[44:47], v[148:151], v[182:185], v[44:47]
	v_mfma_f32_16x16x32_bf16 v[40:43], v[156:159], v[182:185], v[40:43]
	v_mfma_f32_16x16x32_bf16 v[32:35], v[148:151], v[190:193], v[32:35]
	v_mfma_f32_16x16x32_bf16 v[24:27], v[156:159], v[190:193], v[24:27]
	v_mfma_f32_16x16x32_bf16 v[16:19], v[148:151], v[198:201], v[16:19]
	v_mfma_f32_16x16x32_bf16 v[8:11], v[156:159], v[198:201], v[8:11]
	s_barrier
	s_setprio 0
	s_add_u32 s40, s40, 0x20080
	s_addc_u32 s41, s41, 0
	s_add_i32 s42, s42, s48
	s_mov_b32 m0, s42
	v_lshl_add_u64 v[144:145], s[40:41], 0, v[130:131]
	global_load_lds_dwordx4 v[144:145], off
	s_add_i32 m0, s42, 0x2000
	v_lshl_add_u64 v[144:145], s[40:41], 0, v[134:135]
	global_load_lds_dwordx4 v[144:145], off
	s_waitcnt vmcnt(6)
	s_setprio 1
	s_barrier
	v_mfma_f32_16x16x32_bf16 v[52:55], v[202:205], v[160:163], v[52:55]
	v_mfma_f32_16x16x32_bf16 v[48:51], v[212:215], v[160:163], v[48:51]
	v_mfma_f32_16x16x32_bf16 v[36:39], v[202:205], v[168:171], v[36:39]
	v_mfma_f32_16x16x32_bf16 v[28:31], v[212:215], v[168:171], v[28:31]
	v_mfma_f32_16x16x32_bf16 v[20:23], v[202:205], v[186:189], v[20:23]
	v_mfma_f32_16x16x32_bf16 v[12:15], v[212:215], v[186:189], v[12:15]
	v_mfma_f32_16x16x32_bf16 v[4:7], v[202:205], v[194:197], v[4:7]
	v_mfma_f32_16x16x32_bf16 v[0:3], v[212:215], v[194:197], v[0:3]
	v_mfma_f32_16x16x32_bf16 v[52:55], v[206:209], v[164:167], v[52:55]
	v_mfma_f32_16x16x32_bf16 v[48:51], v[216:219], v[164:167], v[48:51]
	v_mfma_f32_16x16x32_bf16 v[36:39], v[206:209], v[182:185], v[36:39]
	v_mfma_f32_16x16x32_bf16 v[28:31], v[216:219], v[182:185], v[28:31]
	v_mfma_f32_16x16x32_bf16 v[20:23], v[206:209], v[190:193], v[20:23]
	v_mfma_f32_16x16x32_bf16 v[12:15], v[216:219], v[190:193], v[12:15]
	v_mfma_f32_16x16x32_bf16 v[4:7], v[206:209], v[198:201], v[4:7]
	v_mfma_f32_16x16x32_bf16 v[0:3], v[216:219], v[198:201], v[0:3]
	s_barrier
	s_setprio 0
	s_add_i32 s63, s63, 2
	s_add_u32 s38, s38, 0x100
	s_addc_u32 s39, s39, 0
	s_add_u32 s61, s61, 0x100
	s_addc_u32 s62, s62, 0
	s_cmp_gt_u32 s63, 5
	s_cbranch_scc0 .LBB0_792
	v_lshl_or_b32 v144, s36, 8, v177
	v_lshl_add_u32 v150, s34, 8, v175
	v_ashrrev_i32_e32 v145, 31, v144
	v_ashrrev_i32_e32 v151, 31, v150
	v_lshlrev_b64 v[144:145], 1, v[144:145]
	v_lshl_add_u64 v[146:147], s[10:11], 0, v[144:145]
	v_lshlrev_b64 v[148:149], 11, v[150:151]
	v_lshl_add_u64 v[152:153], v[146:147], 0, v[148:149]
	global_load_dwordx4 v[156:159], v[152:153], off
	global_load_dwordx4 v[160:163], v[152:153], off offset:256
	v_or_b32_e32 v152, 16, v150
	v_ashrrev_i32_e32 v153, 31, v152
	v_lshlrev_b64 v[170:171], 11, v[152:153]
	v_lshl_add_u64 v[152:153], v[146:147], 0, v[170:171]
	global_load_dwordx4 v[164:167], v[152:153], off
	global_load_dwordx4 v[182:185], v[152:153], off offset:256
	v_or_b32_e32 v152, 32, v150
	v_ashrrev_i32_e32 v153, 31, v152
	v_lshlrev_b64 v[154:155], 11, v[152:153]
	v_lshl_add_u64 v[152:153], v[146:147], 0, v[154:155]
	global_load_dwordx4 v[186:189], v[152:153], off
	global_load_dwordx4 v[190:193], v[152:153], off offset:256
	v_or_b32_e32 v152, 48, v150
	v_ashrrev_i32_e32 v153, 31, v152
	v_lshlrev_b64 v[152:153], 11, v[152:153]
	v_lshl_add_u64 v[168:169], v[146:147], 0, v[152:153]
	global_load_dwordx4 v[194:197], v[168:169], off
	global_load_dwordx4 v[198:201], v[168:169], off offset:256
	s_waitcnt vmcnt(0)
	v_lshlrev_b32_e32 v202, 16, v156
	v_and_b32_e32 v203, 0xffff0000, v156
	v_lshlrev_b32_e32 v204, 16, v157
	v_and_b32_e32 v205, 0xffff0000, v157
	v_lshlrev_b32_e32 v206, 16, v158
	v_and_b32_e32 v207, 0xffff0000, v158
	v_lshlrev_b32_e32 v208, 16, v159
	v_and_b32_e32 v209, 0xffff0000, v159
	v_pk_add_f32 v[126:127], v[126:127], v[204:205]
	v_pk_add_f32 v[124:125], v[124:125], v[202:203]
	v_lshlrev_b32_e32 v224, 16, v166
	v_and_b32_e32 v225, 0xffff0000, v166
	v_lshlrev_b32_e32 v226, 16, v167
	v_and_b32_e32 v227, 0xffff0000, v167
	v_lshlrev_b32_e32 v212, 16, v160
	v_lshlrev_b32_e32 v166, 16, v194
	v_and_b32_e32 v167, 0xffff0000, v194
	v_lshlrev_b32_e32 v172, 16, v195
	v_and_b32_e32 v173, 0xffff0000, v195
	v_pk_add_f32 v[194:195], v[122:123], v[208:209]
	v_pk_add_f32 v[122:123], v[120:121], v[206:207]
	v_mul_f32_e32 v120, v125, v125
	v_mul_f32_e32 v121, v127, v127
	v_fmac_f32_e32 v120, v124, v124
	v_fmac_f32_e32 v121, v126, v126
	v_add_f32_e32 v120, v120, v121
	v_mul_f32_e32 v121, v123, v123
	v_fmac_f32_e32 v121, v122, v122
	v_add_f32_e32 v120, v121, v120
	v_mul_f32_e32 v121, v195, v195
	v_fmac_f32_e32 v121, v194, v194
	v_and_b32_e32 v213, 0xffff0000, v160
	v_lshlrev_b32_e32 v214, 16, v161
	v_and_b32_e32 v215, 0xffff0000, v161
	v_add_f32_e32 v181, v121, v120
	v_cvt_pk_bf16_f32 v120, v124, v125
	v_lshl_add_u64 v[124:125], s[90:91], 0, v[148:149]
	v_lshlrev_b32_e32 v216, 16, v162
	v_and_b32_e32 v217, 0xffff0000, v162
	v_lshlrev_b32_e32 v218, 16, v163
	v_and_b32_e32 v219, 0xffff0000, v163
	v_cvt_pk_bf16_f32 v121, v126, v127
	v_lshl_add_u64 v[124:125], v[124:125], 0, v[144:145]
	v_pk_add_f32 v[118:119], v[118:119], v[214:215]
	v_pk_add_f32 v[116:117], v[116:117], v[212:213]
	v_cvt_pk_bf16_f32 v122, v122, v123
	v_cvt_pk_bf16_f32 v123, v194, v195
	global_store_dwordx4 v[124:125], v[120:123], off
	v_lshlrev_b32_e32 v220, 16, v164
	v_and_b32_e32 v221, 0xffff0000, v164
	v_pk_add_f32 v[120:121], v[114:115], v[218:219]
	v_pk_add_f32 v[114:115], v[112:113], v[216:217]
	v_mul_f32_e32 v112, v117, v117
	v_mul_f32_e32 v113, v119, v119
	v_fmac_f32_e32 v112, v116, v116
	v_fmac_f32_e32 v113, v118, v118
	v_add_f32_e32 v112, v112, v113
	v_mul_f32_e32 v113, v115, v115
	v_fmac_f32_e32 v113, v114, v114
	v_add_f32_e32 v112, v113, v112
	v_mul_f32_e32 v113, v121, v121
	v_fmac_f32_e32 v113, v120, v120
	v_add_f32_e32 v112, v113, v112
	v_lshlrev_b32_e32 v222, 16, v165
	v_and_b32_e32 v223, 0xffff0000, v165
	v_add_f32_e32 v126, v181, v112
	v_cvt_pk_bf16_f32 v112, v116, v117
	v_cvt_pk_bf16_f32 v113, v118, v119
	v_lshl_add_u64 v[116:117], s[90:91], 0, v[170:171]
	v_lshlrev_b32_e32 v230, 16, v184
	v_and_b32_e32 v231, 0xffff0000, v184
	v_lshlrev_b32_e32 v232, 16, v186
	v_and_b32_e32 v233, 0xffff0000, v186
	v_lshlrev_b32_e32 v186, 16, v187
	v_and_b32_e32 v187, 0xffff0000, v187
	v_cvt_pk_bf16_f32 v114, v114, v115
	v_cvt_pk_bf16_f32 v115, v120, v121
	global_store_dwordx4 v[124:125], v[112:115], off offset:256
	v_pk_add_f32 v[110:111], v[110:111], v[222:223]
	v_pk_add_f32 v[108:109], v[108:109], v[220:221]
	v_lshl_add_u64 v[118:119], v[116:117], 0, v[144:145]
	v_cvt_pk_bf16_f32 v112, v108, v109
	v_cvt_pk_bf16_f32 v113, v110, v111
	v_lshlrev_b32_e32 v228, 16, v182
	v_and_b32_e32 v229, 0xffff0000, v182
	v_lshlrev_b32_e32 v182, 16, v183
	v_and_b32_e32 v183, 0xffff0000, v183
	v_lshlrev_b32_e32 v184, 16, v185
	v_and_b32_e32 v185, 0xffff0000, v185
	v_lshlrev_b32_e32 v238, 16, v192
	v_and_b32_e32 v239, 0xffff0000, v192
	v_pk_add_f32 v[106:107], v[106:107], v[226:227]
	v_pk_add_f32 v[104:105], v[104:105], v[224:225]
	v_lshlrev_b32_e32 v156, 16, v200
	v_cvt_pk_bf16_f32 v114, v104, v105
	v_cvt_pk_bf16_f32 v115, v106, v107
	global_store_dwordx4 v[118:119], v[112:115], off
	v_and_b32_e32 v157, 0xffff0000, v200
	v_pk_add_f32 v[102:103], v[102:103], v[182:183]
	v_pk_add_f32 v[112:113], v[92:93], v[230:231]
	v_pk_add_f32 v[92:93], v[98:99], v[186:187]
	v_lshl_add_u64 v[98:99], s[90:91], 0, v[154:155]
	v_pk_add_f32 v[100:101], v[100:101], v[228:229]
	v_pk_add_f32 v[94:95], v[94:95], v[184:185]
	v_cvt_pk_bf16_f32 v114, v100, v101
	v_cvt_pk_bf16_f32 v115, v102, v103
	v_cvt_pk_bf16_f32 v116, v112, v113
	v_lshlrev_b32_e32 v234, 16, v188
	v_cvt_pk_bf16_f32 v117, v94, v95
	global_store_dwordx4 v[118:119], v[114:117], off offset:256
	v_lshl_add_u64 v[118:119], v[98:99], 0, v[144:145]
	v_pk_add_f32 v[98:99], v[76:77], v[238:239]
	v_pk_add_f32 v[76:77], v[82:83], v[172:173]
	v_lshl_add_u64 v[82:83], s[90:91], 0, v[152:153]
	v_lshl_add_u64 v[122:123], v[82:83], 0, v[144:145]
	v_pk_add_f32 v[82:83], v[64:65], v[156:157]
	v_and_b32_e32 v65, 64, v174
	v_and_b32_e32 v235, 0xffff0000, v188
	v_lshlrev_b32_e32 v188, 16, v189
	v_and_b32_e32 v189, 0xffff0000, v189
	v_lshlrev_b32_e32 v236, 16, v190
	v_and_b32_e32 v237, 0xffff0000, v190
	v_pk_add_f32 v[96:97], v[96:97], v[232:233]
	v_xor_b32_e32 v64, 16, v174
	v_cvt_pk_bf16_f32 v114, v96, v97
	v_add_u32_e32 v65, 64, v65
	v_lshlrev_b32_e32 v190, 16, v191
	v_and_b32_e32 v191, 0xffff0000, v191
	v_lshlrev_b32_e32 v192, 16, v193
	v_and_b32_e32 v193, 0xffff0000, v193
	v_pk_add_f32 v[90:91], v[90:91], v[188:189]
	v_pk_add_f32 v[88:89], v[88:89], v[234:235]
	v_cvt_pk_bf16_f32 v115, v92, v93
	v_pk_add_f32 v[84:85], v[84:85], v[236:237]
	v_cvt_pk_bf16_f32 v116, v88, v89
	v_cvt_pk_bf16_f32 v117, v90, v91
	global_store_dwordx4 v[118:119], v[114:117], off
	v_cmp_lt_i32_e32 vcc, v64, v65
	v_lshlrev_b32_e32 v164, 16, v196
	v_cvt_pk_bf16_f32 v114, v84, v85
	v_and_b32_e32 v165, 0xffff0000, v196
	v_lshlrev_b32_e32 v168, 16, v197
	v_and_b32_e32 v169, 0xffff0000, v197
	v_pk_add_f32 v[86:87], v[86:87], v[190:191]
	v_pk_add_f32 v[78:79], v[78:79], v[192:193]
	v_cvt_pk_bf16_f32 v115, v86, v87
	v_cvt_pk_bf16_f32 v116, v98, v99
	v_pk_add_f32 v[80:81], v[80:81], v[166:167]
	v_cvt_pk_bf16_f32 v117, v78, v79
	global_store_dwordx4 v[118:119], v[114:117], off offset:256
	v_cndmask_b32_e32 v64, v174, v64, vcc
	v_pk_add_f32 v[74:75], v[74:75], v[168:169]
	v_cvt_pk_bf16_f32 v114, v80, v81
	v_pk_add_f32 v[72:73], v[72:73], v[164:165]
	v_cvt_pk_bf16_f32 v115, v76, v77
	v_lshlrev_b32_e32 v158, 16, v198
	v_cvt_pk_bf16_f32 v116, v72, v73
	v_cvt_pk_bf16_f32 v117, v74, v75
	global_store_dwordx4 v[122:123], v[114:117], off
	v_and_b32_e32 v159, 0xffff0000, v198
	v_lshlrev_b32_e32 v162, 16, v199
	v_lshlrev_b32_e32 v114, 2, v64
	ds_bpermute_b32 v64, v114, v126
	v_xor_b32_e32 v115, 32, v174
	v_cmp_lt_i32_e32 vcc, v115, v65
	v_and_b32_e32 v163, 0xffff0000, v199
	v_lshlrev_b32_e32 v160, 16, v201
	v_cndmask_b32_e32 v65, v174, v115, vcc
	v_lshlrev_b32_e32 v115, 2, v65
	s_waitcnt lgkmcnt(0)
	v_add_f32_e32 v116, v126, v64
	ds_bpermute_b32 v117, v115, v116
	v_and_b32_e32 v161, 0xffff0000, v201
	v_pk_add_f32 v[70:71], v[70:71], v[162:163]
	v_pk_add_f32 v[68:69], v[68:69], v[158:159]
	v_pk_add_f32 v[66:67], v[66:67], v[160:161]
	v_lshl_add_u64 v[64:65], v[150:151], 2, s[2:3]
	v_cvt_pk_bf16_f32 v118, v68, v69
	v_cvt_pk_bf16_f32 v119, v70, v71
	v_cvt_pk_bf16_f32 v120, v82, v83
	v_cvt_pk_bf16_f32 v121, v66, v67
	global_store_dwordx4 v[122:123], v[118:121], off offset:256
	s_and_saveexec_b64 s[34:35], s[6:7]
	s_cbranch_execz .LBB0_795
	s_waitcnt lgkmcnt(0)
	v_add_f32_e32 v116, v116, v117
	global_atomic_add_f32 v[64:65], v116, off

.LBB0_850:
	ds_read_b128 v[144:147], v151
	ds_read_b128 v[156:159], v151 offset:1024
	ds_read_b128 v[160:163], v151 offset:2048
	ds_read_b128 v[164:167], v151 offset:3072
	s_add_u32 s36, s34, 0xfffc0080
	s_addc_u32 s37, s35, -1
	s_cmp_eq_u32 s66, 12
	s_cselect_b32 s39, s27, s37
	s_cselect_b32 s38, s62, s36
	s_cselect_b32 s37, s25, s65
	s_cselect_b32 s36, s63, s64
	v_lshl_add_u64 v[172:173], s[34:35], 0, v[136:137]
	s_add_i32 m0, s42, 0xc000
	ds_read_b128 v[168:171], v152
	ds_read_b128 v[176:179], v152 offset:1024
	ds_read_b128 v[180:183], v152 offset:2048
	ds_read_b128 v[184:187], v152 offset:3072
	ds_read_b128 v[188:191], v152 offset:4096
	ds_read_b128 v[192:195], v152 offset:5120
	ds_read_b128 v[196:199], v152 offset:6144
	ds_read_b128 v[200:203], v152 offset:7168
	global_load_lds_dwordx4 v[172:173], off
	s_add_i32 m0, s42, 0xe000
	v_lshl_add_u64 v[172:173], s[34:35], 0, v[138:139]
	global_load_lds_dwordx4 v[172:173], off
	s_waitcnt lgkmcnt(8)
	s_setprio 1
	s_barrier
	s_waitcnt lgkmcnt(0)
	v_mfma_f32_16x16x32_bf16 v[124:127], v[144:147], v[168:171], v[124:127]
	v_mfma_f32_16x16x32_bf16 v[120:123], v[160:163], v[168:171], v[120:123]
	v_mfma_f32_16x16x32_bf16 v[116:119], v[144:147], v[180:183], v[116:119]
	v_mfma_f32_16x16x32_bf16 v[112:115], v[160:163], v[180:183], v[112:115]
	v_mfma_f32_16x16x32_bf16 v[92:95], v[144:147], v[188:191], v[92:95]
	v_mfma_f32_16x16x32_bf16 v[88:91], v[160:163], v[188:191], v[88:91]
	v_mfma_f32_16x16x32_bf16 v[76:79], v[144:147], v[196:199], v[76:79]
	v_mfma_f32_16x16x32_bf16 v[72:75], v[160:163], v[196:199], v[72:75]
	v_mfma_f32_16x16x32_bf16 v[124:127], v[156:159], v[176:179], v[124:127]
	v_mfma_f32_16x16x32_bf16 v[120:123], v[164:167], v[176:179], v[120:123]
	v_mfma_f32_16x16x32_bf16 v[116:119], v[156:159], v[184:187], v[116:119]
	v_mfma_f32_16x16x32_bf16 v[112:115], v[164:167], v[184:187], v[112:115]
	v_mfma_f32_16x16x32_bf16 v[92:95], v[156:159], v[192:195], v[92:95]
	v_mfma_f32_16x16x32_bf16 v[88:91], v[164:167], v[192:195], v[88:91]
	v_mfma_f32_16x16x32_bf16 v[76:79], v[156:159], v[200:203], v[76:79]
	v_mfma_f32_16x16x32_bf16 v[72:75], v[164:167], v[200:203], v[72:75]
	s_barrier
	s_setprio 0
	s_add_i32 s67, s55, s41
	v_lshl_add_u64 v[172:173], s[36:37], 0, v[130:131]
	s_mov_b32 m0, s67
	ds_read_b128 v[204:207], v153
	ds_read_b128 v[212:215], v153 offset:1024
	ds_read_b128 v[216:219], v153 offset:2048
	ds_read_b128 v[220:223], v153 offset:3072
	global_load_lds_dwordx4 v[172:173], off
	s_add_i32 m0, s67, 0x2000
	v_lshl_add_u64 v[208:209], s[36:37], 0, v[134:135]
	global_load_lds_dwordx4 v[208:209], off
	s_setprio 1
	s_barrier
	s_waitcnt lgkmcnt(0)
	v_mfma_f32_16x16x32_bf16 v[108:111], v[204:207], v[168:171], v[108:111]
	v_mfma_f32_16x16x32_bf16 v[104:107], v[216:219], v[168:171], v[104:107]
	v_mfma_f32_16x16x32_bf16 v[100:103], v[204:207], v[180:183], v[100:103]
	v_mfma_f32_16x16x32_bf16 v[96:99], v[216:219], v[180:183], v[96:99]
	v_mfma_f32_16x16x32_bf16 v[84:87], v[204:207], v[188:191], v[84:87]
	v_mfma_f32_16x16x32_bf16 v[80:83], v[216:219], v[188:191], v[80:83]
	v_mfma_f32_16x16x32_bf16 v[68:71], v[204:207], v[196:199], v[68:71]
	v_mfma_f32_16x16x32_bf16 v[64:67], v[216:219], v[196:199], v[64:67]
	v_mfma_f32_16x16x32_bf16 v[108:111], v[212:215], v[176:179], v[108:111]
	v_mfma_f32_16x16x32_bf16 v[104:107], v[220:223], v[176:179], v[104:107]
	v_mfma_f32_16x16x32_bf16 v[100:103], v[212:215], v[184:187], v[100:103]
	v_mfma_f32_16x16x32_bf16 v[96:99], v[220:223], v[184:187], v[96:99]
	v_mfma_f32_16x16x32_bf16 v[84:87], v[212:215], v[192:195], v[84:87]
	v_mfma_f32_16x16x32_bf16 v[80:83], v[220:223], v[192:195], v[80:83]
	v_mfma_f32_16x16x32_bf16 v[68:71], v[212:215], v[200:203], v[68:71]
	v_mfma_f32_16x16x32_bf16 v[64:67], v[220:223], v[200:203], v[64:67]
	s_barrier
	s_setprio 0
	s_mov_b32 m0, s42
	v_lshl_add_u64 v[224:225], s[38:39], 0, v[128:129]
	ds_read_b128 v[168:171], v152 offset:16384
	ds_read_b128 v[176:179], v152 offset:17408
	ds_read_b128 v[180:183], v152 offset:18432
	ds_read_b128 v[184:187], v152 offset:19456
	ds_read_b128 v[188:191], v152 offset:20480
	ds_read_b128 v[192:195], v152 offset:21504
	ds_read_b128 v[196:199], v152 offset:22528
	ds_read_b128 v[200:203], v152 offset:23552
	global_load_lds_dwordx4 v[224:225], off
	s_mov_b32 m0, s43
	v_lshl_add_u64 v[226:227], s[38:39], 0, v[132:133]
	global_load_lds_dwordx4 v[226:227], off
	s_setprio 1
	s_barrier
	s_waitcnt lgkmcnt(0)
	v_mfma_f32_16x16x32_bf16 v[60:63], v[144:147], v[168:171], v[60:63]
	v_mfma_f32_16x16x32_bf16 v[56:59], v[160:163], v[168:171], v[56:59]
	v_mfma_f32_16x16x32_bf16 v[44:47], v[144:147], v[180:183], v[44:47]
	v_mfma_f32_16x16x32_bf16 v[40:43], v[160:163], v[180:183], v[40:43]
	v_mfma_f32_16x16x32_bf16 v[28:31], v[144:147], v[188:191], v[28:31]
	v_mfma_f32_16x16x32_bf16 v[24:27], v[160:163], v[188:191], v[24:27]
	v_mfma_f32_16x16x32_bf16 v[12:15], v[144:147], v[196:199], v[12:15]
	v_mfma_f32_16x16x32_bf16 v[8:11], v[160:163], v[196:199], v[8:11]
	v_mfma_f32_16x16x32_bf16 v[60:63], v[156:159], v[176:179], v[60:63]
	v_mfma_f32_16x16x32_bf16 v[56:59], v[164:167], v[176:179], v[56:59]
	v_mfma_f32_16x16x32_bf16 v[44:47], v[156:159], v[184:187], v[44:47]
	v_mfma_f32_16x16x32_bf16 v[40:43], v[164:167], v[184:187], v[40:43]
	v_mfma_f32_16x16x32_bf16 v[28:31], v[156:159], v[192:195], v[28:31]
	v_mfma_f32_16x16x32_bf16 v[24:27], v[164:167], v[192:195], v[24:27]
	v_mfma_f32_16x16x32_bf16 v[12:15], v[156:159], v[200:203], v[12:15]
	v_mfma_f32_16x16x32_bf16 v[8:11], v[164:167], v[200:203], v[8:11]
	s_barrier
	s_setprio 0
	s_add_u32 s68, s36, 0x40000
	s_addc_u32 s69, s37, 0
	s_add_i32 s67, s56, s41
	s_mov_b32 m0, s67
	v_lshl_add_u64 v[144:145], s[68:69], 0, v[130:131]
	global_load_lds_dwordx4 v[144:145], off
	s_add_i32 m0, s67, 0x2000
	v_lshl_add_u64 v[144:145], s[68:69], 0, v[134:135]
	global_load_lds_dwordx4 v[144:145], off
	s_waitcnt vmcnt(6)
	s_setprio 1
	s_barrier
	v_mfma_f32_16x16x32_bf16 v[52:55], v[204:207], v[168:171], v[52:55]
	v_mfma_f32_16x16x32_bf16 v[48:51], v[216:219], v[168:171], v[48:51]
	v_mfma_f32_16x16x32_bf16 v[36:39], v[204:207], v[180:183], v[36:39]
	v_mfma_f32_16x16x32_bf16 v[32:35], v[216:219], v[180:183], v[32:35]
	v_mfma_f32_16x16x32_bf16 v[20:23], v[204:207], v[188:191], v[20:23]
	v_mfma_f32_16x16x32_bf16 v[16:19], v[216:219], v[188:191], v[16:19]
	v_mfma_f32_16x16x32_bf16 v[4:7], v[204:207], v[196:199], v[4:7]
	v_mfma_f32_16x16x32_bf16 v[0:3], v[216:219], v[196:199], v[0:3]
	v_mfma_f32_16x16x32_bf16 v[52:55], v[212:215], v[176:179], v[52:55]
	v_mfma_f32_16x16x32_bf16 v[48:51], v[220:223], v[176:179], v[48:51]
	v_mfma_f32_16x16x32_bf16 v[36:39], v[212:215], v[184:187], v[36:39]
	v_mfma_f32_16x16x32_bf16 v[32:35], v[220:223], v[184:187], v[32:35]
	v_mfma_f32_16x16x32_bf16 v[20:23], v[212:215], v[192:195], v[20:23]
	v_mfma_f32_16x16x32_bf16 v[16:19], v[220:223], v[192:195], v[16:19]
	v_mfma_f32_16x16x32_bf16 v[4:7], v[212:215], v[200:203], v[4:7]
	v_mfma_f32_16x16x32_bf16 v[0:3], v[220:223], v[200:203], v[0:3]
	s_barrier
	s_setprio 0
	s_add_i32 s67, 0, 0x18000
	v_add_u32_e32 v155, s67, v149
	ds_read_b128 v[144:147], v155
	ds_read_b128 v[156:159], v155 offset:1024
	ds_read_b128 v[160:163], v155 offset:2048
	ds_read_b128 v[164:167], v155 offset:3072
	s_add_u32 s38, s38, 0x40000
	s_addc_u32 s39, s39, 0
	s_mov_b32 m0, s48
	v_lshl_add_u64 v[204:205], s[38:39], 0, v[128:129]
	ds_read_b128 v[168:171], v152 offset:32768
	ds_read_b128 v[176:179], v152 offset:33792
	ds_read_b128 v[180:183], v152 offset:34816
	ds_read_b128 v[184:187], v152 offset:35840
	ds_read_b128 v[188:191], v152 offset:36864
	ds_read_b128 v[192:195], v152 offset:37888
	ds_read_b128 v[196:199], v152 offset:38912
	ds_read_b128 v[200:203], v152 offset:39936
	global_load_lds_dwordx4 v[204:205], off
	s_mov_b32 m0, s49
	v_lshl_add_u64 v[204:205], s[38:39], 0, v[132:133]
	global_load_lds_dwordx4 v[204:205], off
	s_waitcnt lgkmcnt(8)
	s_setprio 1
	s_barrier
	s_waitcnt lgkmcnt(0)
	v_mfma_f32_16x16x32_bf16 v[124:127], v[144:147], v[168:171], v[124:127]
	v_mfma_f32_16x16x32_bf16 v[120:123], v[160:163], v[168:171], v[120:123]
	v_mfma_f32_16x16x32_bf16 v[116:119], v[144:147], v[180:183], v[116:119]
	v_mfma_f32_16x16x32_bf16 v[112:115], v[160:163], v[180:183], v[112:115]
	v_mfma_f32_16x16x32_bf16 v[92:95], v[144:147], v[188:191], v[92:95]
	v_mfma_f32_16x16x32_bf16 v[88:91], v[160:163], v[188:191], v[88:91]
	v_mfma_f32_16x16x32_bf16 v[76:79], v[144:147], v[196:199], v[76:79]
	v_mfma_f32_16x16x32_bf16 v[72:75], v[160:163], v[196:199], v[72:75]
	v_mfma_f32_16x16x32_bf16 v[124:127], v[156:159], v[176:179], v[124:127]
	v_mfma_f32_16x16x32_bf16 v[120:123], v[164:167], v[176:179], v[120:123]
	v_mfma_f32_16x16x32_bf16 v[116:119], v[156:159], v[184:187], v[116:119]
	v_mfma_f32_16x16x32_bf16 v[112:115], v[164:167], v[184:187], v[112:115]
	v_mfma_f32_16x16x32_bf16 v[92:95], v[156:159], v[192:195], v[92:95]
	v_mfma_f32_16x16x32_bf16 v[88:91], v[164:167], v[192:195], v[88:91]
	v_mfma_f32_16x16x32_bf16 v[76:79], v[156:159], v[200:203], v[76:79]
	v_mfma_f32_16x16x32_bf16 v[72:75], v[164:167], v[200:203], v[72:75]
	s_barrier
	s_setprio 0
	s_add_i32 s38, 0, 0x1c000
	s_add_i32 s39, s67, s41
	v_add_u32_e32 v155, s38, v149
	v_lshl_add_u64 v[172:173], v[172:173], 0, s[8:9]
	s_mov_b32 m0, s39
	ds_read_b128 v[204:207], v155
	ds_read_b128 v[212:215], v155 offset:1024
	ds_read_b128 v[216:219], v155 offset:2048
	ds_read_b128 v[220:223], v155 offset:3072
	global_load_lds_dwordx4 v[172:173], off
	s_add_i32 m0, s39, 0x2000
	v_lshl_add_u64 v[172:173], v[208:209], 0, s[8:9]
	global_load_lds_dwordx4 v[172:173], off
	s_setprio 1
	s_barrier
	s_waitcnt lgkmcnt(0)
	v_mfma_f32_16x16x32_bf16 v[108:111], v[204:207], v[168:171], v[108:111]
	v_mfma_f32_16x16x32_bf16 v[104:107], v[216:219], v[168:171], v[104:107]
	v_mfma_f32_16x16x32_bf16 v[100:103], v[204:207], v[180:183], v[100:103]
	v_mfma_f32_16x16x32_bf16 v[96:99], v[216:219], v[180:183], v[96:99]
	v_mfma_f32_16x16x32_bf16 v[84:87], v[204:207], v[188:191], v[84:87]
	v_mfma_f32_16x16x32_bf16 v[80:83], v[216:219], v[188:191], v[80:83]
	v_mfma_f32_16x16x32_bf16 v[68:71], v[204:207], v[196:199], v[68:71]
	v_mfma_f32_16x16x32_bf16 v[64:67], v[216:219], v[196:199], v[64:67]
	v_mfma_f32_16x16x32_bf16 v[108:111], v[212:215], v[176:179], v[108:111]
	v_mfma_f32_16x16x32_bf16 v[104:107], v[220:223], v[176:179], v[104:107]
	v_mfma_f32_16x16x32_bf16 v[100:103], v[212:215], v[184:187], v[100:103]
	v_mfma_f32_16x16x32_bf16 v[96:99], v[220:223], v[184:187], v[96:99]
	v_mfma_f32_16x16x32_bf16 v[84:87], v[212:215], v[192:195], v[84:87]
	v_mfma_f32_16x16x32_bf16 v[80:83], v[220:223], v[192:195], v[80:83]
	v_mfma_f32_16x16x32_bf16 v[68:71], v[212:215], v[200:203], v[68:71]
	v_mfma_f32_16x16x32_bf16 v[64:67], v[220:223], v[200:203], v[64:67]
	s_barrier
	s_setprio 0
	s_mov_b32 m0, s51
	v_lshl_add_u64 v[172:173], v[224:225], 0, s[8:9]
	ds_read_b128 v[168:171], v152 offset:49152
	ds_read_b128 v[176:179], v152 offset:50176
	ds_read_b128 v[180:183], v152 offset:51200
	ds_read_b128 v[184:187], v152 offset:52224
	ds_read_b128 v[188:191], v152 offset:53248
	ds_read_b128 v[192:195], v152 offset:54272
	ds_read_b128 v[196:199], v152 offset:55296
	ds_read_b128 v[200:203], v152 offset:56320
	global_load_lds_dwordx4 v[172:173], off
	s_mov_b32 m0, s52
	v_lshl_add_u64 v[172:173], v[226:227], 0, s[8:9]
	global_load_lds_dwordx4 v[172:173], off
	s_setprio 1
	s_barrier
	s_waitcnt lgkmcnt(0)
	v_mfma_f32_16x16x32_bf16 v[60:63], v[144:147], v[168:171], v[60:63]
	v_mfma_f32_16x16x32_bf16 v[56:59], v[160:163], v[168:171], v[56:59]
	v_mfma_f32_16x16x32_bf16 v[44:47], v[144:147], v[180:183], v[44:47]
	v_mfma_f32_16x16x32_bf16 v[40:43], v[160:163], v[180:183], v[40:43]
	v_mfma_f32_16x16x32_bf16 v[28:31], v[144:147], v[188:191], v[28:31]
	v_mfma_f32_16x16x32_bf16 v[24:27], v[160:163], v[188:191], v[24:27]
	v_mfma_f32_16x16x32_bf16 v[12:15], v[144:147], v[196:199], v[12:15]
	v_mfma_f32_16x16x32_bf16 v[8:11], v[160:163], v[196:199], v[8:11]
	v_mfma_f32_16x16x32_bf16 v[60:63], v[156:159], v[176:179], v[60:63]
	v_mfma_f32_16x16x32_bf16 v[56:59], v[164:167], v[176:179], v[56:59]
	v_mfma_f32_16x16x32_bf16 v[44:47], v[156:159], v[184:187], v[44:47]
	v_mfma_f32_16x16x32_bf16 v[40:43], v[164:167], v[184:187], v[40:43]
	v_mfma_f32_16x16x32_bf16 v[28:31], v[156:159], v[192:195], v[28:31]
	v_mfma_f32_16x16x32_bf16 v[24:27], v[164:167], v[192:195], v[24:27]
	v_mfma_f32_16x16x32_bf16 v[12:15], v[156:159], v[200:203], v[12:15]
	v_mfma_f32_16x16x32_bf16 v[8:11], v[164:167], v[200:203], v[8:11]
	s_barrier
	s_setprio 0
	s_add_u32 s36, s36, 0x40080
	s_addc_u32 s37, s37, 0
	s_add_i32 s38, s38, s41
	s_mov_b32 m0, s38
	v_lshl_add_u64 v[144:145], s[36:37], 0, v[130:131]
	global_load_lds_dwordx4 v[144:145], off
	s_add_i32 m0, s38, 0x2000
	v_lshl_add_u64 v[144:145], s[36:37], 0, v[134:135]
	global_load_lds_dwordx4 v[144:145], off
	s_waitcnt vmcnt(6)
	s_setprio 1
	s_barrier
	v_mfma_f32_16x16x32_bf16 v[52:55], v[204:207], v[168:171], v[52:55]
	v_mfma_f32_16x16x32_bf16 v[48:51], v[216:219], v[168:171], v[48:51]
	v_mfma_f32_16x16x32_bf16 v[36:39], v[204:207], v[180:183], v[36:39]
	v_mfma_f32_16x16x32_bf16 v[32:35], v[216:219], v[180:183], v[32:35]
	v_mfma_f32_16x16x32_bf16 v[20:23], v[204:207], v[188:191], v[20:23]
	v_mfma_f32_16x16x32_bf16 v[16:19], v[216:219], v[188:191], v[16:19]
	v_mfma_f32_16x16x32_bf16 v[4:7], v[204:207], v[196:199], v[4:7]
	v_mfma_f32_16x16x32_bf16 v[0:3], v[216:219], v[196:199], v[0:3]
	v_mfma_f32_16x16x32_bf16 v[52:55], v[212:215], v[176:179], v[52:55]
	v_mfma_f32_16x16x32_bf16 v[48:51], v[220:223], v[176:179], v[48:51]
	v_mfma_f32_16x16x32_bf16 v[36:39], v[212:215], v[184:187], v[36:39]
	v_mfma_f32_16x16x32_bf16 v[32:35], v[220:223], v[184:187], v[32:35]
	v_mfma_f32_16x16x32_bf16 v[20:23], v[212:215], v[192:195], v[20:23]
	v_mfma_f32_16x16x32_bf16 v[16:19], v[220:223], v[192:195], v[16:19]
	v_mfma_f32_16x16x32_bf16 v[4:7], v[212:215], v[200:203], v[4:7]
	v_mfma_f32_16x16x32_bf16 v[0:3], v[220:223], v[200:203], v[0:3]
	s_barrier
	s_setprio 0
	s_add_i32 s66, s66, 2
	s_add_u32 s34, s34, 0x100
	s_addc_u32 s35, s35, 0
	s_add_u32 s64, s64, 0x100
	s_addc_u32 s65, s65, 0
	s_cmp_gt_u32 s66, 13
	s_cbranch_scc0 .LBB0_850
	v_lshl_add_u32 v146, s0, 8, v148
	v_ashrrev_i32_e32 v147, 31, v146
	v_lshl_add_u64 v[144:145], v[146:147], 2, s[2:3]
	global_load_dword v155, v[144:145], off
	global_load_dword v162, v[144:145], off offset:64
	global_load_dword v163, v[144:145], off offset:128
	global_load_dword v164, v[144:145], off offset:192
	global_load_dword v165, v[144:145], off offset:512
	global_load_dword v166, v[144:145], off offset:576
	global_load_dword v167, v[144:145], off offset:640
	global_load_dword v168, v[144:145], off offset:704
	v_lshl_or_b32 v144, s1, 8, v150
	v_ashrrev_i32_e32 v145, 31, v144
	v_lshlrev_b64 v[158:159], 13, v[146:147]
	v_lshlrev_b64 v[160:161], 1, v[144:145]
	v_lshl_add_u64 v[144:145], s[92:93], 0, v[158:159]
	v_lshl_add_u64 v[144:145], v[144:145], 0, v[160:161]
	v_or_b32_e32 v156, 16, v146
	v_ashrrev_i32_e32 v157, 31, v156
	v_lshlrev_b64 v[156:157], 13, v[156:157]
	v_lshl_add_u64 v[156:157], s[92:93], 0, v[156:157]
	v_lshl_add_u64 v[156:157], v[156:157], 0, v[160:161]
	s_mov_b64 s[36:37], s[30:31]
	s_mov_b64 s[34:35], s[28:29]
	s_waitcnt vmcnt(0)
	v_fmamk_f32 v147, v155, 0x3a800000, v154
	v_mul_f32_e32 v158, 0x4b800000, v147
	v_cmp_gt_f32_e32 vcc, s57, v147
	v_fmamk_f32 v155, v162, 0x3a800000, v154
	v_mul_f32_e32 v162, 0x4b800000, v155
	v_cndmask_b32_e32 v147, v147, v158, vcc
	v_rsq_f32_e32 v158, v147
	v_cmp_gt_f32_e64 s[0:1], s57, v155
	v_fmamk_f32 v159, v163, 0x3a800000, v154
	v_fmamk_f32 v163, v164, 0x3a800000, v154
	v_cndmask_b32_e64 v155, v155, v162, s[0:1]
	v_rsq_f32_e32 v155, v155
	v_mul_f32_e32 v162, 0x45800000, v158
	v_cndmask_b32_e32 v158, v158, v162, vcc
	v_pk_mul_f32 v[124:125], v[124:125], v[158:159] op_sel_hi:[1,0]
	v_pk_mul_f32 v[104:105], v[104:105], v[158:159] op_sel_hi:[1,0]
	v_fmamk_f32 v164, v165, 0x3a800000, v154
	v_fmamk_f32 v165, v166, 0x3a800000, v154
	v_fmamk_f32 v166, v167, 0x3a800000, v154
	v_mul_f32_e32 v167, 0x45800000, v155
	v_pk_mul_f32 v[126:127], v[126:127], v[158:159] op_sel_hi:[1,0]
	v_pk_mul_f32 v[122:123], v[122:123], v[158:159] op_sel_hi:[1,0]
	v_pk_mul_f32 v[120:121], v[120:121], v[158:159] op_sel_hi:[1,0]
	v_pk_mul_f32 v[108:109], v[108:109], v[158:159] op_sel_hi:[1,0]
	v_pk_mul_f32 v[106:107], v[106:107], v[158:159] op_sel_hi:[1,0]
	v_max_f32_e32 v124, 0, v124
	v_max_f32_e32 v125, 0, v125
	v_max_f32_e32 v104, 0, v104
	v_cndmask_b32_e64 v162, v155, v167, s[0:1]
	v_pk_mul_f32 v[110:111], v[110:111], v[158:159] op_sel_hi:[1,0]
	v_max_f32_e32 v120, 0, v120
	v_max_f32_e32 v121, 0, v121
	v_max_f32_e32 v126, 0, v126
	v_max_f32_e32 v122, 0, v122
	v_max_f32_e32 v127, 0, v127
	v_max_f32_e32 v123, 0, v123
	v_max_f32_e32 v108, 0, v108
	v_max_f32_e32 v109, 0, v109
	v_max_f32_e32 v105, 0, v105
	v_max_f32_e32 v106, 0, v106
	v_max_f32_e32 v107, 0, v107
	v_mul_f32_e32 v124, v124, v124
	v_mul_f32_e32 v125, v125, v125
	v_mul_f32_e32 v155, v104, v104
	v_cvt_pk_bf16_f32 v104, v124, v125
	v_fmamk_f32 v147, v168, 0x3a800000, v154
	v_pk_mul_f32 v[112:113], v[112:113], v[162:163] op_sel_hi:[1,0]
	v_max_f32_e32 v110, 0, v110
	v_max_f32_e32 v111, 0, v111
	v_mul_f32_e32 v120, v120, v120
	v_mul_f32_e32 v121, v121, v121
	v_mul_f32_e32 v126, v126, v126
	v_mul_f32_e32 v122, v122, v122
	v_mul_f32_e32 v127, v127, v127
	v_mul_f32_e32 v123, v123, v123
	v_mul_f32_e32 v108, v108, v108
	v_mul_f32_e32 v109, v109, v109
	v_mul_f32_e32 v158, v105, v105
	v_mul_f32_e32 v167, v106, v106
	v_mul_f32_e32 v168, v107, v107
	v_cvt_pk_bf16_f32 v105, v126, v127
	v_cvt_pk_bf16_f32 v106, v120, v121
	v_cvt_pk_bf16_f32 v107, v122, v123
	global_store_dwordx4 v[144:145], v[104:107], off nt
	v_pk_mul_f32 v[116:117], v[116:117], v[162:163] op_sel_hi:[1,0]
	v_mul_f32_e32 v110, v110, v110
	v_cvt_pk_bf16_f32 v104, v108, v109
	v_mul_f32_e32 v111, v111, v111
	v_cvt_pk_bf16_f32 v105, v110, v111
	v_cvt_pk_bf16_f32 v106, v155, v158
	v_cvt_pk_bf16_f32 v107, v167, v168
	global_store_dwordx4 v[144:145], v[104:107], off offset:256 nt
	v_pk_mul_f32 v[118:119], v[118:119], v[162:163] op_sel_hi:[1,0]
	v_pk_mul_f32 v[114:115], v[114:115], v[162:163] op_sel_hi:[1,0]
	v_max_f32_e32 v104, 0, v112
	v_mul_f32_e32 v106, v104, v104
	v_max_f32_e32 v104, 0, v117
	v_max_f32_e32 v116, 0, v116
	v_max_f32_e32 v107, 0, v113
	v_mul_f32_e32 v104, v104, v104
	v_pk_mul_f32 v[98:99], v[98:99], v[162:163] op_sel_hi:[1,0]
	v_pk_mul_f32 v[96:97], v[96:97], v[162:163] op_sel_hi:[1,0]
	v_mul_f32_e32 v105, v116, v116
	v_mul_f32_e32 v107, v107, v107
	v_max_f32_e32 v108, 0, v118
	v_max_f32_e32 v109, 0, v114
	v_max_f32_e32 v110, 0, v119
	v_max_f32_e32 v111, 0, v115
	v_cvt_pk_bf16_f32 v104, v105, v104
	v_pk_mul_f32 v[102:103], v[102:103], v[162:163] op_sel_hi:[1,0]
	v_pk_mul_f32 v[100:101], v[100:101], v[162:163] op_sel_hi:[1,0]
	v_max_f32_e32 v96, 0, v96
	v_max_f32_e32 v97, 0, v97
	v_max_f32_e32 v98, 0, v98
	v_mul_f32_e32 v108, v108, v108
	v_mul_f32_e32 v109, v109, v109
	v_mul_f32_e32 v110, v110, v110
	v_mul_f32_e32 v111, v111, v111
	v_cvt_pk_bf16_f32 v105, v108, v110
	v_cvt_pk_bf16_f32 v106, v106, v107
	v_cvt_pk_bf16_f32 v107, v109, v111
	global_store_dwordx4 v[156:157], v[104:107], off nt
	v_max_f32_e32 v100, 0, v100
	v_max_f32_e32 v99, 0, v99
	v_mul_f32_e32 v104, v96, v96
	v_max_f32_e32 v96, 0, v101
	v_mul_f32_e32 v101, v97, v97
	v_max_f32_e32 v97, 0, v102
	v_mul_f32_e32 v102, v98, v98
	v_max_f32_e32 v98, 0, v103
	v_mul_f32_e32 v96, v96, v96
	v_mul_f32_e32 v97, v97, v97
	v_mul_f32_e32 v98, v98, v98
	v_mul_f32_e32 v100, v100, v100
	v_mul_f32_e32 v99, v99, v99
	v_cvt_pk_bf16_f32 v96, v100, v96
	v_cvt_pk_bf16_f32 v97, v97, v98
	v_cvt_pk_bf16_f32 v98, v104, v101
	v_cvt_pk_bf16_f32 v99, v102, v99
	global_store_dwordx4 v[156:157], v[96:99], off offset:256 nt
	v_cmp_gt_f32_e32 vcc, s57, v159
	s_mov_b64 s[0:1], 0x100000
	v_mul_f32_e32 v98, 0x4b800000, v159
	v_cndmask_b32_e32 v98, v159, v98, vcc
	v_rsq_f32_e32 v98, v98
	v_or_b32_e32 v96, 32, v146
	v_ashrrev_i32_e32 v97, 31, v96
	v_lshlrev_b64 v[96:97], 13, v[96:97]
	v_mul_f32_e32 v99, 0x45800000, v98
	v_cndmask_b32_e32 v98, v98, v99, vcc
	v_pk_mul_f32 v[88:89], v[88:89], v[98:99] op_sel_hi:[1,0]
	v_pk_mul_f32 v[92:93], v[92:93], v[98:99] op_sel_hi:[1,0]
	v_pk_mul_f32 v[90:91], v[90:91], v[98:99] op_sel_hi:[1,0]
	v_max_f32_e32 v88, 0, v88
	v_pk_mul_f32 v[94:95], v[94:95], v[98:99] op_sel_hi:[1,0]
	v_mul_f32_e32 v99, v88, v88
	v_max_f32_e32 v88, 0, v93
	v_max_f32_e32 v89, 0, v89
	v_max_f32_e32 v90, 0, v90
	v_lshl_add_u64 v[96:97], s[92:93], 0, v[96:97]
	v_max_f32_e32 v92, 0, v92
	v_mul_f32_e32 v88, v88, v88
	v_mul_f32_e32 v93, v89, v89
	v_max_f32_e32 v89, 0, v94
	v_mul_f32_e32 v94, v90, v90
	v_max_f32_e32 v90, 0, v95
	v_max_f32_e32 v91, 0, v91
	v_pk_mul_f32 v[82:83], v[82:83], v[98:99] op_sel_hi:[1,0]
	v_pk_mul_f32 v[80:81], v[80:81], v[98:99] op_sel_hi:[1,0]
	v_lshl_add_u64 v[96:97], v[96:97], 0, v[160:161]
	v_mul_f32_e32 v92, v92, v92
	v_mul_f32_e32 v89, v89, v89
	v_mul_f32_e32 v90, v90, v90
	v_mul_f32_e32 v91, v91, v91
	v_cvt_pk_bf16_f32 v88, v92, v88
	v_pk_mul_f32 v[86:87], v[86:87], v[98:99] op_sel_hi:[1,0]
	v_pk_mul_f32 v[84:85], v[84:85], v[98:99] op_sel_hi:[1,0]
	v_max_f32_e32 v80, 0, v80
	v_max_f32_e32 v81, 0, v81
	v_max_f32_e32 v82, 0, v82
	v_cvt_pk_bf16_f32 v89, v89, v90
	v_cvt_pk_bf16_f32 v90, v99, v93
	v_cvt_pk_bf16_f32 v91, v94, v91
	global_store_dwordx4 v[96:97], v[88:91], off nt
	v_max_f32_e32 v84, 0, v84
	v_max_f32_e32 v83, 0, v83
	v_mul_f32_e32 v88, v80, v80
	v_max_f32_e32 v80, 0, v85
	v_mul_f32_e32 v85, v81, v81
	v_max_f32_e32 v81, 0, v86
	v_mul_f32_e32 v86, v82, v82
	v_max_f32_e32 v82, 0, v87
	v_mul_f32_e32 v80, v80, v80
	v_mul_f32_e32 v81, v81, v81
	v_mul_f32_e32 v82, v82, v82
	v_mul_f32_e32 v84, v84, v84
	v_mul_f32_e32 v83, v83, v83
	v_cvt_pk_bf16_f32 v80, v84, v80
	v_cvt_pk_bf16_f32 v81, v81, v82
	v_cvt_pk_bf16_f32 v82, v88, v85
	v_cvt_pk_bf16_f32 v83, v86, v83
	global_store_dwordx4 v[96:97], v[80:83], off offset:256 nt
	v_cmp_gt_f32_e32 vcc, s57, v163
	s_nop 0
	v_mul_f32_e32 v82, 0x4b800000, v163
	v_cndmask_b32_e32 v82, v163, v82, vcc
	v_rsq_f32_e32 v82, v82
	v_or_b32_e32 v80, 48, v146
	v_ashrrev_i32_e32 v81, 31, v80
	v_lshlrev_b64 v[80:81], 13, v[80:81]
	v_mul_f32_e32 v83, 0x45800000, v82
	v_cndmask_b32_e32 v82, v82, v83, vcc
	v_pk_mul_f32 v[72:73], v[72:73], v[82:83] op_sel_hi:[1,0]
	v_pk_mul_f32 v[76:77], v[76:77], v[82:83] op_sel_hi:[1,0]
	v_pk_mul_f32 v[74:75], v[74:75], v[82:83] op_sel_hi:[1,0]
	v_max_f32_e32 v72, 0, v72
	v_pk_mul_f32 v[78:79], v[78:79], v[82:83] op_sel_hi:[1,0]
	v_mul_f32_e32 v83, v72, v72
	v_max_f32_e32 v72, 0, v77
	v_max_f32_e32 v73, 0, v73
	v_max_f32_e32 v74, 0, v74
	v_lshl_add_u64 v[80:81], s[92:93], 0, v[80:81]
	v_max_f32_e32 v76, 0, v76
	v_mul_f32_e32 v72, v72, v72
	v_mul_f32_e32 v77, v73, v73
	v_max_f32_e32 v73, 0, v78
	v_mul_f32_e32 v78, v74, v74
	v_max_f32_e32 v74, 0, v79
	v_max_f32_e32 v75, 0, v75
	v_pk_mul_f32 v[64:65], v[64:65], v[82:83] op_sel_hi:[1,0]
	v_lshl_add_u64 v[80:81], v[80:81], 0, v[160:161]
	v_mul_f32_e32 v76, v76, v76
	v_mul_f32_e32 v73, v73, v73
	v_mul_f32_e32 v74, v74, v74
	v_mul_f32_e32 v75, v75, v75
	v_cvt_pk_bf16_f32 v72, v76, v72
	v_pk_mul_f32 v[68:69], v[68:69], v[82:83] op_sel_hi:[1,0]
	v_max_f32_e32 v64, 0, v64
	v_cvt_pk_bf16_f32 v73, v73, v74
	v_cvt_pk_bf16_f32 v74, v83, v77
	v_cvt_pk_bf16_f32 v75, v78, v75
	global_store_dwordx4 v[80:81], v[72:75], off nt
	v_max_f32_e32 v68, 0, v68
	v_mul_f32_e32 v68, v68, v68
	v_mul_f32_e32 v72, v64, v64
	v_max_f32_e32 v64, 0, v69
	v_mul_f32_e32 v64, v64, v64
	v_cvt_pk_bf16_f32 v64, v68, v64
	v_mul_f32_e32 v68, 0x4b800000, v164
	v_cmp_gt_f32_e32 vcc, s57, v164
	v_pk_mul_f32 v[66:67], v[66:67], v[82:83] op_sel_hi:[1,0]
	v_pk_mul_f32 v[70:71], v[70:71], v[82:83] op_sel_hi:[1,0]
	v_cndmask_b32_e32 v68, v164, v68, vcc
	v_max_f32_e32 v65, 0, v65
	v_max_f32_e32 v66, 0, v66
	v_rsq_f32_e32 v68, v68
	v_mul_f32_e32 v69, v65, v65
	v_max_f32_e32 v65, 0, v70
	v_mul_f32_e32 v70, v66, v66
	v_max_f32_e32 v66, 0, v71
	v_mul_f32_e32 v65, v65, v65
	v_max_f32_e32 v67, 0, v67
	v_mul_f32_e32 v66, v66, v66
	v_mul_f32_e32 v67, v67, v67
	v_cvt_pk_bf16_f32 v65, v65, v66
	v_cvt_pk_bf16_f32 v66, v72, v69
	v_cvt_pk_bf16_f32 v67, v70, v67
	global_store_dwordx4 v[80:81], v[64:67], off offset:256 nt
	s_nop 1
	v_mul_f32_e32 v66, 0x45800000, v68
	v_cndmask_b32_e32 v66, v68, v66, vcc
	v_pk_mul_f32 v[56:57], v[56:57], v[66:67] op_sel_hi:[1,0]
	v_pk_mul_f32 v[60:61], v[60:61], v[66:67] op_sel_hi:[1,0]
	v_pk_mul_f32 v[58:59], v[58:59], v[66:67] op_sel_hi:[1,0]
	v_max_f32_e32 v56, 0, v56
	v_pk_mul_f32 v[62:63], v[62:63], v[66:67] op_sel_hi:[1,0]
	v_max_f32_e32 v60, 0, v60
	v_mul_f32_e32 v67, v56, v56
	v_max_f32_e32 v56, 0, v61
	v_max_f32_e32 v57, 0, v57
	v_max_f32_e32 v58, 0, v58
	v_mul_f32_e32 v60, v60, v60
	v_mul_f32_e32 v56, v56, v56
	v_mul_f32_e32 v61, v57, v57
	v_max_f32_e32 v57, 0, v62
	v_mul_f32_e32 v62, v58, v58
	v_max_f32_e32 v58, 0, v63
	v_mul_f32_e32 v57, v57, v57
	v_max_f32_e32 v59, 0, v59
	v_mul_f32_e32 v58, v58, v58
	v_cvt_pk_bf16_f32 v56, v60, v56
	v_add_co_u32_e32 v60, vcc, s58, v144
	v_pk_mul_f32 v[48:49], v[48:49], v[66:67] op_sel_hi:[1,0]
	v_mul_f32_e32 v59, v59, v59
	v_cvt_pk_bf16_f32 v57, v57, v58
	v_cvt_pk_bf16_f32 v58, v67, v61
	v_addc_co_u32_e32 v61, vcc, 0, v145, vcc
	v_pk_mul_f32 v[52:53], v[52:53], v[66:67] op_sel_hi:[1,0]
	v_max_f32_e32 v48, 0, v48
	v_cvt_pk_bf16_f32 v59, v62, v59
	global_store_dwordx4 v[60:61], v[56:59], off nt
	v_max_f32_e32 v52, 0, v52
	v_mul_f32_e32 v52, v52, v52
	v_mul_f32_e32 v56, v48, v48
	v_max_f32_e32 v48, 0, v53
	v_mul_f32_e32 v48, v48, v48
	v_cvt_pk_bf16_f32 v48, v52, v48
	v_mul_f32_e32 v52, 0x4b800000, v165
	v_cmp_gt_f32_e32 vcc, s57, v165
	v_pk_mul_f32 v[50:51], v[50:51], v[66:67] op_sel_hi:[1,0]
	v_pk_mul_f32 v[54:55], v[54:55], v[66:67] op_sel_hi:[1,0]
	v_cndmask_b32_e32 v52, v165, v52, vcc
	v_max_f32_e32 v49, 0, v49
	v_max_f32_e32 v50, 0, v50
	v_rsq_f32_e32 v52, v52
	v_mul_f32_e32 v53, v49, v49
	v_max_f32_e32 v49, 0, v54
	v_mul_f32_e32 v54, v50, v50
	v_max_f32_e32 v50, 0, v55
	v_mul_f32_e32 v49, v49, v49
	v_max_f32_e32 v51, 0, v51
	v_mul_f32_e32 v50, v50, v50
	v_lshl_add_u64 v[64:65], v[144:145], 0, s[0:1]
	v_mul_f32_e32 v51, v51, v51
	v_cvt_pk_bf16_f32 v49, v49, v50
	v_cvt_pk_bf16_f32 v50, v56, v53
	v_cvt_pk_bf16_f32 v51, v54, v51
	global_store_dwordx4 v[64:65], v[48:51], off offset:256 nt
	s_mov_b32 s1, s24
	s_mov_b32 s0, s26
	v_mul_f32_e32 v50, 0x45800000, v52
	v_cndmask_b32_e32 v50, v52, v50, vcc
	v_pk_mul_f32 v[40:41], v[40:41], v[50:51] op_sel_hi:[1,0]
	v_pk_mul_f32 v[44:45], v[44:45], v[50:51] op_sel_hi:[1,0]
	v_pk_mul_f32 v[42:43], v[42:43], v[50:51] op_sel_hi:[1,0]
	v_max_f32_e32 v40, 0, v40
	v_pk_mul_f32 v[46:47], v[46:47], v[50:51] op_sel_hi:[1,0]
	v_max_f32_e32 v44, 0, v44
	v_mul_f32_e32 v51, v40, v40
	v_max_f32_e32 v40, 0, v45
	v_max_f32_e32 v41, 0, v41
	v_max_f32_e32 v42, 0, v42
	v_mul_f32_e32 v44, v44, v44
	v_mul_f32_e32 v40, v40, v40
	v_mul_f32_e32 v45, v41, v41
	v_max_f32_e32 v41, 0, v46
	v_mul_f32_e32 v46, v42, v42
	v_max_f32_e32 v42, 0, v47
	v_mul_f32_e32 v41, v41, v41
	v_max_f32_e32 v43, 0, v43
	v_mul_f32_e32 v42, v42, v42
	v_cvt_pk_bf16_f32 v40, v44, v40
	v_add_co_u32_e32 v44, vcc, s59, v144
	v_pk_mul_f32 v[32:33], v[32:33], v[50:51] op_sel_hi:[1,0]
	v_mul_f32_e32 v43, v43, v43
	v_cvt_pk_bf16_f32 v41, v41, v42
	v_cvt_pk_bf16_f32 v42, v51, v45
	v_addc_co_u32_e32 v45, vcc, 0, v145, vcc
	v_pk_mul_f32 v[36:37], v[36:37], v[50:51] op_sel_hi:[1,0]
	v_max_f32_e32 v32, 0, v32
	v_cvt_pk_bf16_f32 v43, v46, v43
	global_store_dwordx4 v[44:45], v[40:43], off nt
	v_max_f32_e32 v36, 0, v36
	v_mul_f32_e32 v36, v36, v36
	v_mul_f32_e32 v40, v32, v32
	v_max_f32_e32 v32, 0, v37
	v_mul_f32_e32 v32, v32, v32
	v_cvt_pk_bf16_f32 v32, v36, v32
	v_mul_f32_e32 v36, 0x4b800000, v166
	v_cmp_gt_f32_e32 vcc, s57, v166
	v_pk_mul_f32 v[34:35], v[34:35], v[50:51] op_sel_hi:[1,0]
	v_pk_mul_f32 v[38:39], v[38:39], v[50:51] op_sel_hi:[1,0]
	v_cndmask_b32_e32 v36, v166, v36, vcc
	v_max_f32_e32 v33, 0, v33
	v_max_f32_e32 v34, 0, v34
	v_rsq_f32_e32 v36, v36
	v_mul_f32_e32 v37, v33, v33
	v_max_f32_e32 v33, 0, v38
	v_mul_f32_e32 v38, v34, v34
	v_max_f32_e32 v34, 0, v39
	v_mul_f32_e32 v33, v33, v33
	v_max_f32_e32 v35, 0, v35
	v_mul_f32_e32 v34, v34, v34
	v_lshl_add_u64 v[48:49], v[144:145], 0, s[18:19]
	v_mul_f32_e32 v35, v35, v35
	v_cvt_pk_bf16_f32 v33, v33, v34
	v_cvt_pk_bf16_f32 v34, v40, v37
	v_cvt_pk_bf16_f32 v35, v38, v35
	global_store_dwordx4 v[48:49], v[32:35], off offset:256 nt
	s_nop 1
	v_mul_f32_e32 v34, 0x45800000, v36
	v_cndmask_b32_e32 v34, v36, v34, vcc
	v_pk_mul_f32 v[24:25], v[24:25], v[34:35] op_sel_hi:[1,0]
	v_pk_mul_f32 v[28:29], v[28:29], v[34:35] op_sel_hi:[1,0]
	v_pk_mul_f32 v[26:27], v[26:27], v[34:35] op_sel_hi:[1,0]
	v_max_f32_e32 v24, 0, v24
	v_pk_mul_f32 v[30:31], v[30:31], v[34:35] op_sel_hi:[1,0]
	v_max_f32_e32 v28, 0, v28
	v_mul_f32_e32 v35, v24, v24
	v_max_f32_e32 v24, 0, v29
	v_max_f32_e32 v25, 0, v25
	v_max_f32_e32 v26, 0, v26
	v_mul_f32_e32 v28, v28, v28
	v_mul_f32_e32 v24, v24, v24
	v_mul_f32_e32 v29, v25, v25
	v_max_f32_e32 v25, 0, v30
	v_mul_f32_e32 v30, v26, v26
	v_max_f32_e32 v26, 0, v31
	v_mul_f32_e32 v25, v25, v25
	v_max_f32_e32 v27, 0, v27
	v_mul_f32_e32 v26, v26, v26
	v_cvt_pk_bf16_f32 v24, v28, v24
	v_add_co_u32_e32 v28, vcc, s60, v144
	v_pk_mul_f32 v[16:17], v[16:17], v[34:35] op_sel_hi:[1,0]
	v_mul_f32_e32 v27, v27, v27
	v_cvt_pk_bf16_f32 v25, v25, v26
	v_cvt_pk_bf16_f32 v26, v35, v29
	v_addc_co_u32_e32 v29, vcc, 0, v145, vcc
	v_pk_mul_f32 v[20:21], v[20:21], v[34:35] op_sel_hi:[1,0]
	v_max_f32_e32 v16, 0, v16
	v_cvt_pk_bf16_f32 v27, v30, v27
	global_store_dwordx4 v[28:29], v[24:27], off nt
	v_max_f32_e32 v20, 0, v20
	v_mul_f32_e32 v20, v20, v20
	v_mul_f32_e32 v24, v16, v16
	v_max_f32_e32 v16, 0, v21
	v_mul_f32_e32 v16, v16, v16
	v_cvt_pk_bf16_f32 v16, v20, v16
	v_mul_f32_e32 v20, 0x4b800000, v147
	v_cmp_gt_f32_e32 vcc, s57, v147
	v_pk_mul_f32 v[18:19], v[18:19], v[34:35] op_sel_hi:[1,0]
	v_pk_mul_f32 v[22:23], v[22:23], v[34:35] op_sel_hi:[1,0]
	v_cndmask_b32_e32 v20, v147, v20, vcc
	v_max_f32_e32 v17, 0, v17
	v_max_f32_e32 v18, 0, v18
	v_rsq_f32_e32 v20, v20
	v_mul_f32_e32 v21, v17, v17
	v_max_f32_e32 v17, 0, v22
	v_mul_f32_e32 v22, v18, v18
	v_max_f32_e32 v18, 0, v23
	v_mul_f32_e32 v17, v17, v17
	v_max_f32_e32 v19, 0, v19
	v_mul_f32_e32 v18, v18, v18
	v_lshl_add_u64 v[32:33], v[144:145], 0, s[20:21]
	v_mul_f32_e32 v19, v19, v19
	v_cvt_pk_bf16_f32 v17, v17, v18
	v_cvt_pk_bf16_f32 v18, v24, v21
	v_cvt_pk_bf16_f32 v19, v22, v19
	global_store_dwordx4 v[32:33], v[16:19], off offset:256 nt
	s_nop 1
	v_mul_f32_e32 v18, 0x45800000, v20
	v_cndmask_b32_e32 v18, v20, v18, vcc
	v_pk_mul_f32 v[8:9], v[8:9], v[18:19] op_sel_hi:[1,0]
	v_pk_mul_f32 v[12:13], v[12:13], v[18:19] op_sel_hi:[1,0]
	v_pk_mul_f32 v[10:11], v[10:11], v[18:19] op_sel_hi:[1,0]
	v_max_f32_e32 v8, 0, v8
	v_pk_mul_f32 v[14:15], v[14:15], v[18:19] op_sel_hi:[1,0]
	v_max_f32_e32 v12, 0, v12
	v_mul_f32_e32 v19, v8, v8
	v_max_f32_e32 v8, 0, v13
	v_max_f32_e32 v9, 0, v9
	v_max_f32_e32 v10, 0, v10
	v_mul_f32_e32 v12, v12, v12
	v_mul_f32_e32 v8, v8, v8
	v_mul_f32_e32 v13, v9, v9
	v_max_f32_e32 v9, 0, v14
	v_mul_f32_e32 v14, v10, v10
	v_max_f32_e32 v10, 0, v15
	v_mul_f32_e32 v9, v9, v9
	v_max_f32_e32 v11, 0, v11
	v_mul_f32_e32 v10, v10, v10
	v_cvt_pk_bf16_f32 v8, v12, v8
	v_add_co_u32_e32 v12, vcc, s61, v144
	v_pk_mul_f32 v[2:3], v[2:3], v[18:19] op_sel_hi:[1,0]
	v_pk_mul_f32 v[0:1], v[0:1], v[18:19] op_sel_hi:[1,0]
	v_mul_f32_e32 v11, v11, v11
	v_cvt_pk_bf16_f32 v9, v9, v10
	v_cvt_pk_bf16_f32 v10, v19, v13
	v_addc_co_u32_e32 v13, vcc, 0, v145, vcc
	v_pk_mul_f32 v[6:7], v[6:7], v[18:19] op_sel_hi:[1,0]
	v_pk_mul_f32 v[4:5], v[4:5], v[18:19] op_sel_hi:[1,0]
	v_max_f32_e32 v0, 0, v0
	v_max_f32_e32 v1, 0, v1
	v_max_f32_e32 v2, 0, v2
	v_cvt_pk_bf16_f32 v11, v14, v11
	global_store_dwordx4 v[12:13], v[8:11], off nt
	v_max_f32_e32 v3, 0, v3
	v_lshl_add_u64 v[16:17], v[144:145], 0, s[22:23]
	v_mul_f32_e32 v8, v0, v0
	v_max_f32_e32 v0, 0, v5
	v_mul_f32_e32 v5, v1, v1
	v_max_f32_e32 v1, 0, v6
	v_mul_f32_e32 v6, v2, v2
	v_max_f32_e32 v2, 0, v7
	v_max_f32_e32 v4, 0, v4
	v_mul_f32_e32 v0, v0, v0
	v_mul_f32_e32 v1, v1, v1
	v_mul_f32_e32 v2, v2, v2
	v_mul_f32_e32 v3, v3, v3
	s_and_b64 vcc, exec, s[6:7]
	v_mul_f32_e32 v4, v4, v4
	v_cvt_pk_bf16_f32 v0, v4, v0
	v_cvt_pk_bf16_f32 v1, v1, v2
	v_cvt_pk_bf16_f32 v2, v8, v5
	v_cvt_pk_bf16_f32 v3, v6, v3
	global_store_dwordx4 v[16:17], v[0:3], off offset:256 nt
	s_cbranch_vccz .LBB0_843
	s_waitcnt vmcnt(0)
	s_cmpk_gt_u32 s33, 0xff
	s_cbranch_scc1 .LBB0_854
	s_barrier

.LBB0_896:
	ds_read_b128 v[144:147], v178
	ds_read_b128 v[148:151], v178 offset:1024
	ds_read_b128 v[152:155], v178 offset:2048
	ds_read_b128 v[156:159], v178 offset:3072
	s_add_u32 s42, s40, 0xfff00080
	s_addc_u32 s43, s41, -1
	s_cmp_eq_u32 s65, 60
	s_cselect_b32 s49, s29, s43
	s_cselect_b32 s48, s37, s42
	s_cselect_b32 s43, s27, s64
	s_cselect_b32 s42, s62, s63
	v_lshl_add_u64 v[172:173], s[40:41], 0, v[136:137]
	s_add_i32 m0, s39, 0xc000
	ds_read_b128 v[160:163], v179
	ds_read_b128 v[164:167], v179 offset:1024
	ds_read_b128 v[168:171], v179 offset:2048
	ds_read_b128 v[182:185], v179 offset:3072
	ds_read_b128 v[186:189], v179 offset:4096
	ds_read_b128 v[190:193], v179 offset:5120
	ds_read_b128 v[194:197], v179 offset:6144
	ds_read_b128 v[198:201], v179 offset:7168
	global_load_lds_dwordx4 v[172:173], off
	s_add_i32 m0, s39, 0xe000
	v_lshl_add_u64 v[172:173], s[40:41], 0, v[138:139]
	global_load_lds_dwordx4 v[172:173], off
	s_waitcnt lgkmcnt(8)
	s_setprio 1
	s_barrier
	s_waitcnt lgkmcnt(0)
	v_mfma_f32_16x16x32_bf16 v[124:127], v[144:147], v[160:163], v[124:127]
	v_mfma_f32_16x16x32_bf16 v[120:123], v[152:155], v[160:163], v[120:123]
	v_mfma_f32_16x16x32_bf16 v[108:111], v[144:147], v[168:171], v[108:111]
	v_mfma_f32_16x16x32_bf16 v[104:107], v[152:155], v[168:171], v[104:107]
	v_mfma_f32_16x16x32_bf16 v[96:99], v[144:147], v[186:189], v[96:99]
	v_mfma_f32_16x16x32_bf16 v[88:91], v[152:155], v[186:189], v[88:91]
	v_mfma_f32_16x16x32_bf16 v[80:83], v[144:147], v[194:197], v[80:83]
	v_mfma_f32_16x16x32_bf16 v[72:75], v[152:155], v[194:197], v[72:75]
	v_mfma_f32_16x16x32_bf16 v[124:127], v[148:151], v[164:167], v[124:127]
	v_mfma_f32_16x16x32_bf16 v[120:123], v[156:159], v[164:167], v[120:123]
	v_mfma_f32_16x16x32_bf16 v[108:111], v[148:151], v[182:185], v[108:111]
	v_mfma_f32_16x16x32_bf16 v[104:107], v[156:159], v[182:185], v[104:107]
	v_mfma_f32_16x16x32_bf16 v[96:99], v[148:151], v[190:193], v[96:99]
	v_mfma_f32_16x16x32_bf16 v[88:91], v[156:159], v[190:193], v[88:91]
	v_mfma_f32_16x16x32_bf16 v[80:83], v[148:151], v[198:201], v[80:83]
	v_mfma_f32_16x16x32_bf16 v[72:75], v[156:159], v[198:201], v[72:75]
	s_barrier
	s_setprio 0
	s_add_i32 s66, s60, s50
	v_lshl_add_u64 v[172:173], s[42:43], 0, v[130:131]
	s_mov_b32 m0, s66
	ds_read_b128 v[202:205], v180
	ds_read_b128 v[206:209], v180 offset:1024
	ds_read_b128 v[212:215], v180 offset:2048
	ds_read_b128 v[216:219], v180 offset:3072
	global_load_lds_dwordx4 v[172:173], off
	s_add_i32 m0, s66, 0x2000
	v_lshl_add_u64 v[220:221], s[42:43], 0, v[134:135]
	global_load_lds_dwordx4 v[220:221], off
	s_setprio 1
	s_barrier
	s_waitcnt lgkmcnt(0)
	v_mfma_f32_16x16x32_bf16 v[116:119], v[202:205], v[160:163], v[116:119]
	v_mfma_f32_16x16x32_bf16 v[112:115], v[212:215], v[160:163], v[112:115]
	v_mfma_f32_16x16x32_bf16 v[100:103], v[202:205], v[168:171], v[100:103]
	v_mfma_f32_16x16x32_bf16 v[92:95], v[212:215], v[168:171], v[92:95]
	v_mfma_f32_16x16x32_bf16 v[84:87], v[202:205], v[186:189], v[84:87]
	v_mfma_f32_16x16x32_bf16 v[76:79], v[212:215], v[186:189], v[76:79]
	v_mfma_f32_16x16x32_bf16 v[68:71], v[202:205], v[194:197], v[68:71]
	v_mfma_f32_16x16x32_bf16 v[64:67], v[212:215], v[194:197], v[64:67]
	v_mfma_f32_16x16x32_bf16 v[116:119], v[206:209], v[164:167], v[116:119]
	v_mfma_f32_16x16x32_bf16 v[112:115], v[216:219], v[164:167], v[112:115]
	v_mfma_f32_16x16x32_bf16 v[100:103], v[206:209], v[182:185], v[100:103]
	v_mfma_f32_16x16x32_bf16 v[92:95], v[216:219], v[182:185], v[92:95]
	v_mfma_f32_16x16x32_bf16 v[84:87], v[206:209], v[190:193], v[84:87]
	v_mfma_f32_16x16x32_bf16 v[76:79], v[216:219], v[190:193], v[76:79]
	v_mfma_f32_16x16x32_bf16 v[68:71], v[206:209], v[198:201], v[68:71]
	v_mfma_f32_16x16x32_bf16 v[64:67], v[216:219], v[198:201], v[64:67]
	s_barrier
	s_setprio 0
	s_mov_b32 m0, s39
	v_lshl_add_u64 v[222:223], s[48:49], 0, v[128:129]
	ds_read_b128 v[160:163], v179 offset:16384
	ds_read_b128 v[164:167], v179 offset:17408
	ds_read_b128 v[168:171], v179 offset:18432
	ds_read_b128 v[182:185], v179 offset:19456
	ds_read_b128 v[186:189], v179 offset:20480
	ds_read_b128 v[190:193], v179 offset:21504
	ds_read_b128 v[194:197], v179 offset:22528
	ds_read_b128 v[198:201], v179 offset:23552
	global_load_lds_dwordx4 v[222:223], off
	s_mov_b32 m0, s51
	v_lshl_add_u64 v[224:225], s[48:49], 0, v[132:133]
	global_load_lds_dwordx4 v[224:225], off
	s_setprio 1
	s_barrier
	s_waitcnt lgkmcnt(0)
	v_mfma_f32_16x16x32_bf16 v[60:63], v[144:147], v[160:163], v[60:63]
	v_mfma_f32_16x16x32_bf16 v[56:59], v[152:155], v[160:163], v[56:59]
	v_mfma_f32_16x16x32_bf16 v[44:47], v[144:147], v[168:171], v[44:47]
	v_mfma_f32_16x16x32_bf16 v[40:43], v[152:155], v[168:171], v[40:43]
	v_mfma_f32_16x16x32_bf16 v[32:35], v[144:147], v[186:189], v[32:35]
	v_mfma_f32_16x16x32_bf16 v[24:27], v[152:155], v[186:189], v[24:27]
	v_mfma_f32_16x16x32_bf16 v[16:19], v[144:147], v[194:197], v[16:19]
	v_mfma_f32_16x16x32_bf16 v[8:11], v[152:155], v[194:197], v[8:11]
	v_mfma_f32_16x16x32_bf16 v[60:63], v[148:151], v[164:167], v[60:63]
	v_mfma_f32_16x16x32_bf16 v[56:59], v[156:159], v[164:167], v[56:59]
	v_mfma_f32_16x16x32_bf16 v[44:47], v[148:151], v[182:185], v[44:47]
	v_mfma_f32_16x16x32_bf16 v[40:43], v[156:159], v[182:185], v[40:43]
	v_mfma_f32_16x16x32_bf16 v[32:35], v[148:151], v[190:193], v[32:35]
	v_mfma_f32_16x16x32_bf16 v[24:27], v[156:159], v[190:193], v[24:27]
	v_mfma_f32_16x16x32_bf16 v[16:19], v[148:151], v[198:201], v[16:19]
	v_mfma_f32_16x16x32_bf16 v[8:11], v[156:159], v[198:201], v[8:11]
	s_barrier
	s_setprio 0
	s_add_u32 s66, s42, 0x100000
	s_addc_u32 s67, s43, 0
	s_add_i32 s68, s61, s50
	s_mov_b32 m0, s68
	v_lshl_add_u64 v[144:145], s[66:67], 0, v[130:131]
	global_load_lds_dwordx4 v[144:145], off
	s_add_i32 m0, s68, 0x2000
	v_lshl_add_u64 v[144:145], s[66:67], 0, v[134:135]
	global_load_lds_dwordx4 v[144:145], off
	s_waitcnt vmcnt(6)
	s_setprio 1
	s_barrier
	v_mfma_f32_16x16x32_bf16 v[52:55], v[202:205], v[160:163], v[52:55]
	v_mfma_f32_16x16x32_bf16 v[48:51], v[212:215], v[160:163], v[48:51]
	v_mfma_f32_16x16x32_bf16 v[36:39], v[202:205], v[168:171], v[36:39]
	v_mfma_f32_16x16x32_bf16 v[28:31], v[212:215], v[168:171], v[28:31]
	v_mfma_f32_16x16x32_bf16 v[20:23], v[202:205], v[186:189], v[20:23]
	v_mfma_f32_16x16x32_bf16 v[12:15], v[212:215], v[186:189], v[12:15]
	v_mfma_f32_16x16x32_bf16 v[4:7], v[202:205], v[194:197], v[4:7]
	v_mfma_f32_16x16x32_bf16 v[0:3], v[212:215], v[194:197], v[0:3]
	v_mfma_f32_16x16x32_bf16 v[52:55], v[206:209], v[164:167], v[52:55]
	v_mfma_f32_16x16x32_bf16 v[48:51], v[216:219], v[164:167], v[48:51]
	v_mfma_f32_16x16x32_bf16 v[36:39], v[206:209], v[182:185], v[36:39]
	v_mfma_f32_16x16x32_bf16 v[28:31], v[216:219], v[182:185], v[28:31]
	v_mfma_f32_16x16x32_bf16 v[20:23], v[206:209], v[190:193], v[20:23]
	v_mfma_f32_16x16x32_bf16 v[12:15], v[216:219], v[190:193], v[12:15]
	v_mfma_f32_16x16x32_bf16 v[4:7], v[206:209], v[198:201], v[4:7]
	v_mfma_f32_16x16x32_bf16 v[0:3], v[216:219], v[198:201], v[0:3]
	s_barrier
	s_setprio 0
	s_add_i32 s66, 0, 0x18000
	v_add_u32_e32 v156, s66, v176
	ds_read_b128 v[144:147], v156
	ds_read_b128 v[148:151], v156 offset:1024
	ds_read_b128 v[152:155], v156 offset:2048
	ds_read_b128 v[156:159], v156 offset:3072
	s_add_u32 s48, s48, 0x100000
	s_addc_u32 s49, s49, 0
	s_mov_b32 m0, s52
	v_lshl_add_u64 v[202:203], s[48:49], 0, v[128:129]
	ds_read_b128 v[160:163], v179 offset:32768
	ds_read_b128 v[164:167], v179 offset:33792
	ds_read_b128 v[168:171], v179 offset:34816
	ds_read_b128 v[182:185], v179 offset:35840
	ds_read_b128 v[186:189], v179 offset:36864
	ds_read_b128 v[190:193], v179 offset:37888
	ds_read_b128 v[194:197], v179 offset:38912
	ds_read_b128 v[198:201], v179 offset:39936
	global_load_lds_dwordx4 v[202:203], off
	s_mov_b32 m0, s53
	v_lshl_add_u64 v[202:203], s[48:49], 0, v[132:133]
	global_load_lds_dwordx4 v[202:203], off
	s_waitcnt lgkmcnt(8)
	s_setprio 1
	s_barrier
	s_waitcnt lgkmcnt(0)
	v_mfma_f32_16x16x32_bf16 v[124:127], v[144:147], v[160:163], v[124:127]
	v_mfma_f32_16x16x32_bf16 v[120:123], v[152:155], v[160:163], v[120:123]
	v_mfma_f32_16x16x32_bf16 v[108:111], v[144:147], v[168:171], v[108:111]
	v_mfma_f32_16x16x32_bf16 v[104:107], v[152:155], v[168:171], v[104:107]
	v_mfma_f32_16x16x32_bf16 v[96:99], v[144:147], v[186:189], v[96:99]
	v_mfma_f32_16x16x32_bf16 v[88:91], v[152:155], v[186:189], v[88:91]
	v_mfma_f32_16x16x32_bf16 v[80:83], v[144:147], v[194:197], v[80:83]
	v_mfma_f32_16x16x32_bf16 v[72:75], v[152:155], v[194:197], v[72:75]
	v_mfma_f32_16x16x32_bf16 v[124:127], v[148:151], v[164:167], v[124:127]
	v_mfma_f32_16x16x32_bf16 v[120:123], v[156:159], v[164:167], v[120:123]
	v_mfma_f32_16x16x32_bf16 v[108:111], v[148:151], v[182:185], v[108:111]
	v_mfma_f32_16x16x32_bf16 v[104:107], v[156:159], v[182:185], v[104:107]
	v_mfma_f32_16x16x32_bf16 v[96:99], v[148:151], v[190:193], v[96:99]
	v_mfma_f32_16x16x32_bf16 v[88:91], v[156:159], v[190:193], v[88:91]
	v_mfma_f32_16x16x32_bf16 v[80:83], v[148:151], v[198:201], v[80:83]
	v_mfma_f32_16x16x32_bf16 v[72:75], v[156:159], v[198:201], v[72:75]
	s_barrier
	s_setprio 0
	s_add_i32 s48, 0, 0x1c000
	s_add_i32 s49, s66, s50
	v_add_u32_e32 v181, s48, v176
	v_lshl_add_u64 v[172:173], v[172:173], 0, s[0:1]
	s_mov_b32 m0, s49
	ds_read_b128 v[202:205], v181
	ds_read_b128 v[206:209], v181 offset:1024
	ds_read_b128 v[212:215], v181 offset:2048
	ds_read_b128 v[216:219], v181 offset:3072
	global_load_lds_dwordx4 v[172:173], off
	s_add_i32 m0, s49, 0x2000
	v_lshl_add_u64 v[172:173], v[220:221], 0, s[0:1]
	global_load_lds_dwordx4 v[172:173], off
	s_setprio 1
	s_barrier
	s_waitcnt lgkmcnt(0)
	v_mfma_f32_16x16x32_bf16 v[116:119], v[202:205], v[160:163], v[116:119]
	v_mfma_f32_16x16x32_bf16 v[112:115], v[212:215], v[160:163], v[112:115]
	v_mfma_f32_16x16x32_bf16 v[100:103], v[202:205], v[168:171], v[100:103]
	v_mfma_f32_16x16x32_bf16 v[92:95], v[212:215], v[168:171], v[92:95]
	v_mfma_f32_16x16x32_bf16 v[84:87], v[202:205], v[186:189], v[84:87]
	v_mfma_f32_16x16x32_bf16 v[76:79], v[212:215], v[186:189], v[76:79]
	v_mfma_f32_16x16x32_bf16 v[68:71], v[202:205], v[194:197], v[68:71]
	v_mfma_f32_16x16x32_bf16 v[64:67], v[212:215], v[194:197], v[64:67]
	v_mfma_f32_16x16x32_bf16 v[116:119], v[206:209], v[164:167], v[116:119]
	v_mfma_f32_16x16x32_bf16 v[112:115], v[216:219], v[164:167], v[112:115]
	v_mfma_f32_16x16x32_bf16 v[100:103], v[206:209], v[182:185], v[100:103]
	v_mfma_f32_16x16x32_bf16 v[92:95], v[216:219], v[182:185], v[92:95]
	v_mfma_f32_16x16x32_bf16 v[84:87], v[206:209], v[190:193], v[84:87]
	v_mfma_f32_16x16x32_bf16 v[76:79], v[216:219], v[190:193], v[76:79]
	v_mfma_f32_16x16x32_bf16 v[68:71], v[206:209], v[198:201], v[68:71]
	v_mfma_f32_16x16x32_bf16 v[64:67], v[216:219], v[198:201], v[64:67]
	s_barrier
	s_setprio 0
	s_mov_b32 m0, s55
	v_lshl_add_u64 v[172:173], v[222:223], 0, s[0:1]
	ds_read_b128 v[160:163], v179 offset:49152
	ds_read_b128 v[164:167], v179 offset:50176
	ds_read_b128 v[168:171], v179 offset:51200
	ds_read_b128 v[182:185], v179 offset:52224
	ds_read_b128 v[186:189], v179 offset:53248
	ds_read_b128 v[190:193], v179 offset:54272
	ds_read_b128 v[194:197], v179 offset:55296
	ds_read_b128 v[198:201], v179 offset:56320
	global_load_lds_dwordx4 v[172:173], off
	s_mov_b32 m0, s56
	v_lshl_add_u64 v[172:173], v[224:225], 0, s[0:1]
	global_load_lds_dwordx4 v[172:173], off
	s_setprio 1
	s_barrier
	s_waitcnt lgkmcnt(0)
	v_mfma_f32_16x16x32_bf16 v[60:63], v[144:147], v[160:163], v[60:63]
	v_mfma_f32_16x16x32_bf16 v[56:59], v[152:155], v[160:163], v[56:59]
	v_mfma_f32_16x16x32_bf16 v[44:47], v[144:147], v[168:171], v[44:47]
	v_mfma_f32_16x16x32_bf16 v[40:43], v[152:155], v[168:171], v[40:43]
	v_mfma_f32_16x16x32_bf16 v[32:35], v[144:147], v[186:189], v[32:35]
	v_mfma_f32_16x16x32_bf16 v[24:27], v[152:155], v[186:189], v[24:27]
	v_mfma_f32_16x16x32_bf16 v[16:19], v[144:147], v[194:197], v[16:19]
	v_mfma_f32_16x16x32_bf16 v[8:11], v[152:155], v[194:197], v[8:11]
	v_mfma_f32_16x16x32_bf16 v[60:63], v[148:151], v[164:167], v[60:63]
	v_mfma_f32_16x16x32_bf16 v[56:59], v[156:159], v[164:167], v[56:59]
	v_mfma_f32_16x16x32_bf16 v[44:47], v[148:151], v[182:185], v[44:47]
	v_mfma_f32_16x16x32_bf16 v[40:43], v[156:159], v[182:185], v[40:43]
	v_mfma_f32_16x16x32_bf16 v[32:35], v[148:151], v[190:193], v[32:35]
	v_mfma_f32_16x16x32_bf16 v[24:27], v[156:159], v[190:193], v[24:27]
	v_mfma_f32_16x16x32_bf16 v[16:19], v[148:151], v[198:201], v[16:19]
	v_mfma_f32_16x16x32_bf16 v[8:11], v[156:159], v[198:201], v[8:11]
	s_barrier
	s_setprio 0
	s_add_u32 s42, s42, 0x100080
	s_addc_u32 s43, s43, 0
	s_add_i32 s48, s48, s50
	s_mov_b32 m0, s48
	v_lshl_add_u64 v[144:145], s[42:43], 0, v[130:131]
	global_load_lds_dwordx4 v[144:145], off
	s_add_i32 m0, s48, 0x2000
	v_lshl_add_u64 v[144:145], s[42:43], 0, v[134:135]
	global_load_lds_dwordx4 v[144:145], off
	s_waitcnt vmcnt(6)
	s_setprio 1
	s_barrier
	v_mfma_f32_16x16x32_bf16 v[52:55], v[202:205], v[160:163], v[52:55]
	v_mfma_f32_16x16x32_bf16 v[48:51], v[212:215], v[160:163], v[48:51]
	v_mfma_f32_16x16x32_bf16 v[36:39], v[202:205], v[168:171], v[36:39]
	v_mfma_f32_16x16x32_bf16 v[28:31], v[212:215], v[168:171], v[28:31]
	v_mfma_f32_16x16x32_bf16 v[20:23], v[202:205], v[186:189], v[20:23]
	v_mfma_f32_16x16x32_bf16 v[12:15], v[212:215], v[186:189], v[12:15]
	v_mfma_f32_16x16x32_bf16 v[4:7], v[202:205], v[194:197], v[4:7]
	v_mfma_f32_16x16x32_bf16 v[0:3], v[212:215], v[194:197], v[0:3]
	v_mfma_f32_16x16x32_bf16 v[52:55], v[206:209], v[164:167], v[52:55]
	v_mfma_f32_16x16x32_bf16 v[48:51], v[216:219], v[164:167], v[48:51]
	v_mfma_f32_16x16x32_bf16 v[36:39], v[206:209], v[182:185], v[36:39]
	v_mfma_f32_16x16x32_bf16 v[28:31], v[216:219], v[182:185], v[28:31]
	v_mfma_f32_16x16x32_bf16 v[20:23], v[206:209], v[190:193], v[20:23]
	v_mfma_f32_16x16x32_bf16 v[12:15], v[216:219], v[190:193], v[12:15]
	v_mfma_f32_16x16x32_bf16 v[4:7], v[206:209], v[198:201], v[4:7]
	v_mfma_f32_16x16x32_bf16 v[0:3], v[216:219], v[198:201], v[0:3]
	s_barrier
	s_setprio 0
	s_add_i32 s65, s65, 2
	s_add_u32 s40, s40, 0x100
	s_addc_u32 s41, s41, 0
	s_add_u32 s63, s63, 0x100
	s_addc_u32 s64, s64, 0
	s_cmp_gt_u32 s65, 61
	s_cbranch_scc0 .LBB0_896
	v_lshl_or_b32 v144, s38, 8, v177
	v_lshl_add_u32 v150, s36, 8, v175
	v_ashrrev_i32_e32 v145, 31, v144
	v_ashrrev_i32_e32 v151, 31, v150
	v_lshlrev_b64 v[144:145], 1, v[144:145]
	v_lshl_add_u64 v[146:147], s[90:91], 0, v[144:145]
	v_lshlrev_b64 v[148:149], 11, v[150:151]
	v_lshl_add_u64 v[152:153], v[146:147], 0, v[148:149]
	global_load_dwordx4 v[156:159], v[152:153], off
	global_load_dwordx4 v[160:163], v[152:153], off offset:256
	v_or_b32_e32 v152, 16, v150
	v_ashrrev_i32_e32 v153, 31, v152
	v_lshlrev_b64 v[170:171], 11, v[152:153]
	v_lshl_add_u64 v[152:153], v[146:147], 0, v[170:171]
	global_load_dwordx4 v[164:167], v[152:153], off
	global_load_dwordx4 v[182:185], v[152:153], off offset:256
	v_or_b32_e32 v152, 32, v150
	v_ashrrev_i32_e32 v153, 31, v152
	v_lshlrev_b64 v[154:155], 11, v[152:153]
	v_lshl_add_u64 v[152:153], v[146:147], 0, v[154:155]
	global_load_dwordx4 v[186:189], v[152:153], off
	global_load_dwordx4 v[190:193], v[152:153], off offset:256
	v_or_b32_e32 v152, 48, v150
	v_ashrrev_i32_e32 v153, 31, v152
	v_lshlrev_b64 v[152:153], 11, v[152:153]
	v_lshl_add_u64 v[168:169], v[146:147], 0, v[152:153]
	global_load_dwordx4 v[194:197], v[168:169], off
	global_load_dwordx4 v[198:201], v[168:169], off offset:256
	s_waitcnt vmcnt(0)
	v_lshlrev_b32_e32 v202, 16, v156
	v_and_b32_e32 v203, 0xffff0000, v156
	v_lshlrev_b32_e32 v204, 16, v157
	v_and_b32_e32 v205, 0xffff0000, v157
	v_lshlrev_b32_e32 v206, 16, v158
	v_and_b32_e32 v207, 0xffff0000, v158
	v_lshlrev_b32_e32 v208, 16, v159
	v_and_b32_e32 v209, 0xffff0000, v159
	v_pk_add_f32 v[126:127], v[126:127], v[204:205]
	v_pk_add_f32 v[124:125], v[124:125], v[202:203]
	v_lshlrev_b32_e32 v224, 16, v166
	v_and_b32_e32 v225, 0xffff0000, v166
	v_lshlrev_b32_e32 v226, 16, v167
	v_and_b32_e32 v227, 0xffff0000, v167
	v_lshlrev_b32_e32 v212, 16, v160
	v_lshlrev_b32_e32 v166, 16, v194
	v_and_b32_e32 v167, 0xffff0000, v194
	v_lshlrev_b32_e32 v172, 16, v195
	v_and_b32_e32 v173, 0xffff0000, v195
	v_pk_add_f32 v[194:195], v[122:123], v[208:209]
	v_pk_add_f32 v[122:123], v[120:121], v[206:207]
	v_mul_f32_e32 v120, v125, v125
	v_mul_f32_e32 v121, v127, v127
	v_fmac_f32_e32 v120, v124, v124
	v_fmac_f32_e32 v121, v126, v126
	v_add_f32_e32 v120, v120, v121
	v_mul_f32_e32 v121, v123, v123
	v_fmac_f32_e32 v121, v122, v122
	v_add_f32_e32 v120, v121, v120
	v_mul_f32_e32 v121, v195, v195
	v_fmac_f32_e32 v121, v194, v194
	v_and_b32_e32 v213, 0xffff0000, v160
	v_lshlrev_b32_e32 v214, 16, v161
	v_and_b32_e32 v215, 0xffff0000, v161
	v_add_f32_e32 v181, v121, v120
	v_cvt_pk_bf16_f32 v120, v124, v125
	v_lshl_add_u64 v[124:125], s[10:11], 0, v[148:149]
	v_lshlrev_b32_e32 v216, 16, v162
	v_and_b32_e32 v217, 0xffff0000, v162
	v_lshlrev_b32_e32 v218, 16, v163
	v_and_b32_e32 v219, 0xffff0000, v163
	v_cvt_pk_bf16_f32 v121, v126, v127
	v_lshl_add_u64 v[124:125], v[124:125], 0, v[144:145]
	v_pk_add_f32 v[118:119], v[118:119], v[214:215]
	v_pk_add_f32 v[116:117], v[116:117], v[212:213]
	v_cvt_pk_bf16_f32 v122, v122, v123
	v_cvt_pk_bf16_f32 v123, v194, v195
	global_store_dwordx4 v[124:125], v[120:123], off
	v_lshlrev_b32_e32 v220, 16, v164
	v_and_b32_e32 v221, 0xffff0000, v164
	v_pk_add_f32 v[120:121], v[114:115], v[218:219]
	v_pk_add_f32 v[114:115], v[112:113], v[216:217]
	v_mul_f32_e32 v112, v117, v117
	v_mul_f32_e32 v113, v119, v119
	v_fmac_f32_e32 v112, v116, v116
	v_fmac_f32_e32 v113, v118, v118
	v_add_f32_e32 v112, v112, v113
	v_mul_f32_e32 v113, v115, v115
	v_fmac_f32_e32 v113, v114, v114
	v_add_f32_e32 v112, v113, v112
	v_mul_f32_e32 v113, v121, v121
	v_fmac_f32_e32 v113, v120, v120
	v_add_f32_e32 v112, v113, v112
	v_lshlrev_b32_e32 v222, 16, v165
	v_and_b32_e32 v223, 0xffff0000, v165
	v_add_f32_e32 v126, v181, v112
	v_cvt_pk_bf16_f32 v112, v116, v117
	v_cvt_pk_bf16_f32 v113, v118, v119
	v_lshl_add_u64 v[116:117], s[10:11], 0, v[170:171]
	v_lshlrev_b32_e32 v230, 16, v184
	v_and_b32_e32 v231, 0xffff0000, v184
	v_lshlrev_b32_e32 v232, 16, v186
	v_and_b32_e32 v233, 0xffff0000, v186
	v_lshlrev_b32_e32 v186, 16, v187
	v_and_b32_e32 v187, 0xffff0000, v187
	v_cvt_pk_bf16_f32 v114, v114, v115
	v_cvt_pk_bf16_f32 v115, v120, v121
	global_store_dwordx4 v[124:125], v[112:115], off offset:256
	v_pk_add_f32 v[110:111], v[110:111], v[222:223]
	v_pk_add_f32 v[108:109], v[108:109], v[220:221]
	v_lshl_add_u64 v[118:119], v[116:117], 0, v[144:145]
	v_cvt_pk_bf16_f32 v112, v108, v109
	v_cvt_pk_bf16_f32 v113, v110, v111
	v_lshlrev_b32_e32 v228, 16, v182
	v_and_b32_e32 v229, 0xffff0000, v182
	v_lshlrev_b32_e32 v182, 16, v183
	v_and_b32_e32 v183, 0xffff0000, v183
	v_lshlrev_b32_e32 v184, 16, v185
	v_and_b32_e32 v185, 0xffff0000, v185
	v_lshlrev_b32_e32 v238, 16, v192
	v_and_b32_e32 v239, 0xffff0000, v192
	v_pk_add_f32 v[106:107], v[106:107], v[226:227]
	v_pk_add_f32 v[104:105], v[104:105], v[224:225]
	v_lshlrev_b32_e32 v156, 16, v200
	v_cvt_pk_bf16_f32 v114, v104, v105
	v_cvt_pk_bf16_f32 v115, v106, v107
	global_store_dwordx4 v[118:119], v[112:115], off
	v_and_b32_e32 v157, 0xffff0000, v200
	v_pk_add_f32 v[102:103], v[102:103], v[182:183]
	v_pk_add_f32 v[112:113], v[92:93], v[230:231]
	v_pk_add_f32 v[92:93], v[98:99], v[186:187]
	v_lshl_add_u64 v[98:99], s[10:11], 0, v[154:155]
	v_pk_add_f32 v[100:101], v[100:101], v[228:229]
	v_pk_add_f32 v[94:95], v[94:95], v[184:185]
	v_cvt_pk_bf16_f32 v114, v100, v101
	v_cvt_pk_bf16_f32 v115, v102, v103
	v_cvt_pk_bf16_f32 v116, v112, v113
	v_lshlrev_b32_e32 v234, 16, v188
	v_cvt_pk_bf16_f32 v117, v94, v95
	global_store_dwordx4 v[118:119], v[114:117], off offset:256
	v_lshl_add_u64 v[118:119], v[98:99], 0, v[144:145]
	v_pk_add_f32 v[98:99], v[76:77], v[238:239]
	v_pk_add_f32 v[76:77], v[82:83], v[172:173]
	v_lshl_add_u64 v[82:83], s[10:11], 0, v[152:153]
	v_lshl_add_u64 v[122:123], v[82:83], 0, v[144:145]
	v_pk_add_f32 v[82:83], v[64:65], v[156:157]
	v_and_b32_e32 v65, 64, v174
	v_and_b32_e32 v235, 0xffff0000, v188
	v_lshlrev_b32_e32 v188, 16, v189
	v_and_b32_e32 v189, 0xffff0000, v189
	v_lshlrev_b32_e32 v236, 16, v190
	v_and_b32_e32 v237, 0xffff0000, v190
	v_pk_add_f32 v[96:97], v[96:97], v[232:233]
	v_xor_b32_e32 v64, 16, v174
	v_cvt_pk_bf16_f32 v114, v96, v97
	v_add_u32_e32 v65, 64, v65
	v_lshlrev_b32_e32 v190, 16, v191
	v_and_b32_e32 v191, 0xffff0000, v191
	v_lshlrev_b32_e32 v192, 16, v193
	v_and_b32_e32 v193, 0xffff0000, v193
	v_pk_add_f32 v[90:91], v[90:91], v[188:189]
	v_pk_add_f32 v[88:89], v[88:89], v[234:235]
	v_cvt_pk_bf16_f32 v115, v92, v93
	v_pk_add_f32 v[84:85], v[84:85], v[236:237]
	v_cvt_pk_bf16_f32 v116, v88, v89
	v_cvt_pk_bf16_f32 v117, v90, v91
	global_store_dwordx4 v[118:119], v[114:117], off
	v_cmp_lt_i32_e32 vcc, v64, v65
	v_lshlrev_b32_e32 v164, 16, v196
	v_cvt_pk_bf16_f32 v114, v84, v85
	v_and_b32_e32 v165, 0xffff0000, v196
	v_lshlrev_b32_e32 v168, 16, v197
	v_and_b32_e32 v169, 0xffff0000, v197
	v_pk_add_f32 v[86:87], v[86:87], v[190:191]
	v_pk_add_f32 v[78:79], v[78:79], v[192:193]
	v_cvt_pk_bf16_f32 v115, v86, v87
	v_cvt_pk_bf16_f32 v116, v98, v99
	v_pk_add_f32 v[80:81], v[80:81], v[166:167]
	v_cvt_pk_bf16_f32 v117, v78, v79
	global_store_dwordx4 v[118:119], v[114:117], off offset:256
	v_cndmask_b32_e32 v64, v174, v64, vcc
	v_pk_add_f32 v[74:75], v[74:75], v[168:169]
	v_cvt_pk_bf16_f32 v114, v80, v81
	v_pk_add_f32 v[72:73], v[72:73], v[164:165]
	v_cvt_pk_bf16_f32 v115, v76, v77
	v_lshlrev_b32_e32 v158, 16, v198
	v_cvt_pk_bf16_f32 v116, v72, v73
	v_cvt_pk_bf16_f32 v117, v74, v75
	global_store_dwordx4 v[122:123], v[114:117], off
	v_and_b32_e32 v159, 0xffff0000, v198
	v_lshlrev_b32_e32 v162, 16, v199
	v_lshlrev_b32_e32 v114, 2, v64
	ds_bpermute_b32 v64, v114, v126
	v_xor_b32_e32 v115, 32, v174
	v_cmp_lt_i32_e32 vcc, v115, v65
	v_and_b32_e32 v163, 0xffff0000, v199
	v_lshlrev_b32_e32 v160, 16, v201
	v_cndmask_b32_e32 v65, v174, v115, vcc
	v_lshlrev_b32_e32 v115, 2, v65
	s_waitcnt lgkmcnt(0)
	v_add_f32_e32 v116, v126, v64
	ds_bpermute_b32 v117, v115, v116
	v_and_b32_e32 v161, 0xffff0000, v201
	v_pk_add_f32 v[70:71], v[70:71], v[162:163]
	v_pk_add_f32 v[68:69], v[68:69], v[158:159]
	v_pk_add_f32 v[66:67], v[66:67], v[160:161]
	v_lshl_add_u64 v[64:65], v[150:151], 2, s[18:19]
	v_cvt_pk_bf16_f32 v118, v68, v69
	v_cvt_pk_bf16_f32 v119, v70, v71
	v_cvt_pk_bf16_f32 v120, v82, v83
	v_cvt_pk_bf16_f32 v121, v66, v67
	global_store_dwordx4 v[122:123], v[118:121], off offset:256
	s_and_saveexec_b64 s[36:37], s[6:7]
	s_cbranch_execz .LBB0_899
	s_waitcnt lgkmcnt(0)
	v_add_f32_e32 v116, v116, v117
	global_atomic_add_f32 v[64:65], v116, off

.LBB0_946:
	ds_read_b128 v[144:147], v153
	ds_read_b128 v[158:161], v153 offset:1024
	ds_read_b128 v[162:165], v153 offset:2048
	ds_read_b128 v[166:169], v153 offset:3072
	s_add_u32 s28, s2, 0xfffc0080
	s_addc_u32 s29, s3, -1
	s_cmp_eq_u32 s58, 12
	s_cselect_b32 s31, s23, s29
	s_cselect_b32 s30, s54, s28
	s_cselect_b32 s29, s21, s57
	s_cselect_b32 s28, s55, s56
	v_lshl_add_u64 v[148:149], s[2:3], 0, v[136:137]
	s_add_i32 m0, s37, 0xc000
	ds_read_b128 v[170:173], v154
	ds_read_b128 v[176:179], v154 offset:1024
	ds_read_b128 v[180:183], v154 offset:2048
	ds_read_b128 v[184:187], v154 offset:3072
	ds_read_b128 v[188:191], v154 offset:4096
	ds_read_b128 v[192:195], v154 offset:5120
	ds_read_b128 v[196:199], v154 offset:6144
	ds_read_b128 v[200:203], v154 offset:7168
	global_load_lds_dwordx4 v[148:149], off
	s_add_i32 m0, s37, 0xe000
	v_lshl_add_u64 v[148:149], s[2:3], 0, v[138:139]
	global_load_lds_dwordx4 v[148:149], off
	s_waitcnt lgkmcnt(8)
	s_setprio 1
	s_barrier
	s_waitcnt lgkmcnt(0)
	v_mfma_f32_16x16x32_bf16 v[124:127], v[144:147], v[170:173], v[124:127]
	v_mfma_f32_16x16x32_bf16 v[120:123], v[162:165], v[170:173], v[120:123]
	v_mfma_f32_16x16x32_bf16 v[116:119], v[144:147], v[180:183], v[116:119]
	v_mfma_f32_16x16x32_bf16 v[112:115], v[162:165], v[180:183], v[112:115]
	v_mfma_f32_16x16x32_bf16 v[104:107], v[144:147], v[188:191], v[104:107]
	v_mfma_f32_16x16x32_bf16 v[96:99], v[162:165], v[188:191], v[96:99]
	v_mfma_f32_16x16x32_bf16 v[76:79], v[144:147], v[196:199], v[76:79]
	v_mfma_f32_16x16x32_bf16 v[72:75], v[162:165], v[196:199], v[72:75]
	v_mfma_f32_16x16x32_bf16 v[124:127], v[158:161], v[176:179], v[124:127]
	v_mfma_f32_16x16x32_bf16 v[120:123], v[166:169], v[176:179], v[120:123]
	v_mfma_f32_16x16x32_bf16 v[116:119], v[158:161], v[184:187], v[116:119]
	v_mfma_f32_16x16x32_bf16 v[112:115], v[166:169], v[184:187], v[112:115]
	v_mfma_f32_16x16x32_bf16 v[104:107], v[158:161], v[192:195], v[104:107]
	v_mfma_f32_16x16x32_bf16 v[96:99], v[166:169], v[192:195], v[96:99]
	v_mfma_f32_16x16x32_bf16 v[76:79], v[158:161], v[200:203], v[76:79]
	v_mfma_f32_16x16x32_bf16 v[72:75], v[166:169], v[200:203], v[72:75]
	s_barrier
	s_setprio 0
	s_add_i32 s59, s50, s34
	v_lshl_add_u64 v[148:149], s[28:29], 0, v[132:133]
	s_mov_b32 m0, s59
	ds_read_b128 v[204:207], v155
	ds_read_b128 v[212:215], v155 offset:1024
	ds_read_b128 v[216:219], v155 offset:2048
	ds_read_b128 v[220:223], v155 offset:3072
	global_load_lds_dwordx4 v[148:149], off
	s_add_i32 m0, s59, 0x2000
	v_lshl_add_u64 v[208:209], s[28:29], 0, v[128:129]
	global_load_lds_dwordx4 v[208:209], off
	s_setprio 1
	s_barrier
	s_waitcnt lgkmcnt(0)
	v_mfma_f32_16x16x32_bf16 v[108:111], v[204:207], v[170:173], v[108:111]
	v_mfma_f32_16x16x32_bf16 v[100:103], v[216:219], v[170:173], v[100:103]
	v_mfma_f32_16x16x32_bf16 v[92:95], v[204:207], v[180:183], v[92:95]
	v_mfma_f32_16x16x32_bf16 v[88:91], v[216:219], v[180:183], v[88:91]
	v_mfma_f32_16x16x32_bf16 v[84:87], v[204:207], v[188:191], v[84:87]
	v_mfma_f32_16x16x32_bf16 v[80:83], v[216:219], v[188:191], v[80:83]
	v_mfma_f32_16x16x32_bf16 v[68:71], v[204:207], v[196:199], v[68:71]
	v_mfma_f32_16x16x32_bf16 v[64:67], v[216:219], v[196:199], v[64:67]
	v_mfma_f32_16x16x32_bf16 v[108:111], v[212:215], v[176:179], v[108:111]
	v_mfma_f32_16x16x32_bf16 v[100:103], v[220:223], v[176:179], v[100:103]
	v_mfma_f32_16x16x32_bf16 v[92:95], v[212:215], v[184:187], v[92:95]
	v_mfma_f32_16x16x32_bf16 v[88:91], v[220:223], v[184:187], v[88:91]
	v_mfma_f32_16x16x32_bf16 v[84:87], v[212:215], v[192:195], v[84:87]
	v_mfma_f32_16x16x32_bf16 v[80:83], v[220:223], v[192:195], v[80:83]
	v_mfma_f32_16x16x32_bf16 v[68:71], v[212:215], v[200:203], v[68:71]
	v_mfma_f32_16x16x32_bf16 v[64:67], v[220:223], v[200:203], v[64:67]
	s_barrier
	s_setprio 0
	s_mov_b32 m0, s37
	v_lshl_add_u64 v[224:225], s[30:31], 0, v[134:135]
	ds_read_b128 v[170:173], v154 offset:16384
	ds_read_b128 v[176:179], v154 offset:17408
	ds_read_b128 v[180:183], v154 offset:18432
	ds_read_b128 v[184:187], v154 offset:19456
	ds_read_b128 v[188:191], v154 offset:20480
	ds_read_b128 v[192:195], v154 offset:21504
	ds_read_b128 v[196:199], v154 offset:22528
	ds_read_b128 v[200:203], v154 offset:23552
	global_load_lds_dwordx4 v[224:225], off
	s_mov_b32 m0, s38
	v_lshl_add_u64 v[226:227], s[30:31], 0, v[130:131]
	global_load_lds_dwordx4 v[226:227], off
	s_setprio 1
	s_barrier
	s_waitcnt lgkmcnt(0)
	v_mfma_f32_16x16x32_bf16 v[60:63], v[144:147], v[170:173], v[60:63]
	v_mfma_f32_16x16x32_bf16 v[56:59], v[162:165], v[170:173], v[56:59]
	v_mfma_f32_16x16x32_bf16 v[44:47], v[144:147], v[180:183], v[44:47]
	v_mfma_f32_16x16x32_bf16 v[40:43], v[162:165], v[180:183], v[40:43]
	v_mfma_f32_16x16x32_bf16 v[28:31], v[144:147], v[188:191], v[28:31]
	v_mfma_f32_16x16x32_bf16 v[24:27], v[162:165], v[188:191], v[24:27]
	v_mfma_f32_16x16x32_bf16 v[12:15], v[144:147], v[196:199], v[12:15]
	v_mfma_f32_16x16x32_bf16 v[8:11], v[162:165], v[196:199], v[8:11]
	v_mfma_f32_16x16x32_bf16 v[60:63], v[158:161], v[176:179], v[60:63]
	v_mfma_f32_16x16x32_bf16 v[56:59], v[166:169], v[176:179], v[56:59]
	v_mfma_f32_16x16x32_bf16 v[44:47], v[158:161], v[184:187], v[44:47]
	v_mfma_f32_16x16x32_bf16 v[40:43], v[166:169], v[184:187], v[40:43]
	v_mfma_f32_16x16x32_bf16 v[28:31], v[158:161], v[192:195], v[28:31]
	v_mfma_f32_16x16x32_bf16 v[24:27], v[166:169], v[192:195], v[24:27]
	v_mfma_f32_16x16x32_bf16 v[12:15], v[158:161], v[200:203], v[12:15]
	v_mfma_f32_16x16x32_bf16 v[8:11], v[166:169], v[200:203], v[8:11]
	s_barrier
	s_setprio 0
	s_add_u32 s60, s28, 0x40000
	s_addc_u32 s61, s29, 0
	s_add_i32 s59, s51, s34
	s_mov_b32 m0, s59
	v_lshl_add_u64 v[144:145], s[60:61], 0, v[132:133]
	global_load_lds_dwordx4 v[144:145], off
	s_add_i32 m0, s59, 0x2000
	v_lshl_add_u64 v[144:145], s[60:61], 0, v[128:129]
	global_load_lds_dwordx4 v[144:145], off
	s_waitcnt vmcnt(6)
	s_setprio 1
	s_barrier
	v_mfma_f32_16x16x32_bf16 v[52:55], v[204:207], v[170:173], v[52:55]
	v_mfma_f32_16x16x32_bf16 v[48:51], v[216:219], v[170:173], v[48:51]
	v_mfma_f32_16x16x32_bf16 v[36:39], v[204:207], v[180:183], v[36:39]
	v_mfma_f32_16x16x32_bf16 v[32:35], v[216:219], v[180:183], v[32:35]
	v_mfma_f32_16x16x32_bf16 v[20:23], v[204:207], v[188:191], v[20:23]
	v_mfma_f32_16x16x32_bf16 v[16:19], v[216:219], v[188:191], v[16:19]
	v_mfma_f32_16x16x32_bf16 v[4:7], v[204:207], v[196:199], v[4:7]
	v_mfma_f32_16x16x32_bf16 v[0:3], v[216:219], v[196:199], v[0:3]
	v_mfma_f32_16x16x32_bf16 v[52:55], v[212:215], v[176:179], v[52:55]
	v_mfma_f32_16x16x32_bf16 v[48:51], v[220:223], v[176:179], v[48:51]
	v_mfma_f32_16x16x32_bf16 v[36:39], v[212:215], v[184:187], v[36:39]
	v_mfma_f32_16x16x32_bf16 v[32:35], v[220:223], v[184:187], v[32:35]
	v_mfma_f32_16x16x32_bf16 v[20:23], v[212:215], v[192:195], v[20:23]
	v_mfma_f32_16x16x32_bf16 v[16:19], v[220:223], v[192:195], v[16:19]
	v_mfma_f32_16x16x32_bf16 v[4:7], v[212:215], v[200:203], v[4:7]
	v_mfma_f32_16x16x32_bf16 v[0:3], v[220:223], v[200:203], v[0:3]
	s_barrier
	s_setprio 0
	s_add_i32 s59, 0, 0x18000
	v_add_u32_e32 v157, s59, v151
	ds_read_b128 v[144:147], v157
	ds_read_b128 v[158:161], v157 offset:1024
	ds_read_b128 v[162:165], v157 offset:2048
	ds_read_b128 v[166:169], v157 offset:3072
	s_add_u32 s30, s30, 0x40000
	s_addc_u32 s31, s31, 0
	s_mov_b32 m0, s39
	v_lshl_add_u64 v[204:205], s[30:31], 0, v[134:135]
	ds_read_b128 v[170:173], v154 offset:32768
	ds_read_b128 v[176:179], v154 offset:33792
	ds_read_b128 v[180:183], v154 offset:34816
	ds_read_b128 v[184:187], v154 offset:35840
	ds_read_b128 v[188:191], v154 offset:36864
	ds_read_b128 v[192:195], v154 offset:37888
	ds_read_b128 v[196:199], v154 offset:38912
	ds_read_b128 v[200:203], v154 offset:39936
	global_load_lds_dwordx4 v[204:205], off
	s_mov_b32 m0, s40
	v_lshl_add_u64 v[204:205], s[30:31], 0, v[130:131]
	global_load_lds_dwordx4 v[204:205], off
	s_waitcnt lgkmcnt(8)
	s_setprio 1
	s_barrier
	s_waitcnt lgkmcnt(0)
	v_mfma_f32_16x16x32_bf16 v[124:127], v[144:147], v[170:173], v[124:127]
	v_mfma_f32_16x16x32_bf16 v[120:123], v[162:165], v[170:173], v[120:123]
	v_mfma_f32_16x16x32_bf16 v[116:119], v[144:147], v[180:183], v[116:119]
	v_mfma_f32_16x16x32_bf16 v[112:115], v[162:165], v[180:183], v[112:115]
	v_mfma_f32_16x16x32_bf16 v[104:107], v[144:147], v[188:191], v[104:107]
	v_mfma_f32_16x16x32_bf16 v[96:99], v[162:165], v[188:191], v[96:99]
	v_mfma_f32_16x16x32_bf16 v[76:79], v[144:147], v[196:199], v[76:79]
	v_mfma_f32_16x16x32_bf16 v[72:75], v[162:165], v[196:199], v[72:75]
	v_mfma_f32_16x16x32_bf16 v[124:127], v[158:161], v[176:179], v[124:127]
	v_mfma_f32_16x16x32_bf16 v[120:123], v[166:169], v[176:179], v[120:123]
	v_mfma_f32_16x16x32_bf16 v[116:119], v[158:161], v[184:187], v[116:119]
	v_mfma_f32_16x16x32_bf16 v[112:115], v[166:169], v[184:187], v[112:115]
	v_mfma_f32_16x16x32_bf16 v[104:107], v[158:161], v[192:195], v[104:107]
	v_mfma_f32_16x16x32_bf16 v[96:99], v[166:169], v[192:195], v[96:99]
	v_mfma_f32_16x16x32_bf16 v[76:79], v[158:161], v[200:203], v[76:79]
	v_mfma_f32_16x16x32_bf16 v[72:75], v[166:169], v[200:203], v[72:75]
	s_barrier
	s_setprio 0
	s_add_i32 s30, 0, 0x1c000
	s_add_i32 s31, s59, s34
	v_add_u32_e32 v157, s30, v151
	v_lshl_add_u64 v[148:149], v[148:149], 0, s[8:9]
	s_mov_b32 m0, s31
	ds_read_b128 v[204:207], v157
	ds_read_b128 v[212:215], v157 offset:1024
	ds_read_b128 v[216:219], v157 offset:2048
	ds_read_b128 v[220:223], v157 offset:3072
	global_load_lds_dwordx4 v[148:149], off
	s_add_i32 m0, s31, 0x2000
	v_lshl_add_u64 v[148:149], v[208:209], 0, s[8:9]
	global_load_lds_dwordx4 v[148:149], off
	s_setprio 1
	s_barrier
	s_waitcnt lgkmcnt(0)
	v_mfma_f32_16x16x32_bf16 v[108:111], v[204:207], v[170:173], v[108:111]
	v_mfma_f32_16x16x32_bf16 v[100:103], v[216:219], v[170:173], v[100:103]
	v_mfma_f32_16x16x32_bf16 v[92:95], v[204:207], v[180:183], v[92:95]
	v_mfma_f32_16x16x32_bf16 v[88:91], v[216:219], v[180:183], v[88:91]
	v_mfma_f32_16x16x32_bf16 v[84:87], v[204:207], v[188:191], v[84:87]
	v_mfma_f32_16x16x32_bf16 v[80:83], v[216:219], v[188:191], v[80:83]
	v_mfma_f32_16x16x32_bf16 v[68:71], v[204:207], v[196:199], v[68:71]
	v_mfma_f32_16x16x32_bf16 v[64:67], v[216:219], v[196:199], v[64:67]
	v_mfma_f32_16x16x32_bf16 v[108:111], v[212:215], v[176:179], v[108:111]
	v_mfma_f32_16x16x32_bf16 v[100:103], v[220:223], v[176:179], v[100:103]
	v_mfma_f32_16x16x32_bf16 v[92:95], v[212:215], v[184:187], v[92:95]
	v_mfma_f32_16x16x32_bf16 v[88:91], v[220:223], v[184:187], v[88:91]
	v_mfma_f32_16x16x32_bf16 v[84:87], v[212:215], v[192:195], v[84:87]
	v_mfma_f32_16x16x32_bf16 v[80:83], v[220:223], v[192:195], v[80:83]
	v_mfma_f32_16x16x32_bf16 v[68:71], v[212:215], v[200:203], v[68:71]
	v_mfma_f32_16x16x32_bf16 v[64:67], v[220:223], v[200:203], v[64:67]
	s_barrier
	s_setprio 0
	s_mov_b32 m0, s42
	v_lshl_add_u64 v[148:149], v[224:225], 0, s[8:9]
	ds_read_b128 v[170:173], v154 offset:49152
	ds_read_b128 v[176:179], v154 offset:50176
	ds_read_b128 v[180:183], v154 offset:51200
	ds_read_b128 v[184:187], v154 offset:52224
	ds_read_b128 v[188:191], v154 offset:53248
	ds_read_b128 v[192:195], v154 offset:54272
	ds_read_b128 v[196:199], v154 offset:55296
	ds_read_b128 v[200:203], v154 offset:56320
	global_load_lds_dwordx4 v[148:149], off
	s_mov_b32 m0, s43
	v_lshl_add_u64 v[148:149], v[226:227], 0, s[8:9]
	global_load_lds_dwordx4 v[148:149], off
	s_setprio 1
	s_barrier
	s_waitcnt lgkmcnt(0)
	v_mfma_f32_16x16x32_bf16 v[60:63], v[144:147], v[170:173], v[60:63]
	v_mfma_f32_16x16x32_bf16 v[56:59], v[162:165], v[170:173], v[56:59]
	v_mfma_f32_16x16x32_bf16 v[44:47], v[144:147], v[180:183], v[44:47]
	v_mfma_f32_16x16x32_bf16 v[40:43], v[162:165], v[180:183], v[40:43]
	v_mfma_f32_16x16x32_bf16 v[28:31], v[144:147], v[188:191], v[28:31]
	v_mfma_f32_16x16x32_bf16 v[24:27], v[162:165], v[188:191], v[24:27]
	v_mfma_f32_16x16x32_bf16 v[12:15], v[144:147], v[196:199], v[12:15]
	v_mfma_f32_16x16x32_bf16 v[8:11], v[162:165], v[196:199], v[8:11]
	v_mfma_f32_16x16x32_bf16 v[60:63], v[158:161], v[176:179], v[60:63]
	v_mfma_f32_16x16x32_bf16 v[56:59], v[166:169], v[176:179], v[56:59]
	v_mfma_f32_16x16x32_bf16 v[44:47], v[158:161], v[184:187], v[44:47]
	v_mfma_f32_16x16x32_bf16 v[40:43], v[166:169], v[184:187], v[40:43]
	v_mfma_f32_16x16x32_bf16 v[28:31], v[158:161], v[192:195], v[28:31]
	v_mfma_f32_16x16x32_bf16 v[24:27], v[166:169], v[192:195], v[24:27]
	v_mfma_f32_16x16x32_bf16 v[12:15], v[158:161], v[200:203], v[12:15]
	v_mfma_f32_16x16x32_bf16 v[8:11], v[166:169], v[200:203], v[8:11]
	s_barrier
	s_setprio 0
	s_add_u32 s28, s28, 0x40080
	s_addc_u32 s29, s29, 0
	s_add_i32 s30, s30, s34
	s_mov_b32 m0, s30
	v_lshl_add_u64 v[144:145], s[28:29], 0, v[132:133]
	global_load_lds_dwordx4 v[144:145], off
	s_add_i32 m0, s30, 0x2000
	v_lshl_add_u64 v[144:145], s[28:29], 0, v[128:129]
	global_load_lds_dwordx4 v[144:145], off
	s_waitcnt vmcnt(6)
	s_setprio 1
	s_barrier
	v_mfma_f32_16x16x32_bf16 v[52:55], v[204:207], v[170:173], v[52:55]
	v_mfma_f32_16x16x32_bf16 v[48:51], v[216:219], v[170:173], v[48:51]
	v_mfma_f32_16x16x32_bf16 v[36:39], v[204:207], v[180:183], v[36:39]
	v_mfma_f32_16x16x32_bf16 v[32:35], v[216:219], v[180:183], v[32:35]
	v_mfma_f32_16x16x32_bf16 v[20:23], v[204:207], v[188:191], v[20:23]
	v_mfma_f32_16x16x32_bf16 v[16:19], v[216:219], v[188:191], v[16:19]
	v_mfma_f32_16x16x32_bf16 v[4:7], v[204:207], v[196:199], v[4:7]
	v_mfma_f32_16x16x32_bf16 v[0:3], v[216:219], v[196:199], v[0:3]
	v_mfma_f32_16x16x32_bf16 v[52:55], v[212:215], v[176:179], v[52:55]
	v_mfma_f32_16x16x32_bf16 v[48:51], v[220:223], v[176:179], v[48:51]
	v_mfma_f32_16x16x32_bf16 v[36:39], v[212:215], v[184:187], v[36:39]
	v_mfma_f32_16x16x32_bf16 v[32:35], v[220:223], v[184:187], v[32:35]
	v_mfma_f32_16x16x32_bf16 v[20:23], v[212:215], v[192:195], v[20:23]
	v_mfma_f32_16x16x32_bf16 v[16:19], v[220:223], v[192:195], v[16:19]
	v_mfma_f32_16x16x32_bf16 v[4:7], v[212:215], v[200:203], v[4:7]
	v_mfma_f32_16x16x32_bf16 v[0:3], v[220:223], v[200:203], v[0:3]
	s_barrier
	s_setprio 0
	s_add_i32 s58, s58, 2
	s_add_u32 s2, s2, 0x100
	s_addc_u32 s3, s3, 0
	s_add_u32 s56, s56, 0x100
	s_addc_u32 s57, s57, 0
	s_cmp_gt_u32 s58, 13
	s_cbranch_scc0 .LBB0_946
	v_lshl_add_u32 v144, s0, 8, v150
	v_ashrrev_i32_e32 v145, 31, v144
	v_lshl_add_u64 v[146:147], v[144:145], 2, s[18:19]
	global_load_dword v145, v[146:147], off
	global_load_dword v157, v[146:147], off offset:64
	global_load_dword v164, v[146:147], off offset:128
	global_load_dword v165, v[146:147], off offset:192
	global_load_dword v166, v[146:147], off offset:512
	global_load_dword v167, v[146:147], off offset:576
	global_load_dword v168, v[146:147], off offset:640
	global_load_dword v169, v[146:147], off offset:704
	v_mov_b64_e32 v[146:147], s[92:93]
	v_or_b32_e32 v160, 16, v144
	v_or_b32_e32 v162, 32, v144
	v_lshl_or_b32 v148, s1, 8, v152
	v_mad_i64_i32 v[158:159], s[0:1], v144, s52, v[146:147]
	v_mad_i64_i32 v[160:161], s[0:1], v160, s52, v[146:147]
	v_mad_i64_i32 v[162:163], s[0:1], v162, s52, v[146:147]
	v_ashrrev_i32_e32 v149, 31, v148
	v_lshlrev_b64 v[148:149], 1, v[148:149]
	v_lshl_add_u64 v[158:159], v[158:159], 0, v[148:149]
	v_lshl_add_u64 v[160:161], v[160:161], 0, v[148:149]
	v_lshl_add_u64 v[162:163], v[162:163], 0, v[148:149]
	v_add_u32_e32 v170, 0x80, v144
	s_mov_b64 s[28:29], s[26:27]
	s_waitcnt vmcnt(0)
	v_fmamk_f32 v145, v145, 0x3a800000, v156
	v_fmamk_f32 v157, v157, 0x3a800000, v156
	v_fmamk_f32 v164, v164, 0x3a800000, v156
	v_fmamk_f32 v171, v165, 0x3a800000, v156
	v_fmamk_f32 v172, v166, 0x3a800000, v156
	v_mul_f32_e32 v165, 0x4b800000, v145
	v_mul_f32_e32 v166, 0x4b800000, v157
	v_cmp_gt_f32_e32 vcc, s53, v145
	v_cmp_gt_f32_e64 s[0:1], s53, v157
	v_fmamk_f32 v173, v167, 0x3a800000, v156
	v_mul_f32_e32 v167, 0x4b800000, v164
	v_cndmask_b32_e32 v145, v145, v165, vcc
	v_cndmask_b32_e64 v157, v157, v166, s[0:1]
	v_cmp_gt_f32_e64 s[2:3], s53, v164
	v_rsq_f32_e32 v145, v145
	v_rsq_f32_e32 v157, v157
	v_cndmask_b32_e64 v164, v164, v167, s[2:3]
	v_rsq_f32_e32 v165, v164
	v_mul_f32_e32 v164, 0x45800000, v145
	v_mul_f32_e32 v166, 0x45800000, v157
	v_cndmask_b32_e32 v164, v145, v164, vcc
	v_mul_f32_e32 v167, 0x45800000, v165
	v_cndmask_b32_e64 v166, v157, v166, s[0:1]
	v_fmamk_f32 v175, v168, 0x3a800000, v156
	v_cndmask_b32_e64 v168, v165, v167, s[2:3]
	v_pk_mul_f32 v[126:127], v[126:127], v[164:165] op_sel_hi:[1,0]
	v_pk_mul_f32 v[124:125], v[124:125], v[164:165] op_sel_hi:[1,0]
	v_pk_mul_f32 v[122:123], v[122:123], v[164:165] op_sel_hi:[1,0]
	v_pk_mul_f32 v[120:121], v[120:121], v[164:165] op_sel_hi:[1,0]
	v_pk_mul_f32 v[110:111], v[110:111], v[164:165] op_sel_hi:[1,0]
	v_pk_mul_f32 v[108:109], v[108:109], v[164:165] op_sel_hi:[1,0]
	v_pk_mul_f32 v[102:103], v[102:103], v[164:165] op_sel_hi:[1,0]
	v_pk_mul_f32 v[100:101], v[100:101], v[164:165] op_sel_hi:[1,0]
	v_pk_mul_f32 v[118:119], v[118:119], v[166:167] op_sel_hi:[1,0]
	v_pk_mul_f32 v[116:117], v[116:117], v[166:167] op_sel_hi:[1,0]
	v_pk_mul_f32 v[114:115], v[114:115], v[166:167] op_sel_hi:[1,0]
	v_pk_mul_f32 v[112:113], v[112:113], v[166:167] op_sel_hi:[1,0]
	v_pk_mul_f32 v[94:95], v[94:95], v[166:167] op_sel_hi:[1,0]
	v_pk_mul_f32 v[92:93], v[92:93], v[166:167] op_sel_hi:[1,0]
	v_pk_mul_f32 v[164:165], v[90:91], v[166:167] op_sel_hi:[1,0]
	v_pk_mul_f32 v[166:167], v[88:89], v[166:167] op_sel_hi:[1,0]
	v_cvt_pk_bf16_f32 v88, v124, v125
	v_cvt_pk_bf16_f32 v89, v126, v127
	v_cvt_pk_bf16_f32 v90, v120, v121
	v_cvt_pk_bf16_f32 v91, v122, v123
	global_store_dwordx4 v[158:159], v[88:91], off nt
	v_fmamk_f32 v169, v169, 0x3a800000, v156
	v_pk_mul_f32 v[106:107], v[106:107], v[168:169] op_sel_hi:[1,0]
	v_cvt_pk_bf16_f32 v88, v108, v109
	v_cvt_pk_bf16_f32 v89, v110, v111
	v_cvt_pk_bf16_f32 v90, v100, v101
	v_cvt_pk_bf16_f32 v91, v102, v103
	global_store_dwordx4 v[158:159], v[88:91], off offset:256 nt
	v_pk_mul_f32 v[104:105], v[104:105], v[168:169] op_sel_hi:[1,0]
	v_pk_mul_f32 v[98:99], v[98:99], v[168:169] op_sel_hi:[1,0]
	v_cvt_pk_bf16_f32 v88, v116, v117
	v_cvt_pk_bf16_f32 v89, v118, v119
	v_cvt_pk_bf16_f32 v90, v112, v113
	v_cvt_pk_bf16_f32 v91, v114, v115
	global_store_dwordx4 v[160:161], v[88:91], off nt
	v_pk_mul_f32 v[96:97], v[96:97], v[168:169] op_sel_hi:[1,0]
	v_pk_mul_f32 v[86:87], v[86:87], v[168:169] op_sel_hi:[1,0]
	v_cvt_pk_bf16_f32 v88, v92, v93
	v_cvt_pk_bf16_f32 v89, v94, v95
	v_cvt_pk_bf16_f32 v90, v166, v167
	v_cvt_pk_bf16_f32 v91, v164, v165
	global_store_dwordx4 v[160:161], v[88:91], off offset:256 nt
	v_pk_mul_f32 v[84:85], v[84:85], v[168:169] op_sel_hi:[1,0]
	v_cmp_gt_f32_e32 vcc, s53, v171
	v_cvt_pk_bf16_f32 v88, v104, v105
	v_cvt_pk_bf16_f32 v89, v106, v107
	v_cvt_pk_bf16_f32 v90, v96, v97
	v_cvt_pk_bf16_f32 v91, v98, v99
	global_store_dwordx4 v[162:163], v[88:91], off nt
	s_mov_b64 s[2:3], s[24:25]
	s_nop 0
	v_pk_mul_f32 v[88:89], v[82:83], v[168:169] op_sel_hi:[1,0]
	v_pk_mul_f32 v[82:83], v[80:81], v[168:169] op_sel_hi:[1,0]
	v_cvt_pk_bf16_f32 v80, v84, v85
	v_cvt_pk_bf16_f32 v81, v86, v87
	s_nop 0
	v_cvt_pk_bf16_f32 v82, v82, v83
	v_cvt_pk_bf16_f32 v83, v88, v89
	global_store_dwordx4 v[162:163], v[80:83], off offset:256 nt
	s_nop 1
	v_mul_f32_e32 v81, 0x4b800000, v171
	v_cndmask_b32_e32 v81, v171, v81, vcc
	v_rsq_f32_e32 v82, v81
	v_or_b32_e32 v80, 48, v144
	v_mad_i64_i32 v[80:81], s[0:1], v80, s52, v[146:147]
	v_mul_f32_e32 v83, 0x45800000, v82
	v_cndmask_b32_e32 v82, v82, v83, vcc
	v_lshl_add_u64 v[80:81], v[80:81], 0, v[148:149]
	v_pk_mul_f32 v[78:79], v[78:79], v[82:83] op_sel_hi:[1,0]
	v_pk_mul_f32 v[76:77], v[76:77], v[82:83] op_sel_hi:[1,0]
	v_pk_mul_f32 v[84:85], v[74:75], v[82:83] op_sel_hi:[1,0]
	v_pk_mul_f32 v[74:75], v[72:73], v[82:83] op_sel_hi:[1,0]
	v_cvt_pk_bf16_f32 v72, v76, v77
	v_cvt_pk_bf16_f32 v73, v78, v79
	v_pk_mul_f32 v[68:69], v[68:69], v[82:83] op_sel_hi:[1,0]
	v_cvt_pk_bf16_f32 v74, v74, v75
	v_cvt_pk_bf16_f32 v75, v84, v85
	global_store_dwordx4 v[80:81], v[72:75], off nt
	v_pk_mul_f32 v[70:71], v[70:71], v[82:83] op_sel_hi:[1,0]
	v_cmp_gt_f32_e32 vcc, s53, v172
	v_pk_mul_f32 v[72:73], v[66:67], v[82:83] op_sel_hi:[1,0]
	v_pk_mul_f32 v[66:67], v[64:65], v[82:83] op_sel_hi:[1,0]
	v_cvt_pk_bf16_f32 v64, v68, v69
	v_cvt_pk_bf16_f32 v65, v70, v71
	s_nop 0
	v_cvt_pk_bf16_f32 v66, v66, v67
	v_cvt_pk_bf16_f32 v67, v72, v73
	global_store_dwordx4 v[80:81], v[64:67], off offset:256 nt
	s_nop 1
	v_mul_f32_e32 v64, 0x4b800000, v172
	v_cndmask_b32_e32 v64, v172, v64, vcc
	v_rsq_f32_e32 v66, v64
	v_mad_i64_i32 v[64:65], s[0:1], v170, s52, v[146:147]
	v_lshl_add_u64 v[64:65], v[64:65], 0, v[148:149]
	v_mul_f32_e32 v67, 0x45800000, v66
	v_cndmask_b32_e32 v66, v66, v67, vcc
	v_pk_mul_f32 v[62:63], v[62:63], v[66:67] op_sel_hi:[1,0]
	v_pk_mul_f32 v[60:61], v[60:61], v[66:67] op_sel_hi:[1,0]
	v_pk_mul_f32 v[68:69], v[58:59], v[66:67] op_sel_hi:[1,0]
	v_pk_mul_f32 v[58:59], v[56:57], v[66:67] op_sel_hi:[1,0]
	v_cvt_pk_bf16_f32 v56, v60, v61
	v_cvt_pk_bf16_f32 v57, v62, v63
	v_pk_mul_f32 v[54:55], v[54:55], v[66:67] op_sel_hi:[1,0]
	v_cvt_pk_bf16_f32 v58, v58, v59
	v_cvt_pk_bf16_f32 v59, v68, v69
	global_store_dwordx4 v[64:65], v[56:59], off nt
	v_pk_mul_f32 v[52:53], v[52:53], v[66:67] op_sel_hi:[1,0]
	v_cmp_gt_f32_e32 vcc, s53, v173
	v_pk_mul_f32 v[56:57], v[50:51], v[66:67] op_sel_hi:[1,0]
	v_pk_mul_f32 v[50:51], v[48:49], v[66:67] op_sel_hi:[1,0]
	v_cvt_pk_bf16_f32 v48, v52, v53
	v_cvt_pk_bf16_f32 v49, v54, v55
	s_nop 0
	v_cvt_pk_bf16_f32 v50, v50, v51
	v_cvt_pk_bf16_f32 v51, v56, v57
	global_store_dwordx4 v[64:65], v[48:51], off offset:256 nt
	s_nop 1
	v_mul_f32_e32 v49, 0x4b800000, v173
	v_cndmask_b32_e32 v49, v173, v49, vcc
	v_rsq_f32_e32 v50, v49
	v_add_u32_e32 v48, 0x90, v144
	v_mad_i64_i32 v[48:49], s[0:1], v48, s52, v[146:147]
	v_mul_f32_e32 v51, 0x45800000, v50
	v_cndmask_b32_e32 v50, v50, v51, vcc
	v_lshl_add_u64 v[48:49], v[48:49], 0, v[148:149]
	v_pk_mul_f32 v[46:47], v[46:47], v[50:51] op_sel_hi:[1,0]
	v_pk_mul_f32 v[44:45], v[44:45], v[50:51] op_sel_hi:[1,0]
	v_pk_mul_f32 v[52:53], v[42:43], v[50:51] op_sel_hi:[1,0]
	v_pk_mul_f32 v[42:43], v[40:41], v[50:51] op_sel_hi:[1,0]
	v_cvt_pk_bf16_f32 v40, v44, v45
	v_cvt_pk_bf16_f32 v41, v46, v47
	v_pk_mul_f32 v[38:39], v[38:39], v[50:51] op_sel_hi:[1,0]
	v_cvt_pk_bf16_f32 v42, v42, v43
	v_cvt_pk_bf16_f32 v43, v52, v53
	global_store_dwordx4 v[48:49], v[40:43], off nt
	v_pk_mul_f32 v[36:37], v[36:37], v[50:51] op_sel_hi:[1,0]
	v_cmp_gt_f32_e32 vcc, s53, v175
	v_pk_mul_f32 v[40:41], v[34:35], v[50:51] op_sel_hi:[1,0]
	v_pk_mul_f32 v[34:35], v[32:33], v[50:51] op_sel_hi:[1,0]
	v_cvt_pk_bf16_f32 v32, v36, v37
	v_cvt_pk_bf16_f32 v33, v38, v39
	s_nop 0
	v_cvt_pk_bf16_f32 v34, v34, v35
	v_cvt_pk_bf16_f32 v35, v40, v41
	global_store_dwordx4 v[48:49], v[32:35], off offset:256 nt
	s_nop 1
	v_mul_f32_e32 v33, 0x4b800000, v175
	v_cndmask_b32_e32 v33, v175, v33, vcc
	v_rsq_f32_e32 v34, v33
	v_add_u32_e32 v32, 0xa0, v144
	v_mad_i64_i32 v[32:33], s[0:1], v32, s52, v[146:147]
	v_mul_f32_e32 v35, 0x45800000, v34
	v_cndmask_b32_e32 v34, v34, v35, vcc
	v_lshl_add_u64 v[32:33], v[32:33], 0, v[148:149]
	v_pk_mul_f32 v[30:31], v[30:31], v[34:35] op_sel_hi:[1,0]
	v_pk_mul_f32 v[28:29], v[28:29], v[34:35] op_sel_hi:[1,0]
	v_pk_mul_f32 v[36:37], v[26:27], v[34:35] op_sel_hi:[1,0]
	v_pk_mul_f32 v[26:27], v[24:25], v[34:35] op_sel_hi:[1,0]
	v_cvt_pk_bf16_f32 v24, v28, v29
	v_cvt_pk_bf16_f32 v25, v30, v31
	v_pk_mul_f32 v[22:23], v[22:23], v[34:35] op_sel_hi:[1,0]
	v_cvt_pk_bf16_f32 v26, v26, v27
	v_cvt_pk_bf16_f32 v27, v36, v37
	global_store_dwordx4 v[32:33], v[24:27], off nt
	v_pk_mul_f32 v[20:21], v[20:21], v[34:35] op_sel_hi:[1,0]
	v_cmp_gt_f32_e32 vcc, s53, v169
	v_pk_mul_f32 v[24:25], v[18:19], v[34:35] op_sel_hi:[1,0]
	v_pk_mul_f32 v[18:19], v[16:17], v[34:35] op_sel_hi:[1,0]
	v_cvt_pk_bf16_f32 v16, v20, v21
	v_cvt_pk_bf16_f32 v17, v22, v23
	s_nop 0
	v_cvt_pk_bf16_f32 v18, v18, v19
	v_cvt_pk_bf16_f32 v19, v24, v25
	global_store_dwordx4 v[32:33], v[16:19], off offset:256 nt
	s_nop 1
	v_mul_f32_e32 v17, 0x4b800000, v169
	v_cndmask_b32_e32 v17, v169, v17, vcc
	v_rsq_f32_e32 v18, v17
	v_add_u32_e32 v16, 0xb0, v144
	v_mad_i64_i32 v[16:17], s[0:1], v16, s52, v[146:147]
	v_mul_f32_e32 v19, 0x45800000, v18
	v_cndmask_b32_e32 v18, v18, v19, vcc
	v_lshl_add_u64 v[16:17], v[16:17], 0, v[148:149]
	v_pk_mul_f32 v[14:15], v[14:15], v[18:19] op_sel_hi:[1,0]
	v_pk_mul_f32 v[12:13], v[12:13], v[18:19] op_sel_hi:[1,0]
	v_pk_mul_f32 v[20:21], v[10:11], v[18:19] op_sel_hi:[1,0]
	v_pk_mul_f32 v[10:11], v[8:9], v[18:19] op_sel_hi:[1,0]
	v_cvt_pk_bf16_f32 v8, v12, v13
	v_cvt_pk_bf16_f32 v9, v14, v15
	s_and_b64 vcc, exec, s[6:7]
	v_cvt_pk_bf16_f32 v10, v10, v11
	v_cvt_pk_bf16_f32 v11, v20, v21
	global_store_dwordx4 v[16:17], v[8:11], off nt
	s_mov_b32 s1, s20
	s_mov_b32 s0, s22
	v_pk_mul_f32 v[8:9], v[2:3], v[18:19] op_sel_hi:[1,0]
	v_pk_mul_f32 v[2:3], v[0:1], v[18:19] op_sel_hi:[1,0]
	v_pk_mul_f32 v[6:7], v[6:7], v[18:19] op_sel_hi:[1,0]
	v_pk_mul_f32 v[4:5], v[4:5], v[18:19] op_sel_hi:[1,0]
	s_nop 0
	v_cvt_pk_bf16_f32 v0, v4, v5
	v_cvt_pk_bf16_f32 v1, v6, v7
	v_cvt_pk_bf16_f32 v2, v2, v3
	v_cvt_pk_bf16_f32 v3, v8, v9
	global_store_dwordx4 v[16:17], v[0:3], off offset:256 nt
	s_cbranch_vccz .LBB0_943
	s_waitcnt vmcnt(0)
	s_cmpk_gt_u32 s33, 0xff
	s_cbranch_scc1 .LBB0_950
	s_barrier

.LBB0_1022:
	ds_read_b128 v[144:147], v178
	ds_read_b128 v[148:151], v178 offset:1024
	ds_read_b128 v[152:155], v178 offset:2048
	ds_read_b128 v[156:159], v178 offset:3072
	s_add_u32 s42, s40, 0xfffc0080
	s_addc_u32 s43, s41, -1
	s_cmp_eq_u32 s64, 12
	s_cselect_b32 s49, s29, s43
	s_cselect_b32 s48, s37, s42
	s_cselect_b32 s43, s27, s63
	s_cselect_b32 s42, s61, s62
	v_lshl_add_u64 v[172:173], s[40:41], 0, v[136:137]
	s_add_i32 m0, s39, 0xc000
	ds_read_b128 v[160:163], v179
	ds_read_b128 v[164:167], v179 offset:1024
	ds_read_b128 v[168:171], v179 offset:2048
	ds_read_b128 v[182:185], v179 offset:3072
	ds_read_b128 v[186:189], v179 offset:4096
	ds_read_b128 v[190:193], v179 offset:5120
	ds_read_b128 v[194:197], v179 offset:6144
	ds_read_b128 v[198:201], v179 offset:7168
	global_load_lds_dwordx4 v[172:173], off
	s_add_i32 m0, s39, 0xe000
	v_lshl_add_u64 v[172:173], s[40:41], 0, v[138:139]
	global_load_lds_dwordx4 v[172:173], off
	s_waitcnt lgkmcnt(8)
	s_setprio 1
	s_barrier
	s_waitcnt lgkmcnt(0)
	v_mfma_f32_16x16x32_bf16 v[124:127], v[144:147], v[160:163], v[124:127]
	v_mfma_f32_16x16x32_bf16 v[120:123], v[152:155], v[160:163], v[120:123]
	v_mfma_f32_16x16x32_bf16 v[108:111], v[144:147], v[168:171], v[108:111]
	v_mfma_f32_16x16x32_bf16 v[104:107], v[152:155], v[168:171], v[104:107]
	v_mfma_f32_16x16x32_bf16 v[96:99], v[144:147], v[186:189], v[96:99]
	v_mfma_f32_16x16x32_bf16 v[88:91], v[152:155], v[186:189], v[88:91]
	v_mfma_f32_16x16x32_bf16 v[80:83], v[144:147], v[194:197], v[80:83]
	v_mfma_f32_16x16x32_bf16 v[72:75], v[152:155], v[194:197], v[72:75]
	v_mfma_f32_16x16x32_bf16 v[124:127], v[148:151], v[164:167], v[124:127]
	v_mfma_f32_16x16x32_bf16 v[120:123], v[156:159], v[164:167], v[120:123]
	v_mfma_f32_16x16x32_bf16 v[108:111], v[148:151], v[182:185], v[108:111]
	v_mfma_f32_16x16x32_bf16 v[104:107], v[156:159], v[182:185], v[104:107]
	v_mfma_f32_16x16x32_bf16 v[96:99], v[148:151], v[190:193], v[96:99]
	v_mfma_f32_16x16x32_bf16 v[88:91], v[156:159], v[190:193], v[88:91]
	v_mfma_f32_16x16x32_bf16 v[80:83], v[148:151], v[198:201], v[80:83]
	v_mfma_f32_16x16x32_bf16 v[72:75], v[156:159], v[198:201], v[72:75]
	s_barrier
	s_setprio 0
	s_add_i32 s65, s59, s50
	v_lshl_add_u64 v[172:173], s[42:43], 0, v[130:131]
	s_mov_b32 m0, s65
	ds_read_b128 v[202:205], v180
	ds_read_b128 v[206:209], v180 offset:1024
	ds_read_b128 v[212:215], v180 offset:2048
	ds_read_b128 v[216:219], v180 offset:3072
	global_load_lds_dwordx4 v[172:173], off
	s_add_i32 m0, s65, 0x2000
	v_lshl_add_u64 v[220:221], s[42:43], 0, v[134:135]
	global_load_lds_dwordx4 v[220:221], off
	s_setprio 1
	s_barrier
	s_waitcnt lgkmcnt(0)
	v_mfma_f32_16x16x32_bf16 v[116:119], v[202:205], v[160:163], v[116:119]
	v_mfma_f32_16x16x32_bf16 v[112:115], v[212:215], v[160:163], v[112:115]
	v_mfma_f32_16x16x32_bf16 v[100:103], v[202:205], v[168:171], v[100:103]
	v_mfma_f32_16x16x32_bf16 v[92:95], v[212:215], v[168:171], v[92:95]
	v_mfma_f32_16x16x32_bf16 v[84:87], v[202:205], v[186:189], v[84:87]
	v_mfma_f32_16x16x32_bf16 v[76:79], v[212:215], v[186:189], v[76:79]
	v_mfma_f32_16x16x32_bf16 v[68:71], v[202:205], v[194:197], v[68:71]
	v_mfma_f32_16x16x32_bf16 v[64:67], v[212:215], v[194:197], v[64:67]
	v_mfma_f32_16x16x32_bf16 v[116:119], v[206:209], v[164:167], v[116:119]
	v_mfma_f32_16x16x32_bf16 v[112:115], v[216:219], v[164:167], v[112:115]
	v_mfma_f32_16x16x32_bf16 v[100:103], v[206:209], v[182:185], v[100:103]
	v_mfma_f32_16x16x32_bf16 v[92:95], v[216:219], v[182:185], v[92:95]
	v_mfma_f32_16x16x32_bf16 v[84:87], v[206:209], v[190:193], v[84:87]
	v_mfma_f32_16x16x32_bf16 v[76:79], v[216:219], v[190:193], v[76:79]
	v_mfma_f32_16x16x32_bf16 v[68:71], v[206:209], v[198:201], v[68:71]
	v_mfma_f32_16x16x32_bf16 v[64:67], v[216:219], v[198:201], v[64:67]
	s_barrier
	s_setprio 0
	s_mov_b32 m0, s39
	v_lshl_add_u64 v[222:223], s[48:49], 0, v[128:129]
	ds_read_b128 v[160:163], v179 offset:16384
	ds_read_b128 v[164:167], v179 offset:17408
	ds_read_b128 v[168:171], v179 offset:18432
	ds_read_b128 v[182:185], v179 offset:19456
	ds_read_b128 v[186:189], v179 offset:20480
	ds_read_b128 v[190:193], v179 offset:21504
	ds_read_b128 v[194:197], v179 offset:22528
	ds_read_b128 v[198:201], v179 offset:23552
	global_load_lds_dwordx4 v[222:223], off
	s_mov_b32 m0, s51
	v_lshl_add_u64 v[224:225], s[48:49], 0, v[132:133]
	global_load_lds_dwordx4 v[224:225], off
	s_setprio 1
	s_barrier
	s_waitcnt lgkmcnt(0)
	v_mfma_f32_16x16x32_bf16 v[60:63], v[144:147], v[160:163], v[60:63]
	v_mfma_f32_16x16x32_bf16 v[56:59], v[152:155], v[160:163], v[56:59]
	v_mfma_f32_16x16x32_bf16 v[44:47], v[144:147], v[168:171], v[44:47]
	v_mfma_f32_16x16x32_bf16 v[40:43], v[152:155], v[168:171], v[40:43]
	v_mfma_f32_16x16x32_bf16 v[32:35], v[144:147], v[186:189], v[32:35]
	v_mfma_f32_16x16x32_bf16 v[24:27], v[152:155], v[186:189], v[24:27]
	v_mfma_f32_16x16x32_bf16 v[16:19], v[144:147], v[194:197], v[16:19]
	v_mfma_f32_16x16x32_bf16 v[8:11], v[152:155], v[194:197], v[8:11]
	v_mfma_f32_16x16x32_bf16 v[60:63], v[148:151], v[164:167], v[60:63]
	v_mfma_f32_16x16x32_bf16 v[56:59], v[156:159], v[164:167], v[56:59]
	v_mfma_f32_16x16x32_bf16 v[44:47], v[148:151], v[182:185], v[44:47]
	v_mfma_f32_16x16x32_bf16 v[40:43], v[156:159], v[182:185], v[40:43]
	v_mfma_f32_16x16x32_bf16 v[32:35], v[148:151], v[190:193], v[32:35]
	v_mfma_f32_16x16x32_bf16 v[24:27], v[156:159], v[190:193], v[24:27]
	v_mfma_f32_16x16x32_bf16 v[16:19], v[148:151], v[198:201], v[16:19]
	v_mfma_f32_16x16x32_bf16 v[8:11], v[156:159], v[198:201], v[8:11]
	s_barrier
	s_setprio 0
	s_add_u32 s66, s42, 0x40000
	s_addc_u32 s67, s43, 0
	s_add_i32 s65, s60, s50
	s_mov_b32 m0, s65
	v_lshl_add_u64 v[144:145], s[66:67], 0, v[130:131]
	global_load_lds_dwordx4 v[144:145], off
	s_add_i32 m0, s65, 0x2000
	v_lshl_add_u64 v[144:145], s[66:67], 0, v[134:135]
	global_load_lds_dwordx4 v[144:145], off
	s_waitcnt vmcnt(6)
	s_setprio 1
	s_barrier
	v_mfma_f32_16x16x32_bf16 v[52:55], v[202:205], v[160:163], v[52:55]
	v_mfma_f32_16x16x32_bf16 v[48:51], v[212:215], v[160:163], v[48:51]
	v_mfma_f32_16x16x32_bf16 v[36:39], v[202:205], v[168:171], v[36:39]
	v_mfma_f32_16x16x32_bf16 v[28:31], v[212:215], v[168:171], v[28:31]
	v_mfma_f32_16x16x32_bf16 v[20:23], v[202:205], v[186:189], v[20:23]
	v_mfma_f32_16x16x32_bf16 v[12:15], v[212:215], v[186:189], v[12:15]
	v_mfma_f32_16x16x32_bf16 v[4:7], v[202:205], v[194:197], v[4:7]
	v_mfma_f32_16x16x32_bf16 v[0:3], v[212:215], v[194:197], v[0:3]
	v_mfma_f32_16x16x32_bf16 v[52:55], v[206:209], v[164:167], v[52:55]
	v_mfma_f32_16x16x32_bf16 v[48:51], v[216:219], v[164:167], v[48:51]
	v_mfma_f32_16x16x32_bf16 v[36:39], v[206:209], v[182:185], v[36:39]
	v_mfma_f32_16x16x32_bf16 v[28:31], v[216:219], v[182:185], v[28:31]
	v_mfma_f32_16x16x32_bf16 v[20:23], v[206:209], v[190:193], v[20:23]
	v_mfma_f32_16x16x32_bf16 v[12:15], v[216:219], v[190:193], v[12:15]
	v_mfma_f32_16x16x32_bf16 v[4:7], v[206:209], v[198:201], v[4:7]
	v_mfma_f32_16x16x32_bf16 v[0:3], v[216:219], v[198:201], v[0:3]
	s_barrier
	s_setprio 0
	s_add_i32 s65, 0, 0x18000
	v_add_u32_e32 v156, s65, v176
	ds_read_b128 v[144:147], v156
	ds_read_b128 v[148:151], v156 offset:1024
	ds_read_b128 v[152:155], v156 offset:2048
	ds_read_b128 v[156:159], v156 offset:3072
	s_add_u32 s48, s48, 0x40000
	s_addc_u32 s49, s49, 0
	s_mov_b32 m0, s52
	v_lshl_add_u64 v[202:203], s[48:49], 0, v[128:129]
	ds_read_b128 v[160:163], v179 offset:32768
	ds_read_b128 v[164:167], v179 offset:33792
	ds_read_b128 v[168:171], v179 offset:34816
	ds_read_b128 v[182:185], v179 offset:35840
	ds_read_b128 v[186:189], v179 offset:36864
	ds_read_b128 v[190:193], v179 offset:37888
	ds_read_b128 v[194:197], v179 offset:38912
	ds_read_b128 v[198:201], v179 offset:39936
	global_load_lds_dwordx4 v[202:203], off
	s_mov_b32 m0, s53
	v_lshl_add_u64 v[202:203], s[48:49], 0, v[132:133]
	global_load_lds_dwordx4 v[202:203], off
	s_waitcnt lgkmcnt(8)
	s_setprio 1
	s_barrier
	s_waitcnt lgkmcnt(0)
	v_mfma_f32_16x16x32_bf16 v[124:127], v[144:147], v[160:163], v[124:127]
	v_mfma_f32_16x16x32_bf16 v[120:123], v[152:155], v[160:163], v[120:123]
	v_mfma_f32_16x16x32_bf16 v[108:111], v[144:147], v[168:171], v[108:111]
	v_mfma_f32_16x16x32_bf16 v[104:107], v[152:155], v[168:171], v[104:107]
	v_mfma_f32_16x16x32_bf16 v[96:99], v[144:147], v[186:189], v[96:99]
	v_mfma_f32_16x16x32_bf16 v[88:91], v[152:155], v[186:189], v[88:91]
	v_mfma_f32_16x16x32_bf16 v[80:83], v[144:147], v[194:197], v[80:83]
	v_mfma_f32_16x16x32_bf16 v[72:75], v[152:155], v[194:197], v[72:75]
	v_mfma_f32_16x16x32_bf16 v[124:127], v[148:151], v[164:167], v[124:127]
	v_mfma_f32_16x16x32_bf16 v[120:123], v[156:159], v[164:167], v[120:123]
	v_mfma_f32_16x16x32_bf16 v[108:111], v[148:151], v[182:185], v[108:111]
	v_mfma_f32_16x16x32_bf16 v[104:107], v[156:159], v[182:185], v[104:107]
	v_mfma_f32_16x16x32_bf16 v[96:99], v[148:151], v[190:193], v[96:99]
	v_mfma_f32_16x16x32_bf16 v[88:91], v[156:159], v[190:193], v[88:91]
	v_mfma_f32_16x16x32_bf16 v[80:83], v[148:151], v[198:201], v[80:83]
	v_mfma_f32_16x16x32_bf16 v[72:75], v[156:159], v[198:201], v[72:75]
	s_barrier
	s_setprio 0
	s_add_i32 s48, 0, 0x1c000
	s_add_i32 s49, s65, s50
	v_add_u32_e32 v181, s48, v176
	v_lshl_add_u64 v[172:173], v[172:173], 0, s[2:3]
	s_mov_b32 m0, s49
	ds_read_b128 v[202:205], v181
	ds_read_b128 v[206:209], v181 offset:1024
	ds_read_b128 v[212:215], v181 offset:2048
	ds_read_b128 v[216:219], v181 offset:3072
	global_load_lds_dwordx4 v[172:173], off
	s_add_i32 m0, s49, 0x2000
	v_lshl_add_u64 v[172:173], v[220:221], 0, s[2:3]
	global_load_lds_dwordx4 v[172:173], off
	s_setprio 1
	s_barrier
	s_waitcnt lgkmcnt(0)
	v_mfma_f32_16x16x32_bf16 v[116:119], v[202:205], v[160:163], v[116:119]
	v_mfma_f32_16x16x32_bf16 v[112:115], v[212:215], v[160:163], v[112:115]
	v_mfma_f32_16x16x32_bf16 v[100:103], v[202:205], v[168:171], v[100:103]
	v_mfma_f32_16x16x32_bf16 v[92:95], v[212:215], v[168:171], v[92:95]
	v_mfma_f32_16x16x32_bf16 v[84:87], v[202:205], v[186:189], v[84:87]
	v_mfma_f32_16x16x32_bf16 v[76:79], v[212:215], v[186:189], v[76:79]
	v_mfma_f32_16x16x32_bf16 v[68:71], v[202:205], v[194:197], v[68:71]
	v_mfma_f32_16x16x32_bf16 v[64:67], v[212:215], v[194:197], v[64:67]
	v_mfma_f32_16x16x32_bf16 v[116:119], v[206:209], v[164:167], v[116:119]
	v_mfma_f32_16x16x32_bf16 v[112:115], v[216:219], v[164:167], v[112:115]
	v_mfma_f32_16x16x32_bf16 v[100:103], v[206:209], v[182:185], v[100:103]
	v_mfma_f32_16x16x32_bf16 v[92:95], v[216:219], v[182:185], v[92:95]
	v_mfma_f32_16x16x32_bf16 v[84:87], v[206:209], v[190:193], v[84:87]
	v_mfma_f32_16x16x32_bf16 v[76:79], v[216:219], v[190:193], v[76:79]
	v_mfma_f32_16x16x32_bf16 v[68:71], v[206:209], v[198:201], v[68:71]
	v_mfma_f32_16x16x32_bf16 v[64:67], v[216:219], v[198:201], v[64:67]
	s_barrier
	s_setprio 0
	s_mov_b32 m0, s55
	v_lshl_add_u64 v[172:173], v[222:223], 0, s[2:3]
	ds_read_b128 v[160:163], v179 offset:49152
	ds_read_b128 v[164:167], v179 offset:50176
	ds_read_b128 v[168:171], v179 offset:51200
	ds_read_b128 v[182:185], v179 offset:52224
	ds_read_b128 v[186:189], v179 offset:53248
	ds_read_b128 v[190:193], v179 offset:54272
	ds_read_b128 v[194:197], v179 offset:55296
	ds_read_b128 v[198:201], v179 offset:56320
	global_load_lds_dwordx4 v[172:173], off
	s_mov_b32 m0, s56
	v_lshl_add_u64 v[172:173], v[224:225], 0, s[2:3]
	global_load_lds_dwordx4 v[172:173], off
	s_setprio 1
	s_barrier
	s_waitcnt lgkmcnt(0)
	v_mfma_f32_16x16x32_bf16 v[60:63], v[144:147], v[160:163], v[60:63]
	v_mfma_f32_16x16x32_bf16 v[56:59], v[152:155], v[160:163], v[56:59]
	v_mfma_f32_16x16x32_bf16 v[44:47], v[144:147], v[168:171], v[44:47]
	v_mfma_f32_16x16x32_bf16 v[40:43], v[152:155], v[168:171], v[40:43]
	v_mfma_f32_16x16x32_bf16 v[32:35], v[144:147], v[186:189], v[32:35]
	v_mfma_f32_16x16x32_bf16 v[24:27], v[152:155], v[186:189], v[24:27]
	v_mfma_f32_16x16x32_bf16 v[16:19], v[144:147], v[194:197], v[16:19]
	v_mfma_f32_16x16x32_bf16 v[8:11], v[152:155], v[194:197], v[8:11]
	v_mfma_f32_16x16x32_bf16 v[60:63], v[148:151], v[164:167], v[60:63]
	v_mfma_f32_16x16x32_bf16 v[56:59], v[156:159], v[164:167], v[56:59]
	v_mfma_f32_16x16x32_bf16 v[44:47], v[148:151], v[182:185], v[44:47]
	v_mfma_f32_16x16x32_bf16 v[40:43], v[156:159], v[182:185], v[40:43]
	v_mfma_f32_16x16x32_bf16 v[32:35], v[148:151], v[190:193], v[32:35]
	v_mfma_f32_16x16x32_bf16 v[24:27], v[156:159], v[190:193], v[24:27]
	v_mfma_f32_16x16x32_bf16 v[16:19], v[148:151], v[198:201], v[16:19]
	v_mfma_f32_16x16x32_bf16 v[8:11], v[156:159], v[198:201], v[8:11]
	s_barrier
	s_setprio 0
	s_add_u32 s42, s42, 0x40080
	s_addc_u32 s43, s43, 0
	s_add_i32 s48, s48, s50
	s_mov_b32 m0, s48
	v_lshl_add_u64 v[144:145], s[42:43], 0, v[130:131]
	global_load_lds_dwordx4 v[144:145], off
	s_add_i32 m0, s48, 0x2000
	v_lshl_add_u64 v[144:145], s[42:43], 0, v[134:135]
	global_load_lds_dwordx4 v[144:145], off
	s_waitcnt vmcnt(6)
	s_setprio 1
	s_barrier
	v_mfma_f32_16x16x32_bf16 v[52:55], v[202:205], v[160:163], v[52:55]
	v_mfma_f32_16x16x32_bf16 v[48:51], v[212:215], v[160:163], v[48:51]
	v_mfma_f32_16x16x32_bf16 v[36:39], v[202:205], v[168:171], v[36:39]
	v_mfma_f32_16x16x32_bf16 v[28:31], v[212:215], v[168:171], v[28:31]
	v_mfma_f32_16x16x32_bf16 v[20:23], v[202:205], v[186:189], v[20:23]
	v_mfma_f32_16x16x32_bf16 v[12:15], v[212:215], v[186:189], v[12:15]
	v_mfma_f32_16x16x32_bf16 v[4:7], v[202:205], v[194:197], v[4:7]
	v_mfma_f32_16x16x32_bf16 v[0:3], v[212:215], v[194:197], v[0:3]
	v_mfma_f32_16x16x32_bf16 v[52:55], v[206:209], v[164:167], v[52:55]
	v_mfma_f32_16x16x32_bf16 v[48:51], v[216:219], v[164:167], v[48:51]
	v_mfma_f32_16x16x32_bf16 v[36:39], v[206:209], v[182:185], v[36:39]
	v_mfma_f32_16x16x32_bf16 v[28:31], v[216:219], v[182:185], v[28:31]
	v_mfma_f32_16x16x32_bf16 v[20:23], v[206:209], v[190:193], v[20:23]
	v_mfma_f32_16x16x32_bf16 v[12:15], v[216:219], v[190:193], v[12:15]
	v_mfma_f32_16x16x32_bf16 v[4:7], v[206:209], v[198:201], v[4:7]
	v_mfma_f32_16x16x32_bf16 v[0:3], v[216:219], v[198:201], v[0:3]
	s_barrier
	s_setprio 0
	s_add_i32 s64, s64, 2
	s_add_u32 s40, s40, 0x100
	s_addc_u32 s41, s41, 0
	s_add_u32 s62, s62, 0x100
	s_addc_u32 s63, s63, 0
	s_cmp_gt_u32 s64, 13
	s_cbranch_scc0 .LBB0_1022
	v_lshl_or_b32 v144, s38, 8, v177
	v_lshl_add_u32 v150, s36, 8, v175
	v_ashrrev_i32_e32 v145, 31, v144
	v_ashrrev_i32_e32 v151, 31, v150
	v_lshlrev_b64 v[144:145], 1, v[144:145]
	v_lshl_add_u64 v[146:147], s[10:11], 0, v[144:145]
	v_lshlrev_b64 v[148:149], 11, v[150:151]
	v_lshl_add_u64 v[152:153], v[146:147], 0, v[148:149]
	global_load_dwordx4 v[156:159], v[152:153], off
	global_load_dwordx4 v[160:163], v[152:153], off offset:256
	v_or_b32_e32 v152, 16, v150
	v_ashrrev_i32_e32 v153, 31, v152
	v_lshlrev_b64 v[170:171], 11, v[152:153]
	v_lshl_add_u64 v[152:153], v[146:147], 0, v[170:171]
	global_load_dwordx4 v[164:167], v[152:153], off
	global_load_dwordx4 v[182:185], v[152:153], off offset:256
	v_or_b32_e32 v152, 32, v150
	v_ashrrev_i32_e32 v153, 31, v152
	v_lshlrev_b64 v[154:155], 11, v[152:153]
	v_lshl_add_u64 v[152:153], v[146:147], 0, v[154:155]
	global_load_dwordx4 v[186:189], v[152:153], off
	global_load_dwordx4 v[190:193], v[152:153], off offset:256
	v_or_b32_e32 v152, 48, v150
	v_ashrrev_i32_e32 v153, 31, v152
	v_lshlrev_b64 v[152:153], 11, v[152:153]
	v_lshl_add_u64 v[168:169], v[146:147], 0, v[152:153]
	global_load_dwordx4 v[194:197], v[168:169], off
	global_load_dwordx4 v[198:201], v[168:169], off offset:256
	s_waitcnt vmcnt(0)
	v_lshlrev_b32_e32 v202, 16, v156
	v_and_b32_e32 v203, 0xffff0000, v156
	v_lshlrev_b32_e32 v204, 16, v157
	v_and_b32_e32 v205, 0xffff0000, v157
	v_lshlrev_b32_e32 v206, 16, v158
	v_and_b32_e32 v207, 0xffff0000, v158
	v_lshlrev_b32_e32 v208, 16, v159
	v_and_b32_e32 v209, 0xffff0000, v159
	v_pk_add_f32 v[126:127], v[126:127], v[204:205]
	v_pk_add_f32 v[124:125], v[124:125], v[202:203]
	v_lshlrev_b32_e32 v224, 16, v166
	v_and_b32_e32 v225, 0xffff0000, v166
	v_lshlrev_b32_e32 v226, 16, v167
	v_and_b32_e32 v227, 0xffff0000, v167
	v_lshlrev_b32_e32 v212, 16, v160
	v_lshlrev_b32_e32 v166, 16, v194
	v_and_b32_e32 v167, 0xffff0000, v194
	v_lshlrev_b32_e32 v172, 16, v195
	v_and_b32_e32 v173, 0xffff0000, v195
	v_pk_add_f32 v[194:195], v[122:123], v[208:209]
	v_pk_add_f32 v[122:123], v[120:121], v[206:207]
	v_mul_f32_e32 v120, v125, v125
	v_mul_f32_e32 v121, v127, v127
	v_fmac_f32_e32 v120, v124, v124
	v_fmac_f32_e32 v121, v126, v126
	v_add_f32_e32 v120, v120, v121
	v_mul_f32_e32 v121, v123, v123
	v_fmac_f32_e32 v121, v122, v122
	v_add_f32_e32 v120, v121, v120
	v_mul_f32_e32 v121, v195, v195
	v_fmac_f32_e32 v121, v194, v194
	v_and_b32_e32 v213, 0xffff0000, v160
	v_lshlrev_b32_e32 v214, 16, v161
	v_and_b32_e32 v215, 0xffff0000, v161
	v_add_f32_e32 v181, v121, v120
	v_cvt_pk_bf16_f32 v120, v124, v125
	v_lshl_add_u64 v[124:125], s[10:11], 0, v[148:149]
	v_lshlrev_b32_e32 v216, 16, v162
	v_and_b32_e32 v217, 0xffff0000, v162
	v_lshlrev_b32_e32 v218, 16, v163
	v_and_b32_e32 v219, 0xffff0000, v163
	v_cvt_pk_bf16_f32 v121, v126, v127
	v_lshl_add_u64 v[124:125], v[124:125], 0, v[144:145]
	v_pk_add_f32 v[118:119], v[118:119], v[214:215]
	v_pk_add_f32 v[116:117], v[116:117], v[212:213]
	v_cvt_pk_bf16_f32 v122, v122, v123
	v_cvt_pk_bf16_f32 v123, v194, v195
	global_store_dwordx4 v[124:125], v[120:123], off
	v_lshlrev_b32_e32 v220, 16, v164
	v_and_b32_e32 v221, 0xffff0000, v164
	v_pk_add_f32 v[120:121], v[114:115], v[218:219]
	v_pk_add_f32 v[114:115], v[112:113], v[216:217]
	v_mul_f32_e32 v112, v117, v117
	v_mul_f32_e32 v113, v119, v119
	v_fmac_f32_e32 v112, v116, v116
	v_fmac_f32_e32 v113, v118, v118
	v_add_f32_e32 v112, v112, v113
	v_mul_f32_e32 v113, v115, v115
	v_fmac_f32_e32 v113, v114, v114
	v_add_f32_e32 v112, v113, v112
	v_mul_f32_e32 v113, v121, v121
	v_fmac_f32_e32 v113, v120, v120
	v_add_f32_e32 v112, v113, v112
	v_lshlrev_b32_e32 v222, 16, v165
	v_and_b32_e32 v223, 0xffff0000, v165
	v_add_f32_e32 v126, v181, v112
	v_cvt_pk_bf16_f32 v112, v116, v117
	v_cvt_pk_bf16_f32 v113, v118, v119
	v_lshl_add_u64 v[116:117], s[10:11], 0, v[170:171]
	v_lshlrev_b32_e32 v230, 16, v184
	v_and_b32_e32 v231, 0xffff0000, v184
	v_lshlrev_b32_e32 v232, 16, v186
	v_and_b32_e32 v233, 0xffff0000, v186
	v_lshlrev_b32_e32 v186, 16, v187
	v_and_b32_e32 v187, 0xffff0000, v187
	v_cvt_pk_bf16_f32 v114, v114, v115
	v_cvt_pk_bf16_f32 v115, v120, v121
	global_store_dwordx4 v[124:125], v[112:115], off offset:256
	v_pk_add_f32 v[110:111], v[110:111], v[222:223]
	v_pk_add_f32 v[108:109], v[108:109], v[220:221]
	v_lshl_add_u64 v[118:119], v[116:117], 0, v[144:145]
	v_cvt_pk_bf16_f32 v112, v108, v109
	v_cvt_pk_bf16_f32 v113, v110, v111
	v_lshlrev_b32_e32 v228, 16, v182
	v_and_b32_e32 v229, 0xffff0000, v182
	v_lshlrev_b32_e32 v182, 16, v183
	v_and_b32_e32 v183, 0xffff0000, v183
	v_lshlrev_b32_e32 v184, 16, v185
	v_and_b32_e32 v185, 0xffff0000, v185
	v_lshlrev_b32_e32 v238, 16, v192
	v_and_b32_e32 v239, 0xffff0000, v192
	v_pk_add_f32 v[106:107], v[106:107], v[226:227]
	v_pk_add_f32 v[104:105], v[104:105], v[224:225]
	v_lshlrev_b32_e32 v156, 16, v200
	v_cvt_pk_bf16_f32 v114, v104, v105
	v_cvt_pk_bf16_f32 v115, v106, v107
	global_store_dwordx4 v[118:119], v[112:115], off
	v_and_b32_e32 v157, 0xffff0000, v200
	v_pk_add_f32 v[102:103], v[102:103], v[182:183]
	v_pk_add_f32 v[112:113], v[92:93], v[230:231]
	v_pk_add_f32 v[92:93], v[98:99], v[186:187]
	v_lshl_add_u64 v[98:99], s[10:11], 0, v[154:155]
	v_pk_add_f32 v[100:101], v[100:101], v[228:229]
	v_pk_add_f32 v[94:95], v[94:95], v[184:185]
	v_cvt_pk_bf16_f32 v114, v100, v101
	v_cvt_pk_bf16_f32 v115, v102, v103
	v_cvt_pk_bf16_f32 v116, v112, v113
	v_lshlrev_b32_e32 v234, 16, v188
	v_cvt_pk_bf16_f32 v117, v94, v95
	global_store_dwordx4 v[118:119], v[114:117], off offset:256
	v_lshl_add_u64 v[118:119], v[98:99], 0, v[144:145]
	v_pk_add_f32 v[98:99], v[76:77], v[238:239]
	v_pk_add_f32 v[76:77], v[82:83], v[172:173]
	v_lshl_add_u64 v[82:83], s[10:11], 0, v[152:153]
	v_lshl_add_u64 v[122:123], v[82:83], 0, v[144:145]
	v_pk_add_f32 v[82:83], v[64:65], v[156:157]
	v_and_b32_e32 v65, 64, v174
	v_and_b32_e32 v235, 0xffff0000, v188
	v_lshlrev_b32_e32 v188, 16, v189
	v_and_b32_e32 v189, 0xffff0000, v189
	v_lshlrev_b32_e32 v236, 16, v190
	v_and_b32_e32 v237, 0xffff0000, v190
	v_pk_add_f32 v[96:97], v[96:97], v[232:233]
	v_xor_b32_e32 v64, 16, v174
	v_cvt_pk_bf16_f32 v114, v96, v97
	v_add_u32_e32 v65, 64, v65
	v_lshlrev_b32_e32 v190, 16, v191
	v_and_b32_e32 v191, 0xffff0000, v191
	v_lshlrev_b32_e32 v192, 16, v193
	v_and_b32_e32 v193, 0xffff0000, v193
	v_pk_add_f32 v[90:91], v[90:91], v[188:189]
	v_pk_add_f32 v[88:89], v[88:89], v[234:235]
	v_cvt_pk_bf16_f32 v115, v92, v93
	v_pk_add_f32 v[84:85], v[84:85], v[236:237]
	v_cvt_pk_bf16_f32 v116, v88, v89
	v_cvt_pk_bf16_f32 v117, v90, v91
	global_store_dwordx4 v[118:119], v[114:117], off
	v_cmp_lt_i32_e32 vcc, v64, v65
	v_lshlrev_b32_e32 v164, 16, v196
	v_cvt_pk_bf16_f32 v114, v84, v85
	v_and_b32_e32 v165, 0xffff0000, v196
	v_lshlrev_b32_e32 v168, 16, v197
	v_and_b32_e32 v169, 0xffff0000, v197
	v_pk_add_f32 v[86:87], v[86:87], v[190:191]
	v_pk_add_f32 v[78:79], v[78:79], v[192:193]
	v_cvt_pk_bf16_f32 v115, v86, v87
	v_cvt_pk_bf16_f32 v116, v98, v99
	v_pk_add_f32 v[80:81], v[80:81], v[166:167]
	v_cvt_pk_bf16_f32 v117, v78, v79
	global_store_dwordx4 v[118:119], v[114:117], off offset:256
	v_cndmask_b32_e32 v64, v174, v64, vcc
	v_pk_add_f32 v[74:75], v[74:75], v[168:169]
	v_cvt_pk_bf16_f32 v114, v80, v81
	v_pk_add_f32 v[72:73], v[72:73], v[164:165]
	v_cvt_pk_bf16_f32 v115, v76, v77
	v_lshlrev_b32_e32 v158, 16, v198
	v_cvt_pk_bf16_f32 v116, v72, v73
	v_cvt_pk_bf16_f32 v117, v74, v75
	global_store_dwordx4 v[122:123], v[114:117], off
	v_and_b32_e32 v159, 0xffff0000, v198
	v_lshlrev_b32_e32 v162, 16, v199
	v_lshlrev_b32_e32 v114, 2, v64
	ds_bpermute_b32 v64, v114, v126
	v_xor_b32_e32 v115, 32, v174
	v_cmp_lt_i32_e32 vcc, v115, v65
	v_and_b32_e32 v163, 0xffff0000, v199
	v_lshlrev_b32_e32 v160, 16, v201
	v_cndmask_b32_e32 v65, v174, v115, vcc
	v_lshlrev_b32_e32 v115, 2, v65
	s_waitcnt lgkmcnt(0)
	v_add_f32_e32 v116, v126, v64
	ds_bpermute_b32 v117, v115, v116
	v_and_b32_e32 v161, 0xffff0000, v201
	v_pk_add_f32 v[70:71], v[70:71], v[162:163]
	v_pk_add_f32 v[68:69], v[68:69], v[158:159]
	v_pk_add_f32 v[66:67], v[66:67], v[160:161]
	v_lshl_add_u64 v[64:65], v[150:151], 2, s[18:19]
	v_cvt_pk_bf16_f32 v118, v68, v69
	v_cvt_pk_bf16_f32 v119, v70, v71
	v_cvt_pk_bf16_f32 v120, v82, v83
	v_cvt_pk_bf16_f32 v121, v66, v67
	global_store_dwordx4 v[122:123], v[118:121], off offset:256
	s_and_saveexec_b64 s[36:37], s[6:7]
	s_cbranch_execz .LBB0_1025
	s_waitcnt lgkmcnt(0)
	v_add_f32_e32 v116, v116, v117
	global_atomic_add_f32 v[64:65], v116, off

.LBB0_1080:
	ds_read_b128 v[144:147], v151
	ds_read_b128 v[156:159], v151 offset:1024
	ds_read_b128 v[160:163], v151 offset:2048
	ds_read_b128 v[164:167], v151 offset:3072
	s_add_u32 s36, s2, 0xfffc0080
	s_addc_u32 s37, s3, -1
	s_cmp_eq_u32 s67, 12
	s_cselect_b32 s39, s29, s37
	s_cselect_b32 s38, s63, s36
	s_cselect_b32 s37, s27, s66
	s_cselect_b32 s36, s64, s65
	v_lshl_add_u64 v[172:173], s[2:3], 0, v[136:137]
	s_add_i32 m0, s48, 0xc000
	ds_read_b128 v[168:171], v152
	ds_read_b128 v[176:179], v152 offset:1024
	ds_read_b128 v[180:183], v152 offset:2048
	ds_read_b128 v[184:187], v152 offset:3072
	ds_read_b128 v[188:191], v152 offset:4096
	ds_read_b128 v[192:195], v152 offset:5120
	ds_read_b128 v[196:199], v152 offset:6144
	ds_read_b128 v[200:203], v152 offset:7168
	global_load_lds_dwordx4 v[172:173], off
	s_add_i32 m0, s48, 0xe000
	v_lshl_add_u64 v[172:173], s[2:3], 0, v[138:139]
	global_load_lds_dwordx4 v[172:173], off
	s_waitcnt lgkmcnt(8)
	s_setprio 1
	s_barrier
	s_waitcnt lgkmcnt(0)
	v_mfma_f32_16x16x32_bf16 v[124:127], v[144:147], v[168:171], v[124:127]
	v_mfma_f32_16x16x32_bf16 v[120:123], v[160:163], v[168:171], v[120:123]
	v_mfma_f32_16x16x32_bf16 v[116:119], v[144:147], v[180:183], v[116:119]
	v_mfma_f32_16x16x32_bf16 v[112:115], v[160:163], v[180:183], v[112:115]
	v_mfma_f32_16x16x32_bf16 v[104:107], v[144:147], v[188:191], v[104:107]
	v_mfma_f32_16x16x32_bf16 v[96:99], v[160:163], v[188:191], v[96:99]
	v_mfma_f32_16x16x32_bf16 v[76:79], v[144:147], v[196:199], v[76:79]
	v_mfma_f32_16x16x32_bf16 v[72:75], v[160:163], v[196:199], v[72:75]
	v_mfma_f32_16x16x32_bf16 v[124:127], v[156:159], v[176:179], v[124:127]
	v_mfma_f32_16x16x32_bf16 v[120:123], v[164:167], v[176:179], v[120:123]
	v_mfma_f32_16x16x32_bf16 v[116:119], v[156:159], v[184:187], v[116:119]
	v_mfma_f32_16x16x32_bf16 v[112:115], v[164:167], v[184:187], v[112:115]
	v_mfma_f32_16x16x32_bf16 v[104:107], v[156:159], v[192:195], v[104:107]
	v_mfma_f32_16x16x32_bf16 v[96:99], v[164:167], v[192:195], v[96:99]
	v_mfma_f32_16x16x32_bf16 v[76:79], v[156:159], v[200:203], v[76:79]
	v_mfma_f32_16x16x32_bf16 v[72:75], v[164:167], v[200:203], v[72:75]
	s_barrier
	s_setprio 0
	s_add_i32 s68, s56, s43
	v_lshl_add_u64 v[172:173], s[36:37], 0, v[130:131]
	s_mov_b32 m0, s68
	ds_read_b128 v[204:207], v153
	ds_read_b128 v[212:215], v153 offset:1024
	ds_read_b128 v[216:219], v153 offset:2048
	ds_read_b128 v[220:223], v153 offset:3072
	global_load_lds_dwordx4 v[172:173], off
	s_add_i32 m0, s68, 0x2000
	v_lshl_add_u64 v[208:209], s[36:37], 0, v[134:135]
	global_load_lds_dwordx4 v[208:209], off
	s_setprio 1
	s_barrier
	s_waitcnt lgkmcnt(0)
	v_mfma_f32_16x16x32_bf16 v[108:111], v[204:207], v[168:171], v[108:111]
	v_mfma_f32_16x16x32_bf16 v[100:103], v[216:219], v[168:171], v[100:103]
	v_mfma_f32_16x16x32_bf16 v[92:95], v[204:207], v[180:183], v[92:95]
	v_mfma_f32_16x16x32_bf16 v[88:91], v[216:219], v[180:183], v[88:91]
	v_mfma_f32_16x16x32_bf16 v[84:87], v[204:207], v[188:191], v[84:87]
	v_mfma_f32_16x16x32_bf16 v[80:83], v[216:219], v[188:191], v[80:83]
	v_mfma_f32_16x16x32_bf16 v[68:71], v[204:207], v[196:199], v[68:71]
	v_mfma_f32_16x16x32_bf16 v[64:67], v[216:219], v[196:199], v[64:67]
	v_mfma_f32_16x16x32_bf16 v[108:111], v[212:215], v[176:179], v[108:111]
	v_mfma_f32_16x16x32_bf16 v[100:103], v[220:223], v[176:179], v[100:103]
	v_mfma_f32_16x16x32_bf16 v[92:95], v[212:215], v[184:187], v[92:95]
	v_mfma_f32_16x16x32_bf16 v[88:91], v[220:223], v[184:187], v[88:91]
	v_mfma_f32_16x16x32_bf16 v[84:87], v[212:215], v[192:195], v[84:87]
	v_mfma_f32_16x16x32_bf16 v[80:83], v[220:223], v[192:195], v[80:83]
	v_mfma_f32_16x16x32_bf16 v[68:71], v[212:215], v[200:203], v[68:71]
	v_mfma_f32_16x16x32_bf16 v[64:67], v[220:223], v[200:203], v[64:67]
	s_barrier
	s_setprio 0
	s_mov_b32 m0, s48
	v_lshl_add_u64 v[224:225], s[38:39], 0, v[128:129]
	ds_read_b128 v[168:171], v152 offset:16384
	ds_read_b128 v[176:179], v152 offset:17408
	ds_read_b128 v[180:183], v152 offset:18432
	ds_read_b128 v[184:187], v152 offset:19456
	ds_read_b128 v[188:191], v152 offset:20480
	ds_read_b128 v[192:195], v152 offset:21504
	ds_read_b128 v[196:199], v152 offset:22528
	ds_read_b128 v[200:203], v152 offset:23552
	global_load_lds_dwordx4 v[224:225], off
	s_mov_b32 m0, s49
	v_lshl_add_u64 v[226:227], s[38:39], 0, v[132:133]
	global_load_lds_dwordx4 v[226:227], off
	s_setprio 1
	s_barrier
	s_waitcnt lgkmcnt(0)
	v_mfma_f32_16x16x32_bf16 v[60:63], v[144:147], v[168:171], v[60:63]
	v_mfma_f32_16x16x32_bf16 v[56:59], v[160:163], v[168:171], v[56:59]
	v_mfma_f32_16x16x32_bf16 v[44:47], v[144:147], v[180:183], v[44:47]
	v_mfma_f32_16x16x32_bf16 v[40:43], v[160:163], v[180:183], v[40:43]
	v_mfma_f32_16x16x32_bf16 v[28:31], v[144:147], v[188:191], v[28:31]
	v_mfma_f32_16x16x32_bf16 v[24:27], v[160:163], v[188:191], v[24:27]
	v_mfma_f32_16x16x32_bf16 v[12:15], v[144:147], v[196:199], v[12:15]
	v_mfma_f32_16x16x32_bf16 v[8:11], v[160:163], v[196:199], v[8:11]
	v_mfma_f32_16x16x32_bf16 v[60:63], v[156:159], v[176:179], v[60:63]
	v_mfma_f32_16x16x32_bf16 v[56:59], v[164:167], v[176:179], v[56:59]
	v_mfma_f32_16x16x32_bf16 v[44:47], v[156:159], v[184:187], v[44:47]
	v_mfma_f32_16x16x32_bf16 v[40:43], v[164:167], v[184:187], v[40:43]
	v_mfma_f32_16x16x32_bf16 v[28:31], v[156:159], v[192:195], v[28:31]
	v_mfma_f32_16x16x32_bf16 v[24:27], v[164:167], v[192:195], v[24:27]
	v_mfma_f32_16x16x32_bf16 v[12:15], v[156:159], v[200:203], v[12:15]
	v_mfma_f32_16x16x32_bf16 v[8:11], v[164:167], v[200:203], v[8:11]
	s_barrier
	s_setprio 0
	s_add_u32 s68, s36, 0x40000
	s_addc_u32 s69, s37, 0
	s_add_i32 s70, s57, s43
	s_mov_b32 m0, s70
	v_lshl_add_u64 v[144:145], s[68:69], 0, v[130:131]
	global_load_lds_dwordx4 v[144:145], off
	s_add_i32 m0, s70, 0x2000
	v_lshl_add_u64 v[144:145], s[68:69], 0, v[134:135]
	global_load_lds_dwordx4 v[144:145], off
	s_waitcnt vmcnt(6)
	s_setprio 1
	s_barrier
	v_mfma_f32_16x16x32_bf16 v[52:55], v[204:207], v[168:171], v[52:55]
	v_mfma_f32_16x16x32_bf16 v[48:51], v[216:219], v[168:171], v[48:51]
	v_mfma_f32_16x16x32_bf16 v[36:39], v[204:207], v[180:183], v[36:39]
	v_mfma_f32_16x16x32_bf16 v[32:35], v[216:219], v[180:183], v[32:35]
	v_mfma_f32_16x16x32_bf16 v[20:23], v[204:207], v[188:191], v[20:23]
	v_mfma_f32_16x16x32_bf16 v[16:19], v[216:219], v[188:191], v[16:19]
	v_mfma_f32_16x16x32_bf16 v[4:7], v[204:207], v[196:199], v[4:7]
	v_mfma_f32_16x16x32_bf16 v[0:3], v[216:219], v[196:199], v[0:3]
	v_mfma_f32_16x16x32_bf16 v[52:55], v[212:215], v[176:179], v[52:55]
	v_mfma_f32_16x16x32_bf16 v[48:51], v[220:223], v[176:179], v[48:51]
	v_mfma_f32_16x16x32_bf16 v[36:39], v[212:215], v[184:187], v[36:39]
	v_mfma_f32_16x16x32_bf16 v[32:35], v[220:223], v[184:187], v[32:35]
	v_mfma_f32_16x16x32_bf16 v[20:23], v[212:215], v[192:195], v[20:23]
	v_mfma_f32_16x16x32_bf16 v[16:19], v[220:223], v[192:195], v[16:19]
	v_mfma_f32_16x16x32_bf16 v[4:7], v[212:215], v[200:203], v[4:7]
	v_mfma_f32_16x16x32_bf16 v[0:3], v[220:223], v[200:203], v[0:3]
	s_barrier
	s_setprio 0
	s_add_i32 s68, 0, 0x18000
	v_add_u32_e32 v155, s68, v149
	ds_read_b128 v[144:147], v155
	ds_read_b128 v[156:159], v155 offset:1024
	ds_read_b128 v[160:163], v155 offset:2048
	ds_read_b128 v[164:167], v155 offset:3072
	s_add_u32 s38, s38, 0x40000
	s_addc_u32 s39, s39, 0
	s_mov_b32 m0, s50
	v_lshl_add_u64 v[204:205], s[38:39], 0, v[128:129]
	ds_read_b128 v[168:171], v152 offset:32768
	ds_read_b128 v[176:179], v152 offset:33792
	ds_read_b128 v[180:183], v152 offset:34816
	ds_read_b128 v[184:187], v152 offset:35840
	ds_read_b128 v[188:191], v152 offset:36864
	ds_read_b128 v[192:195], v152 offset:37888
	ds_read_b128 v[196:199], v152 offset:38912
	ds_read_b128 v[200:203], v152 offset:39936
	global_load_lds_dwordx4 v[204:205], off
	s_mov_b32 m0, s51
	v_lshl_add_u64 v[204:205], s[38:39], 0, v[132:133]
	global_load_lds_dwordx4 v[204:205], off
	s_waitcnt lgkmcnt(8)
	s_setprio 1
	s_barrier
	s_waitcnt lgkmcnt(0)
	v_mfma_f32_16x16x32_bf16 v[124:127], v[144:147], v[168:171], v[124:127]
	v_mfma_f32_16x16x32_bf16 v[120:123], v[160:163], v[168:171], v[120:123]
	v_mfma_f32_16x16x32_bf16 v[116:119], v[144:147], v[180:183], v[116:119]
	v_mfma_f32_16x16x32_bf16 v[112:115], v[160:163], v[180:183], v[112:115]
	v_mfma_f32_16x16x32_bf16 v[104:107], v[144:147], v[188:191], v[104:107]
	v_mfma_f32_16x16x32_bf16 v[96:99], v[160:163], v[188:191], v[96:99]
	v_mfma_f32_16x16x32_bf16 v[76:79], v[144:147], v[196:199], v[76:79]
	v_mfma_f32_16x16x32_bf16 v[72:75], v[160:163], v[196:199], v[72:75]
	v_mfma_f32_16x16x32_bf16 v[124:127], v[156:159], v[176:179], v[124:127]
	v_mfma_f32_16x16x32_bf16 v[120:123], v[164:167], v[176:179], v[120:123]
	v_mfma_f32_16x16x32_bf16 v[116:119], v[156:159], v[184:187], v[116:119]
	v_mfma_f32_16x16x32_bf16 v[112:115], v[164:167], v[184:187], v[112:115]
	v_mfma_f32_16x16x32_bf16 v[104:107], v[156:159], v[192:195], v[104:107]
	v_mfma_f32_16x16x32_bf16 v[96:99], v[164:167], v[192:195], v[96:99]
	v_mfma_f32_16x16x32_bf16 v[76:79], v[156:159], v[200:203], v[76:79]
	v_mfma_f32_16x16x32_bf16 v[72:75], v[164:167], v[200:203], v[72:75]
	s_barrier
	s_setprio 0
	s_add_i32 s38, 0, 0x1c000
	s_add_i32 s39, s68, s43
	v_add_u32_e32 v155, s38, v149
	v_lshl_add_u64 v[172:173], v[172:173], 0, s[8:9]
	s_mov_b32 m0, s39
	ds_read_b128 v[204:207], v155
	ds_read_b128 v[212:215], v155 offset:1024
	ds_read_b128 v[216:219], v155 offset:2048
	ds_read_b128 v[220:223], v155 offset:3072
	global_load_lds_dwordx4 v[172:173], off
	s_add_i32 m0, s39, 0x2000
	v_lshl_add_u64 v[172:173], v[208:209], 0, s[8:9]
	global_load_lds_dwordx4 v[172:173], off
	s_setprio 1
	s_barrier
	s_waitcnt lgkmcnt(0)
	v_mfma_f32_16x16x32_bf16 v[108:111], v[204:207], v[168:171], v[108:111]
	v_mfma_f32_16x16x32_bf16 v[100:103], v[216:219], v[168:171], v[100:103]
	v_mfma_f32_16x16x32_bf16 v[92:95], v[204:207], v[180:183], v[92:95]
	v_mfma_f32_16x16x32_bf16 v[88:91], v[216:219], v[180:183], v[88:91]
	v_mfma_f32_16x16x32_bf16 v[84:87], v[204:207], v[188:191], v[84:87]
	v_mfma_f32_16x16x32_bf16 v[80:83], v[216:219], v[188:191], v[80:83]
	v_mfma_f32_16x16x32_bf16 v[68:71], v[204:207], v[196:199], v[68:71]
	v_mfma_f32_16x16x32_bf16 v[64:67], v[216:219], v[196:199], v[64:67]
	v_mfma_f32_16x16x32_bf16 v[108:111], v[212:215], v[176:179], v[108:111]
	v_mfma_f32_16x16x32_bf16 v[100:103], v[220:223], v[176:179], v[100:103]
	v_mfma_f32_16x16x32_bf16 v[92:95], v[212:215], v[184:187], v[92:95]
	v_mfma_f32_16x16x32_bf16 v[88:91], v[220:223], v[184:187], v[88:91]
	v_mfma_f32_16x16x32_bf16 v[84:87], v[212:215], v[192:195], v[84:87]
	v_mfma_f32_16x16x32_bf16 v[80:83], v[220:223], v[192:195], v[80:83]
	v_mfma_f32_16x16x32_bf16 v[68:71], v[212:215], v[200:203], v[68:71]
	v_mfma_f32_16x16x32_bf16 v[64:67], v[220:223], v[200:203], v[64:67]
	s_barrier
	s_setprio 0
	s_mov_b32 m0, s53
	v_lshl_add_u64 v[172:173], v[224:225], 0, s[8:9]
	ds_read_b128 v[168:171], v152 offset:49152
	ds_read_b128 v[176:179], v152 offset:50176
	ds_read_b128 v[180:183], v152 offset:51200
	ds_read_b128 v[184:187], v152 offset:52224
	ds_read_b128 v[188:191], v152 offset:53248
	ds_read_b128 v[192:195], v152 offset:54272
	ds_read_b128 v[196:199], v152 offset:55296
	ds_read_b128 v[200:203], v152 offset:56320
	global_load_lds_dwordx4 v[172:173], off
	s_mov_b32 m0, s54
	v_lshl_add_u64 v[172:173], v[226:227], 0, s[8:9]
	global_load_lds_dwordx4 v[172:173], off
	s_setprio 1
	s_barrier
	s_waitcnt lgkmcnt(0)
	v_mfma_f32_16x16x32_bf16 v[60:63], v[144:147], v[168:171], v[60:63]
	v_mfma_f32_16x16x32_bf16 v[56:59], v[160:163], v[168:171], v[56:59]
	v_mfma_f32_16x16x32_bf16 v[44:47], v[144:147], v[180:183], v[44:47]
	v_mfma_f32_16x16x32_bf16 v[40:43], v[160:163], v[180:183], v[40:43]
	v_mfma_f32_16x16x32_bf16 v[28:31], v[144:147], v[188:191], v[28:31]
	v_mfma_f32_16x16x32_bf16 v[24:27], v[160:163], v[188:191], v[24:27]
	v_mfma_f32_16x16x32_bf16 v[12:15], v[144:147], v[196:199], v[12:15]
	v_mfma_f32_16x16x32_bf16 v[8:11], v[160:163], v[196:199], v[8:11]
	v_mfma_f32_16x16x32_bf16 v[60:63], v[156:159], v[176:179], v[60:63]
	v_mfma_f32_16x16x32_bf16 v[56:59], v[164:167], v[176:179], v[56:59]
	v_mfma_f32_16x16x32_bf16 v[44:47], v[156:159], v[184:187], v[44:47]
	v_mfma_f32_16x16x32_bf16 v[40:43], v[164:167], v[184:187], v[40:43]
	v_mfma_f32_16x16x32_bf16 v[28:31], v[156:159], v[192:195], v[28:31]
	v_mfma_f32_16x16x32_bf16 v[24:27], v[164:167], v[192:195], v[24:27]
	v_mfma_f32_16x16x32_bf16 v[12:15], v[156:159], v[200:203], v[12:15]
	v_mfma_f32_16x16x32_bf16 v[8:11], v[164:167], v[200:203], v[8:11]
	s_barrier
	s_setprio 0
	s_add_u32 s36, s36, 0x40080
	s_addc_u32 s37, s37, 0
	s_add_i32 s38, s38, s43
	s_mov_b32 m0, s38
	v_lshl_add_u64 v[144:145], s[36:37], 0, v[130:131]
	global_load_lds_dwordx4 v[144:145], off
	s_add_i32 m0, s38, 0x2000
	v_lshl_add_u64 v[144:145], s[36:37], 0, v[134:135]
	global_load_lds_dwordx4 v[144:145], off
	s_waitcnt vmcnt(6)
	s_setprio 1
	s_barrier
	v_mfma_f32_16x16x32_bf16 v[52:55], v[204:207], v[168:171], v[52:55]
	v_mfma_f32_16x16x32_bf16 v[48:51], v[216:219], v[168:171], v[48:51]
	v_mfma_f32_16x16x32_bf16 v[36:39], v[204:207], v[180:183], v[36:39]
	v_mfma_f32_16x16x32_bf16 v[32:35], v[216:219], v[180:183], v[32:35]
	v_mfma_f32_16x16x32_bf16 v[20:23], v[204:207], v[188:191], v[20:23]
	v_mfma_f32_16x16x32_bf16 v[16:19], v[216:219], v[188:191], v[16:19]
	v_mfma_f32_16x16x32_bf16 v[4:7], v[204:207], v[196:199], v[4:7]
	v_mfma_f32_16x16x32_bf16 v[0:3], v[216:219], v[196:199], v[0:3]
	v_mfma_f32_16x16x32_bf16 v[52:55], v[212:215], v[176:179], v[52:55]
	v_mfma_f32_16x16x32_bf16 v[48:51], v[220:223], v[176:179], v[48:51]
	v_mfma_f32_16x16x32_bf16 v[36:39], v[212:215], v[184:187], v[36:39]
	v_mfma_f32_16x16x32_bf16 v[32:35], v[220:223], v[184:187], v[32:35]
	v_mfma_f32_16x16x32_bf16 v[20:23], v[212:215], v[192:195], v[20:23]
	v_mfma_f32_16x16x32_bf16 v[16:19], v[220:223], v[192:195], v[16:19]
	v_mfma_f32_16x16x32_bf16 v[4:7], v[212:215], v[200:203], v[4:7]
	v_mfma_f32_16x16x32_bf16 v[0:3], v[220:223], v[200:203], v[0:3]
	s_barrier
	s_setprio 0
	s_add_i32 s67, s67, 2
	s_add_u32 s2, s2, 0x100
	s_addc_u32 s3, s3, 0
	s_add_u32 s65, s65, 0x100
	s_addc_u32 s66, s66, 0
	s_cmp_gt_u32 s67, 13
	s_cbranch_scc0 .LBB0_1080
	v_lshl_add_u32 v146, s0, 8, v148
	v_ashrrev_i32_e32 v147, 31, v146
	v_lshl_add_u64 v[144:145], v[146:147], 2, s[18:19]
	global_load_dword v155, v[144:145], off
	global_load_dword v164, v[144:145], off offset:64
	global_load_dword v165, v[144:145], off offset:128
	global_load_dword v166, v[144:145], off offset:192
	global_load_dword v167, v[144:145], off offset:512
	global_load_dword v168, v[144:145], off offset:576
	global_load_dword v169, v[144:145], off offset:640
	global_load_dword v170, v[144:145], off offset:704
	v_lshl_or_b32 v144, s1, 8, v150
	v_ashrrev_i32_e32 v145, 31, v144
	v_lshlrev_b64 v[160:161], 10, v[146:147]
	v_lshlrev_b64 v[162:163], 1, v[144:145]
	v_lshl_add_u64 v[144:145], s[92:93], 0, v[160:161]
	v_or_b32_e32 v156, 16, v146
	v_ashrrev_i32_e32 v157, 31, v156
	v_or_b32_e32 v158, 32, v146
	v_lshlrev_b64 v[156:157], 10, v[156:157]
	v_lshl_add_u64 v[144:145], v[144:145], 0, v[162:163]
	v_ashrrev_i32_e32 v159, 31, v158
	v_lshl_add_u64 v[156:157], s[92:93], 0, v[156:157]
	v_lshlrev_b64 v[158:159], 10, v[158:159]
	v_lshl_add_u64 v[156:157], v[156:157], 0, v[162:163]
	v_lshl_add_u64 v[158:159], s[92:93], 0, v[158:159]
	v_lshl_add_u64 v[158:159], v[158:159], 0, v[162:163]
	s_mov_b64 s[36:37], s[34:35]
	s_waitcnt vmcnt(0)
	v_fmamk_f32 v147, v155, 0x3a800000, v154
	v_fmamk_f32 v155, v164, 0x3a800000, v154
	v_fmamk_f32 v160, v165, 0x3a800000, v154
	v_mul_f32_e32 v161, 0x4b800000, v147
	v_mul_f32_e32 v164, 0x4b800000, v155
	v_cmp_gt_f32_e32 vcc, s58, v147
	v_cmp_gt_f32_e64 s[0:1], s58, v155
	v_mul_f32_e32 v165, 0x4b800000, v160
	v_cndmask_b32_e32 v147, v147, v161, vcc
	v_cndmask_b32_e64 v155, v155, v164, s[0:1]
	v_cmp_gt_f32_e64 s[2:3], s58, v160
	v_rsq_f32_e32 v147, v147
	v_rsq_f32_e32 v155, v155
	v_cndmask_b32_e64 v160, v160, v165, s[2:3]
	v_rsq_f32_e32 v160, v160
	v_mul_f32_e32 v161, 0x45800000, v147
	v_mul_f32_e32 v164, 0x45800000, v155
	v_cndmask_b32_e32 v147, v147, v161, vcc
	v_mul_f32_e32 v165, 0x45800000, v160
	v_cndmask_b32_e64 v155, v155, v164, s[0:1]
	v_cndmask_b32_e64 v161, v160, v165, s[2:3]
	v_mul_f32_e32 v160, 0x3e0293ee, v147
	v_mul_f32_e32 v164, 0x3e0293ee, v155
	v_fmamk_f32 v171, v166, 0x3a800000, v154
	v_mul_f32_e32 v166, 0x3e0293ee, v161
	v_pk_mul_f32 v[126:127], v[126:127], v[160:161] op_sel_hi:[1,0]
	v_pk_mul_f32 v[124:125], v[124:125], v[160:161] op_sel_hi:[1,0]
	v_pk_mul_f32 v[122:123], v[122:123], v[160:161] op_sel_hi:[1,0]
	v_pk_mul_f32 v[120:121], v[120:121], v[160:161] op_sel_hi:[1,0]
	v_pk_mul_f32 v[110:111], v[110:111], v[160:161] op_sel_hi:[1,0]
	v_pk_mul_f32 v[108:109], v[108:109], v[160:161] op_sel_hi:[1,0]
	v_pk_mul_f32 v[102:103], v[102:103], v[160:161] op_sel_hi:[1,0]
	v_pk_mul_f32 v[100:101], v[100:101], v[160:161] op_sel_hi:[1,0]
	v_pk_mul_f32 v[118:119], v[118:119], v[164:165] op_sel_hi:[1,0]
	v_pk_mul_f32 v[116:117], v[116:117], v[164:165] op_sel_hi:[1,0]
	v_pk_mul_f32 v[114:115], v[114:115], v[164:165] op_sel_hi:[1,0]
	v_pk_mul_f32 v[112:113], v[112:113], v[164:165] op_sel_hi:[1,0]
	v_pk_mul_f32 v[94:95], v[94:95], v[164:165] op_sel_hi:[1,0]
	v_pk_mul_f32 v[92:93], v[92:93], v[164:165] op_sel_hi:[1,0]
	v_pk_mul_f32 v[160:161], v[90:91], v[164:165] op_sel_hi:[1,0]
	v_pk_mul_f32 v[164:165], v[88:89], v[164:165] op_sel_hi:[1,0]
	v_cvt_pk_bf16_f32 v88, v124, v125
	v_cvt_pk_bf16_f32 v89, v126, v127
	v_cvt_pk_bf16_f32 v90, v120, v121
	v_cvt_pk_bf16_f32 v91, v122, v123
	global_store_dwordx4 v[144:145], v[88:91], off
	v_fmamk_f32 v167, v167, 0x3a800000, v154
	v_pk_mul_f32 v[106:107], v[106:107], v[166:167] op_sel_hi:[1,0]
	v_cvt_pk_bf16_f32 v88, v108, v109
	v_cvt_pk_bf16_f32 v89, v110, v111
	v_cvt_pk_bf16_f32 v90, v100, v101
	v_cvt_pk_bf16_f32 v91, v102, v103
	global_store_dwordx4 v[144:145], v[88:91], off offset:256
	v_pk_mul_f32 v[104:105], v[104:105], v[166:167] op_sel_hi:[1,0]
	v_pk_mul_f32 v[98:99], v[98:99], v[166:167] op_sel_hi:[1,0]
	v_cvt_pk_bf16_f32 v88, v116, v117
	v_cvt_pk_bf16_f32 v89, v118, v119
	v_cvt_pk_bf16_f32 v90, v112, v113
	v_cvt_pk_bf16_f32 v91, v114, v115
	global_store_dwordx4 v[156:157], v[88:91], off
	v_pk_mul_f32 v[96:97], v[96:97], v[166:167] op_sel_hi:[1,0]
	v_pk_mul_f32 v[86:87], v[86:87], v[166:167] op_sel_hi:[1,0]
	v_cvt_pk_bf16_f32 v88, v92, v93
	v_cvt_pk_bf16_f32 v89, v94, v95
	v_cvt_pk_bf16_f32 v90, v164, v165
	v_cvt_pk_bf16_f32 v91, v160, v161
	global_store_dwordx4 v[156:157], v[88:91], off offset:256
	v_pk_mul_f32 v[84:85], v[84:85], v[166:167] op_sel_hi:[1,0]
	v_cmp_gt_f32_e32 vcc, s58, v171
	v_cvt_pk_bf16_f32 v88, v104, v105
	v_cvt_pk_bf16_f32 v89, v106, v107
	v_cvt_pk_bf16_f32 v90, v96, v97
	v_cvt_pk_bf16_f32 v91, v98, v99
	global_store_dwordx4 v[158:159], v[88:91], off
	v_fmamk_f32 v168, v168, 0x3a800000, v154
	v_fmamk_f32 v169, v169, 0x3a800000, v154
	v_pk_mul_f32 v[88:89], v[82:83], v[166:167] op_sel_hi:[1,0]
	v_pk_mul_f32 v[82:83], v[80:81], v[166:167] op_sel_hi:[1,0]
	v_cvt_pk_bf16_f32 v80, v84, v85
	v_cvt_pk_bf16_f32 v81, v86, v87
	v_fmamk_f32 v170, v170, 0x3a800000, v154
	v_cvt_pk_bf16_f32 v82, v82, v83
	v_cvt_pk_bf16_f32 v83, v88, v89
	global_store_dwordx4 v[158:159], v[80:83], off offset:256
	s_mov_b32 s1, s26
	s_mov_b32 s0, s28
	v_mul_f32_e32 v82, 0x4b800000, v171
	v_cndmask_b32_e32 v82, v171, v82, vcc
	v_rsq_f32_e32 v82, v82
	v_or_b32_e32 v80, 48, v146
	v_ashrrev_i32_e32 v81, 31, v80
	v_lshlrev_b64 v[80:81], 10, v[80:81]
	v_mul_f32_e32 v83, 0x45800000, v82
	v_cndmask_b32_e32 v82, v82, v83, vcc
	v_lshl_add_u64 v[80:81], s[92:93], 0, v[80:81]
	v_mul_f32_e32 v82, 0x3e0293ee, v82
	v_lshl_add_u64 v[80:81], v[80:81], 0, v[162:163]
	v_pk_mul_f32 v[78:79], v[78:79], v[82:83] op_sel_hi:[1,0]
	v_pk_mul_f32 v[76:77], v[76:77], v[82:83] op_sel_hi:[1,0]
	v_pk_mul_f32 v[84:85], v[74:75], v[82:83] op_sel_hi:[1,0]
	v_pk_mul_f32 v[74:75], v[72:73], v[82:83] op_sel_hi:[1,0]
	v_cvt_pk_bf16_f32 v72, v76, v77
	v_cvt_pk_bf16_f32 v73, v78, v79
	v_pk_mul_f32 v[70:71], v[70:71], v[82:83] op_sel_hi:[1,0]
	v_cvt_pk_bf16_f32 v74, v74, v75
	v_cvt_pk_bf16_f32 v75, v84, v85
	global_store_dwordx4 v[80:81], v[72:75], off
	v_pk_mul_f32 v[68:69], v[68:69], v[82:83] op_sel_hi:[1,0]
	v_cmp_gt_f32_e32 vcc, s58, v167
	v_pk_mul_f32 v[72:73], v[66:67], v[82:83] op_sel_hi:[1,0]
	v_pk_mul_f32 v[66:67], v[64:65], v[82:83] op_sel_hi:[1,0]
	v_cvt_pk_bf16_f32 v64, v68, v69
	v_cvt_pk_bf16_f32 v65, v70, v71
	s_mov_b64 s[2:3], s[30:31]
	v_cvt_pk_bf16_f32 v66, v66, v67
	v_mul_f32_e32 v67, 0x4b800000, v167
	v_cndmask_b32_e32 v67, v167, v67, vcc
	v_rsq_f32_e32 v68, v67
	v_cvt_pk_bf16_f32 v67, v72, v73
	global_store_dwordx4 v[80:81], v[64:67], off offset:256
	s_nop 1
	v_mul_f32_e32 v66, 0x45800000, v68
	v_cndmask_b32_e32 v66, v68, v66, vcc
	v_mul_f32_e32 v66, 0x3e0293ee, v66
	v_pk_mul_f32 v[60:61], v[60:61], v[66:67] op_sel_hi:[1,0]
	v_pk_mul_f32 v[68:69], v[58:59], v[66:67] op_sel_hi:[1,0]
	v_pk_mul_f32 v[58:59], v[56:57], v[66:67] op_sel_hi:[1,0]
	v_cvt_pk_bf16_f32 v56, v60, v61
	v_add_co_u32_e32 v60, vcc, s59, v144
	v_pk_mul_f32 v[62:63], v[62:63], v[66:67] op_sel_hi:[1,0]
	s_nop 0
	v_addc_co_u32_e32 v61, vcc, 0, v145, vcc
	v_cvt_pk_bf16_f32 v57, v62, v63
	v_cvt_pk_bf16_f32 v58, v58, v59
	v_cvt_pk_bf16_f32 v59, v68, v69
	global_store_dwordx4 v[60:61], v[56:59], off
	v_pk_mul_f32 v[54:55], v[54:55], v[66:67] op_sel_hi:[1,0]
	v_pk_mul_f32 v[52:53], v[52:53], v[66:67] op_sel_hi:[1,0]
	v_pk_mul_f32 v[56:57], v[50:51], v[66:67] op_sel_hi:[1,0]
	v_pk_mul_f32 v[50:51], v[48:49], v[66:67] op_sel_hi:[1,0]
	v_cvt_pk_bf16_f32 v48, v52, v53
	v_cvt_pk_bf16_f32 v49, v54, v55
	v_cmp_gt_f32_e32 vcc, s58, v168
	v_cvt_pk_bf16_f32 v50, v50, v51
	v_mul_f32_e32 v51, 0x4b800000, v168
	v_lshl_add_u64 v[64:65], v[144:145], 0, s[14:15]
	v_cndmask_b32_e32 v51, v168, v51, vcc
	v_rsq_f32_e32 v52, v51
	v_cvt_pk_bf16_f32 v51, v56, v57
	global_store_dwordx4 v[64:65], v[48:51], off offset:256
	s_nop 1
	v_mul_f32_e32 v50, 0x45800000, v52
	v_cndmask_b32_e32 v50, v52, v50, vcc
	v_mul_f32_e32 v50, 0x3e0293ee, v50
	v_pk_mul_f32 v[44:45], v[44:45], v[50:51] op_sel_hi:[1,0]
	v_pk_mul_f32 v[52:53], v[42:43], v[50:51] op_sel_hi:[1,0]
	v_pk_mul_f32 v[42:43], v[40:41], v[50:51] op_sel_hi:[1,0]
	v_cvt_pk_bf16_f32 v40, v44, v45
	v_add_co_u32_e32 v44, vcc, s60, v144
	v_pk_mul_f32 v[46:47], v[46:47], v[50:51] op_sel_hi:[1,0]
	s_nop 0
	v_addc_co_u32_e32 v45, vcc, 0, v145, vcc
	v_cvt_pk_bf16_f32 v41, v46, v47
	v_cvt_pk_bf16_f32 v42, v42, v43
	v_cvt_pk_bf16_f32 v43, v52, v53
	global_store_dwordx4 v[44:45], v[40:43], off
	v_pk_mul_f32 v[38:39], v[38:39], v[50:51] op_sel_hi:[1,0]
	v_pk_mul_f32 v[36:37], v[36:37], v[50:51] op_sel_hi:[1,0]
	v_pk_mul_f32 v[40:41], v[34:35], v[50:51] op_sel_hi:[1,0]
	v_pk_mul_f32 v[34:35], v[32:33], v[50:51] op_sel_hi:[1,0]
	v_cvt_pk_bf16_f32 v32, v36, v37
	v_cvt_pk_bf16_f32 v33, v38, v39
	v_cmp_gt_f32_e32 vcc, s58, v169
	v_cvt_pk_bf16_f32 v34, v34, v35
	v_mul_f32_e32 v35, 0x4b800000, v169
	v_lshl_add_u64 v[48:49], v[144:145], 0, s[20:21]
	v_cndmask_b32_e32 v35, v169, v35, vcc
	v_rsq_f32_e32 v36, v35
	v_cvt_pk_bf16_f32 v35, v40, v41
	global_store_dwordx4 v[48:49], v[32:35], off offset:256
	s_nop 1
	v_mul_f32_e32 v34, 0x45800000, v36
	v_cndmask_b32_e32 v34, v36, v34, vcc
	v_mul_f32_e32 v34, 0x3e0293ee, v34
	v_pk_mul_f32 v[28:29], v[28:29], v[34:35] op_sel_hi:[1,0]
	v_pk_mul_f32 v[36:37], v[26:27], v[34:35] op_sel_hi:[1,0]
	v_pk_mul_f32 v[26:27], v[24:25], v[34:35] op_sel_hi:[1,0]
	v_cvt_pk_bf16_f32 v24, v28, v29
	v_add_co_u32_e32 v28, vcc, s61, v144
	v_pk_mul_f32 v[30:31], v[30:31], v[34:35] op_sel_hi:[1,0]
	s_nop 0
	v_addc_co_u32_e32 v29, vcc, 0, v145, vcc
	v_cvt_pk_bf16_f32 v25, v30, v31
	v_cvt_pk_bf16_f32 v26, v26, v27
	v_cvt_pk_bf16_f32 v27, v36, v37
	global_store_dwordx4 v[28:29], v[24:27], off
	v_pk_mul_f32 v[22:23], v[22:23], v[34:35] op_sel_hi:[1,0]
	v_pk_mul_f32 v[20:21], v[20:21], v[34:35] op_sel_hi:[1,0]
	v_pk_mul_f32 v[24:25], v[18:19], v[34:35] op_sel_hi:[1,0]
	v_pk_mul_f32 v[18:19], v[16:17], v[34:35] op_sel_hi:[1,0]
	v_cvt_pk_bf16_f32 v16, v20, v21
	v_cvt_pk_bf16_f32 v17, v22, v23
	v_cmp_gt_f32_e32 vcc, s58, v170
	v_cvt_pk_bf16_f32 v18, v18, v19
	v_mul_f32_e32 v19, 0x4b800000, v170
	v_lshl_add_u64 v[32:33], v[144:145], 0, s[22:23]
	v_cndmask_b32_e32 v19, v170, v19, vcc
	v_rsq_f32_e32 v20, v19
	v_cvt_pk_bf16_f32 v19, v24, v25
	global_store_dwordx4 v[32:33], v[16:19], off offset:256
	s_nop 1
	v_mul_f32_e32 v18, 0x45800000, v20
	v_cndmask_b32_e32 v18, v20, v18, vcc
	v_mul_f32_e32 v18, 0x3e0293ee, v18
	v_pk_mul_f32 v[12:13], v[12:13], v[18:19] op_sel_hi:[1,0]
	v_pk_mul_f32 v[20:21], v[10:11], v[18:19] op_sel_hi:[1,0]
	v_pk_mul_f32 v[10:11], v[8:9], v[18:19] op_sel_hi:[1,0]
	v_cvt_pk_bf16_f32 v8, v12, v13
	v_add_co_u32_e32 v12, vcc, s62, v144
	v_pk_mul_f32 v[14:15], v[14:15], v[18:19] op_sel_hi:[1,0]
	s_nop 0
	v_addc_co_u32_e32 v13, vcc, 0, v145, vcc
	v_cvt_pk_bf16_f32 v9, v14, v15
	v_lshl_add_u64 v[16:17], v[144:145], 0, s[24:25]
	v_cvt_pk_bf16_f32 v10, v10, v11
	v_cvt_pk_bf16_f32 v11, v20, v21
	global_store_dwordx4 v[12:13], v[8:11], off
	s_and_b64 vcc, exec, s[6:7]
	v_pk_mul_f32 v[6:7], v[6:7], v[18:19] op_sel_hi:[1,0]
	v_pk_mul_f32 v[8:9], v[2:3], v[18:19] op_sel_hi:[1,0]
	v_pk_mul_f32 v[2:3], v[0:1], v[18:19] op_sel_hi:[1,0]
	v_pk_mul_f32 v[4:5], v[4:5], v[18:19] op_sel_hi:[1,0]
	s_nop 0
	v_cvt_pk_bf16_f32 v0, v4, v5
	v_cvt_pk_bf16_f32 v1, v6, v7
	v_cvt_pk_bf16_f32 v2, v2, v3
	v_cvt_pk_bf16_f32 v3, v8, v9
	global_store_dwordx4 v[16:17], v[0:3], off offset:256
	s_cbranch_vccz .LBB0_1073
	s_waitcnt vmcnt(0)
	s_cmpk_gt_u32 s33, 0xff
	s_cbranch_scc1 .LBB0_1084
	s_barrier

.LBB0_1160:
	ds_read_b128 v[144:147], v178
	ds_read_b128 v[148:151], v178 offset:1024
	ds_read_b128 v[152:155], v178 offset:2048
	ds_read_b128 v[156:159], v178 offset:3072
	s_add_u32 s38, s36, 0xfffe0080
	s_addc_u32 s39, s37, -1
	s_cmp_eq_u32 s62, 4
	s_cselect_b32 s41, s25, s39
	s_cselect_b32 s40, s31, s38
	s_cselect_b32 s39, s23, s61
	s_cselect_b32 s38, s59, s60
	v_lshl_add_u64 v[172:173], s[36:37], 0, v[136:137]
	s_add_i32 m0, s35, 0xc000
	ds_read_b128 v[160:163], v179
	ds_read_b128 v[164:167], v179 offset:1024
	ds_read_b128 v[168:171], v179 offset:2048
	ds_read_b128 v[182:185], v179 offset:3072
	ds_read_b128 v[186:189], v179 offset:4096
	ds_read_b128 v[190:193], v179 offset:5120
	ds_read_b128 v[194:197], v179 offset:6144
	ds_read_b128 v[198:201], v179 offset:7168
	global_load_lds_dwordx4 v[172:173], off
	s_add_i32 m0, s35, 0xe000
	v_lshl_add_u64 v[172:173], s[36:37], 0, v[138:139]
	global_load_lds_dwordx4 v[172:173], off
	s_waitcnt lgkmcnt(8)
	s_setprio 1
	s_barrier
	s_waitcnt lgkmcnt(0)
	v_mfma_f32_16x16x32_bf16 v[124:127], v[144:147], v[160:163], v[124:127]
	v_mfma_f32_16x16x32_bf16 v[120:123], v[152:155], v[160:163], v[120:123]
	v_mfma_f32_16x16x32_bf16 v[108:111], v[144:147], v[168:171], v[108:111]
	v_mfma_f32_16x16x32_bf16 v[104:107], v[152:155], v[168:171], v[104:107]
	v_mfma_f32_16x16x32_bf16 v[96:99], v[144:147], v[186:189], v[96:99]
	v_mfma_f32_16x16x32_bf16 v[88:91], v[152:155], v[186:189], v[88:91]
	v_mfma_f32_16x16x32_bf16 v[80:83], v[144:147], v[194:197], v[80:83]
	v_mfma_f32_16x16x32_bf16 v[72:75], v[152:155], v[194:197], v[72:75]
	v_mfma_f32_16x16x32_bf16 v[124:127], v[148:151], v[164:167], v[124:127]
	v_mfma_f32_16x16x32_bf16 v[120:123], v[156:159], v[164:167], v[120:123]
	v_mfma_f32_16x16x32_bf16 v[108:111], v[148:151], v[182:185], v[108:111]
	v_mfma_f32_16x16x32_bf16 v[104:107], v[156:159], v[182:185], v[104:107]
	v_mfma_f32_16x16x32_bf16 v[96:99], v[148:151], v[190:193], v[96:99]
	v_mfma_f32_16x16x32_bf16 v[88:91], v[156:159], v[190:193], v[88:91]
	v_mfma_f32_16x16x32_bf16 v[80:83], v[148:151], v[198:201], v[80:83]
	v_mfma_f32_16x16x32_bf16 v[72:75], v[156:159], v[198:201], v[72:75]
	s_barrier
	s_setprio 0
	s_add_i32 s63, s57, s48
	v_lshl_add_u64 v[172:173], s[38:39], 0, v[130:131]
	s_mov_b32 m0, s63
	ds_read_b128 v[202:205], v180
	ds_read_b128 v[206:209], v180 offset:1024
	ds_read_b128 v[212:215], v180 offset:2048
	ds_read_b128 v[216:219], v180 offset:3072
	global_load_lds_dwordx4 v[172:173], off
	s_add_i32 m0, s63, 0x2000
	v_lshl_add_u64 v[220:221], s[38:39], 0, v[134:135]
	global_load_lds_dwordx4 v[220:221], off
	s_setprio 1
	s_barrier
	s_waitcnt lgkmcnt(0)
	v_mfma_f32_16x16x32_bf16 v[116:119], v[202:205], v[160:163], v[116:119]
	v_mfma_f32_16x16x32_bf16 v[112:115], v[212:215], v[160:163], v[112:115]
	v_mfma_f32_16x16x32_bf16 v[100:103], v[202:205], v[168:171], v[100:103]
	v_mfma_f32_16x16x32_bf16 v[92:95], v[212:215], v[168:171], v[92:95]
	v_mfma_f32_16x16x32_bf16 v[84:87], v[202:205], v[186:189], v[84:87]
	v_mfma_f32_16x16x32_bf16 v[76:79], v[212:215], v[186:189], v[76:79]
	v_mfma_f32_16x16x32_bf16 v[68:71], v[202:205], v[194:197], v[68:71]
	v_mfma_f32_16x16x32_bf16 v[64:67], v[212:215], v[194:197], v[64:67]
	v_mfma_f32_16x16x32_bf16 v[116:119], v[206:209], v[164:167], v[116:119]
	v_mfma_f32_16x16x32_bf16 v[112:115], v[216:219], v[164:167], v[112:115]
	v_mfma_f32_16x16x32_bf16 v[100:103], v[206:209], v[182:185], v[100:103]
	v_mfma_f32_16x16x32_bf16 v[92:95], v[216:219], v[182:185], v[92:95]
	v_mfma_f32_16x16x32_bf16 v[84:87], v[206:209], v[190:193], v[84:87]
	v_mfma_f32_16x16x32_bf16 v[76:79], v[216:219], v[190:193], v[76:79]
	v_mfma_f32_16x16x32_bf16 v[68:71], v[206:209], v[198:201], v[68:71]
	v_mfma_f32_16x16x32_bf16 v[64:67], v[216:219], v[198:201], v[64:67]
	s_barrier
	s_setprio 0
	s_mov_b32 m0, s35
	v_lshl_add_u64 v[222:223], s[40:41], 0, v[128:129]
	ds_read_b128 v[160:163], v179 offset:16384
	ds_read_b128 v[164:167], v179 offset:17408
	ds_read_b128 v[168:171], v179 offset:18432
	ds_read_b128 v[182:185], v179 offset:19456
	ds_read_b128 v[186:189], v179 offset:20480
	ds_read_b128 v[190:193], v179 offset:21504
	ds_read_b128 v[194:197], v179 offset:22528
	ds_read_b128 v[198:201], v179 offset:23552
	global_load_lds_dwordx4 v[222:223], off
	s_mov_b32 m0, s49
	v_lshl_add_u64 v[224:225], s[40:41], 0, v[132:133]
	global_load_lds_dwordx4 v[224:225], off
	s_setprio 1
	s_barrier
	s_waitcnt lgkmcnt(0)
	v_mfma_f32_16x16x32_bf16 v[60:63], v[144:147], v[160:163], v[60:63]
	v_mfma_f32_16x16x32_bf16 v[56:59], v[152:155], v[160:163], v[56:59]
	v_mfma_f32_16x16x32_bf16 v[44:47], v[144:147], v[168:171], v[44:47]
	v_mfma_f32_16x16x32_bf16 v[40:43], v[152:155], v[168:171], v[40:43]
	v_mfma_f32_16x16x32_bf16 v[32:35], v[144:147], v[186:189], v[32:35]
	v_mfma_f32_16x16x32_bf16 v[24:27], v[152:155], v[186:189], v[24:27]
	v_mfma_f32_16x16x32_bf16 v[16:19], v[144:147], v[194:197], v[16:19]
	v_mfma_f32_16x16x32_bf16 v[8:11], v[152:155], v[194:197], v[8:11]
	v_mfma_f32_16x16x32_bf16 v[60:63], v[148:151], v[164:167], v[60:63]
	v_mfma_f32_16x16x32_bf16 v[56:59], v[156:159], v[164:167], v[56:59]
	v_mfma_f32_16x16x32_bf16 v[44:47], v[148:151], v[182:185], v[44:47]
	v_mfma_f32_16x16x32_bf16 v[40:43], v[156:159], v[182:185], v[40:43]
	v_mfma_f32_16x16x32_bf16 v[32:35], v[148:151], v[190:193], v[32:35]
	v_mfma_f32_16x16x32_bf16 v[24:27], v[156:159], v[190:193], v[24:27]
	v_mfma_f32_16x16x32_bf16 v[16:19], v[148:151], v[198:201], v[16:19]
	v_mfma_f32_16x16x32_bf16 v[8:11], v[156:159], v[198:201], v[8:11]
	s_barrier
	s_setprio 0
	s_add_u32 s64, s38, 0x20000
	s_addc_u32 s65, s39, 0
	s_add_i32 s63, s58, s48
	s_mov_b32 m0, s63
	v_lshl_add_u64 v[144:145], s[64:65], 0, v[130:131]
	global_load_lds_dwordx4 v[144:145], off
	s_add_i32 m0, s63, 0x2000
	v_lshl_add_u64 v[144:145], s[64:65], 0, v[134:135]
	global_load_lds_dwordx4 v[144:145], off
	s_waitcnt vmcnt(6)
	s_setprio 1
	s_barrier
	v_mfma_f32_16x16x32_bf16 v[52:55], v[202:205], v[160:163], v[52:55]
	v_mfma_f32_16x16x32_bf16 v[48:51], v[212:215], v[160:163], v[48:51]
	v_mfma_f32_16x16x32_bf16 v[36:39], v[202:205], v[168:171], v[36:39]
	v_mfma_f32_16x16x32_bf16 v[28:31], v[212:215], v[168:171], v[28:31]
	v_mfma_f32_16x16x32_bf16 v[20:23], v[202:205], v[186:189], v[20:23]
	v_mfma_f32_16x16x32_bf16 v[12:15], v[212:215], v[186:189], v[12:15]
	v_mfma_f32_16x16x32_bf16 v[4:7], v[202:205], v[194:197], v[4:7]
	v_mfma_f32_16x16x32_bf16 v[0:3], v[212:215], v[194:197], v[0:3]
	v_mfma_f32_16x16x32_bf16 v[52:55], v[206:209], v[164:167], v[52:55]
	v_mfma_f32_16x16x32_bf16 v[48:51], v[216:219], v[164:167], v[48:51]
	v_mfma_f32_16x16x32_bf16 v[36:39], v[206:209], v[182:185], v[36:39]
	v_mfma_f32_16x16x32_bf16 v[28:31], v[216:219], v[182:185], v[28:31]
	v_mfma_f32_16x16x32_bf16 v[20:23], v[206:209], v[190:193], v[20:23]
	v_mfma_f32_16x16x32_bf16 v[12:15], v[216:219], v[190:193], v[12:15]
	v_mfma_f32_16x16x32_bf16 v[4:7], v[206:209], v[198:201], v[4:7]
	v_mfma_f32_16x16x32_bf16 v[0:3], v[216:219], v[198:201], v[0:3]
	s_barrier
	s_setprio 0
	s_add_i32 s63, 0, 0x18000
	v_add_u32_e32 v156, s63, v176
	ds_read_b128 v[144:147], v156
	ds_read_b128 v[148:151], v156 offset:1024
	ds_read_b128 v[152:155], v156 offset:2048
	ds_read_b128 v[156:159], v156 offset:3072
	s_add_u32 s40, s40, 0x20000
	s_addc_u32 s41, s41, 0
	s_mov_b32 m0, s50
	v_lshl_add_u64 v[202:203], s[40:41], 0, v[128:129]
	ds_read_b128 v[160:163], v179 offset:32768
	ds_read_b128 v[164:167], v179 offset:33792
	ds_read_b128 v[168:171], v179 offset:34816
	ds_read_b128 v[182:185], v179 offset:35840
	ds_read_b128 v[186:189], v179 offset:36864
	ds_read_b128 v[190:193], v179 offset:37888
	ds_read_b128 v[194:197], v179 offset:38912
	ds_read_b128 v[198:201], v179 offset:39936
	global_load_lds_dwordx4 v[202:203], off
	s_mov_b32 m0, s51
	v_lshl_add_u64 v[202:203], s[40:41], 0, v[132:133]
	global_load_lds_dwordx4 v[202:203], off
	s_waitcnt lgkmcnt(8)
	s_setprio 1
	s_barrier
	s_waitcnt lgkmcnt(0)
	v_mfma_f32_16x16x32_bf16 v[124:127], v[144:147], v[160:163], v[124:127]
	v_mfma_f32_16x16x32_bf16 v[120:123], v[152:155], v[160:163], v[120:123]
	v_mfma_f32_16x16x32_bf16 v[108:111], v[144:147], v[168:171], v[108:111]
	v_mfma_f32_16x16x32_bf16 v[104:107], v[152:155], v[168:171], v[104:107]
	v_mfma_f32_16x16x32_bf16 v[96:99], v[144:147], v[186:189], v[96:99]
	v_mfma_f32_16x16x32_bf16 v[88:91], v[152:155], v[186:189], v[88:91]
	v_mfma_f32_16x16x32_bf16 v[80:83], v[144:147], v[194:197], v[80:83]
	v_mfma_f32_16x16x32_bf16 v[72:75], v[152:155], v[194:197], v[72:75]
	v_mfma_f32_16x16x32_bf16 v[124:127], v[148:151], v[164:167], v[124:127]
	v_mfma_f32_16x16x32_bf16 v[120:123], v[156:159], v[164:167], v[120:123]
	v_mfma_f32_16x16x32_bf16 v[108:111], v[148:151], v[182:185], v[108:111]
	v_mfma_f32_16x16x32_bf16 v[104:107], v[156:159], v[182:185], v[104:107]
	v_mfma_f32_16x16x32_bf16 v[96:99], v[148:151], v[190:193], v[96:99]
	v_mfma_f32_16x16x32_bf16 v[88:91], v[156:159], v[190:193], v[88:91]
	v_mfma_f32_16x16x32_bf16 v[80:83], v[148:151], v[198:201], v[80:83]
	v_mfma_f32_16x16x32_bf16 v[72:75], v[156:159], v[198:201], v[72:75]
	s_barrier
	s_setprio 0
	s_add_i32 s40, 0, 0x1c000
	s_add_i32 s41, s63, s48
	v_add_u32_e32 v181, s40, v176
	v_lshl_add_u64 v[172:173], v[172:173], 0, s[0:1]
	s_mov_b32 m0, s41
	ds_read_b128 v[202:205], v181
	ds_read_b128 v[206:209], v181 offset:1024
	ds_read_b128 v[212:215], v181 offset:2048
	ds_read_b128 v[216:219], v181 offset:3072
	global_load_lds_dwordx4 v[172:173], off
	s_add_i32 m0, s41, 0x2000
	v_lshl_add_u64 v[172:173], v[220:221], 0, s[0:1]
	global_load_lds_dwordx4 v[172:173], off
	s_setprio 1
	s_barrier
	s_waitcnt lgkmcnt(0)
	v_mfma_f32_16x16x32_bf16 v[116:119], v[202:205], v[160:163], v[116:119]
	v_mfma_f32_16x16x32_bf16 v[112:115], v[212:215], v[160:163], v[112:115]
	v_mfma_f32_16x16x32_bf16 v[100:103], v[202:205], v[168:171], v[100:103]
	v_mfma_f32_16x16x32_bf16 v[92:95], v[212:215], v[168:171], v[92:95]
	v_mfma_f32_16x16x32_bf16 v[84:87], v[202:205], v[186:189], v[84:87]
	v_mfma_f32_16x16x32_bf16 v[76:79], v[212:215], v[186:189], v[76:79]
	v_mfma_f32_16x16x32_bf16 v[68:71], v[202:205], v[194:197], v[68:71]
	v_mfma_f32_16x16x32_bf16 v[64:67], v[212:215], v[194:197], v[64:67]
	v_mfma_f32_16x16x32_bf16 v[116:119], v[206:209], v[164:167], v[116:119]
	v_mfma_f32_16x16x32_bf16 v[112:115], v[216:219], v[164:167], v[112:115]
	v_mfma_f32_16x16x32_bf16 v[100:103], v[206:209], v[182:185], v[100:103]
	v_mfma_f32_16x16x32_bf16 v[92:95], v[216:219], v[182:185], v[92:95]
	v_mfma_f32_16x16x32_bf16 v[84:87], v[206:209], v[190:193], v[84:87]
	v_mfma_f32_16x16x32_bf16 v[76:79], v[216:219], v[190:193], v[76:79]
	v_mfma_f32_16x16x32_bf16 v[68:71], v[206:209], v[198:201], v[68:71]
	v_mfma_f32_16x16x32_bf16 v[64:67], v[216:219], v[198:201], v[64:67]
	s_barrier
	s_setprio 0
	s_mov_b32 m0, s53
	v_lshl_add_u64 v[172:173], v[222:223], 0, s[0:1]
	ds_read_b128 v[160:163], v179 offset:49152
	ds_read_b128 v[164:167], v179 offset:50176
	ds_read_b128 v[168:171], v179 offset:51200
	ds_read_b128 v[182:185], v179 offset:52224
	ds_read_b128 v[186:189], v179 offset:53248
	ds_read_b128 v[190:193], v179 offset:54272
	ds_read_b128 v[194:197], v179 offset:55296
	ds_read_b128 v[198:201], v179 offset:56320
	global_load_lds_dwordx4 v[172:173], off
	s_mov_b32 m0, s54
	v_lshl_add_u64 v[172:173], v[224:225], 0, s[0:1]
	global_load_lds_dwordx4 v[172:173], off
	s_setprio 1
	s_barrier
	s_waitcnt lgkmcnt(0)
	v_mfma_f32_16x16x32_bf16 v[60:63], v[144:147], v[160:163], v[60:63]
	v_mfma_f32_16x16x32_bf16 v[56:59], v[152:155], v[160:163], v[56:59]
	v_mfma_f32_16x16x32_bf16 v[44:47], v[144:147], v[168:171], v[44:47]
	v_mfma_f32_16x16x32_bf16 v[40:43], v[152:155], v[168:171], v[40:43]
	v_mfma_f32_16x16x32_bf16 v[32:35], v[144:147], v[186:189], v[32:35]
	v_mfma_f32_16x16x32_bf16 v[24:27], v[152:155], v[186:189], v[24:27]
	v_mfma_f32_16x16x32_bf16 v[16:19], v[144:147], v[194:197], v[16:19]
	v_mfma_f32_16x16x32_bf16 v[8:11], v[152:155], v[194:197], v[8:11]
	v_mfma_f32_16x16x32_bf16 v[60:63], v[148:151], v[164:167], v[60:63]
	v_mfma_f32_16x16x32_bf16 v[56:59], v[156:159], v[164:167], v[56:59]
	v_mfma_f32_16x16x32_bf16 v[44:47], v[148:151], v[182:185], v[44:47]
	v_mfma_f32_16x16x32_bf16 v[40:43], v[156:159], v[182:185], v[40:43]
	v_mfma_f32_16x16x32_bf16 v[32:35], v[148:151], v[190:193], v[32:35]
	v_mfma_f32_16x16x32_bf16 v[24:27], v[156:159], v[190:193], v[24:27]
	v_mfma_f32_16x16x32_bf16 v[16:19], v[148:151], v[198:201], v[16:19]
	v_mfma_f32_16x16x32_bf16 v[8:11], v[156:159], v[198:201], v[8:11]
	s_barrier
	s_setprio 0
	s_add_u32 s38, s38, 0x20080
	s_addc_u32 s39, s39, 0
	s_add_i32 s40, s40, s48
	s_mov_b32 m0, s40
	v_lshl_add_u64 v[144:145], s[38:39], 0, v[130:131]
	global_load_lds_dwordx4 v[144:145], off
	s_add_i32 m0, s40, 0x2000
	v_lshl_add_u64 v[144:145], s[38:39], 0, v[134:135]
	global_load_lds_dwordx4 v[144:145], off
	s_waitcnt vmcnt(6)
	s_setprio 1
	s_barrier
	v_mfma_f32_16x16x32_bf16 v[52:55], v[202:205], v[160:163], v[52:55]
	v_mfma_f32_16x16x32_bf16 v[48:51], v[212:215], v[160:163], v[48:51]
	v_mfma_f32_16x16x32_bf16 v[36:39], v[202:205], v[168:171], v[36:39]
	v_mfma_f32_16x16x32_bf16 v[28:31], v[212:215], v[168:171], v[28:31]
	v_mfma_f32_16x16x32_bf16 v[20:23], v[202:205], v[186:189], v[20:23]
	v_mfma_f32_16x16x32_bf16 v[12:15], v[212:215], v[186:189], v[12:15]
	v_mfma_f32_16x16x32_bf16 v[4:7], v[202:205], v[194:197], v[4:7]
	v_mfma_f32_16x16x32_bf16 v[0:3], v[212:215], v[194:197], v[0:3]
	v_mfma_f32_16x16x32_bf16 v[52:55], v[206:209], v[164:167], v[52:55]
	v_mfma_f32_16x16x32_bf16 v[48:51], v[216:219], v[164:167], v[48:51]
	v_mfma_f32_16x16x32_bf16 v[36:39], v[206:209], v[182:185], v[36:39]
	v_mfma_f32_16x16x32_bf16 v[28:31], v[216:219], v[182:185], v[28:31]
	v_mfma_f32_16x16x32_bf16 v[20:23], v[206:209], v[190:193], v[20:23]
	v_mfma_f32_16x16x32_bf16 v[12:15], v[216:219], v[190:193], v[12:15]
	v_mfma_f32_16x16x32_bf16 v[4:7], v[206:209], v[198:201], v[4:7]
	v_mfma_f32_16x16x32_bf16 v[0:3], v[216:219], v[198:201], v[0:3]
	s_barrier
	s_setprio 0
	s_add_i32 s62, s62, 2
	s_add_u32 s36, s36, 0x100
	s_addc_u32 s37, s37, 0
	s_add_u32 s60, s60, 0x100
	s_addc_u32 s61, s61, 0
	s_cmp_gt_u32 s62, 5
	s_cbranch_scc0 .LBB0_1160
	v_lshl_or_b32 v144, s34, 8, v177
	v_lshl_add_u32 v150, s30, 8, v175
	v_ashrrev_i32_e32 v145, 31, v144
	v_ashrrev_i32_e32 v151, 31, v150
	v_lshlrev_b64 v[144:145], 1, v[144:145]
	v_lshl_add_u64 v[146:147], s[10:11], 0, v[144:145]
	v_lshlrev_b64 v[148:149], 11, v[150:151]
	v_lshl_add_u64 v[152:153], v[146:147], 0, v[148:149]
	global_load_dwordx4 v[156:159], v[152:153], off
	global_load_dwordx4 v[160:163], v[152:153], off offset:256
	v_or_b32_e32 v152, 16, v150
	v_ashrrev_i32_e32 v153, 31, v152
	v_lshlrev_b64 v[170:171], 11, v[152:153]
	v_lshl_add_u64 v[152:153], v[146:147], 0, v[170:171]
	global_load_dwordx4 v[164:167], v[152:153], off
	global_load_dwordx4 v[182:185], v[152:153], off offset:256
	v_or_b32_e32 v152, 32, v150
	v_ashrrev_i32_e32 v153, 31, v152
	v_lshlrev_b64 v[154:155], 11, v[152:153]
	v_lshl_add_u64 v[152:153], v[146:147], 0, v[154:155]
	global_load_dwordx4 v[186:189], v[152:153], off
	global_load_dwordx4 v[190:193], v[152:153], off offset:256
	v_or_b32_e32 v152, 48, v150
	v_ashrrev_i32_e32 v153, 31, v152
	v_lshlrev_b64 v[152:153], 11, v[152:153]
	v_lshl_add_u64 v[168:169], v[146:147], 0, v[152:153]
	global_load_dwordx4 v[194:197], v[168:169], off
	global_load_dwordx4 v[198:201], v[168:169], off offset:256
	s_waitcnt vmcnt(0)
	v_lshlrev_b32_e32 v202, 16, v156
	v_and_b32_e32 v203, 0xffff0000, v156
	v_lshlrev_b32_e32 v204, 16, v157
	v_and_b32_e32 v205, 0xffff0000, v157
	v_lshlrev_b32_e32 v206, 16, v158
	v_and_b32_e32 v207, 0xffff0000, v158
	v_lshlrev_b32_e32 v208, 16, v159
	v_and_b32_e32 v209, 0xffff0000, v159
	v_pk_add_f32 v[126:127], v[126:127], v[204:205]
	v_pk_add_f32 v[124:125], v[124:125], v[202:203]
	v_lshlrev_b32_e32 v224, 16, v166
	v_and_b32_e32 v225, 0xffff0000, v166
	v_lshlrev_b32_e32 v226, 16, v167
	v_and_b32_e32 v227, 0xffff0000, v167
	v_lshlrev_b32_e32 v212, 16, v160
	v_lshlrev_b32_e32 v166, 16, v194
	v_and_b32_e32 v167, 0xffff0000, v194
	v_lshlrev_b32_e32 v172, 16, v195
	v_and_b32_e32 v173, 0xffff0000, v195
	v_pk_add_f32 v[194:195], v[122:123], v[208:209]
	v_pk_add_f32 v[122:123], v[120:121], v[206:207]
	v_mul_f32_e32 v120, v125, v125
	v_mul_f32_e32 v121, v127, v127
	v_fmac_f32_e32 v120, v124, v124
	v_fmac_f32_e32 v121, v126, v126
	v_add_f32_e32 v120, v120, v121
	v_mul_f32_e32 v121, v123, v123
	v_fmac_f32_e32 v121, v122, v122
	v_add_f32_e32 v120, v121, v120
	v_mul_f32_e32 v121, v195, v195
	v_fmac_f32_e32 v121, v194, v194
	v_and_b32_e32 v213, 0xffff0000, v160
	v_lshlrev_b32_e32 v214, 16, v161
	v_and_b32_e32 v215, 0xffff0000, v161
	v_add_f32_e32 v181, v121, v120
	v_cvt_pk_bf16_f32 v120, v124, v125
	v_lshl_add_u64 v[124:125], s[90:91], 0, v[148:149]
	v_lshlrev_b32_e32 v216, 16, v162
	v_and_b32_e32 v217, 0xffff0000, v162
	v_lshlrev_b32_e32 v218, 16, v163
	v_and_b32_e32 v219, 0xffff0000, v163
	v_cvt_pk_bf16_f32 v121, v126, v127
	v_lshl_add_u64 v[124:125], v[124:125], 0, v[144:145]
	v_pk_add_f32 v[118:119], v[118:119], v[214:215]
	v_pk_add_f32 v[116:117], v[116:117], v[212:213]
	v_cvt_pk_bf16_f32 v122, v122, v123
	v_cvt_pk_bf16_f32 v123, v194, v195
	global_store_dwordx4 v[124:125], v[120:123], off
	v_lshlrev_b32_e32 v220, 16, v164
	v_and_b32_e32 v221, 0xffff0000, v164
	v_pk_add_f32 v[120:121], v[114:115], v[218:219]
	v_pk_add_f32 v[114:115], v[112:113], v[216:217]
	v_mul_f32_e32 v112, v117, v117
	v_mul_f32_e32 v113, v119, v119
	v_fmac_f32_e32 v112, v116, v116
	v_fmac_f32_e32 v113, v118, v118
	v_add_f32_e32 v112, v112, v113
	v_mul_f32_e32 v113, v115, v115
	v_fmac_f32_e32 v113, v114, v114
	v_add_f32_e32 v112, v113, v112
	v_mul_f32_e32 v113, v121, v121
	v_fmac_f32_e32 v113, v120, v120
	v_add_f32_e32 v112, v113, v112
	v_lshlrev_b32_e32 v222, 16, v165
	v_and_b32_e32 v223, 0xffff0000, v165
	v_add_f32_e32 v126, v181, v112
	v_cvt_pk_bf16_f32 v112, v116, v117
	v_cvt_pk_bf16_f32 v113, v118, v119
	v_lshl_add_u64 v[116:117], s[90:91], 0, v[170:171]
	v_lshlrev_b32_e32 v230, 16, v184
	v_and_b32_e32 v231, 0xffff0000, v184
	v_lshlrev_b32_e32 v232, 16, v186
	v_and_b32_e32 v233, 0xffff0000, v186
	v_lshlrev_b32_e32 v186, 16, v187
	v_and_b32_e32 v187, 0xffff0000, v187
	v_cvt_pk_bf16_f32 v114, v114, v115
	v_cvt_pk_bf16_f32 v115, v120, v121
	global_store_dwordx4 v[124:125], v[112:115], off offset:256
	v_pk_add_f32 v[110:111], v[110:111], v[222:223]
	v_pk_add_f32 v[108:109], v[108:109], v[220:221]
	v_lshl_add_u64 v[118:119], v[116:117], 0, v[144:145]
	v_cvt_pk_bf16_f32 v112, v108, v109
	v_cvt_pk_bf16_f32 v113, v110, v111
	v_lshlrev_b32_e32 v228, 16, v182
	v_and_b32_e32 v229, 0xffff0000, v182
	v_lshlrev_b32_e32 v182, 16, v183
	v_and_b32_e32 v183, 0xffff0000, v183
	v_lshlrev_b32_e32 v184, 16, v185
	v_and_b32_e32 v185, 0xffff0000, v185
	v_lshlrev_b32_e32 v238, 16, v192
	v_and_b32_e32 v239, 0xffff0000, v192
	v_pk_add_f32 v[106:107], v[106:107], v[226:227]
	v_pk_add_f32 v[104:105], v[104:105], v[224:225]
	v_lshlrev_b32_e32 v156, 16, v200
	v_cvt_pk_bf16_f32 v114, v104, v105
	v_cvt_pk_bf16_f32 v115, v106, v107
	global_store_dwordx4 v[118:119], v[112:115], off
	v_and_b32_e32 v157, 0xffff0000, v200
	v_pk_add_f32 v[102:103], v[102:103], v[182:183]
	v_pk_add_f32 v[112:113], v[92:93], v[230:231]
	v_pk_add_f32 v[92:93], v[98:99], v[186:187]
	v_lshl_add_u64 v[98:99], s[90:91], 0, v[154:155]
	v_pk_add_f32 v[100:101], v[100:101], v[228:229]
	v_pk_add_f32 v[94:95], v[94:95], v[184:185]
	v_cvt_pk_bf16_f32 v114, v100, v101
	v_cvt_pk_bf16_f32 v115, v102, v103
	v_cvt_pk_bf16_f32 v116, v112, v113
	v_lshlrev_b32_e32 v234, 16, v188
	v_cvt_pk_bf16_f32 v117, v94, v95
	global_store_dwordx4 v[118:119], v[114:117], off offset:256
	v_lshl_add_u64 v[118:119], v[98:99], 0, v[144:145]
	v_pk_add_f32 v[98:99], v[76:77], v[238:239]
	v_pk_add_f32 v[76:77], v[82:83], v[172:173]
	v_lshl_add_u64 v[82:83], s[90:91], 0, v[152:153]
	v_lshl_add_u64 v[122:123], v[82:83], 0, v[144:145]
	v_pk_add_f32 v[82:83], v[64:65], v[156:157]
	v_and_b32_e32 v65, 64, v174
	v_and_b32_e32 v235, 0xffff0000, v188
	v_lshlrev_b32_e32 v188, 16, v189
	v_and_b32_e32 v189, 0xffff0000, v189
	v_lshlrev_b32_e32 v236, 16, v190
	v_and_b32_e32 v237, 0xffff0000, v190
	v_pk_add_f32 v[96:97], v[96:97], v[232:233]
	v_xor_b32_e32 v64, 16, v174
	v_cvt_pk_bf16_f32 v114, v96, v97
	v_add_u32_e32 v65, 64, v65
	v_lshlrev_b32_e32 v190, 16, v191
	v_and_b32_e32 v191, 0xffff0000, v191
	v_lshlrev_b32_e32 v192, 16, v193
	v_and_b32_e32 v193, 0xffff0000, v193
	v_pk_add_f32 v[90:91], v[90:91], v[188:189]
	v_pk_add_f32 v[88:89], v[88:89], v[234:235]
	v_cvt_pk_bf16_f32 v115, v92, v93
	v_pk_add_f32 v[84:85], v[84:85], v[236:237]
	v_cvt_pk_bf16_f32 v116, v88, v89
	v_cvt_pk_bf16_f32 v117, v90, v91
	global_store_dwordx4 v[118:119], v[114:117], off
	v_cmp_lt_i32_e32 vcc, v64, v65
	v_lshlrev_b32_e32 v164, 16, v196
	v_cvt_pk_bf16_f32 v114, v84, v85
	v_and_b32_e32 v165, 0xffff0000, v196
	v_lshlrev_b32_e32 v168, 16, v197
	v_and_b32_e32 v169, 0xffff0000, v197
	v_pk_add_f32 v[86:87], v[86:87], v[190:191]
	v_pk_add_f32 v[78:79], v[78:79], v[192:193]
	v_cvt_pk_bf16_f32 v115, v86, v87
	v_cvt_pk_bf16_f32 v116, v98, v99
	v_pk_add_f32 v[80:81], v[80:81], v[166:167]
	v_cvt_pk_bf16_f32 v117, v78, v79
	global_store_dwordx4 v[118:119], v[114:117], off offset:256
	v_cndmask_b32_e32 v64, v174, v64, vcc
	v_pk_add_f32 v[74:75], v[74:75], v[168:169]
	v_cvt_pk_bf16_f32 v114, v80, v81
	v_pk_add_f32 v[72:73], v[72:73], v[164:165]
	v_cvt_pk_bf16_f32 v115, v76, v77
	v_lshlrev_b32_e32 v158, 16, v198
	v_cvt_pk_bf16_f32 v116, v72, v73
	v_cvt_pk_bf16_f32 v117, v74, v75
	global_store_dwordx4 v[122:123], v[114:117], off
	v_and_b32_e32 v159, 0xffff0000, v198
	v_lshlrev_b32_e32 v162, 16, v199
	v_lshlrev_b32_e32 v114, 2, v64
	ds_bpermute_b32 v64, v114, v126
	v_xor_b32_e32 v115, 32, v174
	v_cmp_lt_i32_e32 vcc, v115, v65
	v_and_b32_e32 v163, 0xffff0000, v199
	v_lshlrev_b32_e32 v160, 16, v201
	v_cndmask_b32_e32 v65, v174, v115, vcc
	v_lshlrev_b32_e32 v115, 2, v65
	s_waitcnt lgkmcnt(0)
	v_add_f32_e32 v116, v126, v64
	ds_bpermute_b32 v117, v115, v116
	v_and_b32_e32 v161, 0xffff0000, v201
	v_pk_add_f32 v[70:71], v[70:71], v[162:163]
	v_pk_add_f32 v[68:69], v[68:69], v[158:159]
	v_pk_add_f32 v[66:67], v[66:67], v[160:161]
	v_lshl_add_u64 v[64:65], v[150:151], 2, s[8:9]
	v_cvt_pk_bf16_f32 v118, v68, v69
	v_cvt_pk_bf16_f32 v119, v70, v71
	v_cvt_pk_bf16_f32 v120, v82, v83
	v_cvt_pk_bf16_f32 v121, v66, v67
	global_store_dwordx4 v[122:123], v[118:121], off offset:256
	s_and_saveexec_b64 s[30:31], s[2:3]
	s_cbranch_execz .LBB0_1163
	s_waitcnt lgkmcnt(0)
	v_add_f32_e32 v116, v116, v117
	global_atomic_add_f32 v[64:65], v116, off

.LBB0_1218:
	ds_read_b128 v[144:147], v151
	ds_read_b128 v[156:159], v151 offset:1024
	ds_read_b128 v[160:163], v151 offset:2048
	ds_read_b128 v[164:167], v151 offset:3072
	s_add_u32 s30, s28, 0xfffc0080
	s_addc_u32 s31, s29, -1
	s_cmp_eq_u32 s63, 12
	s_cselect_b32 s35, s23, s31
	s_cselect_b32 s34, s59, s30
	s_cselect_b32 s31, s21, s62
	s_cselect_b32 s30, s60, s61
	v_lshl_add_u64 v[172:173], s[28:29], 0, v[136:137]
	s_add_i32 m0, s40, 0xc000
	ds_read_b128 v[168:171], v152
	ds_read_b128 v[176:179], v152 offset:1024
	ds_read_b128 v[180:183], v152 offset:2048
	ds_read_b128 v[184:187], v152 offset:3072
	ds_read_b128 v[188:191], v152 offset:4096
	ds_read_b128 v[192:195], v152 offset:5120
	ds_read_b128 v[196:199], v152 offset:6144
	ds_read_b128 v[200:203], v152 offset:7168
	global_load_lds_dwordx4 v[172:173], off
	s_add_i32 m0, s40, 0xe000
	v_lshl_add_u64 v[172:173], s[28:29], 0, v[138:139]
	global_load_lds_dwordx4 v[172:173], off
	s_waitcnt lgkmcnt(8)
	s_setprio 1
	s_barrier
	s_waitcnt lgkmcnt(0)
	v_mfma_f32_16x16x32_bf16 v[124:127], v[144:147], v[168:171], v[124:127]
	v_mfma_f32_16x16x32_bf16 v[120:123], v[160:163], v[168:171], v[120:123]
	v_mfma_f32_16x16x32_bf16 v[116:119], v[144:147], v[180:183], v[116:119]
	v_mfma_f32_16x16x32_bf16 v[112:115], v[160:163], v[180:183], v[112:115]
	v_mfma_f32_16x16x32_bf16 v[92:95], v[144:147], v[188:191], v[92:95]
	v_mfma_f32_16x16x32_bf16 v[88:91], v[160:163], v[188:191], v[88:91]
	v_mfma_f32_16x16x32_bf16 v[76:79], v[144:147], v[196:199], v[76:79]
	v_mfma_f32_16x16x32_bf16 v[72:75], v[160:163], v[196:199], v[72:75]
	v_mfma_f32_16x16x32_bf16 v[124:127], v[156:159], v[176:179], v[124:127]
	v_mfma_f32_16x16x32_bf16 v[120:123], v[164:167], v[176:179], v[120:123]
	v_mfma_f32_16x16x32_bf16 v[116:119], v[156:159], v[184:187], v[116:119]
	v_mfma_f32_16x16x32_bf16 v[112:115], v[164:167], v[184:187], v[112:115]
	v_mfma_f32_16x16x32_bf16 v[92:95], v[156:159], v[192:195], v[92:95]
	v_mfma_f32_16x16x32_bf16 v[88:91], v[164:167], v[192:195], v[88:91]
	v_mfma_f32_16x16x32_bf16 v[76:79], v[156:159], v[200:203], v[76:79]
	v_mfma_f32_16x16x32_bf16 v[72:75], v[164:167], v[200:203], v[72:75]
	s_barrier
	s_setprio 0
	s_add_i32 s64, s52, s39
	v_lshl_add_u64 v[172:173], s[30:31], 0, v[130:131]
	s_mov_b32 m0, s64
	ds_read_b128 v[204:207], v153
	ds_read_b128 v[212:215], v153 offset:1024
	ds_read_b128 v[216:219], v153 offset:2048
	ds_read_b128 v[220:223], v153 offset:3072
	global_load_lds_dwordx4 v[172:173], off
	s_add_i32 m0, s64, 0x2000
	v_lshl_add_u64 v[208:209], s[30:31], 0, v[134:135]
	global_load_lds_dwordx4 v[208:209], off
	s_setprio 1
	s_barrier
	s_waitcnt lgkmcnt(0)
	v_mfma_f32_16x16x32_bf16 v[108:111], v[204:207], v[168:171], v[108:111]
	v_mfma_f32_16x16x32_bf16 v[104:107], v[216:219], v[168:171], v[104:107]
	v_mfma_f32_16x16x32_bf16 v[100:103], v[204:207], v[180:183], v[100:103]
	v_mfma_f32_16x16x32_bf16 v[96:99], v[216:219], v[180:183], v[96:99]
	v_mfma_f32_16x16x32_bf16 v[84:87], v[204:207], v[188:191], v[84:87]
	v_mfma_f32_16x16x32_bf16 v[80:83], v[216:219], v[188:191], v[80:83]
	v_mfma_f32_16x16x32_bf16 v[68:71], v[204:207], v[196:199], v[68:71]
	v_mfma_f32_16x16x32_bf16 v[64:67], v[216:219], v[196:199], v[64:67]
	v_mfma_f32_16x16x32_bf16 v[108:111], v[212:215], v[176:179], v[108:111]
	v_mfma_f32_16x16x32_bf16 v[104:107], v[220:223], v[176:179], v[104:107]
	v_mfma_f32_16x16x32_bf16 v[100:103], v[212:215], v[184:187], v[100:103]
	v_mfma_f32_16x16x32_bf16 v[96:99], v[220:223], v[184:187], v[96:99]
	v_mfma_f32_16x16x32_bf16 v[84:87], v[212:215], v[192:195], v[84:87]
	v_mfma_f32_16x16x32_bf16 v[80:83], v[220:223], v[192:195], v[80:83]
	v_mfma_f32_16x16x32_bf16 v[68:71], v[212:215], v[200:203], v[68:71]
	v_mfma_f32_16x16x32_bf16 v[64:67], v[220:223], v[200:203], v[64:67]
	s_barrier
	s_setprio 0
	s_mov_b32 m0, s40
	v_lshl_add_u64 v[224:225], s[34:35], 0, v[128:129]
	ds_read_b128 v[168:171], v152 offset:16384
	ds_read_b128 v[176:179], v152 offset:17408
	ds_read_b128 v[180:183], v152 offset:18432
	ds_read_b128 v[184:187], v152 offset:19456
	ds_read_b128 v[188:191], v152 offset:20480
	ds_read_b128 v[192:195], v152 offset:21504
	ds_read_b128 v[196:199], v152 offset:22528
	ds_read_b128 v[200:203], v152 offset:23552
	global_load_lds_dwordx4 v[224:225], off
	s_mov_b32 m0, s41
	v_lshl_add_u64 v[226:227], s[34:35], 0, v[132:133]
	global_load_lds_dwordx4 v[226:227], off
	s_setprio 1
	s_barrier
	s_waitcnt lgkmcnt(0)
	v_mfma_f32_16x16x32_bf16 v[60:63], v[144:147], v[168:171], v[60:63]
	v_mfma_f32_16x16x32_bf16 v[56:59], v[160:163], v[168:171], v[56:59]
	v_mfma_f32_16x16x32_bf16 v[44:47], v[144:147], v[180:183], v[44:47]
	v_mfma_f32_16x16x32_bf16 v[40:43], v[160:163], v[180:183], v[40:43]
	v_mfma_f32_16x16x32_bf16 v[28:31], v[144:147], v[188:191], v[28:31]
	v_mfma_f32_16x16x32_bf16 v[24:27], v[160:163], v[188:191], v[24:27]
	v_mfma_f32_16x16x32_bf16 v[12:15], v[144:147], v[196:199], v[12:15]
	v_mfma_f32_16x16x32_bf16 v[8:11], v[160:163], v[196:199], v[8:11]
	v_mfma_f32_16x16x32_bf16 v[60:63], v[156:159], v[176:179], v[60:63]
	v_mfma_f32_16x16x32_bf16 v[56:59], v[164:167], v[176:179], v[56:59]
	v_mfma_f32_16x16x32_bf16 v[44:47], v[156:159], v[184:187], v[44:47]
	v_mfma_f32_16x16x32_bf16 v[40:43], v[164:167], v[184:187], v[40:43]
	v_mfma_f32_16x16x32_bf16 v[28:31], v[156:159], v[192:195], v[28:31]
	v_mfma_f32_16x16x32_bf16 v[24:27], v[164:167], v[192:195], v[24:27]
	v_mfma_f32_16x16x32_bf16 v[12:15], v[156:159], v[200:203], v[12:15]
	v_mfma_f32_16x16x32_bf16 v[8:11], v[164:167], v[200:203], v[8:11]
	s_barrier
	s_setprio 0
	s_add_u32 s64, s30, 0x40000
	s_addc_u32 s65, s31, 0
	s_add_i32 s66, s53, s39
	s_mov_b32 m0, s66
	v_lshl_add_u64 v[144:145], s[64:65], 0, v[130:131]
	global_load_lds_dwordx4 v[144:145], off
	s_add_i32 m0, s66, 0x2000
	v_lshl_add_u64 v[144:145], s[64:65], 0, v[134:135]
	global_load_lds_dwordx4 v[144:145], off
	s_waitcnt vmcnt(6)
	s_setprio 1
	s_barrier
	v_mfma_f32_16x16x32_bf16 v[52:55], v[204:207], v[168:171], v[52:55]
	v_mfma_f32_16x16x32_bf16 v[48:51], v[216:219], v[168:171], v[48:51]
	v_mfma_f32_16x16x32_bf16 v[36:39], v[204:207], v[180:183], v[36:39]
	v_mfma_f32_16x16x32_bf16 v[32:35], v[216:219], v[180:183], v[32:35]
	v_mfma_f32_16x16x32_bf16 v[20:23], v[204:207], v[188:191], v[20:23]
	v_mfma_f32_16x16x32_bf16 v[16:19], v[216:219], v[188:191], v[16:19]
	v_mfma_f32_16x16x32_bf16 v[4:7], v[204:207], v[196:199], v[4:7]
	v_mfma_f32_16x16x32_bf16 v[0:3], v[216:219], v[196:199], v[0:3]
	v_mfma_f32_16x16x32_bf16 v[52:55], v[212:215], v[176:179], v[52:55]
	v_mfma_f32_16x16x32_bf16 v[48:51], v[220:223], v[176:179], v[48:51]
	v_mfma_f32_16x16x32_bf16 v[36:39], v[212:215], v[184:187], v[36:39]
	v_mfma_f32_16x16x32_bf16 v[32:35], v[220:223], v[184:187], v[32:35]
	v_mfma_f32_16x16x32_bf16 v[20:23], v[212:215], v[192:195], v[20:23]
	v_mfma_f32_16x16x32_bf16 v[16:19], v[220:223], v[192:195], v[16:19]
	v_mfma_f32_16x16x32_bf16 v[4:7], v[212:215], v[200:203], v[4:7]
	v_mfma_f32_16x16x32_bf16 v[0:3], v[220:223], v[200:203], v[0:3]
	s_barrier
	s_setprio 0
	s_add_i32 s64, 0, 0x18000
	v_add_u32_e32 v155, s64, v149
	ds_read_b128 v[144:147], v155
	ds_read_b128 v[156:159], v155 offset:1024
	ds_read_b128 v[160:163], v155 offset:2048
	ds_read_b128 v[164:167], v155 offset:3072
	s_add_u32 s34, s34, 0x40000
	s_addc_u32 s35, s35, 0
	s_mov_b32 m0, s42
	v_lshl_add_u64 v[204:205], s[34:35], 0, v[128:129]
	ds_read_b128 v[168:171], v152 offset:32768
	ds_read_b128 v[176:179], v152 offset:33792
	ds_read_b128 v[180:183], v152 offset:34816
	ds_read_b128 v[184:187], v152 offset:35840
	ds_read_b128 v[188:191], v152 offset:36864
	ds_read_b128 v[192:195], v152 offset:37888
	ds_read_b128 v[196:199], v152 offset:38912
	ds_read_b128 v[200:203], v152 offset:39936
	global_load_lds_dwordx4 v[204:205], off
	s_mov_b32 m0, s43
	v_lshl_add_u64 v[204:205], s[34:35], 0, v[132:133]
	global_load_lds_dwordx4 v[204:205], off
	s_waitcnt lgkmcnt(8)
	s_setprio 1
	s_barrier
	s_waitcnt lgkmcnt(0)
	v_mfma_f32_16x16x32_bf16 v[124:127], v[144:147], v[168:171], v[124:127]
	v_mfma_f32_16x16x32_bf16 v[120:123], v[160:163], v[168:171], v[120:123]
	v_mfma_f32_16x16x32_bf16 v[116:119], v[144:147], v[180:183], v[116:119]
	v_mfma_f32_16x16x32_bf16 v[112:115], v[160:163], v[180:183], v[112:115]
	v_mfma_f32_16x16x32_bf16 v[92:95], v[144:147], v[188:191], v[92:95]
	v_mfma_f32_16x16x32_bf16 v[88:91], v[160:163], v[188:191], v[88:91]
	v_mfma_f32_16x16x32_bf16 v[76:79], v[144:147], v[196:199], v[76:79]
	v_mfma_f32_16x16x32_bf16 v[72:75], v[160:163], v[196:199], v[72:75]
	v_mfma_f32_16x16x32_bf16 v[124:127], v[156:159], v[176:179], v[124:127]
	v_mfma_f32_16x16x32_bf16 v[120:123], v[164:167], v[176:179], v[120:123]
	v_mfma_f32_16x16x32_bf16 v[116:119], v[156:159], v[184:187], v[116:119]
	v_mfma_f32_16x16x32_bf16 v[112:115], v[164:167], v[184:187], v[112:115]
	v_mfma_f32_16x16x32_bf16 v[92:95], v[156:159], v[192:195], v[92:95]
	v_mfma_f32_16x16x32_bf16 v[88:91], v[164:167], v[192:195], v[88:91]
	v_mfma_f32_16x16x32_bf16 v[76:79], v[156:159], v[200:203], v[76:79]
	v_mfma_f32_16x16x32_bf16 v[72:75], v[164:167], v[200:203], v[72:75]
	s_barrier
	s_setprio 0
	s_add_i32 s34, 0, 0x1c000
	s_add_i32 s35, s64, s39
	v_add_u32_e32 v155, s34, v149
	v_lshl_add_u64 v[172:173], v[172:173], 0, s[6:7]
	s_mov_b32 m0, s35
	ds_read_b128 v[204:207], v155
	ds_read_b128 v[212:215], v155 offset:1024
	ds_read_b128 v[216:219], v155 offset:2048
	ds_read_b128 v[220:223], v155 offset:3072
	global_load_lds_dwordx4 v[172:173], off
	s_add_i32 m0, s35, 0x2000
	v_lshl_add_u64 v[172:173], v[208:209], 0, s[6:7]
	global_load_lds_dwordx4 v[172:173], off
	s_setprio 1
	s_barrier
	s_waitcnt lgkmcnt(0)
	v_mfma_f32_16x16x32_bf16 v[108:111], v[204:207], v[168:171], v[108:111]
	v_mfma_f32_16x16x32_bf16 v[104:107], v[216:219], v[168:171], v[104:107]
	v_mfma_f32_16x16x32_bf16 v[100:103], v[204:207], v[180:183], v[100:103]
	v_mfma_f32_16x16x32_bf16 v[96:99], v[216:219], v[180:183], v[96:99]
	v_mfma_f32_16x16x32_bf16 v[84:87], v[204:207], v[188:191], v[84:87]
	v_mfma_f32_16x16x32_bf16 v[80:83], v[216:219], v[188:191], v[80:83]
	v_mfma_f32_16x16x32_bf16 v[68:71], v[204:207], v[196:199], v[68:71]
	v_mfma_f32_16x16x32_bf16 v[64:67], v[216:219], v[196:199], v[64:67]
	v_mfma_f32_16x16x32_bf16 v[108:111], v[212:215], v[176:179], v[108:111]
	v_mfma_f32_16x16x32_bf16 v[104:107], v[220:223], v[176:179], v[104:107]
	v_mfma_f32_16x16x32_bf16 v[100:103], v[212:215], v[184:187], v[100:103]
	v_mfma_f32_16x16x32_bf16 v[96:99], v[220:223], v[184:187], v[96:99]
	v_mfma_f32_16x16x32_bf16 v[84:87], v[212:215], v[192:195], v[84:87]
	v_mfma_f32_16x16x32_bf16 v[80:83], v[220:223], v[192:195], v[80:83]
	v_mfma_f32_16x16x32_bf16 v[68:71], v[212:215], v[200:203], v[68:71]
	v_mfma_f32_16x16x32_bf16 v[64:67], v[220:223], v[200:203], v[64:67]
	s_barrier
	s_setprio 0
	s_mov_b32 m0, s49
	v_lshl_add_u64 v[172:173], v[224:225], 0, s[6:7]
	ds_read_b128 v[168:171], v152 offset:49152
	ds_read_b128 v[176:179], v152 offset:50176
	ds_read_b128 v[180:183], v152 offset:51200
	ds_read_b128 v[184:187], v152 offset:52224
	ds_read_b128 v[188:191], v152 offset:53248
	ds_read_b128 v[192:195], v152 offset:54272
	ds_read_b128 v[196:199], v152 offset:55296
	ds_read_b128 v[200:203], v152 offset:56320
	global_load_lds_dwordx4 v[172:173], off
	s_mov_b32 m0, s50
	v_lshl_add_u64 v[172:173], v[226:227], 0, s[6:7]
	global_load_lds_dwordx4 v[172:173], off
	s_setprio 1
	s_barrier
	s_waitcnt lgkmcnt(0)
	v_mfma_f32_16x16x32_bf16 v[60:63], v[144:147], v[168:171], v[60:63]
	v_mfma_f32_16x16x32_bf16 v[56:59], v[160:163], v[168:171], v[56:59]
	v_mfma_f32_16x16x32_bf16 v[44:47], v[144:147], v[180:183], v[44:47]
	v_mfma_f32_16x16x32_bf16 v[40:43], v[160:163], v[180:183], v[40:43]
	v_mfma_f32_16x16x32_bf16 v[28:31], v[144:147], v[188:191], v[28:31]
	v_mfma_f32_16x16x32_bf16 v[24:27], v[160:163], v[188:191], v[24:27]
	v_mfma_f32_16x16x32_bf16 v[12:15], v[144:147], v[196:199], v[12:15]
	v_mfma_f32_16x16x32_bf16 v[8:11], v[160:163], v[196:199], v[8:11]
	v_mfma_f32_16x16x32_bf16 v[60:63], v[156:159], v[176:179], v[60:63]
	v_mfma_f32_16x16x32_bf16 v[56:59], v[164:167], v[176:179], v[56:59]
	v_mfma_f32_16x16x32_bf16 v[44:47], v[156:159], v[184:187], v[44:47]
	v_mfma_f32_16x16x32_bf16 v[40:43], v[164:167], v[184:187], v[40:43]
	v_mfma_f32_16x16x32_bf16 v[28:31], v[156:159], v[192:195], v[28:31]
	v_mfma_f32_16x16x32_bf16 v[24:27], v[164:167], v[192:195], v[24:27]
	v_mfma_f32_16x16x32_bf16 v[12:15], v[156:159], v[200:203], v[12:15]
	v_mfma_f32_16x16x32_bf16 v[8:11], v[164:167], v[200:203], v[8:11]
	s_barrier
	s_setprio 0
	s_add_u32 s30, s30, 0x40080
	s_addc_u32 s31, s31, 0
	s_add_i32 s34, s34, s39
	s_mov_b32 m0, s34
	v_lshl_add_u64 v[144:145], s[30:31], 0, v[130:131]
	global_load_lds_dwordx4 v[144:145], off
	s_add_i32 m0, s34, 0x2000
	v_lshl_add_u64 v[144:145], s[30:31], 0, v[134:135]
	global_load_lds_dwordx4 v[144:145], off
	s_waitcnt vmcnt(6)
	s_setprio 1
	s_barrier
	v_mfma_f32_16x16x32_bf16 v[52:55], v[204:207], v[168:171], v[52:55]
	v_mfma_f32_16x16x32_bf16 v[48:51], v[216:219], v[168:171], v[48:51]
	v_mfma_f32_16x16x32_bf16 v[36:39], v[204:207], v[180:183], v[36:39]
	v_mfma_f32_16x16x32_bf16 v[32:35], v[216:219], v[180:183], v[32:35]
	v_mfma_f32_16x16x32_bf16 v[20:23], v[204:207], v[188:191], v[20:23]
	v_mfma_f32_16x16x32_bf16 v[16:19], v[216:219], v[188:191], v[16:19]
	v_mfma_f32_16x16x32_bf16 v[4:7], v[204:207], v[196:199], v[4:7]
	v_mfma_f32_16x16x32_bf16 v[0:3], v[216:219], v[196:199], v[0:3]
	v_mfma_f32_16x16x32_bf16 v[52:55], v[212:215], v[176:179], v[52:55]
	v_mfma_f32_16x16x32_bf16 v[48:51], v[220:223], v[176:179], v[48:51]
	v_mfma_f32_16x16x32_bf16 v[36:39], v[212:215], v[184:187], v[36:39]
	v_mfma_f32_16x16x32_bf16 v[32:35], v[220:223], v[184:187], v[32:35]
	v_mfma_f32_16x16x32_bf16 v[20:23], v[212:215], v[192:195], v[20:23]
	v_mfma_f32_16x16x32_bf16 v[16:19], v[220:223], v[192:195], v[16:19]
	v_mfma_f32_16x16x32_bf16 v[4:7], v[212:215], v[200:203], v[4:7]
	v_mfma_f32_16x16x32_bf16 v[0:3], v[220:223], v[200:203], v[0:3]
	s_barrier
	s_setprio 0
	s_add_i32 s63, s63, 2
	s_add_u32 s28, s28, 0x100
	s_addc_u32 s29, s29, 0
	s_add_u32 s61, s61, 0x100
	s_addc_u32 s62, s62, 0
	s_cmp_gt_u32 s63, 13
	s_cbranch_scc0 .LBB0_1218
	v_lshl_add_u32 v146, s0, 8, v148
	v_ashrrev_i32_e32 v147, 31, v146
	v_lshl_add_u64 v[144:145], v[146:147], 2, s[8:9]
	global_load_dword v155, v[144:145], off
	global_load_dword v162, v[144:145], off offset:64
	global_load_dword v163, v[144:145], off offset:128
	global_load_dword v164, v[144:145], off offset:192
	global_load_dword v165, v[144:145], off offset:512
	global_load_dword v166, v[144:145], off offset:576
	global_load_dword v167, v[144:145], off offset:640
	global_load_dword v168, v[144:145], off offset:704
	v_lshl_or_b32 v144, s1, 8, v150
	v_ashrrev_i32_e32 v145, 31, v144
	v_lshlrev_b64 v[158:159], 13, v[146:147]
	v_lshlrev_b64 v[160:161], 1, v[144:145]
	v_lshl_add_u64 v[144:145], s[92:93], 0, v[158:159]
	v_lshl_add_u64 v[144:145], v[144:145], 0, v[160:161]
	v_or_b32_e32 v156, 16, v146
	v_ashrrev_i32_e32 v157, 31, v156
	v_lshlrev_b64 v[156:157], 13, v[156:157]
	v_lshl_add_u64 v[156:157], s[92:93], 0, v[156:157]
	v_lshl_add_u64 v[156:157], v[156:157], 0, v[160:161]
	s_mov_b64 s[30:31], s[26:27]
	s_mov_b64 s[28:29], s[24:25]
	s_waitcnt vmcnt(0)
	v_fmamk_f32 v147, v155, 0x3a800000, v154
	v_mul_f32_e32 v158, 0x4b800000, v147
	v_cmp_gt_f32_e32 vcc, s54, v147
	v_fmamk_f32 v155, v162, 0x3a800000, v154
	v_mul_f32_e32 v162, 0x4b800000, v155
	v_cndmask_b32_e32 v147, v147, v158, vcc
	v_rsq_f32_e32 v158, v147
	v_cmp_gt_f32_e64 s[0:1], s54, v155
	v_fmamk_f32 v159, v163, 0x3a800000, v154
	v_fmamk_f32 v163, v164, 0x3a800000, v154
	v_cndmask_b32_e64 v155, v155, v162, s[0:1]
	v_rsq_f32_e32 v155, v155
	v_mul_f32_e32 v162, 0x45800000, v158
	v_cndmask_b32_e32 v158, v158, v162, vcc
	v_pk_mul_f32 v[124:125], v[124:125], v[158:159] op_sel_hi:[1,0]
	v_pk_mul_f32 v[104:105], v[104:105], v[158:159] op_sel_hi:[1,0]
	v_fmamk_f32 v164, v165, 0x3a800000, v154
	v_fmamk_f32 v165, v166, 0x3a800000, v154
	v_fmamk_f32 v166, v167, 0x3a800000, v154
	v_mul_f32_e32 v167, 0x45800000, v155
	v_pk_mul_f32 v[126:127], v[126:127], v[158:159] op_sel_hi:[1,0]
	v_pk_mul_f32 v[122:123], v[122:123], v[158:159] op_sel_hi:[1,0]
	v_pk_mul_f32 v[120:121], v[120:121], v[158:159] op_sel_hi:[1,0]
	v_pk_mul_f32 v[108:109], v[108:109], v[158:159] op_sel_hi:[1,0]
	v_pk_mul_f32 v[106:107], v[106:107], v[158:159] op_sel_hi:[1,0]
	v_max_f32_e32 v124, 0, v124
	v_max_f32_e32 v125, 0, v125
	v_max_f32_e32 v104, 0, v104
	v_cndmask_b32_e64 v162, v155, v167, s[0:1]
	v_pk_mul_f32 v[110:111], v[110:111], v[158:159] op_sel_hi:[1,0]
	v_max_f32_e32 v120, 0, v120
	v_max_f32_e32 v121, 0, v121
	v_max_f32_e32 v126, 0, v126
	v_max_f32_e32 v122, 0, v122
	v_max_f32_e32 v127, 0, v127
	v_max_f32_e32 v123, 0, v123
	v_max_f32_e32 v108, 0, v108
	v_max_f32_e32 v109, 0, v109
	v_max_f32_e32 v105, 0, v105
	v_max_f32_e32 v106, 0, v106
	v_max_f32_e32 v107, 0, v107
	v_mul_f32_e32 v124, v124, v124
	v_mul_f32_e32 v125, v125, v125
	v_mul_f32_e32 v155, v104, v104
	v_cvt_pk_bf16_f32 v104, v124, v125
	v_fmamk_f32 v147, v168, 0x3a800000, v154
	v_pk_mul_f32 v[112:113], v[112:113], v[162:163] op_sel_hi:[1,0]
	v_max_f32_e32 v110, 0, v110
	v_max_f32_e32 v111, 0, v111
	v_mul_f32_e32 v120, v120, v120
	v_mul_f32_e32 v121, v121, v121
	v_mul_f32_e32 v126, v126, v126
	v_mul_f32_e32 v122, v122, v122
	v_mul_f32_e32 v127, v127, v127
	v_mul_f32_e32 v123, v123, v123
	v_mul_f32_e32 v108, v108, v108
	v_mul_f32_e32 v109, v109, v109
	v_mul_f32_e32 v158, v105, v105
	v_mul_f32_e32 v167, v106, v106
	v_mul_f32_e32 v168, v107, v107
	v_cvt_pk_bf16_f32 v105, v126, v127
	v_cvt_pk_bf16_f32 v106, v120, v121
	v_cvt_pk_bf16_f32 v107, v122, v123
	global_store_dwordx4 v[144:145], v[104:107], off nt
	v_pk_mul_f32 v[116:117], v[116:117], v[162:163] op_sel_hi:[1,0]
	v_mul_f32_e32 v110, v110, v110
	v_cvt_pk_bf16_f32 v104, v108, v109
	v_mul_f32_e32 v111, v111, v111
	v_cvt_pk_bf16_f32 v105, v110, v111
	v_cvt_pk_bf16_f32 v106, v155, v158
	v_cvt_pk_bf16_f32 v107, v167, v168
	global_store_dwordx4 v[144:145], v[104:107], off offset:256 nt
	v_pk_mul_f32 v[118:119], v[118:119], v[162:163] op_sel_hi:[1,0]
	v_pk_mul_f32 v[114:115], v[114:115], v[162:163] op_sel_hi:[1,0]
	v_max_f32_e32 v104, 0, v112
	v_mul_f32_e32 v106, v104, v104
	v_max_f32_e32 v104, 0, v117
	v_max_f32_e32 v116, 0, v116
	v_max_f32_e32 v107, 0, v113
	v_mul_f32_e32 v104, v104, v104
	v_pk_mul_f32 v[98:99], v[98:99], v[162:163] op_sel_hi:[1,0]
	v_pk_mul_f32 v[96:97], v[96:97], v[162:163] op_sel_hi:[1,0]
	v_mul_f32_e32 v105, v116, v116
	v_mul_f32_e32 v107, v107, v107
	v_max_f32_e32 v108, 0, v118
	v_max_f32_e32 v109, 0, v114
	v_max_f32_e32 v110, 0, v119
	v_max_f32_e32 v111, 0, v115
	v_cvt_pk_bf16_f32 v104, v105, v104
	v_pk_mul_f32 v[102:103], v[102:103], v[162:163] op_sel_hi:[1,0]
	v_pk_mul_f32 v[100:101], v[100:101], v[162:163] op_sel_hi:[1,0]
	v_max_f32_e32 v96, 0, v96
	v_max_f32_e32 v97, 0, v97
	v_max_f32_e32 v98, 0, v98
	v_mul_f32_e32 v108, v108, v108
	v_mul_f32_e32 v109, v109, v109
	v_mul_f32_e32 v110, v110, v110
	v_mul_f32_e32 v111, v111, v111
	v_cvt_pk_bf16_f32 v105, v108, v110
	v_cvt_pk_bf16_f32 v106, v106, v107
	v_cvt_pk_bf16_f32 v107, v109, v111
	global_store_dwordx4 v[156:157], v[104:107], off nt
	v_max_f32_e32 v100, 0, v100
	v_max_f32_e32 v99, 0, v99
	v_mul_f32_e32 v104, v96, v96
	v_max_f32_e32 v96, 0, v101
	v_mul_f32_e32 v101, v97, v97
	v_max_f32_e32 v97, 0, v102
	v_mul_f32_e32 v102, v98, v98
	v_max_f32_e32 v98, 0, v103
	v_mul_f32_e32 v96, v96, v96
	v_mul_f32_e32 v97, v97, v97
	v_mul_f32_e32 v98, v98, v98
	v_mul_f32_e32 v100, v100, v100
	v_mul_f32_e32 v99, v99, v99
	v_cvt_pk_bf16_f32 v96, v100, v96
	v_cvt_pk_bf16_f32 v97, v97, v98
	v_cvt_pk_bf16_f32 v98, v104, v101
	v_cvt_pk_bf16_f32 v99, v102, v99
	global_store_dwordx4 v[156:157], v[96:99], off offset:256 nt
	v_cmp_gt_f32_e32 vcc, s54, v159
	s_mov_b32 s1, s20
	v_mul_f32_e32 v98, 0x4b800000, v159
	v_cndmask_b32_e32 v98, v159, v98, vcc
	v_rsq_f32_e32 v98, v98
	v_or_b32_e32 v96, 32, v146
	v_ashrrev_i32_e32 v97, 31, v96
	v_lshlrev_b64 v[96:97], 13, v[96:97]
	v_mul_f32_e32 v99, 0x45800000, v98
	v_cndmask_b32_e32 v98, v98, v99, vcc
	v_pk_mul_f32 v[88:89], v[88:89], v[98:99] op_sel_hi:[1,0]
	v_pk_mul_f32 v[92:93], v[92:93], v[98:99] op_sel_hi:[1,0]
	v_pk_mul_f32 v[90:91], v[90:91], v[98:99] op_sel_hi:[1,0]
	v_max_f32_e32 v88, 0, v88
	v_pk_mul_f32 v[94:95], v[94:95], v[98:99] op_sel_hi:[1,0]
	v_mul_f32_e32 v99, v88, v88
	v_max_f32_e32 v88, 0, v93
	v_max_f32_e32 v89, 0, v89
	v_max_f32_e32 v90, 0, v90
	v_lshl_add_u64 v[96:97], s[92:93], 0, v[96:97]
	v_max_f32_e32 v92, 0, v92
	v_mul_f32_e32 v88, v88, v88
	v_mul_f32_e32 v93, v89, v89
	v_max_f32_e32 v89, 0, v94
	v_mul_f32_e32 v94, v90, v90
	v_max_f32_e32 v90, 0, v95
	v_max_f32_e32 v91, 0, v91
	v_pk_mul_f32 v[82:83], v[82:83], v[98:99] op_sel_hi:[1,0]
	v_pk_mul_f32 v[80:81], v[80:81], v[98:99] op_sel_hi:[1,0]
	v_lshl_add_u64 v[96:97], v[96:97], 0, v[160:161]
	v_mul_f32_e32 v92, v92, v92
	v_mul_f32_e32 v89, v89, v89
	v_mul_f32_e32 v90, v90, v90
	v_mul_f32_e32 v91, v91, v91
	v_cvt_pk_bf16_f32 v88, v92, v88
	v_pk_mul_f32 v[86:87], v[86:87], v[98:99] op_sel_hi:[1,0]
	v_pk_mul_f32 v[84:85], v[84:85], v[98:99] op_sel_hi:[1,0]
	v_max_f32_e32 v80, 0, v80
	v_max_f32_e32 v81, 0, v81
	v_max_f32_e32 v82, 0, v82
	v_cvt_pk_bf16_f32 v89, v89, v90
	v_cvt_pk_bf16_f32 v90, v99, v93
	v_cvt_pk_bf16_f32 v91, v94, v91
	global_store_dwordx4 v[96:97], v[88:91], off nt
	v_max_f32_e32 v84, 0, v84
	v_max_f32_e32 v83, 0, v83
	v_mul_f32_e32 v88, v80, v80
	v_max_f32_e32 v80, 0, v85
	v_mul_f32_e32 v85, v81, v81
	v_max_f32_e32 v81, 0, v86
	v_mul_f32_e32 v86, v82, v82
	v_max_f32_e32 v82, 0, v87
	v_mul_f32_e32 v80, v80, v80
	v_mul_f32_e32 v81, v81, v81
	v_mul_f32_e32 v82, v82, v82
	v_mul_f32_e32 v84, v84, v84
	v_mul_f32_e32 v83, v83, v83
	v_cvt_pk_bf16_f32 v80, v84, v80
	v_cvt_pk_bf16_f32 v81, v81, v82
	v_cvt_pk_bf16_f32 v82, v88, v85
	v_cvt_pk_bf16_f32 v83, v86, v83
	global_store_dwordx4 v[96:97], v[80:83], off offset:256 nt
	v_cmp_gt_f32_e32 vcc, s54, v163
	s_mov_b32 s0, s22
	v_mul_f32_e32 v82, 0x4b800000, v163
	v_cndmask_b32_e32 v82, v163, v82, vcc
	v_rsq_f32_e32 v82, v82
	v_or_b32_e32 v80, 48, v146
	v_ashrrev_i32_e32 v81, 31, v80
	v_lshlrev_b64 v[80:81], 13, v[80:81]
	v_mul_f32_e32 v83, 0x45800000, v82
	v_cndmask_b32_e32 v82, v82, v83, vcc
	v_pk_mul_f32 v[72:73], v[72:73], v[82:83] op_sel_hi:[1,0]
	v_pk_mul_f32 v[76:77], v[76:77], v[82:83] op_sel_hi:[1,0]
	v_pk_mul_f32 v[74:75], v[74:75], v[82:83] op_sel_hi:[1,0]
	v_max_f32_e32 v72, 0, v72
	v_pk_mul_f32 v[78:79], v[78:79], v[82:83] op_sel_hi:[1,0]
	v_mul_f32_e32 v83, v72, v72
	v_max_f32_e32 v72, 0, v77
	v_max_f32_e32 v73, 0, v73
	v_max_f32_e32 v74, 0, v74
	v_lshl_add_u64 v[80:81], s[92:93], 0, v[80:81]
	v_max_f32_e32 v76, 0, v76
	v_mul_f32_e32 v72, v72, v72
	v_mul_f32_e32 v77, v73, v73
	v_max_f32_e32 v73, 0, v78
	v_mul_f32_e32 v78, v74, v74
	v_max_f32_e32 v74, 0, v79
	v_max_f32_e32 v75, 0, v75
	v_pk_mul_f32 v[64:65], v[64:65], v[82:83] op_sel_hi:[1,0]
	v_lshl_add_u64 v[80:81], v[80:81], 0, v[160:161]
	v_mul_f32_e32 v76, v76, v76
	v_mul_f32_e32 v73, v73, v73
	v_mul_f32_e32 v74, v74, v74
	v_mul_f32_e32 v75, v75, v75
	v_cvt_pk_bf16_f32 v72, v76, v72
	v_pk_mul_f32 v[68:69], v[68:69], v[82:83] op_sel_hi:[1,0]
	v_max_f32_e32 v64, 0, v64
	v_cvt_pk_bf16_f32 v73, v73, v74
	v_cvt_pk_bf16_f32 v74, v83, v77
	v_cvt_pk_bf16_f32 v75, v78, v75
	global_store_dwordx4 v[80:81], v[72:75], off nt
	v_max_f32_e32 v68, 0, v68
	v_mul_f32_e32 v68, v68, v68
	v_mul_f32_e32 v72, v64, v64
	v_max_f32_e32 v64, 0, v69
	v_mul_f32_e32 v64, v64, v64
	v_cvt_pk_bf16_f32 v64, v68, v64
	v_mul_f32_e32 v68, 0x4b800000, v164
	v_cmp_gt_f32_e32 vcc, s54, v164
	v_pk_mul_f32 v[66:67], v[66:67], v[82:83] op_sel_hi:[1,0]
	v_pk_mul_f32 v[70:71], v[70:71], v[82:83] op_sel_hi:[1,0]
	v_cndmask_b32_e32 v68, v164, v68, vcc
	v_max_f32_e32 v65, 0, v65
	v_max_f32_e32 v66, 0, v66
	v_rsq_f32_e32 v68, v68
	v_mul_f32_e32 v69, v65, v65
	v_max_f32_e32 v65, 0, v70
	v_mul_f32_e32 v70, v66, v66
	v_max_f32_e32 v66, 0, v71
	v_mul_f32_e32 v65, v65, v65
	v_max_f32_e32 v67, 0, v67
	v_mul_f32_e32 v66, v66, v66
	v_mul_f32_e32 v67, v67, v67
	v_cvt_pk_bf16_f32 v65, v65, v66
	v_cvt_pk_bf16_f32 v66, v72, v69
	v_cvt_pk_bf16_f32 v67, v70, v67
	global_store_dwordx4 v[80:81], v[64:67], off offset:256 nt
	s_nop 1
	v_mul_f32_e32 v66, 0x45800000, v68
	v_cndmask_b32_e32 v66, v68, v66, vcc
	v_pk_mul_f32 v[56:57], v[56:57], v[66:67] op_sel_hi:[1,0]
	v_pk_mul_f32 v[60:61], v[60:61], v[66:67] op_sel_hi:[1,0]
	v_pk_mul_f32 v[58:59], v[58:59], v[66:67] op_sel_hi:[1,0]
	v_max_f32_e32 v56, 0, v56
	v_pk_mul_f32 v[62:63], v[62:63], v[66:67] op_sel_hi:[1,0]
	v_max_f32_e32 v60, 0, v60
	v_mul_f32_e32 v67, v56, v56
	v_max_f32_e32 v56, 0, v61
	v_max_f32_e32 v57, 0, v57
	v_max_f32_e32 v58, 0, v58
	v_mul_f32_e32 v60, v60, v60
	v_mul_f32_e32 v56, v56, v56
	v_mul_f32_e32 v61, v57, v57
	v_max_f32_e32 v57, 0, v62
	v_mul_f32_e32 v62, v58, v58
	v_max_f32_e32 v58, 0, v63
	v_mul_f32_e32 v57, v57, v57
	v_max_f32_e32 v59, 0, v59
	v_mul_f32_e32 v58, v58, v58
	v_cvt_pk_bf16_f32 v56, v60, v56
	v_add_co_u32_e32 v60, vcc, s55, v144
	v_pk_mul_f32 v[48:49], v[48:49], v[66:67] op_sel_hi:[1,0]
	v_mul_f32_e32 v59, v59, v59
	v_cvt_pk_bf16_f32 v57, v57, v58
	v_cvt_pk_bf16_f32 v58, v67, v61
	v_addc_co_u32_e32 v61, vcc, 0, v145, vcc
	v_pk_mul_f32 v[52:53], v[52:53], v[66:67] op_sel_hi:[1,0]
	v_max_f32_e32 v48, 0, v48
	v_cvt_pk_bf16_f32 v59, v62, v59
	global_store_dwordx4 v[60:61], v[56:59], off nt
	v_max_f32_e32 v52, 0, v52
	v_mul_f32_e32 v52, v52, v52
	v_mul_f32_e32 v56, v48, v48
	v_max_f32_e32 v48, 0, v53
	v_mul_f32_e32 v48, v48, v48
	v_cvt_pk_bf16_f32 v48, v52, v48
	v_mul_f32_e32 v52, 0x4b800000, v165
	v_cmp_gt_f32_e32 vcc, s54, v165
	v_pk_mul_f32 v[50:51], v[50:51], v[66:67] op_sel_hi:[1,0]
	v_pk_mul_f32 v[54:55], v[54:55], v[66:67] op_sel_hi:[1,0]
	v_cndmask_b32_e32 v52, v165, v52, vcc
	v_max_f32_e32 v49, 0, v49
	v_max_f32_e32 v50, 0, v50
	v_rsq_f32_e32 v52, v52
	v_mul_f32_e32 v53, v49, v49
	v_max_f32_e32 v49, 0, v54
	v_mul_f32_e32 v54, v50, v50
	v_max_f32_e32 v50, 0, v55
	v_mul_f32_e32 v49, v49, v49
	v_max_f32_e32 v51, 0, v51
	v_mul_f32_e32 v50, v50, v50
	v_lshl_add_u64 v[64:65], v[144:145], 0, s[12:13]
	v_mul_f32_e32 v51, v51, v51
	v_cvt_pk_bf16_f32 v49, v49, v50
	v_cvt_pk_bf16_f32 v50, v56, v53
	v_cvt_pk_bf16_f32 v51, v54, v51
	global_store_dwordx4 v[64:65], v[48:51], off offset:256 nt
	s_nop 1
	v_mul_f32_e32 v50, 0x45800000, v52
	v_cndmask_b32_e32 v50, v52, v50, vcc
	v_pk_mul_f32 v[40:41], v[40:41], v[50:51] op_sel_hi:[1,0]
	v_pk_mul_f32 v[44:45], v[44:45], v[50:51] op_sel_hi:[1,0]
	v_pk_mul_f32 v[42:43], v[42:43], v[50:51] op_sel_hi:[1,0]
	v_max_f32_e32 v40, 0, v40
	v_pk_mul_f32 v[46:47], v[46:47], v[50:51] op_sel_hi:[1,0]
	v_max_f32_e32 v44, 0, v44
	v_mul_f32_e32 v51, v40, v40
	v_max_f32_e32 v40, 0, v45
	v_max_f32_e32 v41, 0, v41
	v_max_f32_e32 v42, 0, v42
	v_mul_f32_e32 v44, v44, v44
	v_mul_f32_e32 v40, v40, v40
	v_mul_f32_e32 v45, v41, v41
	v_max_f32_e32 v41, 0, v46
	v_mul_f32_e32 v46, v42, v42
	v_max_f32_e32 v42, 0, v47
	v_mul_f32_e32 v41, v41, v41
	v_max_f32_e32 v43, 0, v43
	v_mul_f32_e32 v42, v42, v42
	v_cvt_pk_bf16_f32 v40, v44, v40
	v_add_co_u32_e32 v44, vcc, s56, v144
	v_pk_mul_f32 v[32:33], v[32:33], v[50:51] op_sel_hi:[1,0]
	v_mul_f32_e32 v43, v43, v43
	v_cvt_pk_bf16_f32 v41, v41, v42
	v_cvt_pk_bf16_f32 v42, v51, v45
	v_addc_co_u32_e32 v45, vcc, 0, v145, vcc
	v_pk_mul_f32 v[36:37], v[36:37], v[50:51] op_sel_hi:[1,0]
	v_max_f32_e32 v32, 0, v32
	v_cvt_pk_bf16_f32 v43, v46, v43
	global_store_dwordx4 v[44:45], v[40:43], off nt
	v_max_f32_e32 v36, 0, v36
	v_mul_f32_e32 v36, v36, v36
	v_mul_f32_e32 v40, v32, v32
	v_max_f32_e32 v32, 0, v37
	v_mul_f32_e32 v32, v32, v32
	v_cvt_pk_bf16_f32 v32, v36, v32
	v_mul_f32_e32 v36, 0x4b800000, v166
	v_cmp_gt_f32_e32 vcc, s54, v166
	v_pk_mul_f32 v[34:35], v[34:35], v[50:51] op_sel_hi:[1,0]
	v_pk_mul_f32 v[38:39], v[38:39], v[50:51] op_sel_hi:[1,0]
	v_cndmask_b32_e32 v36, v166, v36, vcc
	v_max_f32_e32 v33, 0, v33
	v_max_f32_e32 v34, 0, v34
	v_rsq_f32_e32 v36, v36
	v_mul_f32_e32 v37, v33, v33
	v_max_f32_e32 v33, 0, v38
	v_mul_f32_e32 v38, v34, v34
	v_max_f32_e32 v34, 0, v39
	v_mul_f32_e32 v33, v33, v33
	v_max_f32_e32 v35, 0, v35
	v_mul_f32_e32 v34, v34, v34
	v_lshl_add_u64 v[48:49], v[144:145], 0, s[14:15]
	v_mul_f32_e32 v35, v35, v35
	v_cvt_pk_bf16_f32 v33, v33, v34
	v_cvt_pk_bf16_f32 v34, v40, v37
	v_cvt_pk_bf16_f32 v35, v38, v35
	global_store_dwordx4 v[48:49], v[32:35], off offset:256 nt
	s_nop 1
	v_mul_f32_e32 v34, 0x45800000, v36
	v_cndmask_b32_e32 v34, v36, v34, vcc
	v_pk_mul_f32 v[24:25], v[24:25], v[34:35] op_sel_hi:[1,0]
	v_pk_mul_f32 v[28:29], v[28:29], v[34:35] op_sel_hi:[1,0]
	v_pk_mul_f32 v[26:27], v[26:27], v[34:35] op_sel_hi:[1,0]
	v_max_f32_e32 v24, 0, v24
	v_pk_mul_f32 v[30:31], v[30:31], v[34:35] op_sel_hi:[1,0]
	v_max_f32_e32 v28, 0, v28
	v_mul_f32_e32 v35, v24, v24
	v_max_f32_e32 v24, 0, v29
	v_max_f32_e32 v25, 0, v25
	v_max_f32_e32 v26, 0, v26
	v_mul_f32_e32 v28, v28, v28
	v_mul_f32_e32 v24, v24, v24
	v_mul_f32_e32 v29, v25, v25
	v_max_f32_e32 v25, 0, v30
	v_mul_f32_e32 v30, v26, v26
	v_max_f32_e32 v26, 0, v31
	v_mul_f32_e32 v25, v25, v25
	v_max_f32_e32 v27, 0, v27
	v_mul_f32_e32 v26, v26, v26
	v_cvt_pk_bf16_f32 v24, v28, v24
	v_add_co_u32_e32 v28, vcc, s57, v144
	v_pk_mul_f32 v[16:17], v[16:17], v[34:35] op_sel_hi:[1,0]
	v_mul_f32_e32 v27, v27, v27
	v_cvt_pk_bf16_f32 v25, v25, v26
	v_cvt_pk_bf16_f32 v26, v35, v29
	v_addc_co_u32_e32 v29, vcc, 0, v145, vcc
	v_pk_mul_f32 v[20:21], v[20:21], v[34:35] op_sel_hi:[1,0]
	v_max_f32_e32 v16, 0, v16
	v_cvt_pk_bf16_f32 v27, v30, v27
	global_store_dwordx4 v[28:29], v[24:27], off nt
	v_max_f32_e32 v20, 0, v20
	v_mul_f32_e32 v20, v20, v20
	v_mul_f32_e32 v24, v16, v16
	v_max_f32_e32 v16, 0, v21
	v_mul_f32_e32 v16, v16, v16
	v_cvt_pk_bf16_f32 v16, v20, v16
	v_mul_f32_e32 v20, 0x4b800000, v147
	v_cmp_gt_f32_e32 vcc, s54, v147
	v_pk_mul_f32 v[18:19], v[18:19], v[34:35] op_sel_hi:[1,0]
	v_pk_mul_f32 v[22:23], v[22:23], v[34:35] op_sel_hi:[1,0]
	v_cndmask_b32_e32 v20, v147, v20, vcc
	v_max_f32_e32 v17, 0, v17
	v_max_f32_e32 v18, 0, v18
	v_rsq_f32_e32 v20, v20
	v_mul_f32_e32 v21, v17, v17
	v_max_f32_e32 v17, 0, v22
	v_mul_f32_e32 v22, v18, v18
	v_max_f32_e32 v18, 0, v23
	v_mul_f32_e32 v17, v17, v17
	v_max_f32_e32 v19, 0, v19
	v_mul_f32_e32 v18, v18, v18
	v_lshl_add_u64 v[32:33], v[144:145], 0, s[16:17]
	v_mul_f32_e32 v19, v19, v19
	v_cvt_pk_bf16_f32 v17, v17, v18
	v_cvt_pk_bf16_f32 v18, v24, v21
	v_cvt_pk_bf16_f32 v19, v22, v19
	global_store_dwordx4 v[32:33], v[16:19], off offset:256 nt
	s_nop 1
	v_mul_f32_e32 v18, 0x45800000, v20
	v_cndmask_b32_e32 v18, v20, v18, vcc
	v_pk_mul_f32 v[8:9], v[8:9], v[18:19] op_sel_hi:[1,0]
	v_pk_mul_f32 v[12:13], v[12:13], v[18:19] op_sel_hi:[1,0]
	v_pk_mul_f32 v[10:11], v[10:11], v[18:19] op_sel_hi:[1,0]
	v_max_f32_e32 v8, 0, v8
	v_pk_mul_f32 v[14:15], v[14:15], v[18:19] op_sel_hi:[1,0]
	v_max_f32_e32 v12, 0, v12
	v_mul_f32_e32 v19, v8, v8
	v_max_f32_e32 v8, 0, v13
	v_max_f32_e32 v9, 0, v9
	v_max_f32_e32 v10, 0, v10
	v_mul_f32_e32 v12, v12, v12
	v_mul_f32_e32 v8, v8, v8
	v_mul_f32_e32 v13, v9, v9
	v_max_f32_e32 v9, 0, v14
	v_mul_f32_e32 v14, v10, v10
	v_max_f32_e32 v10, 0, v15
	v_mul_f32_e32 v9, v9, v9
	v_max_f32_e32 v11, 0, v11
	v_mul_f32_e32 v10, v10, v10
	v_cvt_pk_bf16_f32 v8, v12, v8
	v_add_co_u32_e32 v12, vcc, s58, v144
	v_pk_mul_f32 v[2:3], v[2:3], v[18:19] op_sel_hi:[1,0]
	v_pk_mul_f32 v[0:1], v[0:1], v[18:19] op_sel_hi:[1,0]
	v_mul_f32_e32 v11, v11, v11
	v_cvt_pk_bf16_f32 v9, v9, v10
	v_cvt_pk_bf16_f32 v10, v19, v13
	v_addc_co_u32_e32 v13, vcc, 0, v145, vcc
	v_pk_mul_f32 v[6:7], v[6:7], v[18:19] op_sel_hi:[1,0]
	v_pk_mul_f32 v[4:5], v[4:5], v[18:19] op_sel_hi:[1,0]
	v_max_f32_e32 v0, 0, v0
	v_max_f32_e32 v1, 0, v1
	v_max_f32_e32 v2, 0, v2
	v_cvt_pk_bf16_f32 v11, v14, v11
	global_store_dwordx4 v[12:13], v[8:11], off nt
	v_max_f32_e32 v3, 0, v3
	v_lshl_add_u64 v[16:17], v[144:145], 0, s[18:19]
	v_mul_f32_e32 v8, v0, v0
	v_max_f32_e32 v0, 0, v5
	v_mul_f32_e32 v5, v1, v1
	v_max_f32_e32 v1, 0, v6
	v_mul_f32_e32 v6, v2, v2
	v_max_f32_e32 v2, 0, v7
	v_max_f32_e32 v4, 0, v4
	v_mul_f32_e32 v0, v0, v0
	v_mul_f32_e32 v1, v1, v1
	v_mul_f32_e32 v2, v2, v2
	v_mul_f32_e32 v3, v3, v3
	s_and_b64 vcc, exec, s[2:3]
	v_mul_f32_e32 v4, v4, v4
	v_cvt_pk_bf16_f32 v0, v4, v0
	v_cvt_pk_bf16_f32 v1, v1, v2
	v_cvt_pk_bf16_f32 v2, v8, v5
	v_cvt_pk_bf16_f32 v3, v6, v3
	global_store_dwordx4 v[16:17], v[0:3], off offset:256 nt
	s_cbranch_vccz .LBB0_1211
	s_waitcnt vmcnt(0)
	s_cmpk_gt_u32 s33, 0xff
	s_cbranch_scc1 .LBB0_1222
	s_barrier

.LBB0_1264:
	ds_read_b128 v[144:147], v178
	ds_read_b128 v[148:151], v178 offset:1024
	ds_read_b128 v[152:155], v178 offset:2048
	ds_read_b128 v[156:159], v178 offset:3072
	s_add_u32 s34, s30, 0xfff00080
	s_addc_u32 s35, s31, -1
	s_cmp_eq_u32 s58, 60
	s_cselect_b32 s37, s21, s35
	s_cselect_b32 s36, s27, s34
	s_cselect_b32 s35, s19, s57
	s_cselect_b32 s34, s55, s56
	v_lshl_add_u64 v[172:173], s[30:31], 0, v[136:137]
	s_add_i32 m0, s29, 0xc000
	ds_read_b128 v[160:163], v179
	ds_read_b128 v[164:167], v179 offset:1024
	ds_read_b128 v[168:171], v179 offset:2048
	ds_read_b128 v[182:185], v179 offset:3072
	ds_read_b128 v[186:189], v179 offset:4096
	ds_read_b128 v[190:193], v179 offset:5120
	ds_read_b128 v[194:197], v179 offset:6144
	ds_read_b128 v[198:201], v179 offset:7168
	global_load_lds_dwordx4 v[172:173], off
	s_add_i32 m0, s29, 0xe000
	v_lshl_add_u64 v[172:173], s[30:31], 0, v[138:139]
	global_load_lds_dwordx4 v[172:173], off
	s_waitcnt lgkmcnt(8)
	s_setprio 1
	s_barrier
	s_waitcnt lgkmcnt(0)
	v_mfma_f32_16x16x32_bf16 v[124:127], v[144:147], v[160:163], v[124:127]
	v_mfma_f32_16x16x32_bf16 v[120:123], v[152:155], v[160:163], v[120:123]
	v_mfma_f32_16x16x32_bf16 v[108:111], v[144:147], v[168:171], v[108:111]
	v_mfma_f32_16x16x32_bf16 v[104:107], v[152:155], v[168:171], v[104:107]
	v_mfma_f32_16x16x32_bf16 v[96:99], v[144:147], v[186:189], v[96:99]
	v_mfma_f32_16x16x32_bf16 v[88:91], v[152:155], v[186:189], v[88:91]
	v_mfma_f32_16x16x32_bf16 v[80:83], v[144:147], v[194:197], v[80:83]
	v_mfma_f32_16x16x32_bf16 v[72:75], v[152:155], v[194:197], v[72:75]
	v_mfma_f32_16x16x32_bf16 v[124:127], v[148:151], v[164:167], v[124:127]
	v_mfma_f32_16x16x32_bf16 v[120:123], v[156:159], v[164:167], v[120:123]
	v_mfma_f32_16x16x32_bf16 v[108:111], v[148:151], v[182:185], v[108:111]
	v_mfma_f32_16x16x32_bf16 v[104:107], v[156:159], v[182:185], v[104:107]
	v_mfma_f32_16x16x32_bf16 v[96:99], v[148:151], v[190:193], v[96:99]
	v_mfma_f32_16x16x32_bf16 v[88:91], v[156:159], v[190:193], v[88:91]
	v_mfma_f32_16x16x32_bf16 v[80:83], v[148:151], v[198:201], v[80:83]
	v_mfma_f32_16x16x32_bf16 v[72:75], v[156:159], v[198:201], v[72:75]
	s_barrier
	s_setprio 0
	s_add_i32 s59, s53, s40
	v_lshl_add_u64 v[172:173], s[34:35], 0, v[130:131]
	s_mov_b32 m0, s59
	ds_read_b128 v[202:205], v180
	ds_read_b128 v[206:209], v180 offset:1024
	ds_read_b128 v[212:215], v180 offset:2048
	ds_read_b128 v[216:219], v180 offset:3072
	global_load_lds_dwordx4 v[172:173], off
	s_add_i32 m0, s59, 0x2000
	v_lshl_add_u64 v[220:221], s[34:35], 0, v[134:135]
	global_load_lds_dwordx4 v[220:221], off
	s_setprio 1
	s_barrier
	s_waitcnt lgkmcnt(0)
	v_mfma_f32_16x16x32_bf16 v[116:119], v[202:205], v[160:163], v[116:119]
	v_mfma_f32_16x16x32_bf16 v[112:115], v[212:215], v[160:163], v[112:115]
	v_mfma_f32_16x16x32_bf16 v[100:103], v[202:205], v[168:171], v[100:103]
	v_mfma_f32_16x16x32_bf16 v[92:95], v[212:215], v[168:171], v[92:95]
	v_mfma_f32_16x16x32_bf16 v[84:87], v[202:205], v[186:189], v[84:87]
	v_mfma_f32_16x16x32_bf16 v[76:79], v[212:215], v[186:189], v[76:79]
	v_mfma_f32_16x16x32_bf16 v[68:71], v[202:205], v[194:197], v[68:71]
	v_mfma_f32_16x16x32_bf16 v[64:67], v[212:215], v[194:197], v[64:67]
	v_mfma_f32_16x16x32_bf16 v[116:119], v[206:209], v[164:167], v[116:119]
	v_mfma_f32_16x16x32_bf16 v[112:115], v[216:219], v[164:167], v[112:115]
	v_mfma_f32_16x16x32_bf16 v[100:103], v[206:209], v[182:185], v[100:103]
	v_mfma_f32_16x16x32_bf16 v[92:95], v[216:219], v[182:185], v[92:95]
	v_mfma_f32_16x16x32_bf16 v[84:87], v[206:209], v[190:193], v[84:87]
	v_mfma_f32_16x16x32_bf16 v[76:79], v[216:219], v[190:193], v[76:79]
	v_mfma_f32_16x16x32_bf16 v[68:71], v[206:209], v[198:201], v[68:71]
	v_mfma_f32_16x16x32_bf16 v[64:67], v[216:219], v[198:201], v[64:67]
	s_barrier
	s_setprio 0
	s_mov_b32 m0, s29
	v_lshl_add_u64 v[222:223], s[36:37], 0, v[128:129]
	ds_read_b128 v[160:163], v179 offset:16384
	ds_read_b128 v[164:167], v179 offset:17408
	ds_read_b128 v[168:171], v179 offset:18432
	ds_read_b128 v[182:185], v179 offset:19456
	ds_read_b128 v[186:189], v179 offset:20480
	ds_read_b128 v[190:193], v179 offset:21504
	ds_read_b128 v[194:197], v179 offset:22528
	ds_read_b128 v[198:201], v179 offset:23552
	global_load_lds_dwordx4 v[222:223], off
	s_mov_b32 m0, s41
	v_lshl_add_u64 v[224:225], s[36:37], 0, v[132:133]
	global_load_lds_dwordx4 v[224:225], off
	s_setprio 1
	s_barrier
	s_waitcnt lgkmcnt(0)
	v_mfma_f32_16x16x32_bf16 v[60:63], v[144:147], v[160:163], v[60:63]
	v_mfma_f32_16x16x32_bf16 v[56:59], v[152:155], v[160:163], v[56:59]
	v_mfma_f32_16x16x32_bf16 v[44:47], v[144:147], v[168:171], v[44:47]
	v_mfma_f32_16x16x32_bf16 v[40:43], v[152:155], v[168:171], v[40:43]
	v_mfma_f32_16x16x32_bf16 v[32:35], v[144:147], v[186:189], v[32:35]
	v_mfma_f32_16x16x32_bf16 v[24:27], v[152:155], v[186:189], v[24:27]
	v_mfma_f32_16x16x32_bf16 v[16:19], v[144:147], v[194:197], v[16:19]
	v_mfma_f32_16x16x32_bf16 v[8:11], v[152:155], v[194:197], v[8:11]
	v_mfma_f32_16x16x32_bf16 v[60:63], v[148:151], v[164:167], v[60:63]
	v_mfma_f32_16x16x32_bf16 v[56:59], v[156:159], v[164:167], v[56:59]
	v_mfma_f32_16x16x32_bf16 v[44:47], v[148:151], v[182:185], v[44:47]
	v_mfma_f32_16x16x32_bf16 v[40:43], v[156:159], v[182:185], v[40:43]
	v_mfma_f32_16x16x32_bf16 v[32:35], v[148:151], v[190:193], v[32:35]
	v_mfma_f32_16x16x32_bf16 v[24:27], v[156:159], v[190:193], v[24:27]
	v_mfma_f32_16x16x32_bf16 v[16:19], v[148:151], v[198:201], v[16:19]
	v_mfma_f32_16x16x32_bf16 v[8:11], v[156:159], v[198:201], v[8:11]
	s_barrier
	s_setprio 0
	s_add_u32 s60, s34, 0x100000
	s_addc_u32 s61, s35, 0
	s_add_i32 s59, s54, s40
	s_mov_b32 m0, s59
	v_lshl_add_u64 v[144:145], s[60:61], 0, v[130:131]
	global_load_lds_dwordx4 v[144:145], off
	s_add_i32 m0, s59, 0x2000
	v_lshl_add_u64 v[144:145], s[60:61], 0, v[134:135]
	global_load_lds_dwordx4 v[144:145], off
	s_waitcnt vmcnt(6)
	s_setprio 1
	s_barrier
	v_mfma_f32_16x16x32_bf16 v[52:55], v[202:205], v[160:163], v[52:55]
	v_mfma_f32_16x16x32_bf16 v[48:51], v[212:215], v[160:163], v[48:51]
	v_mfma_f32_16x16x32_bf16 v[36:39], v[202:205], v[168:171], v[36:39]
	v_mfma_f32_16x16x32_bf16 v[28:31], v[212:215], v[168:171], v[28:31]
	v_mfma_f32_16x16x32_bf16 v[20:23], v[202:205], v[186:189], v[20:23]
	v_mfma_f32_16x16x32_bf16 v[12:15], v[212:215], v[186:189], v[12:15]
	v_mfma_f32_16x16x32_bf16 v[4:7], v[202:205], v[194:197], v[4:7]
	v_mfma_f32_16x16x32_bf16 v[0:3], v[212:215], v[194:197], v[0:3]
	v_mfma_f32_16x16x32_bf16 v[52:55], v[206:209], v[164:167], v[52:55]
	v_mfma_f32_16x16x32_bf16 v[48:51], v[216:219], v[164:167], v[48:51]
	v_mfma_f32_16x16x32_bf16 v[36:39], v[206:209], v[182:185], v[36:39]
	v_mfma_f32_16x16x32_bf16 v[28:31], v[216:219], v[182:185], v[28:31]
	v_mfma_f32_16x16x32_bf16 v[20:23], v[206:209], v[190:193], v[20:23]
	v_mfma_f32_16x16x32_bf16 v[12:15], v[216:219], v[190:193], v[12:15]
	v_mfma_f32_16x16x32_bf16 v[4:7], v[206:209], v[198:201], v[4:7]
	v_mfma_f32_16x16x32_bf16 v[0:3], v[216:219], v[198:201], v[0:3]
	s_barrier
	s_setprio 0
	s_add_i32 s59, 0, 0x18000
	v_add_u32_e32 v156, s59, v176
	ds_read_b128 v[144:147], v156
	ds_read_b128 v[148:151], v156 offset:1024
	ds_read_b128 v[152:155], v156 offset:2048
	ds_read_b128 v[156:159], v156 offset:3072
	s_add_u32 s36, s36, 0x100000
	s_addc_u32 s37, s37, 0
	s_mov_b32 m0, s42
	v_lshl_add_u64 v[202:203], s[36:37], 0, v[128:129]
	ds_read_b128 v[160:163], v179 offset:32768
	ds_read_b128 v[164:167], v179 offset:33792
	ds_read_b128 v[168:171], v179 offset:34816
	ds_read_b128 v[182:185], v179 offset:35840
	ds_read_b128 v[186:189], v179 offset:36864
	ds_read_b128 v[190:193], v179 offset:37888
	ds_read_b128 v[194:197], v179 offset:38912
	ds_read_b128 v[198:201], v179 offset:39936
	global_load_lds_dwordx4 v[202:203], off
	s_mov_b32 m0, s43
	v_lshl_add_u64 v[202:203], s[36:37], 0, v[132:133]
	global_load_lds_dwordx4 v[202:203], off
	s_waitcnt lgkmcnt(8)
	s_setprio 1
	s_barrier
	s_waitcnt lgkmcnt(0)
	v_mfma_f32_16x16x32_bf16 v[124:127], v[144:147], v[160:163], v[124:127]
	v_mfma_f32_16x16x32_bf16 v[120:123], v[152:155], v[160:163], v[120:123]
	v_mfma_f32_16x16x32_bf16 v[108:111], v[144:147], v[168:171], v[108:111]
	v_mfma_f32_16x16x32_bf16 v[104:107], v[152:155], v[168:171], v[104:107]
	v_mfma_f32_16x16x32_bf16 v[96:99], v[144:147], v[186:189], v[96:99]
	v_mfma_f32_16x16x32_bf16 v[88:91], v[152:155], v[186:189], v[88:91]
	v_mfma_f32_16x16x32_bf16 v[80:83], v[144:147], v[194:197], v[80:83]
	v_mfma_f32_16x16x32_bf16 v[72:75], v[152:155], v[194:197], v[72:75]
	v_mfma_f32_16x16x32_bf16 v[124:127], v[148:151], v[164:167], v[124:127]
	v_mfma_f32_16x16x32_bf16 v[120:123], v[156:159], v[164:167], v[120:123]
	v_mfma_f32_16x16x32_bf16 v[108:111], v[148:151], v[182:185], v[108:111]
	v_mfma_f32_16x16x32_bf16 v[104:107], v[156:159], v[182:185], v[104:107]
	v_mfma_f32_16x16x32_bf16 v[96:99], v[148:151], v[190:193], v[96:99]
	v_mfma_f32_16x16x32_bf16 v[88:91], v[156:159], v[190:193], v[88:91]
	v_mfma_f32_16x16x32_bf16 v[80:83], v[148:151], v[198:201], v[80:83]
	v_mfma_f32_16x16x32_bf16 v[72:75], v[156:159], v[198:201], v[72:75]
	s_barrier
	s_setprio 0
	s_add_i32 s36, 0, 0x1c000
	s_add_i32 s37, s59, s40
	v_add_u32_e32 v181, s36, v176
	v_lshl_add_u64 v[172:173], v[172:173], 0, s[0:1]
	s_mov_b32 m0, s37
	ds_read_b128 v[202:205], v181
	ds_read_b128 v[206:209], v181 offset:1024
	ds_read_b128 v[212:215], v181 offset:2048
	ds_read_b128 v[216:219], v181 offset:3072
	global_load_lds_dwordx4 v[172:173], off
	s_add_i32 m0, s37, 0x2000
	v_lshl_add_u64 v[172:173], v[220:221], 0, s[0:1]
	global_load_lds_dwordx4 v[172:173], off
	s_setprio 1
	s_barrier
	s_waitcnt lgkmcnt(0)
	v_mfma_f32_16x16x32_bf16 v[116:119], v[202:205], v[160:163], v[116:119]
	v_mfma_f32_16x16x32_bf16 v[112:115], v[212:215], v[160:163], v[112:115]
	v_mfma_f32_16x16x32_bf16 v[100:103], v[202:205], v[168:171], v[100:103]
	v_mfma_f32_16x16x32_bf16 v[92:95], v[212:215], v[168:171], v[92:95]
	v_mfma_f32_16x16x32_bf16 v[84:87], v[202:205], v[186:189], v[84:87]
	v_mfma_f32_16x16x32_bf16 v[76:79], v[212:215], v[186:189], v[76:79]
	v_mfma_f32_16x16x32_bf16 v[68:71], v[202:205], v[194:197], v[68:71]
	v_mfma_f32_16x16x32_bf16 v[64:67], v[212:215], v[194:197], v[64:67]
	v_mfma_f32_16x16x32_bf16 v[116:119], v[206:209], v[164:167], v[116:119]
	v_mfma_f32_16x16x32_bf16 v[112:115], v[216:219], v[164:167], v[112:115]
	v_mfma_f32_16x16x32_bf16 v[100:103], v[206:209], v[182:185], v[100:103]
	v_mfma_f32_16x16x32_bf16 v[92:95], v[216:219], v[182:185], v[92:95]
	v_mfma_f32_16x16x32_bf16 v[84:87], v[206:209], v[190:193], v[84:87]
	v_mfma_f32_16x16x32_bf16 v[76:79], v[216:219], v[190:193], v[76:79]
	v_mfma_f32_16x16x32_bf16 v[68:71], v[206:209], v[198:201], v[68:71]
	v_mfma_f32_16x16x32_bf16 v[64:67], v[216:219], v[198:201], v[64:67]
	s_barrier
	s_setprio 0
	s_mov_b32 m0, s49
	v_lshl_add_u64 v[172:173], v[222:223], 0, s[0:1]
	ds_read_b128 v[160:163], v179 offset:49152
	ds_read_b128 v[164:167], v179 offset:50176
	ds_read_b128 v[168:171], v179 offset:51200
	ds_read_b128 v[182:185], v179 offset:52224
	ds_read_b128 v[186:189], v179 offset:53248
	ds_read_b128 v[190:193], v179 offset:54272
	ds_read_b128 v[194:197], v179 offset:55296
	ds_read_b128 v[198:201], v179 offset:56320
	global_load_lds_dwordx4 v[172:173], off
	s_mov_b32 m0, s50
	v_lshl_add_u64 v[172:173], v[224:225], 0, s[0:1]
	global_load_lds_dwordx4 v[172:173], off
	s_setprio 1
	s_barrier
	s_waitcnt lgkmcnt(0)
	v_mfma_f32_16x16x32_bf16 v[60:63], v[144:147], v[160:163], v[60:63]
	v_mfma_f32_16x16x32_bf16 v[56:59], v[152:155], v[160:163], v[56:59]
	v_mfma_f32_16x16x32_bf16 v[44:47], v[144:147], v[168:171], v[44:47]
	v_mfma_f32_16x16x32_bf16 v[40:43], v[152:155], v[168:171], v[40:43]
	v_mfma_f32_16x16x32_bf16 v[32:35], v[144:147], v[186:189], v[32:35]
	v_mfma_f32_16x16x32_bf16 v[24:27], v[152:155], v[186:189], v[24:27]
	v_mfma_f32_16x16x32_bf16 v[16:19], v[144:147], v[194:197], v[16:19]
	v_mfma_f32_16x16x32_bf16 v[8:11], v[152:155], v[194:197], v[8:11]
	v_mfma_f32_16x16x32_bf16 v[60:63], v[148:151], v[164:167], v[60:63]
	v_mfma_f32_16x16x32_bf16 v[56:59], v[156:159], v[164:167], v[56:59]
	v_mfma_f32_16x16x32_bf16 v[44:47], v[148:151], v[182:185], v[44:47]
	v_mfma_f32_16x16x32_bf16 v[40:43], v[156:159], v[182:185], v[40:43]
	v_mfma_f32_16x16x32_bf16 v[32:35], v[148:151], v[190:193], v[32:35]
	v_mfma_f32_16x16x32_bf16 v[24:27], v[156:159], v[190:193], v[24:27]
	v_mfma_f32_16x16x32_bf16 v[16:19], v[148:151], v[198:201], v[16:19]
	v_mfma_f32_16x16x32_bf16 v[8:11], v[156:159], v[198:201], v[8:11]
	s_barrier
	s_setprio 0
	s_add_u32 s34, s34, 0x100080
	s_addc_u32 s35, s35, 0
	s_add_i32 s36, s36, s40
	s_mov_b32 m0, s36
	v_lshl_add_u64 v[144:145], s[34:35], 0, v[130:131]
	global_load_lds_dwordx4 v[144:145], off
	s_add_i32 m0, s36, 0x2000
	v_lshl_add_u64 v[144:145], s[34:35], 0, v[134:135]
	global_load_lds_dwordx4 v[144:145], off
	s_waitcnt vmcnt(6)
	s_setprio 1
	s_barrier
	v_mfma_f32_16x16x32_bf16 v[52:55], v[202:205], v[160:163], v[52:55]
	v_mfma_f32_16x16x32_bf16 v[48:51], v[212:215], v[160:163], v[48:51]
	v_mfma_f32_16x16x32_bf16 v[36:39], v[202:205], v[168:171], v[36:39]
	v_mfma_f32_16x16x32_bf16 v[28:31], v[212:215], v[168:171], v[28:31]
	v_mfma_f32_16x16x32_bf16 v[20:23], v[202:205], v[186:189], v[20:23]
	v_mfma_f32_16x16x32_bf16 v[12:15], v[212:215], v[186:189], v[12:15]
	v_mfma_f32_16x16x32_bf16 v[4:7], v[202:205], v[194:197], v[4:7]
	v_mfma_f32_16x16x32_bf16 v[0:3], v[212:215], v[194:197], v[0:3]
	v_mfma_f32_16x16x32_bf16 v[52:55], v[206:209], v[164:167], v[52:55]
	v_mfma_f32_16x16x32_bf16 v[48:51], v[216:219], v[164:167], v[48:51]
	v_mfma_f32_16x16x32_bf16 v[36:39], v[206:209], v[182:185], v[36:39]
	v_mfma_f32_16x16x32_bf16 v[28:31], v[216:219], v[182:185], v[28:31]
	v_mfma_f32_16x16x32_bf16 v[20:23], v[206:209], v[190:193], v[20:23]
	v_mfma_f32_16x16x32_bf16 v[12:15], v[216:219], v[190:193], v[12:15]
	v_mfma_f32_16x16x32_bf16 v[4:7], v[206:209], v[198:201], v[4:7]
	v_mfma_f32_16x16x32_bf16 v[0:3], v[216:219], v[198:201], v[0:3]
	s_barrier
	s_setprio 0
	s_add_i32 s58, s58, 2
	s_add_u32 s30, s30, 0x100
	s_addc_u32 s31, s31, 0
	s_add_u32 s56, s56, 0x100
	s_addc_u32 s57, s57, 0
	s_cmp_gt_u32 s58, 61
	s_cbranch_scc0 .LBB0_1264
	v_lshl_or_b32 v144, s28, 8, v177
	v_lshl_add_u32 v150, s26, 8, v175
	v_ashrrev_i32_e32 v145, 31, v144
	v_ashrrev_i32_e32 v151, 31, v150
	v_lshlrev_b64 v[144:145], 1, v[144:145]
	v_lshl_add_u64 v[146:147], s[90:91], 0, v[144:145]
	v_lshlrev_b64 v[148:149], 11, v[150:151]
	v_lshl_add_u64 v[152:153], v[146:147], 0, v[148:149]
	global_load_dwordx4 v[156:159], v[152:153], off
	global_load_dwordx4 v[160:163], v[152:153], off offset:256
	v_or_b32_e32 v152, 16, v150
	v_ashrrev_i32_e32 v153, 31, v152
	v_lshlrev_b64 v[170:171], 11, v[152:153]
	v_lshl_add_u64 v[152:153], v[146:147], 0, v[170:171]
	global_load_dwordx4 v[164:167], v[152:153], off
	global_load_dwordx4 v[182:185], v[152:153], off offset:256
	v_or_b32_e32 v152, 32, v150
	v_ashrrev_i32_e32 v153, 31, v152
	v_lshlrev_b64 v[154:155], 11, v[152:153]
	v_lshl_add_u64 v[152:153], v[146:147], 0, v[154:155]
	global_load_dwordx4 v[186:189], v[152:153], off
	global_load_dwordx4 v[190:193], v[152:153], off offset:256
	v_or_b32_e32 v152, 48, v150
	v_ashrrev_i32_e32 v153, 31, v152
	v_lshlrev_b64 v[152:153], 11, v[152:153]
	v_lshl_add_u64 v[168:169], v[146:147], 0, v[152:153]
	global_load_dwordx4 v[194:197], v[168:169], off
	global_load_dwordx4 v[198:201], v[168:169], off offset:256
	s_waitcnt vmcnt(0)
	v_lshlrev_b32_e32 v202, 16, v156
	v_and_b32_e32 v203, 0xffff0000, v156
	v_lshlrev_b32_e32 v204, 16, v157
	v_and_b32_e32 v205, 0xffff0000, v157
	v_lshlrev_b32_e32 v206, 16, v158
	v_and_b32_e32 v207, 0xffff0000, v158
	v_lshlrev_b32_e32 v208, 16, v159
	v_and_b32_e32 v209, 0xffff0000, v159
	v_pk_add_f32 v[126:127], v[126:127], v[204:205]
	v_pk_add_f32 v[124:125], v[124:125], v[202:203]
	v_lshlrev_b32_e32 v224, 16, v166
	v_and_b32_e32 v225, 0xffff0000, v166
	v_lshlrev_b32_e32 v226, 16, v167
	v_and_b32_e32 v227, 0xffff0000, v167
	v_lshlrev_b32_e32 v212, 16, v160
	v_lshlrev_b32_e32 v166, 16, v194
	v_and_b32_e32 v167, 0xffff0000, v194
	v_lshlrev_b32_e32 v172, 16, v195
	v_and_b32_e32 v173, 0xffff0000, v195
	v_pk_add_f32 v[194:195], v[122:123], v[208:209]
	v_pk_add_f32 v[122:123], v[120:121], v[206:207]
	v_mul_f32_e32 v120, v125, v125
	v_mul_f32_e32 v121, v127, v127
	v_fmac_f32_e32 v120, v124, v124
	v_fmac_f32_e32 v121, v126, v126
	v_add_f32_e32 v120, v120, v121
	v_mul_f32_e32 v121, v123, v123
	v_fmac_f32_e32 v121, v122, v122
	v_add_f32_e32 v120, v121, v120
	v_mul_f32_e32 v121, v195, v195
	v_fmac_f32_e32 v121, v194, v194
	v_and_b32_e32 v213, 0xffff0000, v160
	v_lshlrev_b32_e32 v214, 16, v161
	v_and_b32_e32 v215, 0xffff0000, v161
	v_add_f32_e32 v181, v121, v120
	v_cvt_pk_bf16_f32 v120, v124, v125
	v_lshl_add_u64 v[124:125], s[10:11], 0, v[148:149]
	v_lshlrev_b32_e32 v216, 16, v162
	v_and_b32_e32 v217, 0xffff0000, v162
	v_lshlrev_b32_e32 v218, 16, v163
	v_and_b32_e32 v219, 0xffff0000, v163
	v_cvt_pk_bf16_f32 v121, v126, v127
	v_lshl_add_u64 v[124:125], v[124:125], 0, v[144:145]
	v_pk_add_f32 v[118:119], v[118:119], v[214:215]
	v_pk_add_f32 v[116:117], v[116:117], v[212:213]
	v_cvt_pk_bf16_f32 v122, v122, v123
	v_cvt_pk_bf16_f32 v123, v194, v195
	global_store_dwordx4 v[124:125], v[120:123], off
	v_lshlrev_b32_e32 v220, 16, v164
	v_and_b32_e32 v221, 0xffff0000, v164
	v_pk_add_f32 v[120:121], v[114:115], v[218:219]
	v_pk_add_f32 v[114:115], v[112:113], v[216:217]
	v_mul_f32_e32 v112, v117, v117
	v_mul_f32_e32 v113, v119, v119
	v_fmac_f32_e32 v112, v116, v116
	v_fmac_f32_e32 v113, v118, v118
	v_add_f32_e32 v112, v112, v113
	v_mul_f32_e32 v113, v115, v115
	v_fmac_f32_e32 v113, v114, v114
	v_add_f32_e32 v112, v113, v112
	v_mul_f32_e32 v113, v121, v121
	v_fmac_f32_e32 v113, v120, v120
	v_add_f32_e32 v112, v113, v112
	v_lshlrev_b32_e32 v222, 16, v165
	v_and_b32_e32 v223, 0xffff0000, v165
	v_add_f32_e32 v126, v181, v112
	v_cvt_pk_bf16_f32 v112, v116, v117
	v_cvt_pk_bf16_f32 v113, v118, v119
	v_lshl_add_u64 v[116:117], s[10:11], 0, v[170:171]
	v_lshlrev_b32_e32 v230, 16, v184
	v_and_b32_e32 v231, 0xffff0000, v184
	v_lshlrev_b32_e32 v232, 16, v186
	v_and_b32_e32 v233, 0xffff0000, v186
	v_lshlrev_b32_e32 v186, 16, v187
	v_and_b32_e32 v187, 0xffff0000, v187
	v_cvt_pk_bf16_f32 v114, v114, v115
	v_cvt_pk_bf16_f32 v115, v120, v121
	global_store_dwordx4 v[124:125], v[112:115], off offset:256
	v_pk_add_f32 v[110:111], v[110:111], v[222:223]
	v_pk_add_f32 v[108:109], v[108:109], v[220:221]
	v_lshl_add_u64 v[118:119], v[116:117], 0, v[144:145]
	v_cvt_pk_bf16_f32 v112, v108, v109
	v_cvt_pk_bf16_f32 v113, v110, v111
	v_lshlrev_b32_e32 v228, 16, v182
	v_and_b32_e32 v229, 0xffff0000, v182
	v_lshlrev_b32_e32 v182, 16, v183
	v_and_b32_e32 v183, 0xffff0000, v183
	v_lshlrev_b32_e32 v184, 16, v185
	v_and_b32_e32 v185, 0xffff0000, v185
	v_lshlrev_b32_e32 v238, 16, v192
	v_and_b32_e32 v239, 0xffff0000, v192
	v_pk_add_f32 v[106:107], v[106:107], v[226:227]
	v_pk_add_f32 v[104:105], v[104:105], v[224:225]
	v_lshlrev_b32_e32 v156, 16, v200
	v_cvt_pk_bf16_f32 v114, v104, v105
	v_cvt_pk_bf16_f32 v115, v106, v107
	global_store_dwordx4 v[118:119], v[112:115], off
	v_and_b32_e32 v157, 0xffff0000, v200
	v_pk_add_f32 v[102:103], v[102:103], v[182:183]
	v_pk_add_f32 v[112:113], v[92:93], v[230:231]
	v_pk_add_f32 v[92:93], v[98:99], v[186:187]
	v_lshl_add_u64 v[98:99], s[10:11], 0, v[154:155]
	v_pk_add_f32 v[100:101], v[100:101], v[228:229]
	v_pk_add_f32 v[94:95], v[94:95], v[184:185]
	v_cvt_pk_bf16_f32 v114, v100, v101
	v_cvt_pk_bf16_f32 v115, v102, v103
	v_cvt_pk_bf16_f32 v116, v112, v113
	v_lshlrev_b32_e32 v234, 16, v188
	v_cvt_pk_bf16_f32 v117, v94, v95
	global_store_dwordx4 v[118:119], v[114:117], off offset:256
	v_lshl_add_u64 v[118:119], v[98:99], 0, v[144:145]
	v_pk_add_f32 v[98:99], v[76:77], v[238:239]
	v_pk_add_f32 v[76:77], v[82:83], v[172:173]
	v_lshl_add_u64 v[82:83], s[10:11], 0, v[152:153]
	v_lshl_add_u64 v[122:123], v[82:83], 0, v[144:145]
	v_pk_add_f32 v[82:83], v[64:65], v[156:157]
	v_and_b32_e32 v65, 64, v174
	v_and_b32_e32 v235, 0xffff0000, v188
	v_lshlrev_b32_e32 v188, 16, v189
	v_and_b32_e32 v189, 0xffff0000, v189
	v_lshlrev_b32_e32 v236, 16, v190
	v_and_b32_e32 v237, 0xffff0000, v190
	v_pk_add_f32 v[96:97], v[96:97], v[232:233]
	v_xor_b32_e32 v64, 16, v174
	v_cvt_pk_bf16_f32 v114, v96, v97
	v_add_u32_e32 v65, 64, v65
	v_lshlrev_b32_e32 v190, 16, v191
	v_and_b32_e32 v191, 0xffff0000, v191
	v_lshlrev_b32_e32 v192, 16, v193
	v_and_b32_e32 v193, 0xffff0000, v193
	v_pk_add_f32 v[90:91], v[90:91], v[188:189]
	v_pk_add_f32 v[88:89], v[88:89], v[234:235]
	v_cvt_pk_bf16_f32 v115, v92, v93
	v_pk_add_f32 v[84:85], v[84:85], v[236:237]
	v_cvt_pk_bf16_f32 v116, v88, v89
	v_cvt_pk_bf16_f32 v117, v90, v91
	global_store_dwordx4 v[118:119], v[114:117], off
	v_cmp_lt_i32_e32 vcc, v64, v65
	v_lshlrev_b32_e32 v164, 16, v196
	v_cvt_pk_bf16_f32 v114, v84, v85
	v_and_b32_e32 v165, 0xffff0000, v196
	v_lshlrev_b32_e32 v168, 16, v197
	v_and_b32_e32 v169, 0xffff0000, v197
	v_pk_add_f32 v[86:87], v[86:87], v[190:191]
	v_pk_add_f32 v[78:79], v[78:79], v[192:193]
	v_cvt_pk_bf16_f32 v115, v86, v87
	v_cvt_pk_bf16_f32 v116, v98, v99
	v_pk_add_f32 v[80:81], v[80:81], v[166:167]
	v_cvt_pk_bf16_f32 v117, v78, v79
	global_store_dwordx4 v[118:119], v[114:117], off offset:256
	v_cndmask_b32_e32 v64, v174, v64, vcc
	v_pk_add_f32 v[74:75], v[74:75], v[168:169]
	v_cvt_pk_bf16_f32 v114, v80, v81
	v_pk_add_f32 v[72:73], v[72:73], v[164:165]
	v_cvt_pk_bf16_f32 v115, v76, v77
	v_lshlrev_b32_e32 v158, 16, v198
	v_cvt_pk_bf16_f32 v116, v72, v73
	v_cvt_pk_bf16_f32 v117, v74, v75
	global_store_dwordx4 v[122:123], v[114:117], off
	v_and_b32_e32 v159, 0xffff0000, v198
	v_lshlrev_b32_e32 v162, 16, v199
	v_lshlrev_b32_e32 v114, 2, v64
	ds_bpermute_b32 v64, v114, v126
	v_xor_b32_e32 v115, 32, v174
	v_cmp_lt_i32_e32 vcc, v115, v65
	v_and_b32_e32 v163, 0xffff0000, v199
	v_lshlrev_b32_e32 v160, 16, v201
	v_cndmask_b32_e32 v65, v174, v115, vcc
	v_lshlrev_b32_e32 v115, 2, v65
	s_waitcnt lgkmcnt(0)
	v_add_f32_e32 v116, v126, v64
	ds_bpermute_b32 v117, v115, v116
	v_and_b32_e32 v161, 0xffff0000, v201
	v_pk_add_f32 v[70:71], v[70:71], v[162:163]
	v_pk_add_f32 v[68:69], v[68:69], v[158:159]
	v_pk_add_f32 v[66:67], v[66:67], v[160:161]
	v_lshl_add_u64 v[64:65], v[150:151], 2, s[6:7]
	v_cvt_pk_bf16_f32 v118, v68, v69
	v_cvt_pk_bf16_f32 v119, v70, v71
	v_cvt_pk_bf16_f32 v120, v82, v83
	v_cvt_pk_bf16_f32 v121, v66, v67
	global_store_dwordx4 v[122:123], v[118:121], off offset:256
	s_and_saveexec_b64 s[26:27], s[2:3]
	s_cbranch_execz .LBB0_1267
	s_waitcnt lgkmcnt(0)
	v_add_f32_e32 v116, v116, v117
	global_atomic_add_f32 v[64:65], v116, off
